# speedup vs baseline: 1.0080x; 1.0080x over previous
.LBB0_615:
	s_andn2_saveexec_b64 s[0:1], s[0:1]
	v_mul_f32_e32 v7, v6, v6
	v_fmamk_f32 v8, v7, 0xba1345e1, v157
	v_fmaak_f32 v8, v7, v8, 0xbcdac9b8
	v_fmaak_f32 v8, v7, v8, 0x3de703be
	v_fmaak_f32 v8, v7, v8, 0xbec09330
	v_fmaak_f32 v7, v7, v8, 0x3e0375d0
	v_fma_f32 v7, |v6|, v7, |v6|
	s_or_b64 exec, exec, s[0:1]
	v_readlane_b32 s48, v254, 40
	v_lshlrev_b64 v[8:9], 7, v[108:109]
	v_readlane_b32 s58, v254, 50
	v_readlane_b32 s59, v254, 51
	v_lshl_add_u64 v[8:9], v[8:9], 2, v[138:139]
	v_bfi_b32 v3, s78, v4, v3
	v_lshl_add_u64 v[10:11], v[54:55], 2, s[58:59]
	v_lshl_add_u64 v[12:13], v[56:57], 2, s[58:59]
	global_load_dwordx2 v[8:9], v[8:9], off
	s_nop 0
	global_load_dword v10, v[10:11], off
	s_nop 0
	global_load_dword v11, v[12:13], off
	v_mul_f32_e32 v4, 0.5, v5
	v_bfi_b32 v5, s78, v7, v6
	v_mul_f32_e32 v2, 0.5, v2
	v_add_f32_e32 v3, 1.0, v3
	v_add_f32_e32 v5, 1.0, v5
	v_mul_f32_e32 v2, v2, v3
	v_mul_f32_e32 v3, v4, v5
	v_mov_b32_e32 v92, 0
	s_mov_b32 s0, 0
	v_mov_b32_e32 v93, v92
	v_mov_b32_e32 v90, v92
	v_mov_b32_e32 v91, v92
	v_mov_b32_e32 v86, v92
	v_mov_b32_e32 v87, v92
	v_mov_b32_e32 v84, v92
	v_mov_b32_e32 v85, v92
	v_mov_b32_e32 v80, v92
	v_mov_b32_e32 v81, v92
	v_mov_b32_e32 v78, v92
	v_mov_b32_e32 v79, v92
	v_mov_b32_e32 v70, v92
	v_mov_b32_e32 v71, v92
	v_mov_b32_e32 v62, v92
	v_mov_b32_e32 v63, v92
	v_readlane_b32 s49, v254, 41
	v_readlane_b32 s50, v254, 42
	v_readlane_b32 s51, v254, 43
	v_readlane_b32 s52, v254, 44
	v_readlane_b32 s53, v254, 45
	v_readlane_b32 s54, v254, 46
	v_readlane_b32 s55, v254, 47
	v_readlane_b32 s56, v254, 48
	v_readlane_b32 s57, v254, 49
	v_readlane_b32 s60, v254, 52
	v_readlane_b32 s61, v254, 53
	v_readlane_b32 s62, v254, 54
	v_readlane_b32 s63, v254, 55
	s_waitcnt vmcnt(2)
	v_pk_mul_f32 v[2:3], v[2:3], v[8:9]
	s_waitcnt vmcnt(0)
	v_pk_mul_f32 v[24:25], v[2:3], v[10:11]
	ds_write_b64 v149, v[24:25] offset:512
	v_lshl_add_u64 v[244:245], v[144:145], 2, v[136:137]
	global_load_dwordx4 v[228:231], v[244:245], off
	global_load_dwordx4 v[232:235], v[244:245], off offset:16
	global_load_dwordx4 v[236:239], v[244:245], off offset:32
	global_load_dwordx4 v[240:243], v[244:245], off offset:48
	v_add_u32_e32 v34, s2, v108
	v_min_u32_e32 v34, 0x7fff, v34
	v_mov_b32_e32 v35, 0
	v_lshlrev_b64 v[36:37], 9, v[34:35]
	v_lshlrev_b64 v[38:39], 10, v[34:35]
	v_lshlrev_b64 v[40:41], 2, v[34:35]
	v_lshl_add_u64 v[36:37], v[132:133], 0, v[36:37]
	v_lshl_add_u64 v[38:39], v[134:135], 0, v[38:39]
	v_lshl_add_u64 v[42:43], s[68:69], 0, v[40:41]
	v_lshl_add_u64 v[40:41], s[70:71], 0, v[40:41]
	global_load_dword v246, v[36:37], off
	global_load_dword v247, v[36:37], off offset:256
	global_load_dwordx4 v[248:251], v[38:39], off
	global_load_dword v252, v[42:43], off
	global_load_dword v253, v[40:41], off
	s_mov_b32 s0, 0x0f0f0f0f
	s_mov_b32 s1, 0xf0f0f0f0
	v_readfirstlane_b32 s38, v114
	v_readfirstlane_b32 s39, v115
	v_subrev_u32_e32 v100, s38, v114
	ds_read_b128 v[72:75], v1 offset:0
	ds_read_b128 v[94:97], v1 offset:16
	ds_read_b128 v[50:53], v1 offset:32
	ds_read_b128 v[54:57], v1 offset:48
	s_waitcnt lgkmcnt(2)
	v_lshl_add_u32 v72, v72, 9, v100
	v_lshl_add_u32 v73, v73, 9, v100
	v_lshl_add_u32 v74, v74, 9, v100
	v_lshl_add_u32 v75, v75, 9, v100
	v_lshl_add_u32 v94, v94, 9, v100
	v_lshl_add_u32 v95, v95, 9, v100
	v_lshl_add_u32 v96, v96, 9, v100
	v_lshl_add_u32 v97, v97, 9, v100
	global_load_dwordx2 v[164:165], v72, s[38:39]
	global_load_dwordx2 v[166:167], v73, s[38:39]
	global_load_dwordx2 v[168:169], v74, s[38:39]
	global_load_dwordx2 v[170:171], v75, s[38:39]
	global_load_dwordx2 v[172:173], v94, s[38:39]
	global_load_dwordx2 v[174:175], v95, s[38:39]
	global_load_dwordx2 v[176:177], v96, s[38:39]
	global_load_dwordx2 v[178:179], v97, s[38:39]
	ds_read_b128 v[72:75], v1 offset:64
	ds_read_b128 v[94:97], v1 offset:80
	s_waitcnt lgkmcnt(2)
	v_lshl_add_u32 v50, v50, 9, v100
	v_lshl_add_u32 v51, v51, 9, v100
	v_lshl_add_u32 v52, v52, 9, v100
	v_lshl_add_u32 v53, v53, 9, v100
	v_lshl_add_u32 v54, v54, 9, v100
	v_lshl_add_u32 v55, v55, 9, v100
	v_lshl_add_u32 v56, v56, 9, v100
	v_lshl_add_u32 v57, v57, 9, v100
	global_load_dwordx2 v[180:181], v50, s[38:39]
	global_load_dwordx2 v[182:183], v51, s[38:39]
	global_load_dwordx2 v[184:185], v52, s[38:39]
	global_load_dwordx2 v[186:187], v53, s[38:39]
	global_load_dwordx2 v[188:189], v54, s[38:39]
	global_load_dwordx2 v[190:191], v55, s[38:39]
	global_load_dwordx2 v[192:193], v56, s[38:39]
	global_load_dwordx2 v[194:195], v57, s[38:39]
	ds_read_b128 v[50:53], v1 offset:96
	ds_read_b128 v[54:57], v1 offset:112
	s_waitcnt lgkmcnt(2)
	v_lshl_add_u32 v72, v72, 9, v100
	v_lshl_add_u32 v73, v73, 9, v100
	v_lshl_add_u32 v74, v74, 9, v100
	v_lshl_add_u32 v75, v75, 9, v100
	v_lshl_add_u32 v94, v94, 9, v100
	v_lshl_add_u32 v95, v95, 9, v100
	v_lshl_add_u32 v96, v96, 9, v100
	v_lshl_add_u32 v97, v97, 9, v100
	global_load_dwordx2 v[196:197], v72, s[38:39]
	global_load_dwordx2 v[198:199], v73, s[38:39]
	global_load_dwordx2 v[200:201], v74, s[38:39]
	global_load_dwordx2 v[202:203], v75, s[38:39]
	global_load_dwordx2 v[204:205], v94, s[38:39]
	global_load_dwordx2 v[206:207], v95, s[38:39]
	global_load_dwordx2 v[208:209], v96, s[38:39]
	global_load_dwordx2 v[210:211], v97, s[38:39]
	ds_read_b128 v[72:75], v1 offset:128
	ds_read_b128 v[94:97], v1 offset:144
	s_waitcnt lgkmcnt(2)
	v_lshl_add_u32 v50, v50, 9, v100
	v_lshl_add_u32 v51, v51, 9, v100
	v_lshl_add_u32 v52, v52, 9, v100
	v_lshl_add_u32 v53, v53, 9, v100
	v_lshl_add_u32 v54, v54, 9, v100
	v_lshl_add_u32 v55, v55, 9, v100
	v_lshl_add_u32 v56, v56, 9, v100
	v_lshl_add_u32 v57, v57, 9, v100
	global_load_dwordx2 v[212:213], v50, s[38:39]
	global_load_dwordx2 v[214:215], v51, s[38:39]
	global_load_dwordx2 v[216:217], v52, s[38:39]
	global_load_dwordx2 v[218:219], v53, s[38:39]
	global_load_dwordx2 v[220:221], v54, s[38:39]
	global_load_dwordx2 v[222:223], v55, s[38:39]
	global_load_dwordx2 v[224:225], v56, s[38:39]
	global_load_dwordx2 v[226:227], v57, s[38:39]
	s_waitcnt lgkmcnt(0)
	v_lshl_add_u32 v72, v72, 9, v100
	v_lshl_add_u32 v73, v73, 9, v100
	v_lshl_add_u32 v74, v74, 9, v100
	v_lshl_add_u32 v75, v75, 9, v100
	v_lshl_add_u32 v94, v94, 9, v100
	v_lshl_add_u32 v95, v95, 9, v100
	v_lshl_add_u32 v96, v96, 9, v100
	v_lshl_add_u32 v97, v97, 9, v100
	global_load_dwordx2 v[2:3], v72, s[38:39]
	global_load_dwordx2 v[4:5], v73, s[38:39]
	global_load_dwordx2 v[6:7], v74, s[38:39]
	global_load_dwordx2 v[8:9], v75, s[38:39]
	global_load_dwordx2 v[10:11], v94, s[38:39]
	global_load_dwordx2 v[12:13], v95, s[38:39]
	global_load_dwordx2 v[14:15], v96, s[38:39]
	global_load_dwordx2 v[16:17], v97, s[38:39]
	v_add_f32_e32 v146, v24, v25
	ds_bpermute_b32 v147, v150, v146
	s_waitcnt lgkmcnt(0)
	v_add_f32_e32 v146, v146, v147
	ds_bpermute_b32 v147, v151, v146
	s_waitcnt lgkmcnt(0)
	v_add_f32_e32 v146, v146, v147
	ds_bpermute_b32 v147, v152, v146
	s_waitcnt lgkmcnt(0)
	v_add_f32_e32 v146, v146, v147
	ds_bpermute_b32 v147, v153, v146
	s_waitcnt lgkmcnt(0)
	v_add_f32_e32 v146, v146, v147
	ds_bpermute_b32 v147, v154, v146
	s_waitcnt lgkmcnt(0)
	v_add_f32_e32 v101, v146, v147
	ds_bpermute_b32 v162, v155, v101
	ds_read_b128 v[72:75], v1 offset:160
	ds_read_b128 v[94:97], v1 offset:176
	ds_read_b128 v[34:37], v1 offset:512
	ds_read_b128 v[38:41], v1 offset:528
	s_waitcnt lgkmcnt(0)
	v_lshl_add_u32 v72, v72, 9, v100
	v_lshl_add_u32 v73, v73, 9, v100
	v_lshl_add_u32 v74, v74, 9, v100
	v_lshl_add_u32 v75, v75, 9, v100
	v_lshl_add_u32 v94, v94, 9, v100
	v_lshl_add_u32 v95, v95, 9, v100
	v_lshl_add_u32 v96, v96, 9, v100
	v_lshl_add_u32 v97, v97, 9, v100
	global_load_dwordx2 v[18:19], v72, s[38:39]
	global_load_dwordx2 v[20:21], v73, s[38:39]
	global_load_dwordx2 v[22:23], v74, s[38:39]
	global_load_dwordx2 v[24:25], v75, s[38:39]
	global_load_dwordx2 v[26:27], v94, s[38:39]
	global_load_dwordx2 v[28:29], v95, s[38:39]
	global_load_dwordx2 v[30:31], v96, s[38:39]
	global_load_dwordx2 v[32:33], v97, s[38:39]
	ds_read_b128 v[72:75], v1 offset:192
	ds_read_b128 v[94:97], v1 offset:208
	ds_read_b128 v[50:53], v1 offset:544
	ds_read_b128 v[54:57], v1 offset:560
	s_waitcnt vmcnt(40)
	v_and_b32_e32 v68, s0, v164
	v_and_b32_e32 v76, s0, v165
	v_cvt_f32_ubyte0_e32 v98, v68
	v_cvt_f32_ubyte1_e32 v99, v68
	v_cvt_f32_ubyte2_e32 v102, v68
	v_cvt_f32_ubyte3_e32 v103, v68
	v_pk_fma_f32 v[92:93], v[34:35], v[98:99], v[92:93] op_sel_hi:[0,1,1]
	v_cvt_f32_ubyte0_e32 v104, v164
	v_cvt_f32_ubyte1_e32 v105, v164
	v_pk_fma_f32 v[90:91], v[34:35], v[102:103], v[90:91] op_sel_hi:[0,1,1]
	v_cvt_f32_ubyte2_e32 v146, v164
	v_cvt_f32_ubyte3_e32 v147, v164
	v_pk_fma_f32 v[86:87], v[34:35], v[104:105], v[86:87] op_sel_hi:[0,1,1]
	v_cvt_f32_ubyte0_e32 v98, v76
	v_cvt_f32_ubyte1_e32 v99, v76
	v_pk_fma_f32 v[84:85], v[34:35], v[146:147], v[84:85] op_sel_hi:[0,1,1]
	v_and_b32_e32 v82, s0, v166
	v_and_b32_e32 v88, s0, v167
	v_cvt_f32_ubyte2_e32 v102, v76
	v_cvt_f32_ubyte3_e32 v103, v76
	v_pk_fma_f32 v[80:81], v[34:35], v[98:99], v[80:81] op_sel_hi:[0,1,1]
	v_cvt_f32_ubyte0_e32 v104, v165
	v_cvt_f32_ubyte1_e32 v105, v165
	v_pk_fma_f32 v[78:79], v[34:35], v[102:103], v[78:79] op_sel_hi:[0,1,1]
	v_cvt_f32_ubyte2_e32 v146, v165
	v_cvt_f32_ubyte3_e32 v147, v165
	v_pk_fma_f32 v[70:71], v[34:35], v[104:105], v[70:71] op_sel_hi:[0,1,1]
	v_cvt_f32_ubyte0_e32 v98, v82
	v_cvt_f32_ubyte1_e32 v99, v82
	v_pk_fma_f32 v[62:63], v[34:35], v[146:147], v[62:63] op_sel_hi:[0,1,1]
	v_cvt_f32_ubyte2_e32 v102, v82
	v_cvt_f32_ubyte3_e32 v103, v82
	v_pk_fma_f32 v[92:93], v[34:35], v[98:99], v[92:93] op_sel:[1,0,0]
	v_cvt_f32_ubyte0_e32 v104, v166
	v_cvt_f32_ubyte1_e32 v105, v166
	v_pk_fma_f32 v[90:91], v[34:35], v[102:103], v[90:91] op_sel:[1,0,0]
	v_cvt_f32_ubyte2_e32 v146, v166
	v_cvt_f32_ubyte3_e32 v147, v166
	v_pk_fma_f32 v[86:87], v[34:35], v[104:105], v[86:87] op_sel:[1,0,0]
	v_cvt_f32_ubyte0_e32 v98, v88
	v_cvt_f32_ubyte1_e32 v99, v88
	v_pk_fma_f32 v[84:85], v[34:35], v[146:147], v[84:85] op_sel:[1,0,0]
	v_and_b32_e32 v68, s0, v168
	v_and_b32_e32 v76, s0, v169
	v_cvt_f32_ubyte2_e32 v102, v88
	v_cvt_f32_ubyte3_e32 v103, v88
	v_pk_fma_f32 v[80:81], v[34:35], v[98:99], v[80:81] op_sel:[1,0,0]
	v_cvt_f32_ubyte0_e32 v104, v167
	v_cvt_f32_ubyte1_e32 v105, v167
	v_pk_fma_f32 v[78:79], v[34:35], v[102:103], v[78:79] op_sel:[1,0,0]
	v_cvt_f32_ubyte2_e32 v146, v167
	v_cvt_f32_ubyte3_e32 v147, v167
	v_pk_fma_f32 v[70:71], v[34:35], v[104:105], v[70:71] op_sel:[1,0,0]
	v_cvt_f32_ubyte0_e32 v98, v68
	v_cvt_f32_ubyte1_e32 v99, v68
	v_pk_fma_f32 v[62:63], v[34:35], v[146:147], v[62:63] op_sel:[1,0,0]
	v_cvt_f32_ubyte2_e32 v102, v68
	v_cvt_f32_ubyte3_e32 v103, v68
	v_pk_fma_f32 v[92:93], v[36:37], v[98:99], v[92:93] op_sel_hi:[0,1,1]
	v_cvt_f32_ubyte0_e32 v104, v168
	v_cvt_f32_ubyte1_e32 v105, v168
	v_pk_fma_f32 v[90:91], v[36:37], v[102:103], v[90:91] op_sel_hi:[0,1,1]
	v_cvt_f32_ubyte2_e32 v146, v168
	v_cvt_f32_ubyte3_e32 v147, v168
	v_pk_fma_f32 v[86:87], v[36:37], v[104:105], v[86:87] op_sel_hi:[0,1,1]
	v_cvt_f32_ubyte0_e32 v98, v76
	v_cvt_f32_ubyte1_e32 v99, v76
	v_pk_fma_f32 v[84:85], v[36:37], v[146:147], v[84:85] op_sel_hi:[0,1,1]
	v_and_b32_e32 v82, s0, v170
	v_and_b32_e32 v88, s0, v171
	v_cvt_f32_ubyte2_e32 v102, v76
	v_cvt_f32_ubyte3_e32 v103, v76
	v_pk_fma_f32 v[80:81], v[36:37], v[98:99], v[80:81] op_sel_hi:[0,1,1]
	v_cvt_f32_ubyte0_e32 v104, v169
	v_cvt_f32_ubyte1_e32 v105, v169
	v_pk_fma_f32 v[78:79], v[36:37], v[102:103], v[78:79] op_sel_hi:[0,1,1]
	v_cvt_f32_ubyte2_e32 v146, v169
	v_cvt_f32_ubyte3_e32 v147, v169
	v_pk_fma_f32 v[70:71], v[36:37], v[104:105], v[70:71] op_sel_hi:[0,1,1]
	v_cvt_f32_ubyte0_e32 v98, v82
	v_cvt_f32_ubyte1_e32 v99, v82
	v_pk_fma_f32 v[62:63], v[36:37], v[146:147], v[62:63] op_sel_hi:[0,1,1]
	v_cvt_f32_ubyte2_e32 v102, v82
	v_cvt_f32_ubyte3_e32 v103, v82
	v_pk_fma_f32 v[92:93], v[36:37], v[98:99], v[92:93] op_sel:[1,0,0]
	v_cvt_f32_ubyte0_e32 v104, v170
	v_cvt_f32_ubyte1_e32 v105, v170
	v_pk_fma_f32 v[90:91], v[36:37], v[102:103], v[90:91] op_sel:[1,0,0]
	v_cvt_f32_ubyte2_e32 v146, v170
	v_cvt_f32_ubyte3_e32 v147, v170
	v_pk_fma_f32 v[86:87], v[36:37], v[104:105], v[86:87] op_sel:[1,0,0]
	v_cvt_f32_ubyte0_e32 v98, v88
	v_cvt_f32_ubyte1_e32 v99, v88
	v_pk_fma_f32 v[84:85], v[36:37], v[146:147], v[84:85] op_sel:[1,0,0]
	v_and_b32_e32 v68, s0, v172
	v_and_b32_e32 v76, s0, v173
	v_cvt_f32_ubyte2_e32 v102, v88
	v_cvt_f32_ubyte3_e32 v103, v88
	v_pk_fma_f32 v[80:81], v[36:37], v[98:99], v[80:81] op_sel:[1,0,0]
	v_cvt_f32_ubyte0_e32 v104, v171
	v_cvt_f32_ubyte1_e32 v105, v171
	v_pk_fma_f32 v[78:79], v[36:37], v[102:103], v[78:79] op_sel:[1,0,0]
	v_cvt_f32_ubyte2_e32 v146, v171
	v_cvt_f32_ubyte3_e32 v147, v171
	v_pk_fma_f32 v[70:71], v[36:37], v[104:105], v[70:71] op_sel:[1,0,0]
	v_cvt_f32_ubyte0_e32 v98, v68
	v_cvt_f32_ubyte1_e32 v99, v68
	v_pk_fma_f32 v[62:63], v[36:37], v[146:147], v[62:63] op_sel:[1,0,0]
	v_cvt_f32_ubyte2_e32 v102, v68
	v_cvt_f32_ubyte3_e32 v103, v68
	v_pk_fma_f32 v[92:93], v[38:39], v[98:99], v[92:93] op_sel_hi:[0,1,1]
	v_cvt_f32_ubyte0_e32 v104, v172
	v_cvt_f32_ubyte1_e32 v105, v172
	v_pk_fma_f32 v[90:91], v[38:39], v[102:103], v[90:91] op_sel_hi:[0,1,1]
	v_cvt_f32_ubyte2_e32 v146, v172
	v_cvt_f32_ubyte3_e32 v147, v172
	v_pk_fma_f32 v[86:87], v[38:39], v[104:105], v[86:87] op_sel_hi:[0,1,1]
	v_cvt_f32_ubyte0_e32 v98, v76
	v_cvt_f32_ubyte1_e32 v99, v76
	v_pk_fma_f32 v[84:85], v[38:39], v[146:147], v[84:85] op_sel_hi:[0,1,1]
	v_and_b32_e32 v82, s0, v174
	v_and_b32_e32 v88, s0, v175
	v_cvt_f32_ubyte2_e32 v102, v76
	v_cvt_f32_ubyte3_e32 v103, v76
	v_pk_fma_f32 v[80:81], v[38:39], v[98:99], v[80:81] op_sel_hi:[0,1,1]
	v_cvt_f32_ubyte0_e32 v104, v173
	v_cvt_f32_ubyte1_e32 v105, v173
	v_pk_fma_f32 v[78:79], v[38:39], v[102:103], v[78:79] op_sel_hi:[0,1,1]
	v_cvt_f32_ubyte2_e32 v146, v173
	v_cvt_f32_ubyte3_e32 v147, v173
	v_pk_fma_f32 v[70:71], v[38:39], v[104:105], v[70:71] op_sel_hi:[0,1,1]
	v_cvt_f32_ubyte0_e32 v98, v82
	v_cvt_f32_ubyte1_e32 v99, v82
	v_pk_fma_f32 v[62:63], v[38:39], v[146:147], v[62:63] op_sel_hi:[0,1,1]
	v_cvt_f32_ubyte2_e32 v102, v82
	v_cvt_f32_ubyte3_e32 v103, v82
	v_pk_fma_f32 v[92:93], v[38:39], v[98:99], v[92:93] op_sel:[1,0,0]
	v_cvt_f32_ubyte0_e32 v104, v174
	v_cvt_f32_ubyte1_e32 v105, v174
	v_pk_fma_f32 v[90:91], v[38:39], v[102:103], v[90:91] op_sel:[1,0,0]
	v_cvt_f32_ubyte2_e32 v146, v174
	v_cvt_f32_ubyte3_e32 v147, v174
	v_pk_fma_f32 v[86:87], v[38:39], v[104:105], v[86:87] op_sel:[1,0,0]
	v_cvt_f32_ubyte0_e32 v98, v88
	v_cvt_f32_ubyte1_e32 v99, v88
	v_pk_fma_f32 v[84:85], v[38:39], v[146:147], v[84:85] op_sel:[1,0,0]
	v_and_b32_e32 v68, s0, v176
	v_and_b32_e32 v76, s0, v177
	v_cvt_f32_ubyte2_e32 v102, v88
	v_cvt_f32_ubyte3_e32 v103, v88
	v_pk_fma_f32 v[80:81], v[38:39], v[98:99], v[80:81] op_sel:[1,0,0]
	v_cvt_f32_ubyte0_e32 v104, v175
	v_cvt_f32_ubyte1_e32 v105, v175
	v_pk_fma_f32 v[78:79], v[38:39], v[102:103], v[78:79] op_sel:[1,0,0]
	v_cvt_f32_ubyte2_e32 v146, v175
	v_cvt_f32_ubyte3_e32 v147, v175
	v_pk_fma_f32 v[70:71], v[38:39], v[104:105], v[70:71] op_sel:[1,0,0]
	v_cvt_f32_ubyte0_e32 v98, v68
	v_cvt_f32_ubyte1_e32 v99, v68
	v_pk_fma_f32 v[62:63], v[38:39], v[146:147], v[62:63] op_sel:[1,0,0]
	v_cvt_f32_ubyte2_e32 v102, v68
	v_cvt_f32_ubyte3_e32 v103, v68
	v_pk_fma_f32 v[92:93], v[40:41], v[98:99], v[92:93] op_sel_hi:[0,1,1]
	v_cvt_f32_ubyte0_e32 v104, v176
	v_cvt_f32_ubyte1_e32 v105, v176
	v_pk_fma_f32 v[90:91], v[40:41], v[102:103], v[90:91] op_sel_hi:[0,1,1]
	v_cvt_f32_ubyte2_e32 v146, v176
	v_cvt_f32_ubyte3_e32 v147, v176
	v_pk_fma_f32 v[86:87], v[40:41], v[104:105], v[86:87] op_sel_hi:[0,1,1]
	v_cvt_f32_ubyte0_e32 v98, v76
	v_cvt_f32_ubyte1_e32 v99, v76
	v_pk_fma_f32 v[84:85], v[40:41], v[146:147], v[84:85] op_sel_hi:[0,1,1]
	v_and_b32_e32 v82, s0, v178
	v_and_b32_e32 v88, s0, v179
	v_cvt_f32_ubyte2_e32 v102, v76
	v_cvt_f32_ubyte3_e32 v103, v76
	v_pk_fma_f32 v[80:81], v[40:41], v[98:99], v[80:81] op_sel_hi:[0,1,1]
	v_cvt_f32_ubyte0_e32 v104, v177
	v_cvt_f32_ubyte1_e32 v105, v177
	v_pk_fma_f32 v[78:79], v[40:41], v[102:103], v[78:79] op_sel_hi:[0,1,1]
	v_cvt_f32_ubyte2_e32 v146, v177
	v_cvt_f32_ubyte3_e32 v147, v177
	v_pk_fma_f32 v[70:71], v[40:41], v[104:105], v[70:71] op_sel_hi:[0,1,1]
	v_cvt_f32_ubyte0_e32 v98, v82
	v_cvt_f32_ubyte1_e32 v99, v82
	v_pk_fma_f32 v[62:63], v[40:41], v[146:147], v[62:63] op_sel_hi:[0,1,1]
	v_cvt_f32_ubyte2_e32 v102, v82
	v_cvt_f32_ubyte3_e32 v103, v82
	v_pk_fma_f32 v[92:93], v[40:41], v[98:99], v[92:93] op_sel:[1,0,0]
	v_cvt_f32_ubyte0_e32 v104, v178
	v_cvt_f32_ubyte1_e32 v105, v178
	v_pk_fma_f32 v[90:91], v[40:41], v[102:103], v[90:91] op_sel:[1,0,0]
	v_cvt_f32_ubyte2_e32 v146, v178
	v_cvt_f32_ubyte3_e32 v147, v178
	v_pk_fma_f32 v[86:87], v[40:41], v[104:105], v[86:87] op_sel:[1,0,0]
	v_cvt_f32_ubyte0_e32 v98, v88
	v_cvt_f32_ubyte1_e32 v99, v88
	v_pk_fma_f32 v[84:85], v[40:41], v[146:147], v[84:85] op_sel:[1,0,0]
	v_cvt_f32_ubyte2_e32 v102, v88
	v_cvt_f32_ubyte3_e32 v103, v88
	v_pk_fma_f32 v[80:81], v[40:41], v[98:99], v[80:81] op_sel:[1,0,0]
	v_cvt_f32_ubyte0_e32 v104, v179
	v_cvt_f32_ubyte1_e32 v105, v179
	v_pk_fma_f32 v[78:79], v[40:41], v[102:103], v[78:79] op_sel:[1,0,0]
	v_cvt_f32_ubyte2_e32 v146, v179
	v_cvt_f32_ubyte3_e32 v147, v179
	v_pk_fma_f32 v[70:71], v[40:41], v[104:105], v[70:71] op_sel:[1,0,0]
	v_pk_fma_f32 v[62:63], v[40:41], v[146:147], v[62:63] op_sel:[1,0,0]
	s_waitcnt lgkmcnt(0)
	v_lshl_add_u32 v72, v72, 9, v100
	v_lshl_add_u32 v73, v73, 9, v100
	v_lshl_add_u32 v74, v74, 9, v100
	v_lshl_add_u32 v75, v75, 9, v100
	v_lshl_add_u32 v94, v94, 9, v100
	v_lshl_add_u32 v95, v95, 9, v100
	v_lshl_add_u32 v96, v96, 9, v100
	v_lshl_add_u32 v97, v97, 9, v100
	global_load_dwordx2 v[164:165], v72, s[38:39]
	global_load_dwordx2 v[166:167], v73, s[38:39]
	global_load_dwordx2 v[168:169], v74, s[38:39]
	global_load_dwordx2 v[170:171], v75, s[38:39]
	global_load_dwordx2 v[172:173], v94, s[38:39]
	global_load_dwordx2 v[174:175], v95, s[38:39]
	global_load_dwordx2 v[176:177], v96, s[38:39]
	global_load_dwordx2 v[178:179], v97, s[38:39]
	ds_read_b128 v[72:75], v1 offset:224
	ds_read_b128 v[94:97], v1 offset:240
	ds_read_b128 v[34:37], v1 offset:576
	ds_read_b128 v[38:41], v1 offset:592
	s_waitcnt vmcnt(40)
	v_and_b32_e32 v68, s0, v180
	v_and_b32_e32 v76, s0, v181
	v_cvt_f32_ubyte0_e32 v98, v68
	v_cvt_f32_ubyte1_e32 v99, v68
	v_cvt_f32_ubyte2_e32 v102, v68
	v_cvt_f32_ubyte3_e32 v103, v68
	v_pk_fma_f32 v[92:93], v[50:51], v[98:99], v[92:93] op_sel_hi:[0,1,1]
	v_cvt_f32_ubyte0_e32 v104, v180
	v_cvt_f32_ubyte1_e32 v105, v180
	v_pk_fma_f32 v[90:91], v[50:51], v[102:103], v[90:91] op_sel_hi:[0,1,1]
	v_cvt_f32_ubyte2_e32 v146, v180
	v_cvt_f32_ubyte3_e32 v147, v180
	v_pk_fma_f32 v[86:87], v[50:51], v[104:105], v[86:87] op_sel_hi:[0,1,1]
	v_cvt_f32_ubyte0_e32 v98, v76
	v_cvt_f32_ubyte1_e32 v99, v76
	v_pk_fma_f32 v[84:85], v[50:51], v[146:147], v[84:85] op_sel_hi:[0,1,1]
	v_and_b32_e32 v82, s0, v182
	v_and_b32_e32 v88, s0, v183
	v_cvt_f32_ubyte2_e32 v102, v76
	v_cvt_f32_ubyte3_e32 v103, v76
	v_pk_fma_f32 v[80:81], v[50:51], v[98:99], v[80:81] op_sel_hi:[0,1,1]
	v_cvt_f32_ubyte0_e32 v104, v181
	v_cvt_f32_ubyte1_e32 v105, v181
	v_pk_fma_f32 v[78:79], v[50:51], v[102:103], v[78:79] op_sel_hi:[0,1,1]
	v_cvt_f32_ubyte2_e32 v146, v181
	v_cvt_f32_ubyte3_e32 v147, v181
	v_pk_fma_f32 v[70:71], v[50:51], v[104:105], v[70:71] op_sel_hi:[0,1,1]
	v_cvt_f32_ubyte0_e32 v98, v82
	v_cvt_f32_ubyte1_e32 v99, v82
	v_pk_fma_f32 v[62:63], v[50:51], v[146:147], v[62:63] op_sel_hi:[0,1,1]
	v_cvt_f32_ubyte2_e32 v102, v82
	v_cvt_f32_ubyte3_e32 v103, v82
	v_pk_fma_f32 v[92:93], v[50:51], v[98:99], v[92:93] op_sel:[1,0,0]
	v_cvt_f32_ubyte0_e32 v104, v182
	v_cvt_f32_ubyte1_e32 v105, v182
	v_pk_fma_f32 v[90:91], v[50:51], v[102:103], v[90:91] op_sel:[1,0,0]
	v_cvt_f32_ubyte2_e32 v146, v182
	v_cvt_f32_ubyte3_e32 v147, v182
	v_pk_fma_f32 v[86:87], v[50:51], v[104:105], v[86:87] op_sel:[1,0,0]
	v_cvt_f32_ubyte0_e32 v98, v88
	v_cvt_f32_ubyte1_e32 v99, v88
	v_pk_fma_f32 v[84:85], v[50:51], v[146:147], v[84:85] op_sel:[1,0,0]
	v_and_b32_e32 v68, s0, v184
	v_and_b32_e32 v76, s0, v185
	v_cvt_f32_ubyte2_e32 v102, v88
	v_cvt_f32_ubyte3_e32 v103, v88
	v_pk_fma_f32 v[80:81], v[50:51], v[98:99], v[80:81] op_sel:[1,0,0]
	v_cvt_f32_ubyte0_e32 v104, v183
	v_cvt_f32_ubyte1_e32 v105, v183
	v_pk_fma_f32 v[78:79], v[50:51], v[102:103], v[78:79] op_sel:[1,0,0]
	v_cvt_f32_ubyte2_e32 v146, v183
	v_cvt_f32_ubyte3_e32 v147, v183
	v_pk_fma_f32 v[70:71], v[50:51], v[104:105], v[70:71] op_sel:[1,0,0]
	v_cvt_f32_ubyte0_e32 v98, v68
	v_cvt_f32_ubyte1_e32 v99, v68
	v_pk_fma_f32 v[62:63], v[50:51], v[146:147], v[62:63] op_sel:[1,0,0]
	v_cvt_f32_ubyte2_e32 v102, v68
	v_cvt_f32_ubyte3_e32 v103, v68
	v_pk_fma_f32 v[92:93], v[52:53], v[98:99], v[92:93] op_sel_hi:[0,1,1]
	v_cvt_f32_ubyte0_e32 v104, v184
	v_cvt_f32_ubyte1_e32 v105, v184
	v_pk_fma_f32 v[90:91], v[52:53], v[102:103], v[90:91] op_sel_hi:[0,1,1]
	v_cvt_f32_ubyte2_e32 v146, v184
	v_cvt_f32_ubyte3_e32 v147, v184
	v_pk_fma_f32 v[86:87], v[52:53], v[104:105], v[86:87] op_sel_hi:[0,1,1]
	v_cvt_f32_ubyte0_e32 v98, v76
	v_cvt_f32_ubyte1_e32 v99, v76
	v_pk_fma_f32 v[84:85], v[52:53], v[146:147], v[84:85] op_sel_hi:[0,1,1]
	v_and_b32_e32 v82, s0, v186
	v_and_b32_e32 v88, s0, v187
	v_cvt_f32_ubyte2_e32 v102, v76
	v_cvt_f32_ubyte3_e32 v103, v76
	v_pk_fma_f32 v[80:81], v[52:53], v[98:99], v[80:81] op_sel_hi:[0,1,1]
	v_cvt_f32_ubyte0_e32 v104, v185
	v_cvt_f32_ubyte1_e32 v105, v185
	v_pk_fma_f32 v[78:79], v[52:53], v[102:103], v[78:79] op_sel_hi:[0,1,1]
	v_cvt_f32_ubyte2_e32 v146, v185
	v_cvt_f32_ubyte3_e32 v147, v185
	v_pk_fma_f32 v[70:71], v[52:53], v[104:105], v[70:71] op_sel_hi:[0,1,1]
	v_cvt_f32_ubyte0_e32 v98, v82
	v_cvt_f32_ubyte1_e32 v99, v82
	v_pk_fma_f32 v[62:63], v[52:53], v[146:147], v[62:63] op_sel_hi:[0,1,1]
	v_cvt_f32_ubyte2_e32 v102, v82
	v_cvt_f32_ubyte3_e32 v103, v82
	v_pk_fma_f32 v[92:93], v[52:53], v[98:99], v[92:93] op_sel:[1,0,0]
	v_cvt_f32_ubyte0_e32 v104, v186
	v_cvt_f32_ubyte1_e32 v105, v186
	v_pk_fma_f32 v[90:91], v[52:53], v[102:103], v[90:91] op_sel:[1,0,0]
	v_cvt_f32_ubyte2_e32 v146, v186
	v_cvt_f32_ubyte3_e32 v147, v186
	v_pk_fma_f32 v[86:87], v[52:53], v[104:105], v[86:87] op_sel:[1,0,0]
	v_cvt_f32_ubyte0_e32 v98, v88
	v_cvt_f32_ubyte1_e32 v99, v88
	v_pk_fma_f32 v[84:85], v[52:53], v[146:147], v[84:85] op_sel:[1,0,0]
	v_and_b32_e32 v68, s0, v188
	v_and_b32_e32 v76, s0, v189
	v_cvt_f32_ubyte2_e32 v102, v88
	v_cvt_f32_ubyte3_e32 v103, v88
	v_pk_fma_f32 v[80:81], v[52:53], v[98:99], v[80:81] op_sel:[1,0,0]
	v_cvt_f32_ubyte0_e32 v104, v187
	v_cvt_f32_ubyte1_e32 v105, v187
	v_pk_fma_f32 v[78:79], v[52:53], v[102:103], v[78:79] op_sel:[1,0,0]
	v_cvt_f32_ubyte2_e32 v146, v187
	v_cvt_f32_ubyte3_e32 v147, v187
	v_pk_fma_f32 v[70:71], v[52:53], v[104:105], v[70:71] op_sel:[1,0,0]
	v_cvt_f32_ubyte0_e32 v98, v68
	v_cvt_f32_ubyte1_e32 v99, v68
	v_pk_fma_f32 v[62:63], v[52:53], v[146:147], v[62:63] op_sel:[1,0,0]
	v_cvt_f32_ubyte2_e32 v102, v68
	v_cvt_f32_ubyte3_e32 v103, v68
	v_pk_fma_f32 v[92:93], v[54:55], v[98:99], v[92:93] op_sel_hi:[0,1,1]
	v_cvt_f32_ubyte0_e32 v104, v188
	v_cvt_f32_ubyte1_e32 v105, v188
	v_pk_fma_f32 v[90:91], v[54:55], v[102:103], v[90:91] op_sel_hi:[0,1,1]
	v_cvt_f32_ubyte2_e32 v146, v188
	v_cvt_f32_ubyte3_e32 v147, v188
	v_pk_fma_f32 v[86:87], v[54:55], v[104:105], v[86:87] op_sel_hi:[0,1,1]
	v_cvt_f32_ubyte0_e32 v98, v76
	v_cvt_f32_ubyte1_e32 v99, v76
	v_pk_fma_f32 v[84:85], v[54:55], v[146:147], v[84:85] op_sel_hi:[0,1,1]
	v_and_b32_e32 v82, s0, v190
	v_and_b32_e32 v88, s0, v191
	v_cvt_f32_ubyte2_e32 v102, v76
	v_cvt_f32_ubyte3_e32 v103, v76
	v_pk_fma_f32 v[80:81], v[54:55], v[98:99], v[80:81] op_sel_hi:[0,1,1]
	v_cvt_f32_ubyte0_e32 v104, v189
	v_cvt_f32_ubyte1_e32 v105, v189
	v_pk_fma_f32 v[78:79], v[54:55], v[102:103], v[78:79] op_sel_hi:[0,1,1]
	v_cvt_f32_ubyte2_e32 v146, v189
	v_cvt_f32_ubyte3_e32 v147, v189
	v_pk_fma_f32 v[70:71], v[54:55], v[104:105], v[70:71] op_sel_hi:[0,1,1]
	v_cvt_f32_ubyte0_e32 v98, v82
	v_cvt_f32_ubyte1_e32 v99, v82
	v_pk_fma_f32 v[62:63], v[54:55], v[146:147], v[62:63] op_sel_hi:[0,1,1]
	v_cvt_f32_ubyte2_e32 v102, v82
	v_cvt_f32_ubyte3_e32 v103, v82
	v_pk_fma_f32 v[92:93], v[54:55], v[98:99], v[92:93] op_sel:[1,0,0]
	v_cvt_f32_ubyte0_e32 v104, v190
	v_cvt_f32_ubyte1_e32 v105, v190
	v_pk_fma_f32 v[90:91], v[54:55], v[102:103], v[90:91] op_sel:[1,0,0]
	v_cvt_f32_ubyte2_e32 v146, v190
	v_cvt_f32_ubyte3_e32 v147, v190
	v_pk_fma_f32 v[86:87], v[54:55], v[104:105], v[86:87] op_sel:[1,0,0]
	v_cvt_f32_ubyte0_e32 v98, v88
	v_cvt_f32_ubyte1_e32 v99, v88
	v_pk_fma_f32 v[84:85], v[54:55], v[146:147], v[84:85] op_sel:[1,0,0]
	v_and_b32_e32 v68, s0, v192
	v_and_b32_e32 v76, s0, v193
	v_cvt_f32_ubyte2_e32 v102, v88
	v_cvt_f32_ubyte3_e32 v103, v88
	v_pk_fma_f32 v[80:81], v[54:55], v[98:99], v[80:81] op_sel:[1,0,0]
	v_cvt_f32_ubyte0_e32 v104, v191
	v_cvt_f32_ubyte1_e32 v105, v191
	v_pk_fma_f32 v[78:79], v[54:55], v[102:103], v[78:79] op_sel:[1,0,0]
	v_cvt_f32_ubyte2_e32 v146, v191
	v_cvt_f32_ubyte3_e32 v147, v191
	v_pk_fma_f32 v[70:71], v[54:55], v[104:105], v[70:71] op_sel:[1,0,0]
	v_cvt_f32_ubyte0_e32 v98, v68
	v_cvt_f32_ubyte1_e32 v99, v68
	v_pk_fma_f32 v[62:63], v[54:55], v[146:147], v[62:63] op_sel:[1,0,0]
	v_cvt_f32_ubyte2_e32 v102, v68
	v_cvt_f32_ubyte3_e32 v103, v68
	v_pk_fma_f32 v[92:93], v[56:57], v[98:99], v[92:93] op_sel_hi:[0,1,1]
	v_cvt_f32_ubyte0_e32 v104, v192
	v_cvt_f32_ubyte1_e32 v105, v192
	v_pk_fma_f32 v[90:91], v[56:57], v[102:103], v[90:91] op_sel_hi:[0,1,1]
	v_cvt_f32_ubyte2_e32 v146, v192
	v_cvt_f32_ubyte3_e32 v147, v192
	v_pk_fma_f32 v[86:87], v[56:57], v[104:105], v[86:87] op_sel_hi:[0,1,1]
	v_cvt_f32_ubyte0_e32 v98, v76
	v_cvt_f32_ubyte1_e32 v99, v76
	v_pk_fma_f32 v[84:85], v[56:57], v[146:147], v[84:85] op_sel_hi:[0,1,1]
	v_and_b32_e32 v82, s0, v194
	v_and_b32_e32 v88, s0, v195
	v_cvt_f32_ubyte2_e32 v102, v76
	v_cvt_f32_ubyte3_e32 v103, v76
	v_pk_fma_f32 v[80:81], v[56:57], v[98:99], v[80:81] op_sel_hi:[0,1,1]
	v_cvt_f32_ubyte0_e32 v104, v193
	v_cvt_f32_ubyte1_e32 v105, v193
	v_pk_fma_f32 v[78:79], v[56:57], v[102:103], v[78:79] op_sel_hi:[0,1,1]
	v_cvt_f32_ubyte2_e32 v146, v193
	v_cvt_f32_ubyte3_e32 v147, v193
	v_pk_fma_f32 v[70:71], v[56:57], v[104:105], v[70:71] op_sel_hi:[0,1,1]
	v_cvt_f32_ubyte0_e32 v98, v82
	v_cvt_f32_ubyte1_e32 v99, v82
	v_pk_fma_f32 v[62:63], v[56:57], v[146:147], v[62:63] op_sel_hi:[0,1,1]
	v_cvt_f32_ubyte2_e32 v102, v82
	v_cvt_f32_ubyte3_e32 v103, v82
	v_pk_fma_f32 v[92:93], v[56:57], v[98:99], v[92:93] op_sel:[1,0,0]
	v_cvt_f32_ubyte0_e32 v104, v194
	v_cvt_f32_ubyte1_e32 v105, v194
	v_pk_fma_f32 v[90:91], v[56:57], v[102:103], v[90:91] op_sel:[1,0,0]
	v_cvt_f32_ubyte2_e32 v146, v194
	v_cvt_f32_ubyte3_e32 v147, v194
	v_pk_fma_f32 v[86:87], v[56:57], v[104:105], v[86:87] op_sel:[1,0,0]
	v_cvt_f32_ubyte0_e32 v98, v88
	v_cvt_f32_ubyte1_e32 v99, v88
	v_pk_fma_f32 v[84:85], v[56:57], v[146:147], v[84:85] op_sel:[1,0,0]
	v_cvt_f32_ubyte2_e32 v102, v88
	v_cvt_f32_ubyte3_e32 v103, v88
	v_pk_fma_f32 v[80:81], v[56:57], v[98:99], v[80:81] op_sel:[1,0,0]
	v_cvt_f32_ubyte0_e32 v104, v195
	v_cvt_f32_ubyte1_e32 v105, v195
	v_pk_fma_f32 v[78:79], v[56:57], v[102:103], v[78:79] op_sel:[1,0,0]
	v_cvt_f32_ubyte2_e32 v146, v195
	v_cvt_f32_ubyte3_e32 v147, v195
	v_pk_fma_f32 v[70:71], v[56:57], v[104:105], v[70:71] op_sel:[1,0,0]
	v_pk_fma_f32 v[62:63], v[56:57], v[146:147], v[62:63] op_sel:[1,0,0]
	s_waitcnt lgkmcnt(0)
	v_lshl_add_u32 v72, v72, 9, v100
	v_lshl_add_u32 v73, v73, 9, v100
	v_lshl_add_u32 v74, v74, 9, v100
	v_lshl_add_u32 v75, v75, 9, v100
	v_lshl_add_u32 v94, v94, 9, v100
	v_lshl_add_u32 v95, v95, 9, v100
	v_lshl_add_u32 v96, v96, 9, v100
	v_lshl_add_u32 v97, v97, 9, v100
	global_load_dwordx2 v[180:181], v72, s[38:39]
	global_load_dwordx2 v[182:183], v73, s[38:39]
	global_load_dwordx2 v[184:185], v74, s[38:39]
	global_load_dwordx2 v[186:187], v75, s[38:39]
	global_load_dwordx2 v[188:189], v94, s[38:39]
	global_load_dwordx2 v[190:191], v95, s[38:39]
	global_load_dwordx2 v[192:193], v96, s[38:39]
	global_load_dwordx2 v[194:195], v97, s[38:39]
	ds_read_b128 v[72:75], v1 offset:256
	ds_read_b128 v[94:97], v1 offset:272
	ds_read_b128 v[50:53], v1 offset:608
	ds_read_b128 v[54:57], v1 offset:624
	s_waitcnt vmcnt(40)
	v_and_b32_e32 v68, s0, v196
	v_and_b32_e32 v76, s0, v197
	v_cvt_f32_ubyte0_e32 v98, v68
	v_cvt_f32_ubyte1_e32 v99, v68
	v_cvt_f32_ubyte2_e32 v102, v68
	v_cvt_f32_ubyte3_e32 v103, v68
	v_pk_fma_f32 v[92:93], v[34:35], v[98:99], v[92:93] op_sel_hi:[0,1,1]
	v_cvt_f32_ubyte0_e32 v104, v196
	v_cvt_f32_ubyte1_e32 v105, v196
	v_pk_fma_f32 v[90:91], v[34:35], v[102:103], v[90:91] op_sel_hi:[0,1,1]
	v_cvt_f32_ubyte2_e32 v146, v196
	v_cvt_f32_ubyte3_e32 v147, v196
	v_pk_fma_f32 v[86:87], v[34:35], v[104:105], v[86:87] op_sel_hi:[0,1,1]
	v_cvt_f32_ubyte0_e32 v98, v76
	v_cvt_f32_ubyte1_e32 v99, v76
	v_pk_fma_f32 v[84:85], v[34:35], v[146:147], v[84:85] op_sel_hi:[0,1,1]
	v_and_b32_e32 v82, s0, v198
	v_and_b32_e32 v88, s0, v199
	v_cvt_f32_ubyte2_e32 v102, v76
	v_cvt_f32_ubyte3_e32 v103, v76
	v_pk_fma_f32 v[80:81], v[34:35], v[98:99], v[80:81] op_sel_hi:[0,1,1]
	v_cvt_f32_ubyte0_e32 v104, v197
	v_cvt_f32_ubyte1_e32 v105, v197
	v_pk_fma_f32 v[78:79], v[34:35], v[102:103], v[78:79] op_sel_hi:[0,1,1]
	v_cvt_f32_ubyte2_e32 v146, v197
	v_cvt_f32_ubyte3_e32 v147, v197
	v_pk_fma_f32 v[70:71], v[34:35], v[104:105], v[70:71] op_sel_hi:[0,1,1]
	v_cvt_f32_ubyte0_e32 v98, v82
	v_cvt_f32_ubyte1_e32 v99, v82
	v_pk_fma_f32 v[62:63], v[34:35], v[146:147], v[62:63] op_sel_hi:[0,1,1]
	v_cvt_f32_ubyte2_e32 v102, v82
	v_cvt_f32_ubyte3_e32 v103, v82
	v_pk_fma_f32 v[92:93], v[34:35], v[98:99], v[92:93] op_sel:[1,0,0]
	v_cvt_f32_ubyte0_e32 v104, v198
	v_cvt_f32_ubyte1_e32 v105, v198
	v_pk_fma_f32 v[90:91], v[34:35], v[102:103], v[90:91] op_sel:[1,0,0]
	v_cvt_f32_ubyte2_e32 v146, v198
	v_cvt_f32_ubyte3_e32 v147, v198
	v_pk_fma_f32 v[86:87], v[34:35], v[104:105], v[86:87] op_sel:[1,0,0]
	v_cvt_f32_ubyte0_e32 v98, v88
	v_cvt_f32_ubyte1_e32 v99, v88
	v_pk_fma_f32 v[84:85], v[34:35], v[146:147], v[84:85] op_sel:[1,0,0]
	v_and_b32_e32 v68, s0, v200
	v_and_b32_e32 v76, s0, v201
	v_cvt_f32_ubyte2_e32 v102, v88
	v_cvt_f32_ubyte3_e32 v103, v88
	v_pk_fma_f32 v[80:81], v[34:35], v[98:99], v[80:81] op_sel:[1,0,0]
	v_cvt_f32_ubyte0_e32 v104, v199
	v_cvt_f32_ubyte1_e32 v105, v199
	v_pk_fma_f32 v[78:79], v[34:35], v[102:103], v[78:79] op_sel:[1,0,0]
	v_cvt_f32_ubyte2_e32 v146, v199
	v_cvt_f32_ubyte3_e32 v147, v199
	v_pk_fma_f32 v[70:71], v[34:35], v[104:105], v[70:71] op_sel:[1,0,0]
	v_cvt_f32_ubyte0_e32 v98, v68
	v_cvt_f32_ubyte1_e32 v99, v68
	v_pk_fma_f32 v[62:63], v[34:35], v[146:147], v[62:63] op_sel:[1,0,0]
	v_cvt_f32_ubyte2_e32 v102, v68
	v_cvt_f32_ubyte3_e32 v103, v68
	v_pk_fma_f32 v[92:93], v[36:37], v[98:99], v[92:93] op_sel_hi:[0,1,1]
	v_cvt_f32_ubyte0_e32 v104, v200
	v_cvt_f32_ubyte1_e32 v105, v200
	v_pk_fma_f32 v[90:91], v[36:37], v[102:103], v[90:91] op_sel_hi:[0,1,1]
	v_cvt_f32_ubyte2_e32 v146, v200
	v_cvt_f32_ubyte3_e32 v147, v200
	v_pk_fma_f32 v[86:87], v[36:37], v[104:105], v[86:87] op_sel_hi:[0,1,1]
	v_cvt_f32_ubyte0_e32 v98, v76
	v_cvt_f32_ubyte1_e32 v99, v76
	v_pk_fma_f32 v[84:85], v[36:37], v[146:147], v[84:85] op_sel_hi:[0,1,1]
	v_and_b32_e32 v82, s0, v202
	v_and_b32_e32 v88, s0, v203
	v_cvt_f32_ubyte2_e32 v102, v76
	v_cvt_f32_ubyte3_e32 v103, v76
	v_pk_fma_f32 v[80:81], v[36:37], v[98:99], v[80:81] op_sel_hi:[0,1,1]
	v_cvt_f32_ubyte0_e32 v104, v201
	v_cvt_f32_ubyte1_e32 v105, v201
	v_pk_fma_f32 v[78:79], v[36:37], v[102:103], v[78:79] op_sel_hi:[0,1,1]
	v_cvt_f32_ubyte2_e32 v146, v201
	v_cvt_f32_ubyte3_e32 v147, v201
	v_pk_fma_f32 v[70:71], v[36:37], v[104:105], v[70:71] op_sel_hi:[0,1,1]
	v_cvt_f32_ubyte0_e32 v98, v82
	v_cvt_f32_ubyte1_e32 v99, v82
	v_pk_fma_f32 v[62:63], v[36:37], v[146:147], v[62:63] op_sel_hi:[0,1,1]
	v_cvt_f32_ubyte2_e32 v102, v82
	v_cvt_f32_ubyte3_e32 v103, v82
	v_pk_fma_f32 v[92:93], v[36:37], v[98:99], v[92:93] op_sel:[1,0,0]
	v_cvt_f32_ubyte0_e32 v104, v202
	v_cvt_f32_ubyte1_e32 v105, v202
	v_pk_fma_f32 v[90:91], v[36:37], v[102:103], v[90:91] op_sel:[1,0,0]
	v_cvt_f32_ubyte2_e32 v146, v202
	v_cvt_f32_ubyte3_e32 v147, v202
	v_pk_fma_f32 v[86:87], v[36:37], v[104:105], v[86:87] op_sel:[1,0,0]
	v_cvt_f32_ubyte0_e32 v98, v88
	v_cvt_f32_ubyte1_e32 v99, v88
	v_pk_fma_f32 v[84:85], v[36:37], v[146:147], v[84:85] op_sel:[1,0,0]
	v_and_b32_e32 v68, s0, v204
	v_and_b32_e32 v76, s0, v205
	v_cvt_f32_ubyte2_e32 v102, v88
	v_cvt_f32_ubyte3_e32 v103, v88
	v_pk_fma_f32 v[80:81], v[36:37], v[98:99], v[80:81] op_sel:[1,0,0]
	v_cvt_f32_ubyte0_e32 v104, v203
	v_cvt_f32_ubyte1_e32 v105, v203
	v_pk_fma_f32 v[78:79], v[36:37], v[102:103], v[78:79] op_sel:[1,0,0]
	v_cvt_f32_ubyte2_e32 v146, v203
	v_cvt_f32_ubyte3_e32 v147, v203
	v_pk_fma_f32 v[70:71], v[36:37], v[104:105], v[70:71] op_sel:[1,0,0]
	v_cvt_f32_ubyte0_e32 v98, v68
	v_cvt_f32_ubyte1_e32 v99, v68
	v_pk_fma_f32 v[62:63], v[36:37], v[146:147], v[62:63] op_sel:[1,0,0]
	v_cvt_f32_ubyte2_e32 v102, v68
	v_cvt_f32_ubyte3_e32 v103, v68
	v_pk_fma_f32 v[92:93], v[38:39], v[98:99], v[92:93] op_sel_hi:[0,1,1]
	v_cvt_f32_ubyte0_e32 v104, v204
	v_cvt_f32_ubyte1_e32 v105, v204
	v_pk_fma_f32 v[90:91], v[38:39], v[102:103], v[90:91] op_sel_hi:[0,1,1]
	v_cvt_f32_ubyte2_e32 v146, v204
	v_cvt_f32_ubyte3_e32 v147, v204
	v_pk_fma_f32 v[86:87], v[38:39], v[104:105], v[86:87] op_sel_hi:[0,1,1]
	v_cvt_f32_ubyte0_e32 v98, v76
	v_cvt_f32_ubyte1_e32 v99, v76
	v_pk_fma_f32 v[84:85], v[38:39], v[146:147], v[84:85] op_sel_hi:[0,1,1]
	v_and_b32_e32 v82, s0, v206
	v_and_b32_e32 v88, s0, v207
	v_cvt_f32_ubyte2_e32 v102, v76
	v_cvt_f32_ubyte3_e32 v103, v76
	v_pk_fma_f32 v[80:81], v[38:39], v[98:99], v[80:81] op_sel_hi:[0,1,1]
	v_cvt_f32_ubyte0_e32 v104, v205
	v_cvt_f32_ubyte1_e32 v105, v205
	v_pk_fma_f32 v[78:79], v[38:39], v[102:103], v[78:79] op_sel_hi:[0,1,1]
	v_cvt_f32_ubyte2_e32 v146, v205
	v_cvt_f32_ubyte3_e32 v147, v205
	v_pk_fma_f32 v[70:71], v[38:39], v[104:105], v[70:71] op_sel_hi:[0,1,1]
	v_cvt_f32_ubyte0_e32 v98, v82
	v_cvt_f32_ubyte1_e32 v99, v82
	v_pk_fma_f32 v[62:63], v[38:39], v[146:147], v[62:63] op_sel_hi:[0,1,1]
	v_cvt_f32_ubyte2_e32 v102, v82
	v_cvt_f32_ubyte3_e32 v103, v82
	v_pk_fma_f32 v[92:93], v[38:39], v[98:99], v[92:93] op_sel:[1,0,0]
	v_cvt_f32_ubyte0_e32 v104, v206
	v_cvt_f32_ubyte1_e32 v105, v206
	v_pk_fma_f32 v[90:91], v[38:39], v[102:103], v[90:91] op_sel:[1,0,0]
	v_cvt_f32_ubyte2_e32 v146, v206
	v_cvt_f32_ubyte3_e32 v147, v206
	v_pk_fma_f32 v[86:87], v[38:39], v[104:105], v[86:87] op_sel:[1,0,0]
	v_cvt_f32_ubyte0_e32 v98, v88
	v_cvt_f32_ubyte1_e32 v99, v88
	v_pk_fma_f32 v[84:85], v[38:39], v[146:147], v[84:85] op_sel:[1,0,0]
	v_and_b32_e32 v68, s0, v208
	v_and_b32_e32 v76, s0, v209
	v_cvt_f32_ubyte2_e32 v102, v88
	v_cvt_f32_ubyte3_e32 v103, v88
	v_pk_fma_f32 v[80:81], v[38:39], v[98:99], v[80:81] op_sel:[1,0,0]
	v_cvt_f32_ubyte0_e32 v104, v207
	v_cvt_f32_ubyte1_e32 v105, v207
	v_pk_fma_f32 v[78:79], v[38:39], v[102:103], v[78:79] op_sel:[1,0,0]
	v_cvt_f32_ubyte2_e32 v146, v207
	v_cvt_f32_ubyte3_e32 v147, v207
	v_pk_fma_f32 v[70:71], v[38:39], v[104:105], v[70:71] op_sel:[1,0,0]
	v_cvt_f32_ubyte0_e32 v98, v68
	v_cvt_f32_ubyte1_e32 v99, v68
	v_pk_fma_f32 v[62:63], v[38:39], v[146:147], v[62:63] op_sel:[1,0,0]
	v_cvt_f32_ubyte2_e32 v102, v68
	v_cvt_f32_ubyte3_e32 v103, v68
	v_pk_fma_f32 v[92:93], v[40:41], v[98:99], v[92:93] op_sel_hi:[0,1,1]
	v_cvt_f32_ubyte0_e32 v104, v208
	v_cvt_f32_ubyte1_e32 v105, v208
	v_pk_fma_f32 v[90:91], v[40:41], v[102:103], v[90:91] op_sel_hi:[0,1,1]
	v_cvt_f32_ubyte2_e32 v146, v208
	v_cvt_f32_ubyte3_e32 v147, v208
	v_pk_fma_f32 v[86:87], v[40:41], v[104:105], v[86:87] op_sel_hi:[0,1,1]
	v_cvt_f32_ubyte0_e32 v98, v76
	v_cvt_f32_ubyte1_e32 v99, v76
	v_pk_fma_f32 v[84:85], v[40:41], v[146:147], v[84:85] op_sel_hi:[0,1,1]
	v_and_b32_e32 v82, s0, v210
	v_and_b32_e32 v88, s0, v211
	v_cvt_f32_ubyte2_e32 v102, v76
	v_cvt_f32_ubyte3_e32 v103, v76
	v_pk_fma_f32 v[80:81], v[40:41], v[98:99], v[80:81] op_sel_hi:[0,1,1]
	v_cvt_f32_ubyte0_e32 v104, v209
	v_cvt_f32_ubyte1_e32 v105, v209
	v_pk_fma_f32 v[78:79], v[40:41], v[102:103], v[78:79] op_sel_hi:[0,1,1]
	v_cvt_f32_ubyte2_e32 v146, v209
	v_cvt_f32_ubyte3_e32 v147, v209
	v_pk_fma_f32 v[70:71], v[40:41], v[104:105], v[70:71] op_sel_hi:[0,1,1]
	v_cvt_f32_ubyte0_e32 v98, v82
	v_cvt_f32_ubyte1_e32 v99, v82
	v_pk_fma_f32 v[62:63], v[40:41], v[146:147], v[62:63] op_sel_hi:[0,1,1]
	v_cvt_f32_ubyte2_e32 v102, v82
	v_cvt_f32_ubyte3_e32 v103, v82
	v_pk_fma_f32 v[92:93], v[40:41], v[98:99], v[92:93] op_sel:[1,0,0]
	v_cvt_f32_ubyte0_e32 v104, v210
	v_cvt_f32_ubyte1_e32 v105, v210
	v_pk_fma_f32 v[90:91], v[40:41], v[102:103], v[90:91] op_sel:[1,0,0]
	v_cvt_f32_ubyte2_e32 v146, v210
	v_cvt_f32_ubyte3_e32 v147, v210
	v_pk_fma_f32 v[86:87], v[40:41], v[104:105], v[86:87] op_sel:[1,0,0]
	v_cvt_f32_ubyte0_e32 v98, v88
	v_cvt_f32_ubyte1_e32 v99, v88
	v_pk_fma_f32 v[84:85], v[40:41], v[146:147], v[84:85] op_sel:[1,0,0]
	v_cvt_f32_ubyte2_e32 v102, v88
	v_cvt_f32_ubyte3_e32 v103, v88
	v_pk_fma_f32 v[80:81], v[40:41], v[98:99], v[80:81] op_sel:[1,0,0]
	v_cvt_f32_ubyte0_e32 v104, v211
	v_cvt_f32_ubyte1_e32 v105, v211
	v_pk_fma_f32 v[78:79], v[40:41], v[102:103], v[78:79] op_sel:[1,0,0]
	v_cvt_f32_ubyte2_e32 v146, v211
	v_cvt_f32_ubyte3_e32 v147, v211
	v_pk_fma_f32 v[70:71], v[40:41], v[104:105], v[70:71] op_sel:[1,0,0]
	v_pk_fma_f32 v[62:63], v[40:41], v[146:147], v[62:63] op_sel:[1,0,0]
	s_waitcnt lgkmcnt(0)
	v_lshl_add_u32 v72, v72, 9, v100
	v_lshl_add_u32 v73, v73, 9, v100
	v_lshl_add_u32 v74, v74, 9, v100
	v_lshl_add_u32 v75, v75, 9, v100
	v_lshl_add_u32 v94, v94, 9, v100
	v_lshl_add_u32 v95, v95, 9, v100
	v_lshl_add_u32 v96, v96, 9, v100
	v_lshl_add_u32 v97, v97, 9, v100
	global_load_dwordx2 v[196:197], v72, s[38:39]
	global_load_dwordx2 v[198:199], v73, s[38:39]
	global_load_dwordx2 v[200:201], v74, s[38:39]
	global_load_dwordx2 v[202:203], v75, s[38:39]
	global_load_dwordx2 v[204:205], v94, s[38:39]
	global_load_dwordx2 v[206:207], v95, s[38:39]
	global_load_dwordx2 v[208:209], v96, s[38:39]
	global_load_dwordx2 v[210:211], v97, s[38:39]
	ds_read_b128 v[72:75], v1 offset:288
	ds_read_b128 v[94:97], v1 offset:304
	ds_read_b128 v[34:37], v1 offset:640
	ds_read_b128 v[38:41], v1 offset:656
	s_waitcnt vmcnt(40)
	v_and_b32_e32 v68, s0, v212
	v_and_b32_e32 v76, s0, v213
	v_cvt_f32_ubyte0_e32 v98, v68
	v_cvt_f32_ubyte1_e32 v99, v68
	v_cvt_f32_ubyte2_e32 v102, v68
	v_cvt_f32_ubyte3_e32 v103, v68
	v_pk_fma_f32 v[92:93], v[50:51], v[98:99], v[92:93] op_sel_hi:[0,1,1]
	v_cvt_f32_ubyte0_e32 v104, v212
	v_cvt_f32_ubyte1_e32 v105, v212
	v_pk_fma_f32 v[90:91], v[50:51], v[102:103], v[90:91] op_sel_hi:[0,1,1]
	v_cvt_f32_ubyte2_e32 v146, v212
	v_cvt_f32_ubyte3_e32 v147, v212
	v_pk_fma_f32 v[86:87], v[50:51], v[104:105], v[86:87] op_sel_hi:[0,1,1]
	v_cvt_f32_ubyte0_e32 v98, v76
	v_cvt_f32_ubyte1_e32 v99, v76
	v_pk_fma_f32 v[84:85], v[50:51], v[146:147], v[84:85] op_sel_hi:[0,1,1]
	v_and_b32_e32 v82, s0, v214
	v_and_b32_e32 v88, s0, v215
	v_cvt_f32_ubyte2_e32 v102, v76
	v_cvt_f32_ubyte3_e32 v103, v76
	v_pk_fma_f32 v[80:81], v[50:51], v[98:99], v[80:81] op_sel_hi:[0,1,1]
	v_cvt_f32_ubyte0_e32 v104, v213
	v_cvt_f32_ubyte1_e32 v105, v213
	v_pk_fma_f32 v[78:79], v[50:51], v[102:103], v[78:79] op_sel_hi:[0,1,1]
	v_cvt_f32_ubyte2_e32 v146, v213
	v_cvt_f32_ubyte3_e32 v147, v213
	v_pk_fma_f32 v[70:71], v[50:51], v[104:105], v[70:71] op_sel_hi:[0,1,1]
	v_cvt_f32_ubyte0_e32 v98, v82
	v_cvt_f32_ubyte1_e32 v99, v82
	v_pk_fma_f32 v[62:63], v[50:51], v[146:147], v[62:63] op_sel_hi:[0,1,1]
	v_cvt_f32_ubyte2_e32 v102, v82
	v_cvt_f32_ubyte3_e32 v103, v82
	v_pk_fma_f32 v[92:93], v[50:51], v[98:99], v[92:93] op_sel:[1,0,0]
	v_cvt_f32_ubyte0_e32 v104, v214
	v_cvt_f32_ubyte1_e32 v105, v214
	v_pk_fma_f32 v[90:91], v[50:51], v[102:103], v[90:91] op_sel:[1,0,0]
	v_cvt_f32_ubyte2_e32 v146, v214
	v_cvt_f32_ubyte3_e32 v147, v214
	v_pk_fma_f32 v[86:87], v[50:51], v[104:105], v[86:87] op_sel:[1,0,0]
	v_cvt_f32_ubyte0_e32 v98, v88
	v_cvt_f32_ubyte1_e32 v99, v88
	v_pk_fma_f32 v[84:85], v[50:51], v[146:147], v[84:85] op_sel:[1,0,0]
	v_and_b32_e32 v68, s0, v216
	v_and_b32_e32 v76, s0, v217
	v_cvt_f32_ubyte2_e32 v102, v88
	v_cvt_f32_ubyte3_e32 v103, v88
	v_pk_fma_f32 v[80:81], v[50:51], v[98:99], v[80:81] op_sel:[1,0,0]
	v_cvt_f32_ubyte0_e32 v104, v215
	v_cvt_f32_ubyte1_e32 v105, v215
	v_pk_fma_f32 v[78:79], v[50:51], v[102:103], v[78:79] op_sel:[1,0,0]
	v_cvt_f32_ubyte2_e32 v146, v215
	v_cvt_f32_ubyte3_e32 v147, v215
	v_pk_fma_f32 v[70:71], v[50:51], v[104:105], v[70:71] op_sel:[1,0,0]
	v_cvt_f32_ubyte0_e32 v98, v68
	v_cvt_f32_ubyte1_e32 v99, v68
	v_pk_fma_f32 v[62:63], v[50:51], v[146:147], v[62:63] op_sel:[1,0,0]
	v_cvt_f32_ubyte2_e32 v102, v68
	v_cvt_f32_ubyte3_e32 v103, v68
	v_pk_fma_f32 v[92:93], v[52:53], v[98:99], v[92:93] op_sel_hi:[0,1,1]
	v_cvt_f32_ubyte0_e32 v104, v216
	v_cvt_f32_ubyte1_e32 v105, v216
	v_pk_fma_f32 v[90:91], v[52:53], v[102:103], v[90:91] op_sel_hi:[0,1,1]
	v_cvt_f32_ubyte2_e32 v146, v216
	v_cvt_f32_ubyte3_e32 v147, v216
	v_pk_fma_f32 v[86:87], v[52:53], v[104:105], v[86:87] op_sel_hi:[0,1,1]
	v_cvt_f32_ubyte0_e32 v98, v76
	v_cvt_f32_ubyte1_e32 v99, v76
	v_pk_fma_f32 v[84:85], v[52:53], v[146:147], v[84:85] op_sel_hi:[0,1,1]
	v_and_b32_e32 v82, s0, v218
	v_and_b32_e32 v88, s0, v219
	v_cvt_f32_ubyte2_e32 v102, v76
	v_cvt_f32_ubyte3_e32 v103, v76
	v_pk_fma_f32 v[80:81], v[52:53], v[98:99], v[80:81] op_sel_hi:[0,1,1]
	v_cvt_f32_ubyte0_e32 v104, v217
	v_cvt_f32_ubyte1_e32 v105, v217
	v_pk_fma_f32 v[78:79], v[52:53], v[102:103], v[78:79] op_sel_hi:[0,1,1]
	v_cvt_f32_ubyte2_e32 v146, v217
	v_cvt_f32_ubyte3_e32 v147, v217
	v_pk_fma_f32 v[70:71], v[52:53], v[104:105], v[70:71] op_sel_hi:[0,1,1]
	v_cvt_f32_ubyte0_e32 v98, v82
	v_cvt_f32_ubyte1_e32 v99, v82
	v_pk_fma_f32 v[62:63], v[52:53], v[146:147], v[62:63] op_sel_hi:[0,1,1]
	v_cvt_f32_ubyte2_e32 v102, v82
	v_cvt_f32_ubyte3_e32 v103, v82
	v_pk_fma_f32 v[92:93], v[52:53], v[98:99], v[92:93] op_sel:[1,0,0]
	v_cvt_f32_ubyte0_e32 v104, v218
	v_cvt_f32_ubyte1_e32 v105, v218
	v_pk_fma_f32 v[90:91], v[52:53], v[102:103], v[90:91] op_sel:[1,0,0]
	v_cvt_f32_ubyte2_e32 v146, v218
	v_cvt_f32_ubyte3_e32 v147, v218
	v_pk_fma_f32 v[86:87], v[52:53], v[104:105], v[86:87] op_sel:[1,0,0]
	v_cvt_f32_ubyte0_e32 v98, v88
	v_cvt_f32_ubyte1_e32 v99, v88
	v_pk_fma_f32 v[84:85], v[52:53], v[146:147], v[84:85] op_sel:[1,0,0]
	v_and_b32_e32 v68, s0, v220
	v_and_b32_e32 v76, s0, v221
	v_cvt_f32_ubyte2_e32 v102, v88
	v_cvt_f32_ubyte3_e32 v103, v88
	v_pk_fma_f32 v[80:81], v[52:53], v[98:99], v[80:81] op_sel:[1,0,0]
	v_cvt_f32_ubyte0_e32 v104, v219
	v_cvt_f32_ubyte1_e32 v105, v219
	v_pk_fma_f32 v[78:79], v[52:53], v[102:103], v[78:79] op_sel:[1,0,0]
	v_cvt_f32_ubyte2_e32 v146, v219
	v_cvt_f32_ubyte3_e32 v147, v219
	v_pk_fma_f32 v[70:71], v[52:53], v[104:105], v[70:71] op_sel:[1,0,0]
	v_cvt_f32_ubyte0_e32 v98, v68
	v_cvt_f32_ubyte1_e32 v99, v68
	v_pk_fma_f32 v[62:63], v[52:53], v[146:147], v[62:63] op_sel:[1,0,0]
	v_cvt_f32_ubyte2_e32 v102, v68
	v_cvt_f32_ubyte3_e32 v103, v68
	v_pk_fma_f32 v[92:93], v[54:55], v[98:99], v[92:93] op_sel_hi:[0,1,1]
	v_cvt_f32_ubyte0_e32 v104, v220
	v_cvt_f32_ubyte1_e32 v105, v220
	v_pk_fma_f32 v[90:91], v[54:55], v[102:103], v[90:91] op_sel_hi:[0,1,1]
	v_cvt_f32_ubyte2_e32 v146, v220
	v_cvt_f32_ubyte3_e32 v147, v220
	v_pk_fma_f32 v[86:87], v[54:55], v[104:105], v[86:87] op_sel_hi:[0,1,1]
	v_cvt_f32_ubyte0_e32 v98, v76
	v_cvt_f32_ubyte1_e32 v99, v76
	v_pk_fma_f32 v[84:85], v[54:55], v[146:147], v[84:85] op_sel_hi:[0,1,1]
	v_and_b32_e32 v82, s0, v222
	v_and_b32_e32 v88, s0, v223
	v_cvt_f32_ubyte2_e32 v102, v76
	v_cvt_f32_ubyte3_e32 v103, v76
	v_pk_fma_f32 v[80:81], v[54:55], v[98:99], v[80:81] op_sel_hi:[0,1,1]
	v_cvt_f32_ubyte0_e32 v104, v221
	v_cvt_f32_ubyte1_e32 v105, v221
	v_pk_fma_f32 v[78:79], v[54:55], v[102:103], v[78:79] op_sel_hi:[0,1,1]
	v_cvt_f32_ubyte2_e32 v146, v221
	v_cvt_f32_ubyte3_e32 v147, v221
	v_pk_fma_f32 v[70:71], v[54:55], v[104:105], v[70:71] op_sel_hi:[0,1,1]
	v_cvt_f32_ubyte0_e32 v98, v82
	v_cvt_f32_ubyte1_e32 v99, v82
	v_pk_fma_f32 v[62:63], v[54:55], v[146:147], v[62:63] op_sel_hi:[0,1,1]
	v_cvt_f32_ubyte2_e32 v102, v82
	v_cvt_f32_ubyte3_e32 v103, v82
	v_pk_fma_f32 v[92:93], v[54:55], v[98:99], v[92:93] op_sel:[1,0,0]
	v_cvt_f32_ubyte0_e32 v104, v222
	v_cvt_f32_ubyte1_e32 v105, v222
	v_pk_fma_f32 v[90:91], v[54:55], v[102:103], v[90:91] op_sel:[1,0,0]
	v_cvt_f32_ubyte2_e32 v146, v222
	v_cvt_f32_ubyte3_e32 v147, v222
	v_pk_fma_f32 v[86:87], v[54:55], v[104:105], v[86:87] op_sel:[1,0,0]
	v_cvt_f32_ubyte0_e32 v98, v88
	v_cvt_f32_ubyte1_e32 v99, v88
	v_pk_fma_f32 v[84:85], v[54:55], v[146:147], v[84:85] op_sel:[1,0,0]
	v_and_b32_e32 v68, s0, v224
	v_and_b32_e32 v76, s0, v225
	v_cvt_f32_ubyte2_e32 v102, v88
	v_cvt_f32_ubyte3_e32 v103, v88
	v_pk_fma_f32 v[80:81], v[54:55], v[98:99], v[80:81] op_sel:[1,0,0]
	v_cvt_f32_ubyte0_e32 v104, v223
	v_cvt_f32_ubyte1_e32 v105, v223
	v_pk_fma_f32 v[78:79], v[54:55], v[102:103], v[78:79] op_sel:[1,0,0]
	v_cvt_f32_ubyte2_e32 v146, v223
	v_cvt_f32_ubyte3_e32 v147, v223
	v_pk_fma_f32 v[70:71], v[54:55], v[104:105], v[70:71] op_sel:[1,0,0]
	v_cvt_f32_ubyte0_e32 v98, v68
	v_cvt_f32_ubyte1_e32 v99, v68
	v_pk_fma_f32 v[62:63], v[54:55], v[146:147], v[62:63] op_sel:[1,0,0]
	v_cvt_f32_ubyte2_e32 v102, v68
	v_cvt_f32_ubyte3_e32 v103, v68
	v_pk_fma_f32 v[92:93], v[56:57], v[98:99], v[92:93] op_sel_hi:[0,1,1]
	v_cvt_f32_ubyte0_e32 v104, v224
	v_cvt_f32_ubyte1_e32 v105, v224
	v_pk_fma_f32 v[90:91], v[56:57], v[102:103], v[90:91] op_sel_hi:[0,1,1]
	v_cvt_f32_ubyte2_e32 v146, v224
	v_cvt_f32_ubyte3_e32 v147, v224
	v_pk_fma_f32 v[86:87], v[56:57], v[104:105], v[86:87] op_sel_hi:[0,1,1]
	v_cvt_f32_ubyte0_e32 v98, v76
	v_cvt_f32_ubyte1_e32 v99, v76
	v_pk_fma_f32 v[84:85], v[56:57], v[146:147], v[84:85] op_sel_hi:[0,1,1]
	v_and_b32_e32 v82, s0, v226
	v_and_b32_e32 v88, s0, v227
	v_cvt_f32_ubyte2_e32 v102, v76
	v_cvt_f32_ubyte3_e32 v103, v76
	v_pk_fma_f32 v[80:81], v[56:57], v[98:99], v[80:81] op_sel_hi:[0,1,1]
	v_cvt_f32_ubyte0_e32 v104, v225
	v_cvt_f32_ubyte1_e32 v105, v225
	v_pk_fma_f32 v[78:79], v[56:57], v[102:103], v[78:79] op_sel_hi:[0,1,1]
	v_cvt_f32_ubyte2_e32 v146, v225
	v_cvt_f32_ubyte3_e32 v147, v225
	v_pk_fma_f32 v[70:71], v[56:57], v[104:105], v[70:71] op_sel_hi:[0,1,1]
	v_cvt_f32_ubyte0_e32 v98, v82
	v_cvt_f32_ubyte1_e32 v99, v82
	v_pk_fma_f32 v[62:63], v[56:57], v[146:147], v[62:63] op_sel_hi:[0,1,1]
	v_cvt_f32_ubyte2_e32 v102, v82
	v_cvt_f32_ubyte3_e32 v103, v82
	v_pk_fma_f32 v[92:93], v[56:57], v[98:99], v[92:93] op_sel:[1,0,0]
	v_cvt_f32_ubyte0_e32 v104, v226
	v_cvt_f32_ubyte1_e32 v105, v226
	v_pk_fma_f32 v[90:91], v[56:57], v[102:103], v[90:91] op_sel:[1,0,0]
	v_cvt_f32_ubyte2_e32 v146, v226
	v_cvt_f32_ubyte3_e32 v147, v226
	v_pk_fma_f32 v[86:87], v[56:57], v[104:105], v[86:87] op_sel:[1,0,0]
	v_cvt_f32_ubyte0_e32 v98, v88
	v_cvt_f32_ubyte1_e32 v99, v88
	v_pk_fma_f32 v[84:85], v[56:57], v[146:147], v[84:85] op_sel:[1,0,0]
	v_cvt_f32_ubyte2_e32 v102, v88
	v_cvt_f32_ubyte3_e32 v103, v88
	v_pk_fma_f32 v[80:81], v[56:57], v[98:99], v[80:81] op_sel:[1,0,0]
	v_cvt_f32_ubyte0_e32 v104, v227
	v_cvt_f32_ubyte1_e32 v105, v227
	v_pk_fma_f32 v[78:79], v[56:57], v[102:103], v[78:79] op_sel:[1,0,0]
	v_cvt_f32_ubyte2_e32 v146, v227
	v_cvt_f32_ubyte3_e32 v147, v227
	v_pk_fma_f32 v[70:71], v[56:57], v[104:105], v[70:71] op_sel:[1,0,0]
	v_pk_fma_f32 v[62:63], v[56:57], v[146:147], v[62:63] op_sel:[1,0,0]
	s_waitcnt lgkmcnt(0)
	v_lshl_add_u32 v72, v72, 9, v100
	v_lshl_add_u32 v73, v73, 9, v100
	v_lshl_add_u32 v74, v74, 9, v100
	v_lshl_add_u32 v75, v75, 9, v100
	v_lshl_add_u32 v94, v94, 9, v100
	v_lshl_add_u32 v95, v95, 9, v100
	v_lshl_add_u32 v96, v96, 9, v100
	v_lshl_add_u32 v97, v97, 9, v100
	global_load_dwordx2 v[212:213], v72, s[38:39]
	global_load_dwordx2 v[214:215], v73, s[38:39]
	global_load_dwordx2 v[216:217], v74, s[38:39]
	global_load_dwordx2 v[218:219], v75, s[38:39]
	global_load_dwordx2 v[220:221], v94, s[38:39]
	global_load_dwordx2 v[222:223], v95, s[38:39]
	global_load_dwordx2 v[224:225], v96, s[38:39]
	global_load_dwordx2 v[226:227], v97, s[38:39]
	ds_read_b128 v[72:75], v1 offset:320
	ds_read_b128 v[94:97], v1 offset:336
	ds_read_b128 v[50:53], v1 offset:672
	ds_read_b128 v[54:57], v1 offset:688
	s_waitcnt vmcnt(40)
	v_and_b32_e32 v68, s0, v2
	v_and_b32_e32 v76, s0, v3
	v_cvt_f32_ubyte0_e32 v98, v68
	v_cvt_f32_ubyte1_e32 v99, v68
	v_cvt_f32_ubyte2_e32 v102, v68
	v_cvt_f32_ubyte3_e32 v103, v68
	v_pk_fma_f32 v[92:93], v[34:35], v[98:99], v[92:93] op_sel_hi:[0,1,1]
	v_cvt_f32_ubyte0_e32 v104, v2
	v_cvt_f32_ubyte1_e32 v105, v2
	v_pk_fma_f32 v[90:91], v[34:35], v[102:103], v[90:91] op_sel_hi:[0,1,1]
	v_cvt_f32_ubyte2_e32 v146, v2
	v_cvt_f32_ubyte3_e32 v147, v2
	v_pk_fma_f32 v[86:87], v[34:35], v[104:105], v[86:87] op_sel_hi:[0,1,1]
	v_cvt_f32_ubyte0_e32 v98, v76
	v_cvt_f32_ubyte1_e32 v99, v76
	v_pk_fma_f32 v[84:85], v[34:35], v[146:147], v[84:85] op_sel_hi:[0,1,1]
	v_and_b32_e32 v82, s0, v4
	v_and_b32_e32 v88, s0, v5
	v_cvt_f32_ubyte2_e32 v102, v76
	v_cvt_f32_ubyte3_e32 v103, v76
	v_pk_fma_f32 v[80:81], v[34:35], v[98:99], v[80:81] op_sel_hi:[0,1,1]
	v_cvt_f32_ubyte0_e32 v104, v3
	v_cvt_f32_ubyte1_e32 v105, v3
	v_pk_fma_f32 v[78:79], v[34:35], v[102:103], v[78:79] op_sel_hi:[0,1,1]
	v_cvt_f32_ubyte2_e32 v146, v3
	v_cvt_f32_ubyte3_e32 v147, v3
	v_pk_fma_f32 v[70:71], v[34:35], v[104:105], v[70:71] op_sel_hi:[0,1,1]
	v_cvt_f32_ubyte0_e32 v98, v82
	v_cvt_f32_ubyte1_e32 v99, v82
	v_pk_fma_f32 v[62:63], v[34:35], v[146:147], v[62:63] op_sel_hi:[0,1,1]
	v_cvt_f32_ubyte2_e32 v102, v82
	v_cvt_f32_ubyte3_e32 v103, v82
	v_pk_fma_f32 v[92:93], v[34:35], v[98:99], v[92:93] op_sel:[1,0,0]
	v_cvt_f32_ubyte0_e32 v104, v4
	v_cvt_f32_ubyte1_e32 v105, v4
	v_pk_fma_f32 v[90:91], v[34:35], v[102:103], v[90:91] op_sel:[1,0,0]
	v_cvt_f32_ubyte2_e32 v146, v4
	v_cvt_f32_ubyte3_e32 v147, v4
	v_pk_fma_f32 v[86:87], v[34:35], v[104:105], v[86:87] op_sel:[1,0,0]
	v_cvt_f32_ubyte0_e32 v98, v88
	v_cvt_f32_ubyte1_e32 v99, v88
	v_pk_fma_f32 v[84:85], v[34:35], v[146:147], v[84:85] op_sel:[1,0,0]
	v_and_b32_e32 v68, s0, v6
	v_and_b32_e32 v76, s0, v7
	v_cvt_f32_ubyte2_e32 v102, v88
	v_cvt_f32_ubyte3_e32 v103, v88
	v_pk_fma_f32 v[80:81], v[34:35], v[98:99], v[80:81] op_sel:[1,0,0]
	v_cvt_f32_ubyte0_e32 v104, v5
	v_cvt_f32_ubyte1_e32 v105, v5
	v_pk_fma_f32 v[78:79], v[34:35], v[102:103], v[78:79] op_sel:[1,0,0]
	v_cvt_f32_ubyte2_e32 v146, v5
	v_cvt_f32_ubyte3_e32 v147, v5
	v_pk_fma_f32 v[70:71], v[34:35], v[104:105], v[70:71] op_sel:[1,0,0]
	v_cvt_f32_ubyte0_e32 v98, v68
	v_cvt_f32_ubyte1_e32 v99, v68
	v_pk_fma_f32 v[62:63], v[34:35], v[146:147], v[62:63] op_sel:[1,0,0]
	v_cvt_f32_ubyte2_e32 v102, v68
	v_cvt_f32_ubyte3_e32 v103, v68
	v_pk_fma_f32 v[92:93], v[36:37], v[98:99], v[92:93] op_sel_hi:[0,1,1]
	v_cvt_f32_ubyte0_e32 v104, v6
	v_cvt_f32_ubyte1_e32 v105, v6
	v_pk_fma_f32 v[90:91], v[36:37], v[102:103], v[90:91] op_sel_hi:[0,1,1]
	v_cvt_f32_ubyte2_e32 v146, v6
	v_cvt_f32_ubyte3_e32 v147, v6
	v_pk_fma_f32 v[86:87], v[36:37], v[104:105], v[86:87] op_sel_hi:[0,1,1]
	v_cvt_f32_ubyte0_e32 v98, v76
	v_cvt_f32_ubyte1_e32 v99, v76
	v_pk_fma_f32 v[84:85], v[36:37], v[146:147], v[84:85] op_sel_hi:[0,1,1]
	v_and_b32_e32 v82, s0, v8
	v_and_b32_e32 v88, s0, v9
	v_cvt_f32_ubyte2_e32 v102, v76
	v_cvt_f32_ubyte3_e32 v103, v76
	v_pk_fma_f32 v[80:81], v[36:37], v[98:99], v[80:81] op_sel_hi:[0,1,1]
	v_cvt_f32_ubyte0_e32 v104, v7
	v_cvt_f32_ubyte1_e32 v105, v7
	v_pk_fma_f32 v[78:79], v[36:37], v[102:103], v[78:79] op_sel_hi:[0,1,1]
	v_cvt_f32_ubyte2_e32 v146, v7
	v_cvt_f32_ubyte3_e32 v147, v7
	v_pk_fma_f32 v[70:71], v[36:37], v[104:105], v[70:71] op_sel_hi:[0,1,1]
	v_cvt_f32_ubyte0_e32 v98, v82
	v_cvt_f32_ubyte1_e32 v99, v82
	v_pk_fma_f32 v[62:63], v[36:37], v[146:147], v[62:63] op_sel_hi:[0,1,1]
	v_cvt_f32_ubyte2_e32 v102, v82
	v_cvt_f32_ubyte3_e32 v103, v82
	v_pk_fma_f32 v[92:93], v[36:37], v[98:99], v[92:93] op_sel:[1,0,0]
	v_cvt_f32_ubyte0_e32 v104, v8
	v_cvt_f32_ubyte1_e32 v105, v8
	v_pk_fma_f32 v[90:91], v[36:37], v[102:103], v[90:91] op_sel:[1,0,0]
	v_cvt_f32_ubyte2_e32 v146, v8
	v_cvt_f32_ubyte3_e32 v147, v8
	v_pk_fma_f32 v[86:87], v[36:37], v[104:105], v[86:87] op_sel:[1,0,0]
	v_cvt_f32_ubyte0_e32 v98, v88
	v_cvt_f32_ubyte1_e32 v99, v88
	v_pk_fma_f32 v[84:85], v[36:37], v[146:147], v[84:85] op_sel:[1,0,0]
	v_and_b32_e32 v68, s0, v10
	v_and_b32_e32 v76, s0, v11
	v_cvt_f32_ubyte2_e32 v102, v88
	v_cvt_f32_ubyte3_e32 v103, v88
	v_pk_fma_f32 v[80:81], v[36:37], v[98:99], v[80:81] op_sel:[1,0,0]
	v_cvt_f32_ubyte0_e32 v104, v9
	v_cvt_f32_ubyte1_e32 v105, v9
	v_pk_fma_f32 v[78:79], v[36:37], v[102:103], v[78:79] op_sel:[1,0,0]
	v_cvt_f32_ubyte2_e32 v146, v9
	v_cvt_f32_ubyte3_e32 v147, v9
	v_pk_fma_f32 v[70:71], v[36:37], v[104:105], v[70:71] op_sel:[1,0,0]
	v_cvt_f32_ubyte0_e32 v98, v68
	v_cvt_f32_ubyte1_e32 v99, v68
	v_pk_fma_f32 v[62:63], v[36:37], v[146:147], v[62:63] op_sel:[1,0,0]
	v_cvt_f32_ubyte2_e32 v102, v68
	v_cvt_f32_ubyte3_e32 v103, v68
	v_pk_fma_f32 v[92:93], v[38:39], v[98:99], v[92:93] op_sel_hi:[0,1,1]
	v_cvt_f32_ubyte0_e32 v104, v10
	v_cvt_f32_ubyte1_e32 v105, v10
	v_pk_fma_f32 v[90:91], v[38:39], v[102:103], v[90:91] op_sel_hi:[0,1,1]
	v_cvt_f32_ubyte2_e32 v146, v10
	v_cvt_f32_ubyte3_e32 v147, v10
	v_pk_fma_f32 v[86:87], v[38:39], v[104:105], v[86:87] op_sel_hi:[0,1,1]
	v_cvt_f32_ubyte0_e32 v98, v76
	v_cvt_f32_ubyte1_e32 v99, v76
	v_pk_fma_f32 v[84:85], v[38:39], v[146:147], v[84:85] op_sel_hi:[0,1,1]
	v_and_b32_e32 v82, s0, v12
	v_and_b32_e32 v88, s0, v13
	v_cvt_f32_ubyte2_e32 v102, v76
	v_cvt_f32_ubyte3_e32 v103, v76
	v_pk_fma_f32 v[80:81], v[38:39], v[98:99], v[80:81] op_sel_hi:[0,1,1]
	v_cvt_f32_ubyte0_e32 v104, v11
	v_cvt_f32_ubyte1_e32 v105, v11
	v_pk_fma_f32 v[78:79], v[38:39], v[102:103], v[78:79] op_sel_hi:[0,1,1]
	v_cvt_f32_ubyte2_e32 v146, v11
	v_cvt_f32_ubyte3_e32 v147, v11
	v_pk_fma_f32 v[70:71], v[38:39], v[104:105], v[70:71] op_sel_hi:[0,1,1]
	v_cvt_f32_ubyte0_e32 v98, v82
	v_cvt_f32_ubyte1_e32 v99, v82
	v_pk_fma_f32 v[62:63], v[38:39], v[146:147], v[62:63] op_sel_hi:[0,1,1]
	v_cvt_f32_ubyte2_e32 v102, v82
	v_cvt_f32_ubyte3_e32 v103, v82
	v_pk_fma_f32 v[92:93], v[38:39], v[98:99], v[92:93] op_sel:[1,0,0]
	v_cvt_f32_ubyte0_e32 v104, v12
	v_cvt_f32_ubyte1_e32 v105, v12
	v_pk_fma_f32 v[90:91], v[38:39], v[102:103], v[90:91] op_sel:[1,0,0]
	v_cvt_f32_ubyte2_e32 v146, v12
	v_cvt_f32_ubyte3_e32 v147, v12
	v_pk_fma_f32 v[86:87], v[38:39], v[104:105], v[86:87] op_sel:[1,0,0]
	v_cvt_f32_ubyte0_e32 v98, v88
	v_cvt_f32_ubyte1_e32 v99, v88
	v_pk_fma_f32 v[84:85], v[38:39], v[146:147], v[84:85] op_sel:[1,0,0]
	v_and_b32_e32 v68, s0, v14
	v_and_b32_e32 v76, s0, v15
	v_cvt_f32_ubyte2_e32 v102, v88
	v_cvt_f32_ubyte3_e32 v103, v88
	v_pk_fma_f32 v[80:81], v[38:39], v[98:99], v[80:81] op_sel:[1,0,0]
	v_cvt_f32_ubyte0_e32 v104, v13
	v_cvt_f32_ubyte1_e32 v105, v13
	v_pk_fma_f32 v[78:79], v[38:39], v[102:103], v[78:79] op_sel:[1,0,0]
	v_cvt_f32_ubyte2_e32 v146, v13
	v_cvt_f32_ubyte3_e32 v147, v13
	v_pk_fma_f32 v[70:71], v[38:39], v[104:105], v[70:71] op_sel:[1,0,0]
	v_cvt_f32_ubyte0_e32 v98, v68
	v_cvt_f32_ubyte1_e32 v99, v68
	v_pk_fma_f32 v[62:63], v[38:39], v[146:147], v[62:63] op_sel:[1,0,0]
	v_cvt_f32_ubyte2_e32 v102, v68
	v_cvt_f32_ubyte3_e32 v103, v68
	v_pk_fma_f32 v[92:93], v[40:41], v[98:99], v[92:93] op_sel_hi:[0,1,1]
	v_cvt_f32_ubyte0_e32 v104, v14
	v_cvt_f32_ubyte1_e32 v105, v14
	v_pk_fma_f32 v[90:91], v[40:41], v[102:103], v[90:91] op_sel_hi:[0,1,1]
	v_cvt_f32_ubyte2_e32 v146, v14
	v_cvt_f32_ubyte3_e32 v147, v14
	v_pk_fma_f32 v[86:87], v[40:41], v[104:105], v[86:87] op_sel_hi:[0,1,1]
	v_cvt_f32_ubyte0_e32 v98, v76
	v_cvt_f32_ubyte1_e32 v99, v76
	v_pk_fma_f32 v[84:85], v[40:41], v[146:147], v[84:85] op_sel_hi:[0,1,1]
	v_and_b32_e32 v82, s0, v16
	v_and_b32_e32 v88, s0, v17
	v_cvt_f32_ubyte2_e32 v102, v76
	v_cvt_f32_ubyte3_e32 v103, v76
	v_pk_fma_f32 v[80:81], v[40:41], v[98:99], v[80:81] op_sel_hi:[0,1,1]
	v_cvt_f32_ubyte0_e32 v104, v15
	v_cvt_f32_ubyte1_e32 v105, v15
	v_pk_fma_f32 v[78:79], v[40:41], v[102:103], v[78:79] op_sel_hi:[0,1,1]
	v_cvt_f32_ubyte2_e32 v146, v15
	v_cvt_f32_ubyte3_e32 v147, v15
	v_pk_fma_f32 v[70:71], v[40:41], v[104:105], v[70:71] op_sel_hi:[0,1,1]
	v_cvt_f32_ubyte0_e32 v98, v82
	v_cvt_f32_ubyte1_e32 v99, v82
	v_pk_fma_f32 v[62:63], v[40:41], v[146:147], v[62:63] op_sel_hi:[0,1,1]
	v_cvt_f32_ubyte2_e32 v102, v82
	v_cvt_f32_ubyte3_e32 v103, v82
	v_pk_fma_f32 v[92:93], v[40:41], v[98:99], v[92:93] op_sel:[1,0,0]
	v_cvt_f32_ubyte0_e32 v104, v16
	v_cvt_f32_ubyte1_e32 v105, v16
	v_pk_fma_f32 v[90:91], v[40:41], v[102:103], v[90:91] op_sel:[1,0,0]
	v_cvt_f32_ubyte2_e32 v146, v16
	v_cvt_f32_ubyte3_e32 v147, v16
	v_pk_fma_f32 v[86:87], v[40:41], v[104:105], v[86:87] op_sel:[1,0,0]
	v_cvt_f32_ubyte0_e32 v98, v88
	v_cvt_f32_ubyte1_e32 v99, v88
	v_pk_fma_f32 v[84:85], v[40:41], v[146:147], v[84:85] op_sel:[1,0,0]
	v_cvt_f32_ubyte2_e32 v102, v88
	v_cvt_f32_ubyte3_e32 v103, v88
	v_pk_fma_f32 v[80:81], v[40:41], v[98:99], v[80:81] op_sel:[1,0,0]
	v_cvt_f32_ubyte0_e32 v104, v17
	v_cvt_f32_ubyte1_e32 v105, v17
	v_pk_fma_f32 v[78:79], v[40:41], v[102:103], v[78:79] op_sel:[1,0,0]
	v_cvt_f32_ubyte2_e32 v146, v17
	v_cvt_f32_ubyte3_e32 v147, v17
	v_pk_fma_f32 v[70:71], v[40:41], v[104:105], v[70:71] op_sel:[1,0,0]
	v_pk_fma_f32 v[62:63], v[40:41], v[146:147], v[62:63] op_sel:[1,0,0]
	s_waitcnt lgkmcnt(0)
	v_lshl_add_u32 v72, v72, 9, v100
	v_lshl_add_u32 v73, v73, 9, v100
	v_lshl_add_u32 v74, v74, 9, v100
	v_lshl_add_u32 v75, v75, 9, v100
	v_lshl_add_u32 v94, v94, 9, v100
	v_lshl_add_u32 v95, v95, 9, v100
	v_lshl_add_u32 v96, v96, 9, v100
	v_lshl_add_u32 v97, v97, 9, v100
	global_load_dwordx2 v[2:3], v72, s[38:39]
	global_load_dwordx2 v[4:5], v73, s[38:39]
	global_load_dwordx2 v[6:7], v74, s[38:39]
	global_load_dwordx2 v[8:9], v75, s[38:39]
	global_load_dwordx2 v[10:11], v94, s[38:39]
	global_load_dwordx2 v[12:13], v95, s[38:39]
	global_load_dwordx2 v[14:15], v96, s[38:39]
	global_load_dwordx2 v[16:17], v97, s[38:39]
	ds_read_b128 v[72:75], v1 offset:352
	ds_read_b128 v[94:97], v1 offset:368
	ds_read_b128 v[34:37], v1 offset:704
	ds_read_b128 v[38:41], v1 offset:720
	s_waitcnt vmcnt(40)
	v_and_b32_e32 v68, s0, v18
	v_and_b32_e32 v76, s0, v19
	v_cvt_f32_ubyte0_e32 v98, v68
	v_cvt_f32_ubyte1_e32 v99, v68
	v_cvt_f32_ubyte2_e32 v102, v68
	v_cvt_f32_ubyte3_e32 v103, v68
	v_pk_fma_f32 v[92:93], v[50:51], v[98:99], v[92:93] op_sel_hi:[0,1,1]
	v_cvt_f32_ubyte0_e32 v104, v18
	v_cvt_f32_ubyte1_e32 v105, v18
	v_pk_fma_f32 v[90:91], v[50:51], v[102:103], v[90:91] op_sel_hi:[0,1,1]
	v_cvt_f32_ubyte2_e32 v146, v18
	v_cvt_f32_ubyte3_e32 v147, v18
	v_pk_fma_f32 v[86:87], v[50:51], v[104:105], v[86:87] op_sel_hi:[0,1,1]
	v_cvt_f32_ubyte0_e32 v98, v76
	v_cvt_f32_ubyte1_e32 v99, v76
	v_pk_fma_f32 v[84:85], v[50:51], v[146:147], v[84:85] op_sel_hi:[0,1,1]
	v_and_b32_e32 v82, s0, v20
	v_and_b32_e32 v88, s0, v21
	v_cvt_f32_ubyte2_e32 v102, v76
	v_cvt_f32_ubyte3_e32 v103, v76
	v_pk_fma_f32 v[80:81], v[50:51], v[98:99], v[80:81] op_sel_hi:[0,1,1]
	v_cvt_f32_ubyte0_e32 v104, v19
	v_cvt_f32_ubyte1_e32 v105, v19
	v_pk_fma_f32 v[78:79], v[50:51], v[102:103], v[78:79] op_sel_hi:[0,1,1]
	v_cvt_f32_ubyte2_e32 v146, v19
	v_cvt_f32_ubyte3_e32 v147, v19
	v_pk_fma_f32 v[70:71], v[50:51], v[104:105], v[70:71] op_sel_hi:[0,1,1]
	v_cvt_f32_ubyte0_e32 v98, v82
	v_cvt_f32_ubyte1_e32 v99, v82
	v_pk_fma_f32 v[62:63], v[50:51], v[146:147], v[62:63] op_sel_hi:[0,1,1]
	v_cvt_f32_ubyte2_e32 v102, v82
	v_cvt_f32_ubyte3_e32 v103, v82
	v_pk_fma_f32 v[92:93], v[50:51], v[98:99], v[92:93] op_sel:[1,0,0]
	v_cvt_f32_ubyte0_e32 v104, v20
	v_cvt_f32_ubyte1_e32 v105, v20
	v_pk_fma_f32 v[90:91], v[50:51], v[102:103], v[90:91] op_sel:[1,0,0]
	v_cvt_f32_ubyte2_e32 v146, v20
	v_cvt_f32_ubyte3_e32 v147, v20
	v_pk_fma_f32 v[86:87], v[50:51], v[104:105], v[86:87] op_sel:[1,0,0]
	v_cvt_f32_ubyte0_e32 v98, v88
	v_cvt_f32_ubyte1_e32 v99, v88
	v_pk_fma_f32 v[84:85], v[50:51], v[146:147], v[84:85] op_sel:[1,0,0]
	v_and_b32_e32 v68, s0, v22
	v_and_b32_e32 v76, s0, v23
	v_cvt_f32_ubyte2_e32 v102, v88
	v_cvt_f32_ubyte3_e32 v103, v88
	v_pk_fma_f32 v[80:81], v[50:51], v[98:99], v[80:81] op_sel:[1,0,0]
	v_cvt_f32_ubyte0_e32 v104, v21
	v_cvt_f32_ubyte1_e32 v105, v21
	v_pk_fma_f32 v[78:79], v[50:51], v[102:103], v[78:79] op_sel:[1,0,0]
	v_cvt_f32_ubyte2_e32 v146, v21
	v_cvt_f32_ubyte3_e32 v147, v21
	v_pk_fma_f32 v[70:71], v[50:51], v[104:105], v[70:71] op_sel:[1,0,0]
	v_cvt_f32_ubyte0_e32 v98, v68
	v_cvt_f32_ubyte1_e32 v99, v68
	v_pk_fma_f32 v[62:63], v[50:51], v[146:147], v[62:63] op_sel:[1,0,0]
	v_cvt_f32_ubyte2_e32 v102, v68
	v_cvt_f32_ubyte3_e32 v103, v68
	v_pk_fma_f32 v[92:93], v[52:53], v[98:99], v[92:93] op_sel_hi:[0,1,1]
	v_cvt_f32_ubyte0_e32 v104, v22
	v_cvt_f32_ubyte1_e32 v105, v22
	v_pk_fma_f32 v[90:91], v[52:53], v[102:103], v[90:91] op_sel_hi:[0,1,1]
	v_cvt_f32_ubyte2_e32 v146, v22
	v_cvt_f32_ubyte3_e32 v147, v22
	v_pk_fma_f32 v[86:87], v[52:53], v[104:105], v[86:87] op_sel_hi:[0,1,1]
	v_cvt_f32_ubyte0_e32 v98, v76
	v_cvt_f32_ubyte1_e32 v99, v76
	v_pk_fma_f32 v[84:85], v[52:53], v[146:147], v[84:85] op_sel_hi:[0,1,1]
	v_and_b32_e32 v82, s0, v24
	v_and_b32_e32 v88, s0, v25
	v_cvt_f32_ubyte2_e32 v102, v76
	v_cvt_f32_ubyte3_e32 v103, v76
	v_pk_fma_f32 v[80:81], v[52:53], v[98:99], v[80:81] op_sel_hi:[0,1,1]
	v_cvt_f32_ubyte0_e32 v104, v23
	v_cvt_f32_ubyte1_e32 v105, v23
	v_pk_fma_f32 v[78:79], v[52:53], v[102:103], v[78:79] op_sel_hi:[0,1,1]
	v_cvt_f32_ubyte2_e32 v146, v23
	v_cvt_f32_ubyte3_e32 v147, v23
	v_pk_fma_f32 v[70:71], v[52:53], v[104:105], v[70:71] op_sel_hi:[0,1,1]
	v_cvt_f32_ubyte0_e32 v98, v82
	v_cvt_f32_ubyte1_e32 v99, v82
	v_pk_fma_f32 v[62:63], v[52:53], v[146:147], v[62:63] op_sel_hi:[0,1,1]
	v_cvt_f32_ubyte2_e32 v102, v82
	v_cvt_f32_ubyte3_e32 v103, v82
	v_pk_fma_f32 v[92:93], v[52:53], v[98:99], v[92:93] op_sel:[1,0,0]
	v_cvt_f32_ubyte0_e32 v104, v24
	v_cvt_f32_ubyte1_e32 v105, v24
	v_pk_fma_f32 v[90:91], v[52:53], v[102:103], v[90:91] op_sel:[1,0,0]
	v_cvt_f32_ubyte2_e32 v146, v24
	v_cvt_f32_ubyte3_e32 v147, v24
	v_pk_fma_f32 v[86:87], v[52:53], v[104:105], v[86:87] op_sel:[1,0,0]
	v_cvt_f32_ubyte0_e32 v98, v88
	v_cvt_f32_ubyte1_e32 v99, v88
	v_pk_fma_f32 v[84:85], v[52:53], v[146:147], v[84:85] op_sel:[1,0,0]
	v_and_b32_e32 v68, s0, v26
	v_and_b32_e32 v76, s0, v27
	v_cvt_f32_ubyte2_e32 v102, v88
	v_cvt_f32_ubyte3_e32 v103, v88
	v_pk_fma_f32 v[80:81], v[52:53], v[98:99], v[80:81] op_sel:[1,0,0]
	v_cvt_f32_ubyte0_e32 v104, v25
	v_cvt_f32_ubyte1_e32 v105, v25
	v_pk_fma_f32 v[78:79], v[52:53], v[102:103], v[78:79] op_sel:[1,0,0]
	v_cvt_f32_ubyte2_e32 v146, v25
	v_cvt_f32_ubyte3_e32 v147, v25
	v_pk_fma_f32 v[70:71], v[52:53], v[104:105], v[70:71] op_sel:[1,0,0]
	v_cvt_f32_ubyte0_e32 v98, v68
	v_cvt_f32_ubyte1_e32 v99, v68
	v_pk_fma_f32 v[62:63], v[52:53], v[146:147], v[62:63] op_sel:[1,0,0]
	v_cvt_f32_ubyte2_e32 v102, v68
	v_cvt_f32_ubyte3_e32 v103, v68
	v_pk_fma_f32 v[92:93], v[54:55], v[98:99], v[92:93] op_sel_hi:[0,1,1]
	v_cvt_f32_ubyte0_e32 v104, v26
	v_cvt_f32_ubyte1_e32 v105, v26
	v_pk_fma_f32 v[90:91], v[54:55], v[102:103], v[90:91] op_sel_hi:[0,1,1]
	v_cvt_f32_ubyte2_e32 v146, v26
	v_cvt_f32_ubyte3_e32 v147, v26
	v_pk_fma_f32 v[86:87], v[54:55], v[104:105], v[86:87] op_sel_hi:[0,1,1]
	v_cvt_f32_ubyte0_e32 v98, v76
	v_cvt_f32_ubyte1_e32 v99, v76
	v_pk_fma_f32 v[84:85], v[54:55], v[146:147], v[84:85] op_sel_hi:[0,1,1]
	v_and_b32_e32 v82, s0, v28
	v_and_b32_e32 v88, s0, v29
	v_cvt_f32_ubyte2_e32 v102, v76
	v_cvt_f32_ubyte3_e32 v103, v76
	v_pk_fma_f32 v[80:81], v[54:55], v[98:99], v[80:81] op_sel_hi:[0,1,1]
	v_cvt_f32_ubyte0_e32 v104, v27
	v_cvt_f32_ubyte1_e32 v105, v27
	v_pk_fma_f32 v[78:79], v[54:55], v[102:103], v[78:79] op_sel_hi:[0,1,1]
	v_cvt_f32_ubyte2_e32 v146, v27
	v_cvt_f32_ubyte3_e32 v147, v27
	v_pk_fma_f32 v[70:71], v[54:55], v[104:105], v[70:71] op_sel_hi:[0,1,1]
	v_cvt_f32_ubyte0_e32 v98, v82
	v_cvt_f32_ubyte1_e32 v99, v82
	v_pk_fma_f32 v[62:63], v[54:55], v[146:147], v[62:63] op_sel_hi:[0,1,1]
	v_cvt_f32_ubyte2_e32 v102, v82
	v_cvt_f32_ubyte3_e32 v103, v82
	v_pk_fma_f32 v[92:93], v[54:55], v[98:99], v[92:93] op_sel:[1,0,0]
	v_cvt_f32_ubyte0_e32 v104, v28
	v_cvt_f32_ubyte1_e32 v105, v28
	v_pk_fma_f32 v[90:91], v[54:55], v[102:103], v[90:91] op_sel:[1,0,0]
	v_cvt_f32_ubyte2_e32 v146, v28
	v_cvt_f32_ubyte3_e32 v147, v28
	v_pk_fma_f32 v[86:87], v[54:55], v[104:105], v[86:87] op_sel:[1,0,0]
	v_cvt_f32_ubyte0_e32 v98, v88
	v_cvt_f32_ubyte1_e32 v99, v88
	v_pk_fma_f32 v[84:85], v[54:55], v[146:147], v[84:85] op_sel:[1,0,0]
	v_and_b32_e32 v68, s0, v30
	v_and_b32_e32 v76, s0, v31
	v_cvt_f32_ubyte2_e32 v102, v88
	v_cvt_f32_ubyte3_e32 v103, v88
	v_pk_fma_f32 v[80:81], v[54:55], v[98:99], v[80:81] op_sel:[1,0,0]
	v_cvt_f32_ubyte0_e32 v104, v29
	v_cvt_f32_ubyte1_e32 v105, v29
	v_pk_fma_f32 v[78:79], v[54:55], v[102:103], v[78:79] op_sel:[1,0,0]
	v_cvt_f32_ubyte2_e32 v146, v29
	v_cvt_f32_ubyte3_e32 v147, v29
	v_pk_fma_f32 v[70:71], v[54:55], v[104:105], v[70:71] op_sel:[1,0,0]
	v_cvt_f32_ubyte0_e32 v98, v68
	v_cvt_f32_ubyte1_e32 v99, v68
	v_pk_fma_f32 v[62:63], v[54:55], v[146:147], v[62:63] op_sel:[1,0,0]
	v_cvt_f32_ubyte2_e32 v102, v68
	v_cvt_f32_ubyte3_e32 v103, v68
	v_pk_fma_f32 v[92:93], v[56:57], v[98:99], v[92:93] op_sel_hi:[0,1,1]
	v_cvt_f32_ubyte0_e32 v104, v30
	v_cvt_f32_ubyte1_e32 v105, v30
	v_pk_fma_f32 v[90:91], v[56:57], v[102:103], v[90:91] op_sel_hi:[0,1,1]
	v_cvt_f32_ubyte2_e32 v146, v30
	v_cvt_f32_ubyte3_e32 v147, v30
	v_pk_fma_f32 v[86:87], v[56:57], v[104:105], v[86:87] op_sel_hi:[0,1,1]
	v_cvt_f32_ubyte0_e32 v98, v76
	v_cvt_f32_ubyte1_e32 v99, v76
	v_pk_fma_f32 v[84:85], v[56:57], v[146:147], v[84:85] op_sel_hi:[0,1,1]
	v_and_b32_e32 v82, s0, v32
	v_and_b32_e32 v88, s0, v33
	v_cvt_f32_ubyte2_e32 v102, v76
	v_cvt_f32_ubyte3_e32 v103, v76
	v_pk_fma_f32 v[80:81], v[56:57], v[98:99], v[80:81] op_sel_hi:[0,1,1]
	v_cvt_f32_ubyte0_e32 v104, v31
	v_cvt_f32_ubyte1_e32 v105, v31
	v_pk_fma_f32 v[78:79], v[56:57], v[102:103], v[78:79] op_sel_hi:[0,1,1]
	v_cvt_f32_ubyte2_e32 v146, v31
	v_cvt_f32_ubyte3_e32 v147, v31
	v_pk_fma_f32 v[70:71], v[56:57], v[104:105], v[70:71] op_sel_hi:[0,1,1]
	v_cvt_f32_ubyte0_e32 v98, v82
	v_cvt_f32_ubyte1_e32 v99, v82
	v_pk_fma_f32 v[62:63], v[56:57], v[146:147], v[62:63] op_sel_hi:[0,1,1]
	v_cvt_f32_ubyte2_e32 v102, v82
	v_cvt_f32_ubyte3_e32 v103, v82
	v_pk_fma_f32 v[92:93], v[56:57], v[98:99], v[92:93] op_sel:[1,0,0]
	v_cvt_f32_ubyte0_e32 v104, v32
	v_cvt_f32_ubyte1_e32 v105, v32
	v_pk_fma_f32 v[90:91], v[56:57], v[102:103], v[90:91] op_sel:[1,0,0]
	v_cvt_f32_ubyte2_e32 v146, v32
	v_cvt_f32_ubyte3_e32 v147, v32
	v_pk_fma_f32 v[86:87], v[56:57], v[104:105], v[86:87] op_sel:[1,0,0]
	v_cvt_f32_ubyte0_e32 v98, v88
	v_cvt_f32_ubyte1_e32 v99, v88
	v_pk_fma_f32 v[84:85], v[56:57], v[146:147], v[84:85] op_sel:[1,0,0]
	v_cvt_f32_ubyte2_e32 v102, v88
	v_cvt_f32_ubyte3_e32 v103, v88
	v_pk_fma_f32 v[80:81], v[56:57], v[98:99], v[80:81] op_sel:[1,0,0]
	v_cvt_f32_ubyte0_e32 v104, v33
	v_cvt_f32_ubyte1_e32 v105, v33
	v_pk_fma_f32 v[78:79], v[56:57], v[102:103], v[78:79] op_sel:[1,0,0]
	v_cvt_f32_ubyte2_e32 v146, v33
	v_cvt_f32_ubyte3_e32 v147, v33
	v_pk_fma_f32 v[70:71], v[56:57], v[104:105], v[70:71] op_sel:[1,0,0]
	v_pk_fma_f32 v[62:63], v[56:57], v[146:147], v[62:63] op_sel:[1,0,0]
	s_waitcnt lgkmcnt(0)
	v_lshl_add_u32 v72, v72, 9, v100
	v_lshl_add_u32 v73, v73, 9, v100
	v_lshl_add_u32 v74, v74, 9, v100
	v_lshl_add_u32 v75, v75, 9, v100
	v_lshl_add_u32 v94, v94, 9, v100
	v_lshl_add_u32 v95, v95, 9, v100
	v_lshl_add_u32 v96, v96, 9, v100
	v_lshl_add_u32 v97, v97, 9, v100
	global_load_dwordx2 v[18:19], v72, s[38:39]
	global_load_dwordx2 v[20:21], v73, s[38:39]
	global_load_dwordx2 v[22:23], v74, s[38:39]
	global_load_dwordx2 v[24:25], v75, s[38:39]
	global_load_dwordx2 v[26:27], v94, s[38:39]
	global_load_dwordx2 v[28:29], v95, s[38:39]
	global_load_dwordx2 v[30:31], v96, s[38:39]
	global_load_dwordx2 v[32:33], v97, s[38:39]
	ds_read_b128 v[72:75], v1 offset:384
	ds_read_b128 v[94:97], v1 offset:400
	ds_read_b128 v[50:53], v1 offset:736
	ds_read_b128 v[54:57], v1 offset:752
	s_waitcnt vmcnt(40)
	v_and_b32_e32 v68, s0, v164
	v_and_b32_e32 v76, s0, v165
	v_cvt_f32_ubyte0_e32 v98, v68
	v_cvt_f32_ubyte1_e32 v99, v68
	v_cvt_f32_ubyte2_e32 v102, v68
	v_cvt_f32_ubyte3_e32 v103, v68
	v_pk_fma_f32 v[92:93], v[34:35], v[98:99], v[92:93] op_sel_hi:[0,1,1]
	v_cvt_f32_ubyte0_e32 v104, v164
	v_cvt_f32_ubyte1_e32 v105, v164
	v_pk_fma_f32 v[90:91], v[34:35], v[102:103], v[90:91] op_sel_hi:[0,1,1]
	v_cvt_f32_ubyte2_e32 v146, v164
	v_cvt_f32_ubyte3_e32 v147, v164
	v_pk_fma_f32 v[86:87], v[34:35], v[104:105], v[86:87] op_sel_hi:[0,1,1]
	v_cvt_f32_ubyte0_e32 v98, v76
	v_cvt_f32_ubyte1_e32 v99, v76
	v_pk_fma_f32 v[84:85], v[34:35], v[146:147], v[84:85] op_sel_hi:[0,1,1]
	v_and_b32_e32 v82, s0, v166
	v_and_b32_e32 v88, s0, v167
	v_cvt_f32_ubyte2_e32 v102, v76
	v_cvt_f32_ubyte3_e32 v103, v76
	v_pk_fma_f32 v[80:81], v[34:35], v[98:99], v[80:81] op_sel_hi:[0,1,1]
	v_cvt_f32_ubyte0_e32 v104, v165
	v_cvt_f32_ubyte1_e32 v105, v165
	v_pk_fma_f32 v[78:79], v[34:35], v[102:103], v[78:79] op_sel_hi:[0,1,1]
	v_cvt_f32_ubyte2_e32 v146, v165
	v_cvt_f32_ubyte3_e32 v147, v165
	v_pk_fma_f32 v[70:71], v[34:35], v[104:105], v[70:71] op_sel_hi:[0,1,1]
	v_cvt_f32_ubyte0_e32 v98, v82
	v_cvt_f32_ubyte1_e32 v99, v82
	v_pk_fma_f32 v[62:63], v[34:35], v[146:147], v[62:63] op_sel_hi:[0,1,1]
	v_cvt_f32_ubyte2_e32 v102, v82
	v_cvt_f32_ubyte3_e32 v103, v82
	v_pk_fma_f32 v[92:93], v[34:35], v[98:99], v[92:93] op_sel:[1,0,0]
	v_cvt_f32_ubyte0_e32 v104, v166
	v_cvt_f32_ubyte1_e32 v105, v166
	v_pk_fma_f32 v[90:91], v[34:35], v[102:103], v[90:91] op_sel:[1,0,0]
	v_cvt_f32_ubyte2_e32 v146, v166
	v_cvt_f32_ubyte3_e32 v147, v166
	v_pk_fma_f32 v[86:87], v[34:35], v[104:105], v[86:87] op_sel:[1,0,0]
	v_cvt_f32_ubyte0_e32 v98, v88
	v_cvt_f32_ubyte1_e32 v99, v88
	v_pk_fma_f32 v[84:85], v[34:35], v[146:147], v[84:85] op_sel:[1,0,0]
	v_and_b32_e32 v68, s0, v168
	v_and_b32_e32 v76, s0, v169
	v_cvt_f32_ubyte2_e32 v102, v88
	v_cvt_f32_ubyte3_e32 v103, v88
	v_pk_fma_f32 v[80:81], v[34:35], v[98:99], v[80:81] op_sel:[1,0,0]
	v_cvt_f32_ubyte0_e32 v104, v167
	v_cvt_f32_ubyte1_e32 v105, v167
	v_pk_fma_f32 v[78:79], v[34:35], v[102:103], v[78:79] op_sel:[1,0,0]
	v_cvt_f32_ubyte2_e32 v146, v167
	v_cvt_f32_ubyte3_e32 v147, v167
	v_pk_fma_f32 v[70:71], v[34:35], v[104:105], v[70:71] op_sel:[1,0,0]
	v_cvt_f32_ubyte0_e32 v98, v68
	v_cvt_f32_ubyte1_e32 v99, v68
	v_pk_fma_f32 v[62:63], v[34:35], v[146:147], v[62:63] op_sel:[1,0,0]
	v_cvt_f32_ubyte2_e32 v102, v68
	v_cvt_f32_ubyte3_e32 v103, v68
	v_pk_fma_f32 v[92:93], v[36:37], v[98:99], v[92:93] op_sel_hi:[0,1,1]
	v_cvt_f32_ubyte0_e32 v104, v168
	v_cvt_f32_ubyte1_e32 v105, v168
	v_pk_fma_f32 v[90:91], v[36:37], v[102:103], v[90:91] op_sel_hi:[0,1,1]
	v_cvt_f32_ubyte2_e32 v146, v168
	v_cvt_f32_ubyte3_e32 v147, v168
	v_pk_fma_f32 v[86:87], v[36:37], v[104:105], v[86:87] op_sel_hi:[0,1,1]
	v_cvt_f32_ubyte0_e32 v98, v76
	v_cvt_f32_ubyte1_e32 v99, v76
	v_pk_fma_f32 v[84:85], v[36:37], v[146:147], v[84:85] op_sel_hi:[0,1,1]
	v_and_b32_e32 v82, s0, v170
	v_and_b32_e32 v88, s0, v171
	v_cvt_f32_ubyte2_e32 v102, v76
	v_cvt_f32_ubyte3_e32 v103, v76
	v_pk_fma_f32 v[80:81], v[36:37], v[98:99], v[80:81] op_sel_hi:[0,1,1]
	v_cvt_f32_ubyte0_e32 v104, v169
	v_cvt_f32_ubyte1_e32 v105, v169
	v_pk_fma_f32 v[78:79], v[36:37], v[102:103], v[78:79] op_sel_hi:[0,1,1]
	v_cvt_f32_ubyte2_e32 v146, v169
	v_cvt_f32_ubyte3_e32 v147, v169
	v_pk_fma_f32 v[70:71], v[36:37], v[104:105], v[70:71] op_sel_hi:[0,1,1]
	v_cvt_f32_ubyte0_e32 v98, v82
	v_cvt_f32_ubyte1_e32 v99, v82
	v_pk_fma_f32 v[62:63], v[36:37], v[146:147], v[62:63] op_sel_hi:[0,1,1]
	v_cvt_f32_ubyte2_e32 v102, v82
	v_cvt_f32_ubyte3_e32 v103, v82
	v_pk_fma_f32 v[92:93], v[36:37], v[98:99], v[92:93] op_sel:[1,0,0]
	v_cvt_f32_ubyte0_e32 v104, v170
	v_cvt_f32_ubyte1_e32 v105, v170
	v_pk_fma_f32 v[90:91], v[36:37], v[102:103], v[90:91] op_sel:[1,0,0]
	v_cvt_f32_ubyte2_e32 v146, v170
	v_cvt_f32_ubyte3_e32 v147, v170
	v_pk_fma_f32 v[86:87], v[36:37], v[104:105], v[86:87] op_sel:[1,0,0]
	v_cvt_f32_ubyte0_e32 v98, v88
	v_cvt_f32_ubyte1_e32 v99, v88
	v_pk_fma_f32 v[84:85], v[36:37], v[146:147], v[84:85] op_sel:[1,0,0]
	v_and_b32_e32 v68, s0, v172
	v_and_b32_e32 v76, s0, v173
	v_cvt_f32_ubyte2_e32 v102, v88
	v_cvt_f32_ubyte3_e32 v103, v88
	v_pk_fma_f32 v[80:81], v[36:37], v[98:99], v[80:81] op_sel:[1,0,0]
	v_cvt_f32_ubyte0_e32 v104, v171
	v_cvt_f32_ubyte1_e32 v105, v171
	v_pk_fma_f32 v[78:79], v[36:37], v[102:103], v[78:79] op_sel:[1,0,0]
	v_cvt_f32_ubyte2_e32 v146, v171
	v_cvt_f32_ubyte3_e32 v147, v171
	v_pk_fma_f32 v[70:71], v[36:37], v[104:105], v[70:71] op_sel:[1,0,0]
	v_cvt_f32_ubyte0_e32 v98, v68
	v_cvt_f32_ubyte1_e32 v99, v68
	v_pk_fma_f32 v[62:63], v[36:37], v[146:147], v[62:63] op_sel:[1,0,0]
	v_cvt_f32_ubyte2_e32 v102, v68
	v_cvt_f32_ubyte3_e32 v103, v68
	v_pk_fma_f32 v[92:93], v[38:39], v[98:99], v[92:93] op_sel_hi:[0,1,1]
	v_cvt_f32_ubyte0_e32 v104, v172
	v_cvt_f32_ubyte1_e32 v105, v172
	v_pk_fma_f32 v[90:91], v[38:39], v[102:103], v[90:91] op_sel_hi:[0,1,1]
	v_cvt_f32_ubyte2_e32 v146, v172
	v_cvt_f32_ubyte3_e32 v147, v172
	v_pk_fma_f32 v[86:87], v[38:39], v[104:105], v[86:87] op_sel_hi:[0,1,1]
	v_cvt_f32_ubyte0_e32 v98, v76
	v_cvt_f32_ubyte1_e32 v99, v76
	v_pk_fma_f32 v[84:85], v[38:39], v[146:147], v[84:85] op_sel_hi:[0,1,1]
	v_and_b32_e32 v82, s0, v174
	v_and_b32_e32 v88, s0, v175
	v_cvt_f32_ubyte2_e32 v102, v76
	v_cvt_f32_ubyte3_e32 v103, v76
	v_pk_fma_f32 v[80:81], v[38:39], v[98:99], v[80:81] op_sel_hi:[0,1,1]
	v_cvt_f32_ubyte0_e32 v104, v173
	v_cvt_f32_ubyte1_e32 v105, v173
	v_pk_fma_f32 v[78:79], v[38:39], v[102:103], v[78:79] op_sel_hi:[0,1,1]
	v_cvt_f32_ubyte2_e32 v146, v173
	v_cvt_f32_ubyte3_e32 v147, v173
	v_pk_fma_f32 v[70:71], v[38:39], v[104:105], v[70:71] op_sel_hi:[0,1,1]
	v_cvt_f32_ubyte0_e32 v98, v82
	v_cvt_f32_ubyte1_e32 v99, v82
	v_pk_fma_f32 v[62:63], v[38:39], v[146:147], v[62:63] op_sel_hi:[0,1,1]
	v_cvt_f32_ubyte2_e32 v102, v82
	v_cvt_f32_ubyte3_e32 v103, v82
	v_pk_fma_f32 v[92:93], v[38:39], v[98:99], v[92:93] op_sel:[1,0,0]
	v_cvt_f32_ubyte0_e32 v104, v174
	v_cvt_f32_ubyte1_e32 v105, v174
	v_pk_fma_f32 v[90:91], v[38:39], v[102:103], v[90:91] op_sel:[1,0,0]
	v_cvt_f32_ubyte2_e32 v146, v174
	v_cvt_f32_ubyte3_e32 v147, v174
	v_pk_fma_f32 v[86:87], v[38:39], v[104:105], v[86:87] op_sel:[1,0,0]
	v_cvt_f32_ubyte0_e32 v98, v88
	v_cvt_f32_ubyte1_e32 v99, v88
	v_pk_fma_f32 v[84:85], v[38:39], v[146:147], v[84:85] op_sel:[1,0,0]
	v_and_b32_e32 v68, s0, v176
	v_and_b32_e32 v76, s0, v177
	v_cvt_f32_ubyte2_e32 v102, v88
	v_cvt_f32_ubyte3_e32 v103, v88
	v_pk_fma_f32 v[80:81], v[38:39], v[98:99], v[80:81] op_sel:[1,0,0]
	v_cvt_f32_ubyte0_e32 v104, v175
	v_cvt_f32_ubyte1_e32 v105, v175
	v_pk_fma_f32 v[78:79], v[38:39], v[102:103], v[78:79] op_sel:[1,0,0]
	v_cvt_f32_ubyte2_e32 v146, v175
	v_cvt_f32_ubyte3_e32 v147, v175
	v_pk_fma_f32 v[70:71], v[38:39], v[104:105], v[70:71] op_sel:[1,0,0]
	v_cvt_f32_ubyte0_e32 v98, v68
	v_cvt_f32_ubyte1_e32 v99, v68
	v_pk_fma_f32 v[62:63], v[38:39], v[146:147], v[62:63] op_sel:[1,0,0]
	v_cvt_f32_ubyte2_e32 v102, v68
	v_cvt_f32_ubyte3_e32 v103, v68
	v_pk_fma_f32 v[92:93], v[40:41], v[98:99], v[92:93] op_sel_hi:[0,1,1]
	v_cvt_f32_ubyte0_e32 v104, v176
	v_cvt_f32_ubyte1_e32 v105, v176
	v_pk_fma_f32 v[90:91], v[40:41], v[102:103], v[90:91] op_sel_hi:[0,1,1]
	v_cvt_f32_ubyte2_e32 v146, v176
	v_cvt_f32_ubyte3_e32 v147, v176
	v_pk_fma_f32 v[86:87], v[40:41], v[104:105], v[86:87] op_sel_hi:[0,1,1]
	v_cvt_f32_ubyte0_e32 v98, v76
	v_cvt_f32_ubyte1_e32 v99, v76
	v_pk_fma_f32 v[84:85], v[40:41], v[146:147], v[84:85] op_sel_hi:[0,1,1]
	v_and_b32_e32 v82, s0, v178
	v_and_b32_e32 v88, s0, v179
	v_cvt_f32_ubyte2_e32 v102, v76
	v_cvt_f32_ubyte3_e32 v103, v76
	v_pk_fma_f32 v[80:81], v[40:41], v[98:99], v[80:81] op_sel_hi:[0,1,1]
	v_cvt_f32_ubyte0_e32 v104, v177
	v_cvt_f32_ubyte1_e32 v105, v177
	v_pk_fma_f32 v[78:79], v[40:41], v[102:103], v[78:79] op_sel_hi:[0,1,1]
	v_cvt_f32_ubyte2_e32 v146, v177
	v_cvt_f32_ubyte3_e32 v147, v177
	v_pk_fma_f32 v[70:71], v[40:41], v[104:105], v[70:71] op_sel_hi:[0,1,1]
	v_cvt_f32_ubyte0_e32 v98, v82
	v_cvt_f32_ubyte1_e32 v99, v82
	v_pk_fma_f32 v[62:63], v[40:41], v[146:147], v[62:63] op_sel_hi:[0,1,1]
	v_cvt_f32_ubyte2_e32 v102, v82
	v_cvt_f32_ubyte3_e32 v103, v82
	v_pk_fma_f32 v[92:93], v[40:41], v[98:99], v[92:93] op_sel:[1,0,0]
	v_cvt_f32_ubyte0_e32 v104, v178
	v_cvt_f32_ubyte1_e32 v105, v178
	v_pk_fma_f32 v[90:91], v[40:41], v[102:103], v[90:91] op_sel:[1,0,0]
	v_cvt_f32_ubyte2_e32 v146, v178
	v_cvt_f32_ubyte3_e32 v147, v178
	v_pk_fma_f32 v[86:87], v[40:41], v[104:105], v[86:87] op_sel:[1,0,0]
	v_cvt_f32_ubyte0_e32 v98, v88
	v_cvt_f32_ubyte1_e32 v99, v88
	v_pk_fma_f32 v[84:85], v[40:41], v[146:147], v[84:85] op_sel:[1,0,0]
	v_cvt_f32_ubyte2_e32 v102, v88
	v_cvt_f32_ubyte3_e32 v103, v88
	v_pk_fma_f32 v[80:81], v[40:41], v[98:99], v[80:81] op_sel:[1,0,0]
	v_cvt_f32_ubyte0_e32 v104, v179
	v_cvt_f32_ubyte1_e32 v105, v179
	v_pk_fma_f32 v[78:79], v[40:41], v[102:103], v[78:79] op_sel:[1,0,0]
	v_cvt_f32_ubyte2_e32 v146, v179
	v_cvt_f32_ubyte3_e32 v147, v179
	v_pk_fma_f32 v[70:71], v[40:41], v[104:105], v[70:71] op_sel:[1,0,0]
	v_pk_fma_f32 v[62:63], v[40:41], v[146:147], v[62:63] op_sel:[1,0,0]
	s_waitcnt lgkmcnt(0)
	v_lshl_add_u32 v72, v72, 9, v100
	v_lshl_add_u32 v73, v73, 9, v100
	v_lshl_add_u32 v74, v74, 9, v100
	v_lshl_add_u32 v75, v75, 9, v100
	v_lshl_add_u32 v94, v94, 9, v100
	v_lshl_add_u32 v95, v95, 9, v100
	v_lshl_add_u32 v96, v96, 9, v100
	v_lshl_add_u32 v97, v97, 9, v100
	global_load_dwordx2 v[164:165], v72, s[38:39]
	global_load_dwordx2 v[166:167], v73, s[38:39]
	global_load_dwordx2 v[168:169], v74, s[38:39]
	global_load_dwordx2 v[170:171], v75, s[38:39]
	global_load_dwordx2 v[172:173], v94, s[38:39]
	global_load_dwordx2 v[174:175], v95, s[38:39]
	global_load_dwordx2 v[176:177], v96, s[38:39]
	global_load_dwordx2 v[178:179], v97, s[38:39]
	ds_read_b128 v[72:75], v1 offset:416
	ds_read_b128 v[94:97], v1 offset:432
	ds_read_b128 v[34:37], v1 offset:768
	ds_read_b128 v[38:41], v1 offset:784
	s_waitcnt vmcnt(40)
	v_and_b32_e32 v68, s0, v180
	v_and_b32_e32 v76, s0, v181
	v_cvt_f32_ubyte0_e32 v98, v68
	v_cvt_f32_ubyte1_e32 v99, v68
	v_cvt_f32_ubyte2_e32 v102, v68
	v_cvt_f32_ubyte3_e32 v103, v68
	v_pk_fma_f32 v[92:93], v[50:51], v[98:99], v[92:93] op_sel_hi:[0,1,1]
	v_cvt_f32_ubyte0_e32 v104, v180
	v_cvt_f32_ubyte1_e32 v105, v180
	v_pk_fma_f32 v[90:91], v[50:51], v[102:103], v[90:91] op_sel_hi:[0,1,1]
	v_cvt_f32_ubyte2_e32 v146, v180
	v_cvt_f32_ubyte3_e32 v147, v180
	v_pk_fma_f32 v[86:87], v[50:51], v[104:105], v[86:87] op_sel_hi:[0,1,1]
	v_cvt_f32_ubyte0_e32 v98, v76
	v_cvt_f32_ubyte1_e32 v99, v76
	v_pk_fma_f32 v[84:85], v[50:51], v[146:147], v[84:85] op_sel_hi:[0,1,1]
	v_and_b32_e32 v82, s0, v182
	v_and_b32_e32 v88, s0, v183
	v_cvt_f32_ubyte2_e32 v102, v76
	v_cvt_f32_ubyte3_e32 v103, v76
	v_pk_fma_f32 v[80:81], v[50:51], v[98:99], v[80:81] op_sel_hi:[0,1,1]
	v_cvt_f32_ubyte0_e32 v104, v181
	v_cvt_f32_ubyte1_e32 v105, v181
	v_pk_fma_f32 v[78:79], v[50:51], v[102:103], v[78:79] op_sel_hi:[0,1,1]
	v_cvt_f32_ubyte2_e32 v146, v181
	v_cvt_f32_ubyte3_e32 v147, v181
	v_pk_fma_f32 v[70:71], v[50:51], v[104:105], v[70:71] op_sel_hi:[0,1,1]
	v_cvt_f32_ubyte0_e32 v98, v82
	v_cvt_f32_ubyte1_e32 v99, v82
	v_pk_fma_f32 v[62:63], v[50:51], v[146:147], v[62:63] op_sel_hi:[0,1,1]
	v_cvt_f32_ubyte2_e32 v102, v82
	v_cvt_f32_ubyte3_e32 v103, v82
	v_pk_fma_f32 v[92:93], v[50:51], v[98:99], v[92:93] op_sel:[1,0,0]
	v_cvt_f32_ubyte0_e32 v104, v182
	v_cvt_f32_ubyte1_e32 v105, v182
	v_pk_fma_f32 v[90:91], v[50:51], v[102:103], v[90:91] op_sel:[1,0,0]
	v_cvt_f32_ubyte2_e32 v146, v182
	v_cvt_f32_ubyte3_e32 v147, v182
	v_pk_fma_f32 v[86:87], v[50:51], v[104:105], v[86:87] op_sel:[1,0,0]
	v_cvt_f32_ubyte0_e32 v98, v88
	v_cvt_f32_ubyte1_e32 v99, v88
	v_pk_fma_f32 v[84:85], v[50:51], v[146:147], v[84:85] op_sel:[1,0,0]
	v_and_b32_e32 v68, s0, v184
	v_and_b32_e32 v76, s0, v185
	v_cvt_f32_ubyte2_e32 v102, v88
	v_cvt_f32_ubyte3_e32 v103, v88
	v_pk_fma_f32 v[80:81], v[50:51], v[98:99], v[80:81] op_sel:[1,0,0]
	v_cvt_f32_ubyte0_e32 v104, v183
	v_cvt_f32_ubyte1_e32 v105, v183
	v_pk_fma_f32 v[78:79], v[50:51], v[102:103], v[78:79] op_sel:[1,0,0]
	v_cvt_f32_ubyte2_e32 v146, v183
	v_cvt_f32_ubyte3_e32 v147, v183
	v_pk_fma_f32 v[70:71], v[50:51], v[104:105], v[70:71] op_sel:[1,0,0]
	v_cvt_f32_ubyte0_e32 v98, v68
	v_cvt_f32_ubyte1_e32 v99, v68
	v_pk_fma_f32 v[62:63], v[50:51], v[146:147], v[62:63] op_sel:[1,0,0]
	v_cvt_f32_ubyte2_e32 v102, v68
	v_cvt_f32_ubyte3_e32 v103, v68
	v_pk_fma_f32 v[92:93], v[52:53], v[98:99], v[92:93] op_sel_hi:[0,1,1]
	v_cvt_f32_ubyte0_e32 v104, v184
	v_cvt_f32_ubyte1_e32 v105, v184
	v_pk_fma_f32 v[90:91], v[52:53], v[102:103], v[90:91] op_sel_hi:[0,1,1]
	v_cvt_f32_ubyte2_e32 v146, v184
	v_cvt_f32_ubyte3_e32 v147, v184
	v_pk_fma_f32 v[86:87], v[52:53], v[104:105], v[86:87] op_sel_hi:[0,1,1]
	v_cvt_f32_ubyte0_e32 v98, v76
	v_cvt_f32_ubyte1_e32 v99, v76
	v_pk_fma_f32 v[84:85], v[52:53], v[146:147], v[84:85] op_sel_hi:[0,1,1]
	v_and_b32_e32 v82, s0, v186
	v_and_b32_e32 v88, s0, v187
	v_cvt_f32_ubyte2_e32 v102, v76
	v_cvt_f32_ubyte3_e32 v103, v76
	v_pk_fma_f32 v[80:81], v[52:53], v[98:99], v[80:81] op_sel_hi:[0,1,1]
	v_cvt_f32_ubyte0_e32 v104, v185
	v_cvt_f32_ubyte1_e32 v105, v185
	v_pk_fma_f32 v[78:79], v[52:53], v[102:103], v[78:79] op_sel_hi:[0,1,1]
	v_cvt_f32_ubyte2_e32 v146, v185
	v_cvt_f32_ubyte3_e32 v147, v185
	v_pk_fma_f32 v[70:71], v[52:53], v[104:105], v[70:71] op_sel_hi:[0,1,1]
	v_cvt_f32_ubyte0_e32 v98, v82
	v_cvt_f32_ubyte1_e32 v99, v82
	v_pk_fma_f32 v[62:63], v[52:53], v[146:147], v[62:63] op_sel_hi:[0,1,1]
	v_cvt_f32_ubyte2_e32 v102, v82
	v_cvt_f32_ubyte3_e32 v103, v82
	v_pk_fma_f32 v[92:93], v[52:53], v[98:99], v[92:93] op_sel:[1,0,0]
	v_cvt_f32_ubyte0_e32 v104, v186
	v_cvt_f32_ubyte1_e32 v105, v186
	v_pk_fma_f32 v[90:91], v[52:53], v[102:103], v[90:91] op_sel:[1,0,0]
	v_cvt_f32_ubyte2_e32 v146, v186
	v_cvt_f32_ubyte3_e32 v147, v186
	v_pk_fma_f32 v[86:87], v[52:53], v[104:105], v[86:87] op_sel:[1,0,0]
	v_cvt_f32_ubyte0_e32 v98, v88
	v_cvt_f32_ubyte1_e32 v99, v88
	v_pk_fma_f32 v[84:85], v[52:53], v[146:147], v[84:85] op_sel:[1,0,0]
	v_and_b32_e32 v68, s0, v188
	v_and_b32_e32 v76, s0, v189
	v_cvt_f32_ubyte2_e32 v102, v88
	v_cvt_f32_ubyte3_e32 v103, v88
	v_pk_fma_f32 v[80:81], v[52:53], v[98:99], v[80:81] op_sel:[1,0,0]
	v_cvt_f32_ubyte0_e32 v104, v187
	v_cvt_f32_ubyte1_e32 v105, v187
	v_pk_fma_f32 v[78:79], v[52:53], v[102:103], v[78:79] op_sel:[1,0,0]
	v_cvt_f32_ubyte2_e32 v146, v187
	v_cvt_f32_ubyte3_e32 v147, v187
	v_pk_fma_f32 v[70:71], v[52:53], v[104:105], v[70:71] op_sel:[1,0,0]
	v_cvt_f32_ubyte0_e32 v98, v68
	v_cvt_f32_ubyte1_e32 v99, v68
	v_pk_fma_f32 v[62:63], v[52:53], v[146:147], v[62:63] op_sel:[1,0,0]
	v_cvt_f32_ubyte2_e32 v102, v68
	v_cvt_f32_ubyte3_e32 v103, v68
	v_pk_fma_f32 v[92:93], v[54:55], v[98:99], v[92:93] op_sel_hi:[0,1,1]
	v_cvt_f32_ubyte0_e32 v104, v188
	v_cvt_f32_ubyte1_e32 v105, v188
	v_pk_fma_f32 v[90:91], v[54:55], v[102:103], v[90:91] op_sel_hi:[0,1,1]
	v_cvt_f32_ubyte2_e32 v146, v188
	v_cvt_f32_ubyte3_e32 v147, v188
	v_pk_fma_f32 v[86:87], v[54:55], v[104:105], v[86:87] op_sel_hi:[0,1,1]
	v_cvt_f32_ubyte0_e32 v98, v76
	v_cvt_f32_ubyte1_e32 v99, v76
	v_pk_fma_f32 v[84:85], v[54:55], v[146:147], v[84:85] op_sel_hi:[0,1,1]
	v_and_b32_e32 v82, s0, v190
	v_and_b32_e32 v88, s0, v191
	v_cvt_f32_ubyte2_e32 v102, v76
	v_cvt_f32_ubyte3_e32 v103, v76
	v_pk_fma_f32 v[80:81], v[54:55], v[98:99], v[80:81] op_sel_hi:[0,1,1]
	v_cvt_f32_ubyte0_e32 v104, v189
	v_cvt_f32_ubyte1_e32 v105, v189
	v_pk_fma_f32 v[78:79], v[54:55], v[102:103], v[78:79] op_sel_hi:[0,1,1]
	v_cvt_f32_ubyte2_e32 v146, v189
	v_cvt_f32_ubyte3_e32 v147, v189
	v_pk_fma_f32 v[70:71], v[54:55], v[104:105], v[70:71] op_sel_hi:[0,1,1]
	v_cvt_f32_ubyte0_e32 v98, v82
	v_cvt_f32_ubyte1_e32 v99, v82
	v_pk_fma_f32 v[62:63], v[54:55], v[146:147], v[62:63] op_sel_hi:[0,1,1]
	v_cvt_f32_ubyte2_e32 v102, v82
	v_cvt_f32_ubyte3_e32 v103, v82
	v_pk_fma_f32 v[92:93], v[54:55], v[98:99], v[92:93] op_sel:[1,0,0]
	v_cvt_f32_ubyte0_e32 v104, v190
	v_cvt_f32_ubyte1_e32 v105, v190
	v_pk_fma_f32 v[90:91], v[54:55], v[102:103], v[90:91] op_sel:[1,0,0]
	v_cvt_f32_ubyte2_e32 v146, v190
	v_cvt_f32_ubyte3_e32 v147, v190
	v_pk_fma_f32 v[86:87], v[54:55], v[104:105], v[86:87] op_sel:[1,0,0]
	v_cvt_f32_ubyte0_e32 v98, v88
	v_cvt_f32_ubyte1_e32 v99, v88
	v_pk_fma_f32 v[84:85], v[54:55], v[146:147], v[84:85] op_sel:[1,0,0]
	v_and_b32_e32 v68, s0, v192
	v_and_b32_e32 v76, s0, v193
	v_cvt_f32_ubyte2_e32 v102, v88
	v_cvt_f32_ubyte3_e32 v103, v88
	v_pk_fma_f32 v[80:81], v[54:55], v[98:99], v[80:81] op_sel:[1,0,0]
	v_cvt_f32_ubyte0_e32 v104, v191
	v_cvt_f32_ubyte1_e32 v105, v191
	v_pk_fma_f32 v[78:79], v[54:55], v[102:103], v[78:79] op_sel:[1,0,0]
	v_cvt_f32_ubyte2_e32 v146, v191
	v_cvt_f32_ubyte3_e32 v147, v191
	v_pk_fma_f32 v[70:71], v[54:55], v[104:105], v[70:71] op_sel:[1,0,0]
	v_cvt_f32_ubyte0_e32 v98, v68
	v_cvt_f32_ubyte1_e32 v99, v68
	v_pk_fma_f32 v[62:63], v[54:55], v[146:147], v[62:63] op_sel:[1,0,0]
	v_cvt_f32_ubyte2_e32 v102, v68
	v_cvt_f32_ubyte3_e32 v103, v68
	v_pk_fma_f32 v[92:93], v[56:57], v[98:99], v[92:93] op_sel_hi:[0,1,1]
	v_cvt_f32_ubyte0_e32 v104, v192
	v_cvt_f32_ubyte1_e32 v105, v192
	v_pk_fma_f32 v[90:91], v[56:57], v[102:103], v[90:91] op_sel_hi:[0,1,1]
	v_cvt_f32_ubyte2_e32 v146, v192
	v_cvt_f32_ubyte3_e32 v147, v192
	v_pk_fma_f32 v[86:87], v[56:57], v[104:105], v[86:87] op_sel_hi:[0,1,1]
	v_cvt_f32_ubyte0_e32 v98, v76
	v_cvt_f32_ubyte1_e32 v99, v76
	v_pk_fma_f32 v[84:85], v[56:57], v[146:147], v[84:85] op_sel_hi:[0,1,1]
	v_and_b32_e32 v82, s0, v194
	v_and_b32_e32 v88, s0, v195
	v_cvt_f32_ubyte2_e32 v102, v76
	v_cvt_f32_ubyte3_e32 v103, v76
	v_pk_fma_f32 v[80:81], v[56:57], v[98:99], v[80:81] op_sel_hi:[0,1,1]
	v_cvt_f32_ubyte0_e32 v104, v193
	v_cvt_f32_ubyte1_e32 v105, v193
	v_pk_fma_f32 v[78:79], v[56:57], v[102:103], v[78:79] op_sel_hi:[0,1,1]
	v_cvt_f32_ubyte2_e32 v146, v193
	v_cvt_f32_ubyte3_e32 v147, v193
	v_pk_fma_f32 v[70:71], v[56:57], v[104:105], v[70:71] op_sel_hi:[0,1,1]
	v_cvt_f32_ubyte0_e32 v98, v82
	v_cvt_f32_ubyte1_e32 v99, v82
	v_pk_fma_f32 v[62:63], v[56:57], v[146:147], v[62:63] op_sel_hi:[0,1,1]
	v_cvt_f32_ubyte2_e32 v102, v82
	v_cvt_f32_ubyte3_e32 v103, v82
	v_pk_fma_f32 v[92:93], v[56:57], v[98:99], v[92:93] op_sel:[1,0,0]
	v_cvt_f32_ubyte0_e32 v104, v194
	v_cvt_f32_ubyte1_e32 v105, v194
	v_pk_fma_f32 v[90:91], v[56:57], v[102:103], v[90:91] op_sel:[1,0,0]
	v_cvt_f32_ubyte2_e32 v146, v194
	v_cvt_f32_ubyte3_e32 v147, v194
	v_pk_fma_f32 v[86:87], v[56:57], v[104:105], v[86:87] op_sel:[1,0,0]
	v_cvt_f32_ubyte0_e32 v98, v88
	v_cvt_f32_ubyte1_e32 v99, v88
	v_pk_fma_f32 v[84:85], v[56:57], v[146:147], v[84:85] op_sel:[1,0,0]
	v_cvt_f32_ubyte2_e32 v102, v88
	v_cvt_f32_ubyte3_e32 v103, v88
	v_pk_fma_f32 v[80:81], v[56:57], v[98:99], v[80:81] op_sel:[1,0,0]
	v_cvt_f32_ubyte0_e32 v104, v195
	v_cvt_f32_ubyte1_e32 v105, v195
	v_pk_fma_f32 v[78:79], v[56:57], v[102:103], v[78:79] op_sel:[1,0,0]
	v_cvt_f32_ubyte2_e32 v146, v195
	v_cvt_f32_ubyte3_e32 v147, v195
	v_pk_fma_f32 v[70:71], v[56:57], v[104:105], v[70:71] op_sel:[1,0,0]
	v_pk_fma_f32 v[62:63], v[56:57], v[146:147], v[62:63] op_sel:[1,0,0]
	s_waitcnt lgkmcnt(0)
	v_lshl_add_u32 v72, v72, 9, v100
	v_lshl_add_u32 v73, v73, 9, v100
	v_lshl_add_u32 v74, v74, 9, v100
	v_lshl_add_u32 v75, v75, 9, v100
	v_lshl_add_u32 v94, v94, 9, v100
	v_lshl_add_u32 v95, v95, 9, v100
	v_lshl_add_u32 v96, v96, 9, v100
	v_lshl_add_u32 v97, v97, 9, v100
	global_load_dwordx2 v[180:181], v72, s[38:39]
	global_load_dwordx2 v[182:183], v73, s[38:39]
	global_load_dwordx2 v[184:185], v74, s[38:39]
	global_load_dwordx2 v[186:187], v75, s[38:39]
	global_load_dwordx2 v[188:189], v94, s[38:39]
	global_load_dwordx2 v[190:191], v95, s[38:39]
	global_load_dwordx2 v[192:193], v96, s[38:39]
	global_load_dwordx2 v[194:195], v97, s[38:39]
	ds_read_b128 v[72:75], v1 offset:448
	ds_read_b128 v[94:97], v1 offset:464
	ds_read_b128 v[50:53], v1 offset:800
	ds_read_b128 v[54:57], v1 offset:816
	s_waitcnt vmcnt(40)
	v_and_b32_e32 v68, s0, v196
	v_and_b32_e32 v76, s0, v197
	v_cvt_f32_ubyte0_e32 v98, v68
	v_cvt_f32_ubyte1_e32 v99, v68
	v_cvt_f32_ubyte2_e32 v102, v68
	v_cvt_f32_ubyte3_e32 v103, v68
	v_pk_fma_f32 v[92:93], v[34:35], v[98:99], v[92:93] op_sel_hi:[0,1,1]
	v_cvt_f32_ubyte0_e32 v104, v196
	v_cvt_f32_ubyte1_e32 v105, v196
	v_pk_fma_f32 v[90:91], v[34:35], v[102:103], v[90:91] op_sel_hi:[0,1,1]
	v_cvt_f32_ubyte2_e32 v146, v196
	v_cvt_f32_ubyte3_e32 v147, v196
	v_pk_fma_f32 v[86:87], v[34:35], v[104:105], v[86:87] op_sel_hi:[0,1,1]
	v_cvt_f32_ubyte0_e32 v98, v76
	v_cvt_f32_ubyte1_e32 v99, v76
	v_pk_fma_f32 v[84:85], v[34:35], v[146:147], v[84:85] op_sel_hi:[0,1,1]
	v_and_b32_e32 v82, s0, v198
	v_and_b32_e32 v88, s0, v199
	v_cvt_f32_ubyte2_e32 v102, v76
	v_cvt_f32_ubyte3_e32 v103, v76
	v_pk_fma_f32 v[80:81], v[34:35], v[98:99], v[80:81] op_sel_hi:[0,1,1]
	v_cvt_f32_ubyte0_e32 v104, v197
	v_cvt_f32_ubyte1_e32 v105, v197
	v_pk_fma_f32 v[78:79], v[34:35], v[102:103], v[78:79] op_sel_hi:[0,1,1]
	v_cvt_f32_ubyte2_e32 v146, v197
	v_cvt_f32_ubyte3_e32 v147, v197
	v_pk_fma_f32 v[70:71], v[34:35], v[104:105], v[70:71] op_sel_hi:[0,1,1]
	v_cvt_f32_ubyte0_e32 v98, v82
	v_cvt_f32_ubyte1_e32 v99, v82
	v_pk_fma_f32 v[62:63], v[34:35], v[146:147], v[62:63] op_sel_hi:[0,1,1]
	v_cvt_f32_ubyte2_e32 v102, v82
	v_cvt_f32_ubyte3_e32 v103, v82
	v_pk_fma_f32 v[92:93], v[34:35], v[98:99], v[92:93] op_sel:[1,0,0]
	v_cvt_f32_ubyte0_e32 v104, v198
	v_cvt_f32_ubyte1_e32 v105, v198
	v_pk_fma_f32 v[90:91], v[34:35], v[102:103], v[90:91] op_sel:[1,0,0]
	v_cvt_f32_ubyte2_e32 v146, v198
	v_cvt_f32_ubyte3_e32 v147, v198
	v_pk_fma_f32 v[86:87], v[34:35], v[104:105], v[86:87] op_sel:[1,0,0]
	v_cvt_f32_ubyte0_e32 v98, v88
	v_cvt_f32_ubyte1_e32 v99, v88
	v_pk_fma_f32 v[84:85], v[34:35], v[146:147], v[84:85] op_sel:[1,0,0]
	v_and_b32_e32 v68, s0, v200
	v_and_b32_e32 v76, s0, v201
	v_cvt_f32_ubyte2_e32 v102, v88
	v_cvt_f32_ubyte3_e32 v103, v88
	v_pk_fma_f32 v[80:81], v[34:35], v[98:99], v[80:81] op_sel:[1,0,0]
	v_cvt_f32_ubyte0_e32 v104, v199
	v_cvt_f32_ubyte1_e32 v105, v199
	v_pk_fma_f32 v[78:79], v[34:35], v[102:103], v[78:79] op_sel:[1,0,0]
	v_cvt_f32_ubyte2_e32 v146, v199
	v_cvt_f32_ubyte3_e32 v147, v199
	v_pk_fma_f32 v[70:71], v[34:35], v[104:105], v[70:71] op_sel:[1,0,0]
	v_cvt_f32_ubyte0_e32 v98, v68
	v_cvt_f32_ubyte1_e32 v99, v68
	v_pk_fma_f32 v[62:63], v[34:35], v[146:147], v[62:63] op_sel:[1,0,0]
	v_cvt_f32_ubyte2_e32 v102, v68
	v_cvt_f32_ubyte3_e32 v103, v68
	v_pk_fma_f32 v[92:93], v[36:37], v[98:99], v[92:93] op_sel_hi:[0,1,1]
	v_cvt_f32_ubyte0_e32 v104, v200
	v_cvt_f32_ubyte1_e32 v105, v200
	v_pk_fma_f32 v[90:91], v[36:37], v[102:103], v[90:91] op_sel_hi:[0,1,1]
	v_cvt_f32_ubyte2_e32 v146, v200
	v_cvt_f32_ubyte3_e32 v147, v200
	v_pk_fma_f32 v[86:87], v[36:37], v[104:105], v[86:87] op_sel_hi:[0,1,1]
	v_cvt_f32_ubyte0_e32 v98, v76
	v_cvt_f32_ubyte1_e32 v99, v76
	v_pk_fma_f32 v[84:85], v[36:37], v[146:147], v[84:85] op_sel_hi:[0,1,1]
	v_and_b32_e32 v82, s0, v202
	v_and_b32_e32 v88, s0, v203
	v_cvt_f32_ubyte2_e32 v102, v76
	v_cvt_f32_ubyte3_e32 v103, v76
	v_pk_fma_f32 v[80:81], v[36:37], v[98:99], v[80:81] op_sel_hi:[0,1,1]
	v_cvt_f32_ubyte0_e32 v104, v201
	v_cvt_f32_ubyte1_e32 v105, v201
	v_pk_fma_f32 v[78:79], v[36:37], v[102:103], v[78:79] op_sel_hi:[0,1,1]
	v_cvt_f32_ubyte2_e32 v146, v201
	v_cvt_f32_ubyte3_e32 v147, v201
	v_pk_fma_f32 v[70:71], v[36:37], v[104:105], v[70:71] op_sel_hi:[0,1,1]
	v_cvt_f32_ubyte0_e32 v98, v82
	v_cvt_f32_ubyte1_e32 v99, v82
	v_pk_fma_f32 v[62:63], v[36:37], v[146:147], v[62:63] op_sel_hi:[0,1,1]
	v_cvt_f32_ubyte2_e32 v102, v82
	v_cvt_f32_ubyte3_e32 v103, v82
	v_pk_fma_f32 v[92:93], v[36:37], v[98:99], v[92:93] op_sel:[1,0,0]
	v_cvt_f32_ubyte0_e32 v104, v202
	v_cvt_f32_ubyte1_e32 v105, v202
	v_pk_fma_f32 v[90:91], v[36:37], v[102:103], v[90:91] op_sel:[1,0,0]
	v_cvt_f32_ubyte2_e32 v146, v202
	v_cvt_f32_ubyte3_e32 v147, v202
	v_pk_fma_f32 v[86:87], v[36:37], v[104:105], v[86:87] op_sel:[1,0,0]
	v_cvt_f32_ubyte0_e32 v98, v88
	v_cvt_f32_ubyte1_e32 v99, v88
	v_pk_fma_f32 v[84:85], v[36:37], v[146:147], v[84:85] op_sel:[1,0,0]
	v_and_b32_e32 v68, s0, v204
	v_and_b32_e32 v76, s0, v205
	v_cvt_f32_ubyte2_e32 v102, v88
	v_cvt_f32_ubyte3_e32 v103, v88
	v_pk_fma_f32 v[80:81], v[36:37], v[98:99], v[80:81] op_sel:[1,0,0]
	v_cvt_f32_ubyte0_e32 v104, v203
	v_cvt_f32_ubyte1_e32 v105, v203
	v_pk_fma_f32 v[78:79], v[36:37], v[102:103], v[78:79] op_sel:[1,0,0]
	v_cvt_f32_ubyte2_e32 v146, v203
	v_cvt_f32_ubyte3_e32 v147, v203
	v_pk_fma_f32 v[70:71], v[36:37], v[104:105], v[70:71] op_sel:[1,0,0]
	v_cvt_f32_ubyte0_e32 v98, v68
	v_cvt_f32_ubyte1_e32 v99, v68
	v_pk_fma_f32 v[62:63], v[36:37], v[146:147], v[62:63] op_sel:[1,0,0]
	v_cvt_f32_ubyte2_e32 v102, v68
	v_cvt_f32_ubyte3_e32 v103, v68
	v_pk_fma_f32 v[92:93], v[38:39], v[98:99], v[92:93] op_sel_hi:[0,1,1]
	v_cvt_f32_ubyte0_e32 v104, v204
	v_cvt_f32_ubyte1_e32 v105, v204
	v_pk_fma_f32 v[90:91], v[38:39], v[102:103], v[90:91] op_sel_hi:[0,1,1]
	v_cvt_f32_ubyte2_e32 v146, v204
	v_cvt_f32_ubyte3_e32 v147, v204
	v_pk_fma_f32 v[86:87], v[38:39], v[104:105], v[86:87] op_sel_hi:[0,1,1]
	v_cvt_f32_ubyte0_e32 v98, v76
	v_cvt_f32_ubyte1_e32 v99, v76
	v_pk_fma_f32 v[84:85], v[38:39], v[146:147], v[84:85] op_sel_hi:[0,1,1]
	v_and_b32_e32 v82, s0, v206
	v_and_b32_e32 v88, s0, v207
	v_cvt_f32_ubyte2_e32 v102, v76
	v_cvt_f32_ubyte3_e32 v103, v76
	v_pk_fma_f32 v[80:81], v[38:39], v[98:99], v[80:81] op_sel_hi:[0,1,1]
	v_cvt_f32_ubyte0_e32 v104, v205
	v_cvt_f32_ubyte1_e32 v105, v205
	v_pk_fma_f32 v[78:79], v[38:39], v[102:103], v[78:79] op_sel_hi:[0,1,1]
	v_cvt_f32_ubyte2_e32 v146, v205
	v_cvt_f32_ubyte3_e32 v147, v205
	v_pk_fma_f32 v[70:71], v[38:39], v[104:105], v[70:71] op_sel_hi:[0,1,1]
	v_cvt_f32_ubyte0_e32 v98, v82
	v_cvt_f32_ubyte1_e32 v99, v82
	v_pk_fma_f32 v[62:63], v[38:39], v[146:147], v[62:63] op_sel_hi:[0,1,1]
	v_cvt_f32_ubyte2_e32 v102, v82
	v_cvt_f32_ubyte3_e32 v103, v82
	v_pk_fma_f32 v[92:93], v[38:39], v[98:99], v[92:93] op_sel:[1,0,0]
	v_cvt_f32_ubyte0_e32 v104, v206
	v_cvt_f32_ubyte1_e32 v105, v206
	v_pk_fma_f32 v[90:91], v[38:39], v[102:103], v[90:91] op_sel:[1,0,0]
	v_cvt_f32_ubyte2_e32 v146, v206
	v_cvt_f32_ubyte3_e32 v147, v206
	v_pk_fma_f32 v[86:87], v[38:39], v[104:105], v[86:87] op_sel:[1,0,0]
	v_cvt_f32_ubyte0_e32 v98, v88
	v_cvt_f32_ubyte1_e32 v99, v88
	v_pk_fma_f32 v[84:85], v[38:39], v[146:147], v[84:85] op_sel:[1,0,0]
	v_and_b32_e32 v68, s0, v208
	v_and_b32_e32 v76, s0, v209
	v_cvt_f32_ubyte2_e32 v102, v88
	v_cvt_f32_ubyte3_e32 v103, v88
	v_pk_fma_f32 v[80:81], v[38:39], v[98:99], v[80:81] op_sel:[1,0,0]
	v_cvt_f32_ubyte0_e32 v104, v207
	v_cvt_f32_ubyte1_e32 v105, v207
	v_pk_fma_f32 v[78:79], v[38:39], v[102:103], v[78:79] op_sel:[1,0,0]
	v_cvt_f32_ubyte2_e32 v146, v207
	v_cvt_f32_ubyte3_e32 v147, v207
	v_pk_fma_f32 v[70:71], v[38:39], v[104:105], v[70:71] op_sel:[1,0,0]
	v_cvt_f32_ubyte0_e32 v98, v68
	v_cvt_f32_ubyte1_e32 v99, v68
	v_pk_fma_f32 v[62:63], v[38:39], v[146:147], v[62:63] op_sel:[1,0,0]
	v_cvt_f32_ubyte2_e32 v102, v68
	v_cvt_f32_ubyte3_e32 v103, v68
	v_pk_fma_f32 v[92:93], v[40:41], v[98:99], v[92:93] op_sel_hi:[0,1,1]
	v_cvt_f32_ubyte0_e32 v104, v208
	v_cvt_f32_ubyte1_e32 v105, v208
	v_pk_fma_f32 v[90:91], v[40:41], v[102:103], v[90:91] op_sel_hi:[0,1,1]
	v_cvt_f32_ubyte2_e32 v146, v208
	v_cvt_f32_ubyte3_e32 v147, v208
	v_pk_fma_f32 v[86:87], v[40:41], v[104:105], v[86:87] op_sel_hi:[0,1,1]
	v_cvt_f32_ubyte0_e32 v98, v76
	v_cvt_f32_ubyte1_e32 v99, v76
	v_pk_fma_f32 v[84:85], v[40:41], v[146:147], v[84:85] op_sel_hi:[0,1,1]
	v_and_b32_e32 v82, s0, v210
	v_and_b32_e32 v88, s0, v211
	v_cvt_f32_ubyte2_e32 v102, v76
	v_cvt_f32_ubyte3_e32 v103, v76
	v_pk_fma_f32 v[80:81], v[40:41], v[98:99], v[80:81] op_sel_hi:[0,1,1]
	v_cvt_f32_ubyte0_e32 v104, v209
	v_cvt_f32_ubyte1_e32 v105, v209
	v_pk_fma_f32 v[78:79], v[40:41], v[102:103], v[78:79] op_sel_hi:[0,1,1]
	v_cvt_f32_ubyte2_e32 v146, v209
	v_cvt_f32_ubyte3_e32 v147, v209
	v_pk_fma_f32 v[70:71], v[40:41], v[104:105], v[70:71] op_sel_hi:[0,1,1]
	v_cvt_f32_ubyte0_e32 v98, v82
	v_cvt_f32_ubyte1_e32 v99, v82
	v_pk_fma_f32 v[62:63], v[40:41], v[146:147], v[62:63] op_sel_hi:[0,1,1]
	v_cvt_f32_ubyte2_e32 v102, v82
	v_cvt_f32_ubyte3_e32 v103, v82
	v_pk_fma_f32 v[92:93], v[40:41], v[98:99], v[92:93] op_sel:[1,0,0]
	v_cvt_f32_ubyte0_e32 v104, v210
	v_cvt_f32_ubyte1_e32 v105, v210
	v_pk_fma_f32 v[90:91], v[40:41], v[102:103], v[90:91] op_sel:[1,0,0]
	v_cvt_f32_ubyte2_e32 v146, v210
	v_cvt_f32_ubyte3_e32 v147, v210
	v_pk_fma_f32 v[86:87], v[40:41], v[104:105], v[86:87] op_sel:[1,0,0]
	v_cvt_f32_ubyte0_e32 v98, v88
	v_cvt_f32_ubyte1_e32 v99, v88
	v_pk_fma_f32 v[84:85], v[40:41], v[146:147], v[84:85] op_sel:[1,0,0]
	v_cvt_f32_ubyte2_e32 v102, v88
	v_cvt_f32_ubyte3_e32 v103, v88
	v_pk_fma_f32 v[80:81], v[40:41], v[98:99], v[80:81] op_sel:[1,0,0]
	v_cvt_f32_ubyte0_e32 v104, v211
	v_cvt_f32_ubyte1_e32 v105, v211
	v_pk_fma_f32 v[78:79], v[40:41], v[102:103], v[78:79] op_sel:[1,0,0]
	v_cvt_f32_ubyte2_e32 v146, v211
	v_cvt_f32_ubyte3_e32 v147, v211
	v_pk_fma_f32 v[70:71], v[40:41], v[104:105], v[70:71] op_sel:[1,0,0]
	v_pk_fma_f32 v[62:63], v[40:41], v[146:147], v[62:63] op_sel:[1,0,0]
	s_waitcnt lgkmcnt(0)
	v_lshl_add_u32 v72, v72, 9, v100
	v_lshl_add_u32 v73, v73, 9, v100
	v_lshl_add_u32 v74, v74, 9, v100
	v_lshl_add_u32 v75, v75, 9, v100
	v_lshl_add_u32 v94, v94, 9, v100
	v_lshl_add_u32 v95, v95, 9, v100
	v_lshl_add_u32 v96, v96, 9, v100
	v_lshl_add_u32 v97, v97, 9, v100
	global_load_dwordx2 v[196:197], v72, s[38:39]
	global_load_dwordx2 v[198:199], v73, s[38:39]
	global_load_dwordx2 v[200:201], v74, s[38:39]
	global_load_dwordx2 v[202:203], v75, s[38:39]
	global_load_dwordx2 v[204:205], v94, s[38:39]
	global_load_dwordx2 v[206:207], v95, s[38:39]
	global_load_dwordx2 v[208:209], v96, s[38:39]
	global_load_dwordx2 v[210:211], v97, s[38:39]
	ds_read_b128 v[72:75], v1 offset:480
	ds_read_b128 v[94:97], v1 offset:496
	ds_read_b128 v[34:37], v1 offset:832
	ds_read_b128 v[38:41], v1 offset:848
	s_waitcnt vmcnt(40)
	v_and_b32_e32 v68, s0, v212
	v_and_b32_e32 v76, s0, v213
	v_cvt_f32_ubyte0_e32 v98, v68
	v_cvt_f32_ubyte1_e32 v99, v68
	v_cvt_f32_ubyte2_e32 v102, v68
	v_cvt_f32_ubyte3_e32 v103, v68
	v_pk_fma_f32 v[92:93], v[50:51], v[98:99], v[92:93] op_sel_hi:[0,1,1]
	v_cvt_f32_ubyte0_e32 v104, v212
	v_cvt_f32_ubyte1_e32 v105, v212
	v_pk_fma_f32 v[90:91], v[50:51], v[102:103], v[90:91] op_sel_hi:[0,1,1]
	v_cvt_f32_ubyte2_e32 v146, v212
	v_cvt_f32_ubyte3_e32 v147, v212
	v_pk_fma_f32 v[86:87], v[50:51], v[104:105], v[86:87] op_sel_hi:[0,1,1]
	v_cvt_f32_ubyte0_e32 v98, v76
	v_cvt_f32_ubyte1_e32 v99, v76
	v_pk_fma_f32 v[84:85], v[50:51], v[146:147], v[84:85] op_sel_hi:[0,1,1]
	v_and_b32_e32 v82, s0, v214
	v_and_b32_e32 v88, s0, v215
	v_cvt_f32_ubyte2_e32 v102, v76
	v_cvt_f32_ubyte3_e32 v103, v76
	v_pk_fma_f32 v[80:81], v[50:51], v[98:99], v[80:81] op_sel_hi:[0,1,1]
	v_cvt_f32_ubyte0_e32 v104, v213
	v_cvt_f32_ubyte1_e32 v105, v213
	v_pk_fma_f32 v[78:79], v[50:51], v[102:103], v[78:79] op_sel_hi:[0,1,1]
	v_cvt_f32_ubyte2_e32 v146, v213
	v_cvt_f32_ubyte3_e32 v147, v213
	v_pk_fma_f32 v[70:71], v[50:51], v[104:105], v[70:71] op_sel_hi:[0,1,1]
	v_cvt_f32_ubyte0_e32 v98, v82
	v_cvt_f32_ubyte1_e32 v99, v82
	v_pk_fma_f32 v[62:63], v[50:51], v[146:147], v[62:63] op_sel_hi:[0,1,1]
	v_cvt_f32_ubyte2_e32 v102, v82
	v_cvt_f32_ubyte3_e32 v103, v82
	v_pk_fma_f32 v[92:93], v[50:51], v[98:99], v[92:93] op_sel:[1,0,0]
	v_cvt_f32_ubyte0_e32 v104, v214
	v_cvt_f32_ubyte1_e32 v105, v214
	v_pk_fma_f32 v[90:91], v[50:51], v[102:103], v[90:91] op_sel:[1,0,0]
	v_cvt_f32_ubyte2_e32 v146, v214
	v_cvt_f32_ubyte3_e32 v147, v214
	v_pk_fma_f32 v[86:87], v[50:51], v[104:105], v[86:87] op_sel:[1,0,0]
	v_cvt_f32_ubyte0_e32 v98, v88
	v_cvt_f32_ubyte1_e32 v99, v88
	v_pk_fma_f32 v[84:85], v[50:51], v[146:147], v[84:85] op_sel:[1,0,0]
	v_and_b32_e32 v68, s0, v216
	v_and_b32_e32 v76, s0, v217
	v_cvt_f32_ubyte2_e32 v102, v88
	v_cvt_f32_ubyte3_e32 v103, v88
	v_pk_fma_f32 v[80:81], v[50:51], v[98:99], v[80:81] op_sel:[1,0,0]
	v_cvt_f32_ubyte0_e32 v104, v215
	v_cvt_f32_ubyte1_e32 v105, v215
	v_pk_fma_f32 v[78:79], v[50:51], v[102:103], v[78:79] op_sel:[1,0,0]
	v_cvt_f32_ubyte2_e32 v146, v215
	v_cvt_f32_ubyte3_e32 v147, v215
	v_pk_fma_f32 v[70:71], v[50:51], v[104:105], v[70:71] op_sel:[1,0,0]
	v_cvt_f32_ubyte0_e32 v98, v68
	v_cvt_f32_ubyte1_e32 v99, v68
	v_pk_fma_f32 v[62:63], v[50:51], v[146:147], v[62:63] op_sel:[1,0,0]
	v_cvt_f32_ubyte2_e32 v102, v68
	v_cvt_f32_ubyte3_e32 v103, v68
	v_pk_fma_f32 v[92:93], v[52:53], v[98:99], v[92:93] op_sel_hi:[0,1,1]
	v_cvt_f32_ubyte0_e32 v104, v216
	v_cvt_f32_ubyte1_e32 v105, v216
	v_pk_fma_f32 v[90:91], v[52:53], v[102:103], v[90:91] op_sel_hi:[0,1,1]
	v_cvt_f32_ubyte2_e32 v146, v216
	v_cvt_f32_ubyte3_e32 v147, v216
	v_pk_fma_f32 v[86:87], v[52:53], v[104:105], v[86:87] op_sel_hi:[0,1,1]
	v_cvt_f32_ubyte0_e32 v98, v76
	v_cvt_f32_ubyte1_e32 v99, v76
	v_pk_fma_f32 v[84:85], v[52:53], v[146:147], v[84:85] op_sel_hi:[0,1,1]
	v_and_b32_e32 v82, s0, v218
	v_and_b32_e32 v88, s0, v219
	v_cvt_f32_ubyte2_e32 v102, v76
	v_cvt_f32_ubyte3_e32 v103, v76
	v_pk_fma_f32 v[80:81], v[52:53], v[98:99], v[80:81] op_sel_hi:[0,1,1]
	v_cvt_f32_ubyte0_e32 v104, v217
	v_cvt_f32_ubyte1_e32 v105, v217
	v_pk_fma_f32 v[78:79], v[52:53], v[102:103], v[78:79] op_sel_hi:[0,1,1]
	v_cvt_f32_ubyte2_e32 v146, v217
	v_cvt_f32_ubyte3_e32 v147, v217
	v_pk_fma_f32 v[70:71], v[52:53], v[104:105], v[70:71] op_sel_hi:[0,1,1]
	v_cvt_f32_ubyte0_e32 v98, v82
	v_cvt_f32_ubyte1_e32 v99, v82
	v_pk_fma_f32 v[62:63], v[52:53], v[146:147], v[62:63] op_sel_hi:[0,1,1]
	v_cvt_f32_ubyte2_e32 v102, v82
	v_cvt_f32_ubyte3_e32 v103, v82
	v_pk_fma_f32 v[92:93], v[52:53], v[98:99], v[92:93] op_sel:[1,0,0]
	v_cvt_f32_ubyte0_e32 v104, v218
	v_cvt_f32_ubyte1_e32 v105, v218
	v_pk_fma_f32 v[90:91], v[52:53], v[102:103], v[90:91] op_sel:[1,0,0]
	v_cvt_f32_ubyte2_e32 v146, v218
	v_cvt_f32_ubyte3_e32 v147, v218
	v_pk_fma_f32 v[86:87], v[52:53], v[104:105], v[86:87] op_sel:[1,0,0]
	v_cvt_f32_ubyte0_e32 v98, v88
	v_cvt_f32_ubyte1_e32 v99, v88
	v_pk_fma_f32 v[84:85], v[52:53], v[146:147], v[84:85] op_sel:[1,0,0]
	v_and_b32_e32 v68, s0, v220
	v_and_b32_e32 v76, s0, v221
	v_cvt_f32_ubyte2_e32 v102, v88
	v_cvt_f32_ubyte3_e32 v103, v88
	v_pk_fma_f32 v[80:81], v[52:53], v[98:99], v[80:81] op_sel:[1,0,0]
	v_cvt_f32_ubyte0_e32 v104, v219
	v_cvt_f32_ubyte1_e32 v105, v219
	v_pk_fma_f32 v[78:79], v[52:53], v[102:103], v[78:79] op_sel:[1,0,0]
	v_cvt_f32_ubyte2_e32 v146, v219
	v_cvt_f32_ubyte3_e32 v147, v219
	v_pk_fma_f32 v[70:71], v[52:53], v[104:105], v[70:71] op_sel:[1,0,0]
	v_cvt_f32_ubyte0_e32 v98, v68
	v_cvt_f32_ubyte1_e32 v99, v68
	v_pk_fma_f32 v[62:63], v[52:53], v[146:147], v[62:63] op_sel:[1,0,0]
	v_cvt_f32_ubyte2_e32 v102, v68
	v_cvt_f32_ubyte3_e32 v103, v68
	v_pk_fma_f32 v[92:93], v[54:55], v[98:99], v[92:93] op_sel_hi:[0,1,1]
	v_cvt_f32_ubyte0_e32 v104, v220
	v_cvt_f32_ubyte1_e32 v105, v220
	v_pk_fma_f32 v[90:91], v[54:55], v[102:103], v[90:91] op_sel_hi:[0,1,1]
	v_cvt_f32_ubyte2_e32 v146, v220
	v_cvt_f32_ubyte3_e32 v147, v220
	v_pk_fma_f32 v[86:87], v[54:55], v[104:105], v[86:87] op_sel_hi:[0,1,1]
	v_cvt_f32_ubyte0_e32 v98, v76
	v_cvt_f32_ubyte1_e32 v99, v76
	v_pk_fma_f32 v[84:85], v[54:55], v[146:147], v[84:85] op_sel_hi:[0,1,1]
	v_and_b32_e32 v82, s0, v222
	v_and_b32_e32 v88, s0, v223
	v_cvt_f32_ubyte2_e32 v102, v76
	v_cvt_f32_ubyte3_e32 v103, v76
	v_pk_fma_f32 v[80:81], v[54:55], v[98:99], v[80:81] op_sel_hi:[0,1,1]
	v_cvt_f32_ubyte0_e32 v104, v221
	v_cvt_f32_ubyte1_e32 v105, v221
	v_pk_fma_f32 v[78:79], v[54:55], v[102:103], v[78:79] op_sel_hi:[0,1,1]
	v_cvt_f32_ubyte2_e32 v146, v221
	v_cvt_f32_ubyte3_e32 v147, v221
	v_pk_fma_f32 v[70:71], v[54:55], v[104:105], v[70:71] op_sel_hi:[0,1,1]
	v_cvt_f32_ubyte0_e32 v98, v82
	v_cvt_f32_ubyte1_e32 v99, v82
	v_pk_fma_f32 v[62:63], v[54:55], v[146:147], v[62:63] op_sel_hi:[0,1,1]
	v_cvt_f32_ubyte2_e32 v102, v82
	v_cvt_f32_ubyte3_e32 v103, v82
	v_pk_fma_f32 v[92:93], v[54:55], v[98:99], v[92:93] op_sel:[1,0,0]
	v_cvt_f32_ubyte0_e32 v104, v222
	v_cvt_f32_ubyte1_e32 v105, v222
	v_pk_fma_f32 v[90:91], v[54:55], v[102:103], v[90:91] op_sel:[1,0,0]
	v_cvt_f32_ubyte2_e32 v146, v222
	v_cvt_f32_ubyte3_e32 v147, v222
	v_pk_fma_f32 v[86:87], v[54:55], v[104:105], v[86:87] op_sel:[1,0,0]
	v_cvt_f32_ubyte0_e32 v98, v88
	v_cvt_f32_ubyte1_e32 v99, v88
	v_pk_fma_f32 v[84:85], v[54:55], v[146:147], v[84:85] op_sel:[1,0,0]
	v_and_b32_e32 v68, s0, v224
	v_and_b32_e32 v76, s0, v225
	v_cvt_f32_ubyte2_e32 v102, v88
	v_cvt_f32_ubyte3_e32 v103, v88
	v_pk_fma_f32 v[80:81], v[54:55], v[98:99], v[80:81] op_sel:[1,0,0]
	v_cvt_f32_ubyte0_e32 v104, v223
	v_cvt_f32_ubyte1_e32 v105, v223
	v_pk_fma_f32 v[78:79], v[54:55], v[102:103], v[78:79] op_sel:[1,0,0]
	v_cvt_f32_ubyte2_e32 v146, v223
	v_cvt_f32_ubyte3_e32 v147, v223
	v_pk_fma_f32 v[70:71], v[54:55], v[104:105], v[70:71] op_sel:[1,0,0]
	v_cvt_f32_ubyte0_e32 v98, v68
	v_cvt_f32_ubyte1_e32 v99, v68
	v_pk_fma_f32 v[62:63], v[54:55], v[146:147], v[62:63] op_sel:[1,0,0]
	v_cvt_f32_ubyte2_e32 v102, v68
	v_cvt_f32_ubyte3_e32 v103, v68
	v_pk_fma_f32 v[92:93], v[56:57], v[98:99], v[92:93] op_sel_hi:[0,1,1]
	v_cvt_f32_ubyte0_e32 v104, v224
	v_cvt_f32_ubyte1_e32 v105, v224
	v_pk_fma_f32 v[90:91], v[56:57], v[102:103], v[90:91] op_sel_hi:[0,1,1]
	v_cvt_f32_ubyte2_e32 v146, v224
	v_cvt_f32_ubyte3_e32 v147, v224
	v_pk_fma_f32 v[86:87], v[56:57], v[104:105], v[86:87] op_sel_hi:[0,1,1]
	v_cvt_f32_ubyte0_e32 v98, v76
	v_cvt_f32_ubyte1_e32 v99, v76
	v_pk_fma_f32 v[84:85], v[56:57], v[146:147], v[84:85] op_sel_hi:[0,1,1]
	v_and_b32_e32 v82, s0, v226
	v_and_b32_e32 v88, s0, v227
	v_cvt_f32_ubyte2_e32 v102, v76
	v_cvt_f32_ubyte3_e32 v103, v76
	v_pk_fma_f32 v[80:81], v[56:57], v[98:99], v[80:81] op_sel_hi:[0,1,1]
	v_cvt_f32_ubyte0_e32 v104, v225
	v_cvt_f32_ubyte1_e32 v105, v225
	v_pk_fma_f32 v[78:79], v[56:57], v[102:103], v[78:79] op_sel_hi:[0,1,1]
	v_cvt_f32_ubyte2_e32 v146, v225
	v_cvt_f32_ubyte3_e32 v147, v225
	v_pk_fma_f32 v[70:71], v[56:57], v[104:105], v[70:71] op_sel_hi:[0,1,1]
	v_cvt_f32_ubyte0_e32 v98, v82
	v_cvt_f32_ubyte1_e32 v99, v82
	v_pk_fma_f32 v[62:63], v[56:57], v[146:147], v[62:63] op_sel_hi:[0,1,1]
	v_cvt_f32_ubyte2_e32 v102, v82
	v_cvt_f32_ubyte3_e32 v103, v82
	v_pk_fma_f32 v[92:93], v[56:57], v[98:99], v[92:93] op_sel:[1,0,0]
	v_cvt_f32_ubyte0_e32 v104, v226
	v_cvt_f32_ubyte1_e32 v105, v226
	v_pk_fma_f32 v[90:91], v[56:57], v[102:103], v[90:91] op_sel:[1,0,0]
	v_cvt_f32_ubyte2_e32 v146, v226
	v_cvt_f32_ubyte3_e32 v147, v226
	v_pk_fma_f32 v[86:87], v[56:57], v[104:105], v[86:87] op_sel:[1,0,0]
	v_cvt_f32_ubyte0_e32 v98, v88
	v_cvt_f32_ubyte1_e32 v99, v88
	v_pk_fma_f32 v[84:85], v[56:57], v[146:147], v[84:85] op_sel:[1,0,0]
	v_cvt_f32_ubyte2_e32 v102, v88
	v_cvt_f32_ubyte3_e32 v103, v88
	v_pk_fma_f32 v[80:81], v[56:57], v[98:99], v[80:81] op_sel:[1,0,0]
	v_cvt_f32_ubyte0_e32 v104, v227
	v_cvt_f32_ubyte1_e32 v105, v227
	v_pk_fma_f32 v[78:79], v[56:57], v[102:103], v[78:79] op_sel:[1,0,0]
	v_cvt_f32_ubyte2_e32 v146, v227
	v_cvt_f32_ubyte3_e32 v147, v227
	v_pk_fma_f32 v[70:71], v[56:57], v[104:105], v[70:71] op_sel:[1,0,0]
	v_pk_fma_f32 v[62:63], v[56:57], v[146:147], v[62:63] op_sel:[1,0,0]
	s_waitcnt lgkmcnt(0)
	v_lshl_add_u32 v72, v72, 9, v100
	v_lshl_add_u32 v73, v73, 9, v100
	v_lshl_add_u32 v74, v74, 9, v100
	v_lshl_add_u32 v75, v75, 9, v100
	v_lshl_add_u32 v94, v94, 9, v100
	v_lshl_add_u32 v95, v95, 9, v100
	v_lshl_add_u32 v96, v96, 9, v100
	v_lshl_add_u32 v97, v97, 9, v100
	global_load_dwordx2 v[212:213], v72, s[38:39]
	global_load_dwordx2 v[214:215], v73, s[38:39]
	global_load_dwordx2 v[216:217], v74, s[38:39]
	global_load_dwordx2 v[218:219], v75, s[38:39]
	global_load_dwordx2 v[220:221], v94, s[38:39]
	global_load_dwordx2 v[222:223], v95, s[38:39]
	global_load_dwordx2 v[224:225], v96, s[38:39]
	global_load_dwordx2 v[226:227], v97, s[38:39]
	ds_read_b128 v[50:53], v1 offset:864
	ds_read_b128 v[54:57], v1 offset:880
	s_waitcnt vmcnt(40)
	v_and_b32_e32 v68, s0, v2
	v_and_b32_e32 v76, s0, v3
	v_cvt_f32_ubyte0_e32 v98, v68
	v_cvt_f32_ubyte1_e32 v99, v68
	v_cvt_f32_ubyte2_e32 v102, v68
	v_cvt_f32_ubyte3_e32 v103, v68
	v_pk_fma_f32 v[92:93], v[34:35], v[98:99], v[92:93] op_sel_hi:[0,1,1]
	v_cvt_f32_ubyte0_e32 v104, v2
	v_cvt_f32_ubyte1_e32 v105, v2
	v_pk_fma_f32 v[90:91], v[34:35], v[102:103], v[90:91] op_sel_hi:[0,1,1]
	v_cvt_f32_ubyte2_e32 v146, v2
	v_cvt_f32_ubyte3_e32 v147, v2
	v_pk_fma_f32 v[86:87], v[34:35], v[104:105], v[86:87] op_sel_hi:[0,1,1]
	v_cvt_f32_ubyte0_e32 v98, v76
	v_cvt_f32_ubyte1_e32 v99, v76
	v_pk_fma_f32 v[84:85], v[34:35], v[146:147], v[84:85] op_sel_hi:[0,1,1]
	v_and_b32_e32 v82, s0, v4
	v_and_b32_e32 v88, s0, v5
	v_cvt_f32_ubyte2_e32 v102, v76
	v_cvt_f32_ubyte3_e32 v103, v76
	v_pk_fma_f32 v[80:81], v[34:35], v[98:99], v[80:81] op_sel_hi:[0,1,1]
	v_cvt_f32_ubyte0_e32 v104, v3
	v_cvt_f32_ubyte1_e32 v105, v3
	v_pk_fma_f32 v[78:79], v[34:35], v[102:103], v[78:79] op_sel_hi:[0,1,1]
	v_cvt_f32_ubyte2_e32 v146, v3
	v_cvt_f32_ubyte3_e32 v147, v3
	v_pk_fma_f32 v[70:71], v[34:35], v[104:105], v[70:71] op_sel_hi:[0,1,1]
	v_cvt_f32_ubyte0_e32 v98, v82
	v_cvt_f32_ubyte1_e32 v99, v82
	v_pk_fma_f32 v[62:63], v[34:35], v[146:147], v[62:63] op_sel_hi:[0,1,1]
	v_cvt_f32_ubyte2_e32 v102, v82
	v_cvt_f32_ubyte3_e32 v103, v82
	v_pk_fma_f32 v[92:93], v[34:35], v[98:99], v[92:93] op_sel:[1,0,0]
	v_cvt_f32_ubyte0_e32 v104, v4
	v_cvt_f32_ubyte1_e32 v105, v4
	v_pk_fma_f32 v[90:91], v[34:35], v[102:103], v[90:91] op_sel:[1,0,0]
	v_cvt_f32_ubyte2_e32 v146, v4
	v_cvt_f32_ubyte3_e32 v147, v4
	v_pk_fma_f32 v[86:87], v[34:35], v[104:105], v[86:87] op_sel:[1,0,0]
	v_cvt_f32_ubyte0_e32 v98, v88
	v_cvt_f32_ubyte1_e32 v99, v88
	v_pk_fma_f32 v[84:85], v[34:35], v[146:147], v[84:85] op_sel:[1,0,0]
	v_and_b32_e32 v68, s0, v6
	v_and_b32_e32 v76, s0, v7
	v_cvt_f32_ubyte2_e32 v102, v88
	v_cvt_f32_ubyte3_e32 v103, v88
	v_pk_fma_f32 v[80:81], v[34:35], v[98:99], v[80:81] op_sel:[1,0,0]
	v_cvt_f32_ubyte0_e32 v104, v5
	v_cvt_f32_ubyte1_e32 v105, v5
	v_pk_fma_f32 v[78:79], v[34:35], v[102:103], v[78:79] op_sel:[1,0,0]
	v_cvt_f32_ubyte2_e32 v146, v5
	v_cvt_f32_ubyte3_e32 v147, v5
	v_pk_fma_f32 v[70:71], v[34:35], v[104:105], v[70:71] op_sel:[1,0,0]
	v_cvt_f32_ubyte0_e32 v98, v68
	v_cvt_f32_ubyte1_e32 v99, v68
	v_pk_fma_f32 v[62:63], v[34:35], v[146:147], v[62:63] op_sel:[1,0,0]
	v_cvt_f32_ubyte2_e32 v102, v68
	v_cvt_f32_ubyte3_e32 v103, v68
	v_pk_fma_f32 v[92:93], v[36:37], v[98:99], v[92:93] op_sel_hi:[0,1,1]
	v_cvt_f32_ubyte0_e32 v104, v6
	v_cvt_f32_ubyte1_e32 v105, v6
	v_pk_fma_f32 v[90:91], v[36:37], v[102:103], v[90:91] op_sel_hi:[0,1,1]
	v_cvt_f32_ubyte2_e32 v146, v6
	v_cvt_f32_ubyte3_e32 v147, v6
	v_pk_fma_f32 v[86:87], v[36:37], v[104:105], v[86:87] op_sel_hi:[0,1,1]
	v_cvt_f32_ubyte0_e32 v98, v76
	v_cvt_f32_ubyte1_e32 v99, v76
	v_pk_fma_f32 v[84:85], v[36:37], v[146:147], v[84:85] op_sel_hi:[0,1,1]
	v_and_b32_e32 v82, s0, v8
	v_and_b32_e32 v88, s0, v9
	v_cvt_f32_ubyte2_e32 v102, v76
	v_cvt_f32_ubyte3_e32 v103, v76
	v_pk_fma_f32 v[80:81], v[36:37], v[98:99], v[80:81] op_sel_hi:[0,1,1]
	v_cvt_f32_ubyte0_e32 v104, v7
	v_cvt_f32_ubyte1_e32 v105, v7
	v_pk_fma_f32 v[78:79], v[36:37], v[102:103], v[78:79] op_sel_hi:[0,1,1]
	v_cvt_f32_ubyte2_e32 v146, v7
	v_cvt_f32_ubyte3_e32 v147, v7
	v_pk_fma_f32 v[70:71], v[36:37], v[104:105], v[70:71] op_sel_hi:[0,1,1]
	v_cvt_f32_ubyte0_e32 v98, v82
	v_cvt_f32_ubyte1_e32 v99, v82
	v_pk_fma_f32 v[62:63], v[36:37], v[146:147], v[62:63] op_sel_hi:[0,1,1]
	v_cvt_f32_ubyte2_e32 v102, v82
	v_cvt_f32_ubyte3_e32 v103, v82
	v_pk_fma_f32 v[92:93], v[36:37], v[98:99], v[92:93] op_sel:[1,0,0]
	v_cvt_f32_ubyte0_e32 v104, v8
	v_cvt_f32_ubyte1_e32 v105, v8
	v_pk_fma_f32 v[90:91], v[36:37], v[102:103], v[90:91] op_sel:[1,0,0]
	v_cvt_f32_ubyte2_e32 v146, v8
	v_cvt_f32_ubyte3_e32 v147, v8
	v_pk_fma_f32 v[86:87], v[36:37], v[104:105], v[86:87] op_sel:[1,0,0]
	v_cvt_f32_ubyte0_e32 v98, v88
	v_cvt_f32_ubyte1_e32 v99, v88
	v_pk_fma_f32 v[84:85], v[36:37], v[146:147], v[84:85] op_sel:[1,0,0]
	v_and_b32_e32 v68, s0, v10
	v_and_b32_e32 v76, s0, v11
	v_cvt_f32_ubyte2_e32 v102, v88
	v_cvt_f32_ubyte3_e32 v103, v88
	v_pk_fma_f32 v[80:81], v[36:37], v[98:99], v[80:81] op_sel:[1,0,0]
	v_cvt_f32_ubyte0_e32 v104, v9
	v_cvt_f32_ubyte1_e32 v105, v9
	v_pk_fma_f32 v[78:79], v[36:37], v[102:103], v[78:79] op_sel:[1,0,0]
	v_cvt_f32_ubyte2_e32 v146, v9
	v_cvt_f32_ubyte3_e32 v147, v9
	v_pk_fma_f32 v[70:71], v[36:37], v[104:105], v[70:71] op_sel:[1,0,0]
	v_cvt_f32_ubyte0_e32 v98, v68
	v_cvt_f32_ubyte1_e32 v99, v68
	v_pk_fma_f32 v[62:63], v[36:37], v[146:147], v[62:63] op_sel:[1,0,0]
	v_cvt_f32_ubyte2_e32 v102, v68
	v_cvt_f32_ubyte3_e32 v103, v68
	v_pk_fma_f32 v[92:93], v[38:39], v[98:99], v[92:93] op_sel_hi:[0,1,1]
	v_cvt_f32_ubyte0_e32 v104, v10
	v_cvt_f32_ubyte1_e32 v105, v10
	v_pk_fma_f32 v[90:91], v[38:39], v[102:103], v[90:91] op_sel_hi:[0,1,1]
	v_cvt_f32_ubyte2_e32 v146, v10
	v_cvt_f32_ubyte3_e32 v147, v10
	v_pk_fma_f32 v[86:87], v[38:39], v[104:105], v[86:87] op_sel_hi:[0,1,1]
	v_cvt_f32_ubyte0_e32 v98, v76
	v_cvt_f32_ubyte1_e32 v99, v76
	v_pk_fma_f32 v[84:85], v[38:39], v[146:147], v[84:85] op_sel_hi:[0,1,1]
	v_and_b32_e32 v82, s0, v12
	v_and_b32_e32 v88, s0, v13
	v_cvt_f32_ubyte2_e32 v102, v76
	v_cvt_f32_ubyte3_e32 v103, v76
	v_pk_fma_f32 v[80:81], v[38:39], v[98:99], v[80:81] op_sel_hi:[0,1,1]
	v_cvt_f32_ubyte0_e32 v104, v11
	v_cvt_f32_ubyte1_e32 v105, v11
	v_pk_fma_f32 v[78:79], v[38:39], v[102:103], v[78:79] op_sel_hi:[0,1,1]
	v_cvt_f32_ubyte2_e32 v146, v11
	v_cvt_f32_ubyte3_e32 v147, v11
	v_pk_fma_f32 v[70:71], v[38:39], v[104:105], v[70:71] op_sel_hi:[0,1,1]
	v_cvt_f32_ubyte0_e32 v98, v82
	v_cvt_f32_ubyte1_e32 v99, v82
	v_pk_fma_f32 v[62:63], v[38:39], v[146:147], v[62:63] op_sel_hi:[0,1,1]
	v_cvt_f32_ubyte2_e32 v102, v82
	v_cvt_f32_ubyte3_e32 v103, v82
	v_pk_fma_f32 v[92:93], v[38:39], v[98:99], v[92:93] op_sel:[1,0,0]
	v_cvt_f32_ubyte0_e32 v104, v12
	v_cvt_f32_ubyte1_e32 v105, v12
	v_pk_fma_f32 v[90:91], v[38:39], v[102:103], v[90:91] op_sel:[1,0,0]
	v_cvt_f32_ubyte2_e32 v146, v12
	v_cvt_f32_ubyte3_e32 v147, v12
	v_pk_fma_f32 v[86:87], v[38:39], v[104:105], v[86:87] op_sel:[1,0,0]
	v_cvt_f32_ubyte0_e32 v98, v88
	v_cvt_f32_ubyte1_e32 v99, v88
	v_pk_fma_f32 v[84:85], v[38:39], v[146:147], v[84:85] op_sel:[1,0,0]
	v_and_b32_e32 v68, s0, v14
	v_and_b32_e32 v76, s0, v15
	v_cvt_f32_ubyte2_e32 v102, v88
	v_cvt_f32_ubyte3_e32 v103, v88
	v_pk_fma_f32 v[80:81], v[38:39], v[98:99], v[80:81] op_sel:[1,0,0]
	v_cvt_f32_ubyte0_e32 v104, v13
	v_cvt_f32_ubyte1_e32 v105, v13
	v_pk_fma_f32 v[78:79], v[38:39], v[102:103], v[78:79] op_sel:[1,0,0]
	v_cvt_f32_ubyte2_e32 v146, v13
	v_cvt_f32_ubyte3_e32 v147, v13
	v_pk_fma_f32 v[70:71], v[38:39], v[104:105], v[70:71] op_sel:[1,0,0]
	v_cvt_f32_ubyte0_e32 v98, v68
	v_cvt_f32_ubyte1_e32 v99, v68
	v_pk_fma_f32 v[62:63], v[38:39], v[146:147], v[62:63] op_sel:[1,0,0]
	v_cvt_f32_ubyte2_e32 v102, v68
	v_cvt_f32_ubyte3_e32 v103, v68
	v_pk_fma_f32 v[92:93], v[40:41], v[98:99], v[92:93] op_sel_hi:[0,1,1]
	v_cvt_f32_ubyte0_e32 v104, v14
	v_cvt_f32_ubyte1_e32 v105, v14
	v_pk_fma_f32 v[90:91], v[40:41], v[102:103], v[90:91] op_sel_hi:[0,1,1]
	v_cvt_f32_ubyte2_e32 v146, v14
	v_cvt_f32_ubyte3_e32 v147, v14
	v_pk_fma_f32 v[86:87], v[40:41], v[104:105], v[86:87] op_sel_hi:[0,1,1]
	v_cvt_f32_ubyte0_e32 v98, v76
	v_cvt_f32_ubyte1_e32 v99, v76
	v_pk_fma_f32 v[84:85], v[40:41], v[146:147], v[84:85] op_sel_hi:[0,1,1]
	v_and_b32_e32 v82, s0, v16
	v_and_b32_e32 v88, s0, v17
	v_cvt_f32_ubyte2_e32 v102, v76
	v_cvt_f32_ubyte3_e32 v103, v76
	v_pk_fma_f32 v[80:81], v[40:41], v[98:99], v[80:81] op_sel_hi:[0,1,1]
	v_cvt_f32_ubyte0_e32 v104, v15
	v_cvt_f32_ubyte1_e32 v105, v15
	v_pk_fma_f32 v[78:79], v[40:41], v[102:103], v[78:79] op_sel_hi:[0,1,1]
	v_cvt_f32_ubyte2_e32 v146, v15
	v_cvt_f32_ubyte3_e32 v147, v15
	v_pk_fma_f32 v[70:71], v[40:41], v[104:105], v[70:71] op_sel_hi:[0,1,1]
	v_cvt_f32_ubyte0_e32 v98, v82
	v_cvt_f32_ubyte1_e32 v99, v82
	v_pk_fma_f32 v[62:63], v[40:41], v[146:147], v[62:63] op_sel_hi:[0,1,1]
	v_cvt_f32_ubyte2_e32 v102, v82
	v_cvt_f32_ubyte3_e32 v103, v82
	v_pk_fma_f32 v[92:93], v[40:41], v[98:99], v[92:93] op_sel:[1,0,0]
	v_cvt_f32_ubyte0_e32 v104, v16
	v_cvt_f32_ubyte1_e32 v105, v16
	v_pk_fma_f32 v[90:91], v[40:41], v[102:103], v[90:91] op_sel:[1,0,0]
	v_cvt_f32_ubyte2_e32 v146, v16
	v_cvt_f32_ubyte3_e32 v147, v16
	v_pk_fma_f32 v[86:87], v[40:41], v[104:105], v[86:87] op_sel:[1,0,0]
	v_cvt_f32_ubyte0_e32 v98, v88
	v_cvt_f32_ubyte1_e32 v99, v88
	v_pk_fma_f32 v[84:85], v[40:41], v[146:147], v[84:85] op_sel:[1,0,0]
	v_cvt_f32_ubyte2_e32 v102, v88
	v_cvt_f32_ubyte3_e32 v103, v88
	v_pk_fma_f32 v[80:81], v[40:41], v[98:99], v[80:81] op_sel:[1,0,0]
	v_cvt_f32_ubyte0_e32 v104, v17
	v_cvt_f32_ubyte1_e32 v105, v17
	v_pk_fma_f32 v[78:79], v[40:41], v[102:103], v[78:79] op_sel:[1,0,0]
	v_cvt_f32_ubyte2_e32 v146, v17
	v_cvt_f32_ubyte3_e32 v147, v17
	v_pk_fma_f32 v[70:71], v[40:41], v[104:105], v[70:71] op_sel:[1,0,0]
	v_pk_fma_f32 v[62:63], v[40:41], v[146:147], v[62:63] op_sel:[1,0,0]
	s_waitcnt lgkmcnt(0)
	ds_read_b128 v[34:37], v1 offset:896
	ds_read_b128 v[38:41], v1 offset:912
	s_waitcnt vmcnt(32)
	v_and_b32_e32 v68, s0, v18
	v_and_b32_e32 v76, s0, v19
	v_cvt_f32_ubyte0_e32 v98, v68
	v_cvt_f32_ubyte1_e32 v99, v68
	v_cvt_f32_ubyte2_e32 v102, v68
	v_cvt_f32_ubyte3_e32 v103, v68
	v_pk_fma_f32 v[92:93], v[50:51], v[98:99], v[92:93] op_sel_hi:[0,1,1]
	v_cvt_f32_ubyte0_e32 v104, v18
	v_cvt_f32_ubyte1_e32 v105, v18
	v_pk_fma_f32 v[90:91], v[50:51], v[102:103], v[90:91] op_sel_hi:[0,1,1]
	v_cvt_f32_ubyte2_e32 v146, v18
	v_cvt_f32_ubyte3_e32 v147, v18
	v_pk_fma_f32 v[86:87], v[50:51], v[104:105], v[86:87] op_sel_hi:[0,1,1]
	v_cvt_f32_ubyte0_e32 v98, v76
	v_cvt_f32_ubyte1_e32 v99, v76
	v_pk_fma_f32 v[84:85], v[50:51], v[146:147], v[84:85] op_sel_hi:[0,1,1]
	v_and_b32_e32 v82, s0, v20
	v_and_b32_e32 v88, s0, v21
	v_cvt_f32_ubyte2_e32 v102, v76
	v_cvt_f32_ubyte3_e32 v103, v76
	v_pk_fma_f32 v[80:81], v[50:51], v[98:99], v[80:81] op_sel_hi:[0,1,1]
	v_cvt_f32_ubyte0_e32 v104, v19
	v_cvt_f32_ubyte1_e32 v105, v19
	v_pk_fma_f32 v[78:79], v[50:51], v[102:103], v[78:79] op_sel_hi:[0,1,1]
	v_cvt_f32_ubyte2_e32 v146, v19
	v_cvt_f32_ubyte3_e32 v147, v19
	v_pk_fma_f32 v[70:71], v[50:51], v[104:105], v[70:71] op_sel_hi:[0,1,1]
	v_cvt_f32_ubyte0_e32 v98, v82
	v_cvt_f32_ubyte1_e32 v99, v82
	v_pk_fma_f32 v[62:63], v[50:51], v[146:147], v[62:63] op_sel_hi:[0,1,1]
	v_cvt_f32_ubyte2_e32 v102, v82
	v_cvt_f32_ubyte3_e32 v103, v82
	v_pk_fma_f32 v[92:93], v[50:51], v[98:99], v[92:93] op_sel:[1,0,0]
	v_cvt_f32_ubyte0_e32 v104, v20
	v_cvt_f32_ubyte1_e32 v105, v20
	v_pk_fma_f32 v[90:91], v[50:51], v[102:103], v[90:91] op_sel:[1,0,0]
	v_cvt_f32_ubyte2_e32 v146, v20
	v_cvt_f32_ubyte3_e32 v147, v20
	v_pk_fma_f32 v[86:87], v[50:51], v[104:105], v[86:87] op_sel:[1,0,0]
	v_cvt_f32_ubyte0_e32 v98, v88
	v_cvt_f32_ubyte1_e32 v99, v88
	v_pk_fma_f32 v[84:85], v[50:51], v[146:147], v[84:85] op_sel:[1,0,0]
	v_and_b32_e32 v68, s0, v22
	v_and_b32_e32 v76, s0, v23
	v_cvt_f32_ubyte2_e32 v102, v88
	v_cvt_f32_ubyte3_e32 v103, v88
	v_pk_fma_f32 v[80:81], v[50:51], v[98:99], v[80:81] op_sel:[1,0,0]
	v_cvt_f32_ubyte0_e32 v104, v21
	v_cvt_f32_ubyte1_e32 v105, v21
	v_pk_fma_f32 v[78:79], v[50:51], v[102:103], v[78:79] op_sel:[1,0,0]
	v_cvt_f32_ubyte2_e32 v146, v21
	v_cvt_f32_ubyte3_e32 v147, v21
	v_pk_fma_f32 v[70:71], v[50:51], v[104:105], v[70:71] op_sel:[1,0,0]
	v_cvt_f32_ubyte0_e32 v98, v68
	v_cvt_f32_ubyte1_e32 v99, v68
	v_pk_fma_f32 v[62:63], v[50:51], v[146:147], v[62:63] op_sel:[1,0,0]
	v_cvt_f32_ubyte2_e32 v102, v68
	v_cvt_f32_ubyte3_e32 v103, v68
	v_pk_fma_f32 v[92:93], v[52:53], v[98:99], v[92:93] op_sel_hi:[0,1,1]
	v_cvt_f32_ubyte0_e32 v104, v22
	v_cvt_f32_ubyte1_e32 v105, v22
	v_pk_fma_f32 v[90:91], v[52:53], v[102:103], v[90:91] op_sel_hi:[0,1,1]
	v_cvt_f32_ubyte2_e32 v146, v22
	v_cvt_f32_ubyte3_e32 v147, v22
	v_pk_fma_f32 v[86:87], v[52:53], v[104:105], v[86:87] op_sel_hi:[0,1,1]
	v_cvt_f32_ubyte0_e32 v98, v76
	v_cvt_f32_ubyte1_e32 v99, v76
	v_pk_fma_f32 v[84:85], v[52:53], v[146:147], v[84:85] op_sel_hi:[0,1,1]
	v_and_b32_e32 v82, s0, v24
	v_and_b32_e32 v88, s0, v25
	v_cvt_f32_ubyte2_e32 v102, v76
	v_cvt_f32_ubyte3_e32 v103, v76
	v_pk_fma_f32 v[80:81], v[52:53], v[98:99], v[80:81] op_sel_hi:[0,1,1]
	v_cvt_f32_ubyte0_e32 v104, v23
	v_cvt_f32_ubyte1_e32 v105, v23
	v_pk_fma_f32 v[78:79], v[52:53], v[102:103], v[78:79] op_sel_hi:[0,1,1]
	v_cvt_f32_ubyte2_e32 v146, v23
	v_cvt_f32_ubyte3_e32 v147, v23
	v_pk_fma_f32 v[70:71], v[52:53], v[104:105], v[70:71] op_sel_hi:[0,1,1]
	v_cvt_f32_ubyte0_e32 v98, v82
	v_cvt_f32_ubyte1_e32 v99, v82
	v_pk_fma_f32 v[62:63], v[52:53], v[146:147], v[62:63] op_sel_hi:[0,1,1]
	v_cvt_f32_ubyte2_e32 v102, v82
	v_cvt_f32_ubyte3_e32 v103, v82
	v_pk_fma_f32 v[92:93], v[52:53], v[98:99], v[92:93] op_sel:[1,0,0]
	v_cvt_f32_ubyte0_e32 v104, v24
	v_cvt_f32_ubyte1_e32 v105, v24
	v_pk_fma_f32 v[90:91], v[52:53], v[102:103], v[90:91] op_sel:[1,0,0]
	v_cvt_f32_ubyte2_e32 v146, v24
	v_cvt_f32_ubyte3_e32 v147, v24
	v_pk_fma_f32 v[86:87], v[52:53], v[104:105], v[86:87] op_sel:[1,0,0]
	v_cvt_f32_ubyte0_e32 v98, v88
	v_cvt_f32_ubyte1_e32 v99, v88
	v_pk_fma_f32 v[84:85], v[52:53], v[146:147], v[84:85] op_sel:[1,0,0]
	v_and_b32_e32 v68, s0, v26
	v_and_b32_e32 v76, s0, v27
	v_cvt_f32_ubyte2_e32 v102, v88
	v_cvt_f32_ubyte3_e32 v103, v88
	v_pk_fma_f32 v[80:81], v[52:53], v[98:99], v[80:81] op_sel:[1,0,0]
	v_cvt_f32_ubyte0_e32 v104, v25
	v_cvt_f32_ubyte1_e32 v105, v25
	v_pk_fma_f32 v[78:79], v[52:53], v[102:103], v[78:79] op_sel:[1,0,0]
	v_cvt_f32_ubyte2_e32 v146, v25
	v_cvt_f32_ubyte3_e32 v147, v25
	v_pk_fma_f32 v[70:71], v[52:53], v[104:105], v[70:71] op_sel:[1,0,0]
	v_cvt_f32_ubyte0_e32 v98, v68
	v_cvt_f32_ubyte1_e32 v99, v68
	v_pk_fma_f32 v[62:63], v[52:53], v[146:147], v[62:63] op_sel:[1,0,0]
	v_cvt_f32_ubyte2_e32 v102, v68
	v_cvt_f32_ubyte3_e32 v103, v68
	v_pk_fma_f32 v[92:93], v[54:55], v[98:99], v[92:93] op_sel_hi:[0,1,1]
	v_cvt_f32_ubyte0_e32 v104, v26
	v_cvt_f32_ubyte1_e32 v105, v26
	v_pk_fma_f32 v[90:91], v[54:55], v[102:103], v[90:91] op_sel_hi:[0,1,1]
	v_cvt_f32_ubyte2_e32 v146, v26
	v_cvt_f32_ubyte3_e32 v147, v26
	v_pk_fma_f32 v[86:87], v[54:55], v[104:105], v[86:87] op_sel_hi:[0,1,1]
	v_cvt_f32_ubyte0_e32 v98, v76
	v_cvt_f32_ubyte1_e32 v99, v76
	v_pk_fma_f32 v[84:85], v[54:55], v[146:147], v[84:85] op_sel_hi:[0,1,1]
	v_and_b32_e32 v82, s0, v28
	v_and_b32_e32 v88, s0, v29
	v_cvt_f32_ubyte2_e32 v102, v76
	v_cvt_f32_ubyte3_e32 v103, v76
	v_pk_fma_f32 v[80:81], v[54:55], v[98:99], v[80:81] op_sel_hi:[0,1,1]
	v_cvt_f32_ubyte0_e32 v104, v27
	v_cvt_f32_ubyte1_e32 v105, v27
	v_pk_fma_f32 v[78:79], v[54:55], v[102:103], v[78:79] op_sel_hi:[0,1,1]
	v_cvt_f32_ubyte2_e32 v146, v27
	v_cvt_f32_ubyte3_e32 v147, v27
	v_pk_fma_f32 v[70:71], v[54:55], v[104:105], v[70:71] op_sel_hi:[0,1,1]
	v_cvt_f32_ubyte0_e32 v98, v82
	v_cvt_f32_ubyte1_e32 v99, v82
	v_pk_fma_f32 v[62:63], v[54:55], v[146:147], v[62:63] op_sel_hi:[0,1,1]
	v_cvt_f32_ubyte2_e32 v102, v82
	v_cvt_f32_ubyte3_e32 v103, v82
	v_pk_fma_f32 v[92:93], v[54:55], v[98:99], v[92:93] op_sel:[1,0,0]
	v_cvt_f32_ubyte0_e32 v104, v28
	v_cvt_f32_ubyte1_e32 v105, v28
	v_pk_fma_f32 v[90:91], v[54:55], v[102:103], v[90:91] op_sel:[1,0,0]
	v_cvt_f32_ubyte2_e32 v146, v28
	v_cvt_f32_ubyte3_e32 v147, v28
	v_pk_fma_f32 v[86:87], v[54:55], v[104:105], v[86:87] op_sel:[1,0,0]
	v_cvt_f32_ubyte0_e32 v98, v88
	v_cvt_f32_ubyte1_e32 v99, v88
	v_pk_fma_f32 v[84:85], v[54:55], v[146:147], v[84:85] op_sel:[1,0,0]
	v_and_b32_e32 v68, s0, v30
	v_and_b32_e32 v76, s0, v31
	v_cvt_f32_ubyte2_e32 v102, v88
	v_cvt_f32_ubyte3_e32 v103, v88
	v_pk_fma_f32 v[80:81], v[54:55], v[98:99], v[80:81] op_sel:[1,0,0]
	v_cvt_f32_ubyte0_e32 v104, v29
	v_cvt_f32_ubyte1_e32 v105, v29
	v_pk_fma_f32 v[78:79], v[54:55], v[102:103], v[78:79] op_sel:[1,0,0]
	v_cvt_f32_ubyte2_e32 v146, v29
	v_cvt_f32_ubyte3_e32 v147, v29
	v_pk_fma_f32 v[70:71], v[54:55], v[104:105], v[70:71] op_sel:[1,0,0]
	v_cvt_f32_ubyte0_e32 v98, v68
	v_cvt_f32_ubyte1_e32 v99, v68
	v_pk_fma_f32 v[62:63], v[54:55], v[146:147], v[62:63] op_sel:[1,0,0]
	v_cvt_f32_ubyte2_e32 v102, v68
	v_cvt_f32_ubyte3_e32 v103, v68
	v_pk_fma_f32 v[92:93], v[56:57], v[98:99], v[92:93] op_sel_hi:[0,1,1]
	v_cvt_f32_ubyte0_e32 v104, v30
	v_cvt_f32_ubyte1_e32 v105, v30
	v_pk_fma_f32 v[90:91], v[56:57], v[102:103], v[90:91] op_sel_hi:[0,1,1]
	v_cvt_f32_ubyte2_e32 v146, v30
	v_cvt_f32_ubyte3_e32 v147, v30
	v_pk_fma_f32 v[86:87], v[56:57], v[104:105], v[86:87] op_sel_hi:[0,1,1]
	v_cvt_f32_ubyte0_e32 v98, v76
	v_cvt_f32_ubyte1_e32 v99, v76
	v_pk_fma_f32 v[84:85], v[56:57], v[146:147], v[84:85] op_sel_hi:[0,1,1]
	v_and_b32_e32 v82, s0, v32
	v_and_b32_e32 v88, s0, v33
	v_cvt_f32_ubyte2_e32 v102, v76
	v_cvt_f32_ubyte3_e32 v103, v76
	v_pk_fma_f32 v[80:81], v[56:57], v[98:99], v[80:81] op_sel_hi:[0,1,1]
	v_cvt_f32_ubyte0_e32 v104, v31
	v_cvt_f32_ubyte1_e32 v105, v31
	v_pk_fma_f32 v[78:79], v[56:57], v[102:103], v[78:79] op_sel_hi:[0,1,1]
	v_cvt_f32_ubyte2_e32 v146, v31
	v_cvt_f32_ubyte3_e32 v147, v31
	v_pk_fma_f32 v[70:71], v[56:57], v[104:105], v[70:71] op_sel_hi:[0,1,1]
	v_cvt_f32_ubyte0_e32 v98, v82
	v_cvt_f32_ubyte1_e32 v99, v82
	v_pk_fma_f32 v[62:63], v[56:57], v[146:147], v[62:63] op_sel_hi:[0,1,1]
	v_cvt_f32_ubyte2_e32 v102, v82
	v_cvt_f32_ubyte3_e32 v103, v82
	v_pk_fma_f32 v[92:93], v[56:57], v[98:99], v[92:93] op_sel:[1,0,0]
	v_cvt_f32_ubyte0_e32 v104, v32
	v_cvt_f32_ubyte1_e32 v105, v32
	v_pk_fma_f32 v[90:91], v[56:57], v[102:103], v[90:91] op_sel:[1,0,0]
	v_cvt_f32_ubyte2_e32 v146, v32
	v_cvt_f32_ubyte3_e32 v147, v32
	v_pk_fma_f32 v[86:87], v[56:57], v[104:105], v[86:87] op_sel:[1,0,0]
	v_cvt_f32_ubyte0_e32 v98, v88
	v_cvt_f32_ubyte1_e32 v99, v88
	v_pk_fma_f32 v[84:85], v[56:57], v[146:147], v[84:85] op_sel:[1,0,0]
	v_cvt_f32_ubyte2_e32 v102, v88
	v_cvt_f32_ubyte3_e32 v103, v88
	v_pk_fma_f32 v[80:81], v[56:57], v[98:99], v[80:81] op_sel:[1,0,0]
	v_cvt_f32_ubyte0_e32 v104, v33
	v_cvt_f32_ubyte1_e32 v105, v33
	v_pk_fma_f32 v[78:79], v[56:57], v[102:103], v[78:79] op_sel:[1,0,0]
	v_cvt_f32_ubyte2_e32 v146, v33
	v_cvt_f32_ubyte3_e32 v147, v33
	v_pk_fma_f32 v[70:71], v[56:57], v[104:105], v[70:71] op_sel:[1,0,0]
	v_pk_fma_f32 v[62:63], v[56:57], v[146:147], v[62:63] op_sel:[1,0,0]
	s_waitcnt lgkmcnt(0)
	ds_read_b128 v[50:53], v1 offset:928
	ds_read_b128 v[54:57], v1 offset:944
	s_waitcnt vmcnt(24)
	v_and_b32_e32 v68, s0, v164
	v_and_b32_e32 v76, s0, v165
	v_cvt_f32_ubyte0_e32 v98, v68
	v_cvt_f32_ubyte1_e32 v99, v68
	v_cvt_f32_ubyte2_e32 v102, v68
	v_cvt_f32_ubyte3_e32 v103, v68
	v_pk_fma_f32 v[92:93], v[34:35], v[98:99], v[92:93] op_sel_hi:[0,1,1]
	v_cvt_f32_ubyte0_e32 v104, v164
	v_cvt_f32_ubyte1_e32 v105, v164
	v_pk_fma_f32 v[90:91], v[34:35], v[102:103], v[90:91] op_sel_hi:[0,1,1]
	v_cvt_f32_ubyte2_e32 v146, v164
	v_cvt_f32_ubyte3_e32 v147, v164
	v_pk_fma_f32 v[86:87], v[34:35], v[104:105], v[86:87] op_sel_hi:[0,1,1]
	v_cvt_f32_ubyte0_e32 v98, v76
	v_cvt_f32_ubyte1_e32 v99, v76
	v_pk_fma_f32 v[84:85], v[34:35], v[146:147], v[84:85] op_sel_hi:[0,1,1]
	v_and_b32_e32 v82, s0, v166
	v_and_b32_e32 v88, s0, v167
	v_cvt_f32_ubyte2_e32 v102, v76
	v_cvt_f32_ubyte3_e32 v103, v76
	v_pk_fma_f32 v[80:81], v[34:35], v[98:99], v[80:81] op_sel_hi:[0,1,1]
	v_cvt_f32_ubyte0_e32 v104, v165
	v_cvt_f32_ubyte1_e32 v105, v165
	v_pk_fma_f32 v[78:79], v[34:35], v[102:103], v[78:79] op_sel_hi:[0,1,1]
	v_cvt_f32_ubyte2_e32 v146, v165
	v_cvt_f32_ubyte3_e32 v147, v165
	v_pk_fma_f32 v[70:71], v[34:35], v[104:105], v[70:71] op_sel_hi:[0,1,1]
	v_cvt_f32_ubyte0_e32 v98, v82
	v_cvt_f32_ubyte1_e32 v99, v82
	v_pk_fma_f32 v[62:63], v[34:35], v[146:147], v[62:63] op_sel_hi:[0,1,1]
	v_cvt_f32_ubyte2_e32 v102, v82
	v_cvt_f32_ubyte3_e32 v103, v82
	v_pk_fma_f32 v[92:93], v[34:35], v[98:99], v[92:93] op_sel:[1,0,0]
	v_cvt_f32_ubyte0_e32 v104, v166
	v_cvt_f32_ubyte1_e32 v105, v166
	v_pk_fma_f32 v[90:91], v[34:35], v[102:103], v[90:91] op_sel:[1,0,0]
	v_cvt_f32_ubyte2_e32 v146, v166
	v_cvt_f32_ubyte3_e32 v147, v166
	v_pk_fma_f32 v[86:87], v[34:35], v[104:105], v[86:87] op_sel:[1,0,0]
	v_cvt_f32_ubyte0_e32 v98, v88
	v_cvt_f32_ubyte1_e32 v99, v88
	v_pk_fma_f32 v[84:85], v[34:35], v[146:147], v[84:85] op_sel:[1,0,0]
	v_and_b32_e32 v68, s0, v168
	v_and_b32_e32 v76, s0, v169
	v_cvt_f32_ubyte2_e32 v102, v88
	v_cvt_f32_ubyte3_e32 v103, v88
	v_pk_fma_f32 v[80:81], v[34:35], v[98:99], v[80:81] op_sel:[1,0,0]
	v_cvt_f32_ubyte0_e32 v104, v167
	v_cvt_f32_ubyte1_e32 v105, v167
	v_pk_fma_f32 v[78:79], v[34:35], v[102:103], v[78:79] op_sel:[1,0,0]
	v_cvt_f32_ubyte2_e32 v146, v167
	v_cvt_f32_ubyte3_e32 v147, v167
	v_pk_fma_f32 v[70:71], v[34:35], v[104:105], v[70:71] op_sel:[1,0,0]
	v_cvt_f32_ubyte0_e32 v98, v68
	v_cvt_f32_ubyte1_e32 v99, v68
	v_pk_fma_f32 v[62:63], v[34:35], v[146:147], v[62:63] op_sel:[1,0,0]
	v_cvt_f32_ubyte2_e32 v102, v68
	v_cvt_f32_ubyte3_e32 v103, v68
	v_pk_fma_f32 v[92:93], v[36:37], v[98:99], v[92:93] op_sel_hi:[0,1,1]
	v_cvt_f32_ubyte0_e32 v104, v168
	v_cvt_f32_ubyte1_e32 v105, v168
	v_pk_fma_f32 v[90:91], v[36:37], v[102:103], v[90:91] op_sel_hi:[0,1,1]
	v_cvt_f32_ubyte2_e32 v146, v168
	v_cvt_f32_ubyte3_e32 v147, v168
	v_pk_fma_f32 v[86:87], v[36:37], v[104:105], v[86:87] op_sel_hi:[0,1,1]
	v_cvt_f32_ubyte0_e32 v98, v76
	v_cvt_f32_ubyte1_e32 v99, v76
	v_pk_fma_f32 v[84:85], v[36:37], v[146:147], v[84:85] op_sel_hi:[0,1,1]
	v_and_b32_e32 v82, s0, v170
	v_and_b32_e32 v88, s0, v171
	v_cvt_f32_ubyte2_e32 v102, v76
	v_cvt_f32_ubyte3_e32 v103, v76
	v_pk_fma_f32 v[80:81], v[36:37], v[98:99], v[80:81] op_sel_hi:[0,1,1]
	v_cvt_f32_ubyte0_e32 v104, v169
	v_cvt_f32_ubyte1_e32 v105, v169
	v_pk_fma_f32 v[78:79], v[36:37], v[102:103], v[78:79] op_sel_hi:[0,1,1]
	v_cvt_f32_ubyte2_e32 v146, v169
	v_cvt_f32_ubyte3_e32 v147, v169
	v_pk_fma_f32 v[70:71], v[36:37], v[104:105], v[70:71] op_sel_hi:[0,1,1]
	v_cvt_f32_ubyte0_e32 v98, v82
	v_cvt_f32_ubyte1_e32 v99, v82
	v_pk_fma_f32 v[62:63], v[36:37], v[146:147], v[62:63] op_sel_hi:[0,1,1]
	v_cvt_f32_ubyte2_e32 v102, v82
	v_cvt_f32_ubyte3_e32 v103, v82
	v_pk_fma_f32 v[92:93], v[36:37], v[98:99], v[92:93] op_sel:[1,0,0]
	v_cvt_f32_ubyte0_e32 v104, v170
	v_cvt_f32_ubyte1_e32 v105, v170
	v_pk_fma_f32 v[90:91], v[36:37], v[102:103], v[90:91] op_sel:[1,0,0]
	v_cvt_f32_ubyte2_e32 v146, v170
	v_cvt_f32_ubyte3_e32 v147, v170
	v_pk_fma_f32 v[86:87], v[36:37], v[104:105], v[86:87] op_sel:[1,0,0]
	v_cvt_f32_ubyte0_e32 v98, v88
	v_cvt_f32_ubyte1_e32 v99, v88
	v_pk_fma_f32 v[84:85], v[36:37], v[146:147], v[84:85] op_sel:[1,0,0]
	v_and_b32_e32 v68, s0, v172
	v_and_b32_e32 v76, s0, v173
	v_cvt_f32_ubyte2_e32 v102, v88
	v_cvt_f32_ubyte3_e32 v103, v88
	v_pk_fma_f32 v[80:81], v[36:37], v[98:99], v[80:81] op_sel:[1,0,0]
	v_cvt_f32_ubyte0_e32 v104, v171
	v_cvt_f32_ubyte1_e32 v105, v171
	v_pk_fma_f32 v[78:79], v[36:37], v[102:103], v[78:79] op_sel:[1,0,0]
	v_cvt_f32_ubyte2_e32 v146, v171
	v_cvt_f32_ubyte3_e32 v147, v171
	v_pk_fma_f32 v[70:71], v[36:37], v[104:105], v[70:71] op_sel:[1,0,0]
	v_cvt_f32_ubyte0_e32 v98, v68
	v_cvt_f32_ubyte1_e32 v99, v68
	v_pk_fma_f32 v[62:63], v[36:37], v[146:147], v[62:63] op_sel:[1,0,0]
	v_cvt_f32_ubyte2_e32 v102, v68
	v_cvt_f32_ubyte3_e32 v103, v68
	v_pk_fma_f32 v[92:93], v[38:39], v[98:99], v[92:93] op_sel_hi:[0,1,1]
	v_cvt_f32_ubyte0_e32 v104, v172
	v_cvt_f32_ubyte1_e32 v105, v172
	v_pk_fma_f32 v[90:91], v[38:39], v[102:103], v[90:91] op_sel_hi:[0,1,1]
	v_cvt_f32_ubyte2_e32 v146, v172
	v_cvt_f32_ubyte3_e32 v147, v172
	v_pk_fma_f32 v[86:87], v[38:39], v[104:105], v[86:87] op_sel_hi:[0,1,1]
	v_cvt_f32_ubyte0_e32 v98, v76
	v_cvt_f32_ubyte1_e32 v99, v76
	v_pk_fma_f32 v[84:85], v[38:39], v[146:147], v[84:85] op_sel_hi:[0,1,1]
	v_and_b32_e32 v82, s0, v174
	v_and_b32_e32 v88, s0, v175
	v_cvt_f32_ubyte2_e32 v102, v76
	v_cvt_f32_ubyte3_e32 v103, v76
	v_pk_fma_f32 v[80:81], v[38:39], v[98:99], v[80:81] op_sel_hi:[0,1,1]
	v_cvt_f32_ubyte0_e32 v104, v173
	v_cvt_f32_ubyte1_e32 v105, v173
	v_pk_fma_f32 v[78:79], v[38:39], v[102:103], v[78:79] op_sel_hi:[0,1,1]
	v_cvt_f32_ubyte2_e32 v146, v173
	v_cvt_f32_ubyte3_e32 v147, v173
	v_pk_fma_f32 v[70:71], v[38:39], v[104:105], v[70:71] op_sel_hi:[0,1,1]
	v_cvt_f32_ubyte0_e32 v98, v82
	v_cvt_f32_ubyte1_e32 v99, v82
	v_pk_fma_f32 v[62:63], v[38:39], v[146:147], v[62:63] op_sel_hi:[0,1,1]
	v_cvt_f32_ubyte2_e32 v102, v82
	v_cvt_f32_ubyte3_e32 v103, v82
	v_pk_fma_f32 v[92:93], v[38:39], v[98:99], v[92:93] op_sel:[1,0,0]
	v_cvt_f32_ubyte0_e32 v104, v174
	v_cvt_f32_ubyte1_e32 v105, v174
	v_pk_fma_f32 v[90:91], v[38:39], v[102:103], v[90:91] op_sel:[1,0,0]
	v_cvt_f32_ubyte2_e32 v146, v174
	v_cvt_f32_ubyte3_e32 v147, v174
	v_pk_fma_f32 v[86:87], v[38:39], v[104:105], v[86:87] op_sel:[1,0,0]
	v_cvt_f32_ubyte0_e32 v98, v88
	v_cvt_f32_ubyte1_e32 v99, v88
	v_pk_fma_f32 v[84:85], v[38:39], v[146:147], v[84:85] op_sel:[1,0,0]
	v_and_b32_e32 v68, s0, v176
	v_and_b32_e32 v76, s0, v177
	v_cvt_f32_ubyte2_e32 v102, v88
	v_cvt_f32_ubyte3_e32 v103, v88
	v_pk_fma_f32 v[80:81], v[38:39], v[98:99], v[80:81] op_sel:[1,0,0]
	v_cvt_f32_ubyte0_e32 v104, v175
	v_cvt_f32_ubyte1_e32 v105, v175
	v_pk_fma_f32 v[78:79], v[38:39], v[102:103], v[78:79] op_sel:[1,0,0]
	v_cvt_f32_ubyte2_e32 v146, v175
	v_cvt_f32_ubyte3_e32 v147, v175
	v_pk_fma_f32 v[70:71], v[38:39], v[104:105], v[70:71] op_sel:[1,0,0]
	v_cvt_f32_ubyte0_e32 v98, v68
	v_cvt_f32_ubyte1_e32 v99, v68
	v_pk_fma_f32 v[62:63], v[38:39], v[146:147], v[62:63] op_sel:[1,0,0]
	v_cvt_f32_ubyte2_e32 v102, v68
	v_cvt_f32_ubyte3_e32 v103, v68
	v_pk_fma_f32 v[92:93], v[40:41], v[98:99], v[92:93] op_sel_hi:[0,1,1]
	v_cvt_f32_ubyte0_e32 v104, v176
	v_cvt_f32_ubyte1_e32 v105, v176
	v_pk_fma_f32 v[90:91], v[40:41], v[102:103], v[90:91] op_sel_hi:[0,1,1]
	v_cvt_f32_ubyte2_e32 v146, v176
	v_cvt_f32_ubyte3_e32 v147, v176
	v_pk_fma_f32 v[86:87], v[40:41], v[104:105], v[86:87] op_sel_hi:[0,1,1]
	v_cvt_f32_ubyte0_e32 v98, v76
	v_cvt_f32_ubyte1_e32 v99, v76
	v_pk_fma_f32 v[84:85], v[40:41], v[146:147], v[84:85] op_sel_hi:[0,1,1]
	v_and_b32_e32 v82, s0, v178
	v_and_b32_e32 v88, s0, v179
	v_cvt_f32_ubyte2_e32 v102, v76
	v_cvt_f32_ubyte3_e32 v103, v76
	v_pk_fma_f32 v[80:81], v[40:41], v[98:99], v[80:81] op_sel_hi:[0,1,1]
	v_cvt_f32_ubyte0_e32 v104, v177
	v_cvt_f32_ubyte1_e32 v105, v177
	v_pk_fma_f32 v[78:79], v[40:41], v[102:103], v[78:79] op_sel_hi:[0,1,1]
	v_cvt_f32_ubyte2_e32 v146, v177
	v_cvt_f32_ubyte3_e32 v147, v177
	v_pk_fma_f32 v[70:71], v[40:41], v[104:105], v[70:71] op_sel_hi:[0,1,1]
	v_cvt_f32_ubyte0_e32 v98, v82
	v_cvt_f32_ubyte1_e32 v99, v82
	v_pk_fma_f32 v[62:63], v[40:41], v[146:147], v[62:63] op_sel_hi:[0,1,1]
	v_cvt_f32_ubyte2_e32 v102, v82
	v_cvt_f32_ubyte3_e32 v103, v82
	v_pk_fma_f32 v[92:93], v[40:41], v[98:99], v[92:93] op_sel:[1,0,0]
	v_cvt_f32_ubyte0_e32 v104, v178
	v_cvt_f32_ubyte1_e32 v105, v178
	v_pk_fma_f32 v[90:91], v[40:41], v[102:103], v[90:91] op_sel:[1,0,0]
	v_cvt_f32_ubyte2_e32 v146, v178
	v_cvt_f32_ubyte3_e32 v147, v178
	v_pk_fma_f32 v[86:87], v[40:41], v[104:105], v[86:87] op_sel:[1,0,0]
	v_cvt_f32_ubyte0_e32 v98, v88
	v_cvt_f32_ubyte1_e32 v99, v88
	v_pk_fma_f32 v[84:85], v[40:41], v[146:147], v[84:85] op_sel:[1,0,0]
	v_cvt_f32_ubyte2_e32 v102, v88
	v_cvt_f32_ubyte3_e32 v103, v88
	v_pk_fma_f32 v[80:81], v[40:41], v[98:99], v[80:81] op_sel:[1,0,0]
	v_cvt_f32_ubyte0_e32 v104, v179
	v_cvt_f32_ubyte1_e32 v105, v179
	v_pk_fma_f32 v[78:79], v[40:41], v[102:103], v[78:79] op_sel:[1,0,0]
	v_cvt_f32_ubyte2_e32 v146, v179
	v_cvt_f32_ubyte3_e32 v147, v179
	v_pk_fma_f32 v[70:71], v[40:41], v[104:105], v[70:71] op_sel:[1,0,0]
	v_pk_fma_f32 v[62:63], v[40:41], v[146:147], v[62:63] op_sel:[1,0,0]
	s_waitcnt lgkmcnt(0)
	ds_read_b128 v[34:37], v1 offset:960
	ds_read_b128 v[38:41], v1 offset:976
	s_waitcnt vmcnt(16)
	v_and_b32_e32 v68, s0, v180
	v_and_b32_e32 v76, s0, v181
	v_cvt_f32_ubyte0_e32 v98, v68
	v_cvt_f32_ubyte1_e32 v99, v68
	v_cvt_f32_ubyte2_e32 v102, v68
	v_cvt_f32_ubyte3_e32 v103, v68
	v_pk_fma_f32 v[92:93], v[50:51], v[98:99], v[92:93] op_sel_hi:[0,1,1]
	v_cvt_f32_ubyte0_e32 v104, v180
	v_cvt_f32_ubyte1_e32 v105, v180
	v_pk_fma_f32 v[90:91], v[50:51], v[102:103], v[90:91] op_sel_hi:[0,1,1]
	v_cvt_f32_ubyte2_e32 v146, v180
	v_cvt_f32_ubyte3_e32 v147, v180
	v_pk_fma_f32 v[86:87], v[50:51], v[104:105], v[86:87] op_sel_hi:[0,1,1]
	v_cvt_f32_ubyte0_e32 v98, v76
	v_cvt_f32_ubyte1_e32 v99, v76
	v_pk_fma_f32 v[84:85], v[50:51], v[146:147], v[84:85] op_sel_hi:[0,1,1]
	v_and_b32_e32 v82, s0, v182
	v_and_b32_e32 v88, s0, v183
	v_cvt_f32_ubyte2_e32 v102, v76
	v_cvt_f32_ubyte3_e32 v103, v76
	v_pk_fma_f32 v[80:81], v[50:51], v[98:99], v[80:81] op_sel_hi:[0,1,1]
	v_cvt_f32_ubyte0_e32 v104, v181
	v_cvt_f32_ubyte1_e32 v105, v181
	v_pk_fma_f32 v[78:79], v[50:51], v[102:103], v[78:79] op_sel_hi:[0,1,1]
	v_cvt_f32_ubyte2_e32 v146, v181
	v_cvt_f32_ubyte3_e32 v147, v181
	v_pk_fma_f32 v[70:71], v[50:51], v[104:105], v[70:71] op_sel_hi:[0,1,1]
	v_cvt_f32_ubyte0_e32 v98, v82
	v_cvt_f32_ubyte1_e32 v99, v82
	v_pk_fma_f32 v[62:63], v[50:51], v[146:147], v[62:63] op_sel_hi:[0,1,1]
	v_cvt_f32_ubyte2_e32 v102, v82
	v_cvt_f32_ubyte3_e32 v103, v82
	v_pk_fma_f32 v[92:93], v[50:51], v[98:99], v[92:93] op_sel:[1,0,0]
	v_cvt_f32_ubyte0_e32 v104, v182
	v_cvt_f32_ubyte1_e32 v105, v182
	v_pk_fma_f32 v[90:91], v[50:51], v[102:103], v[90:91] op_sel:[1,0,0]
	v_cvt_f32_ubyte2_e32 v146, v182
	v_cvt_f32_ubyte3_e32 v147, v182
	v_pk_fma_f32 v[86:87], v[50:51], v[104:105], v[86:87] op_sel:[1,0,0]
	v_cvt_f32_ubyte0_e32 v98, v88
	v_cvt_f32_ubyte1_e32 v99, v88
	v_pk_fma_f32 v[84:85], v[50:51], v[146:147], v[84:85] op_sel:[1,0,0]
	v_and_b32_e32 v68, s0, v184
	v_and_b32_e32 v76, s0, v185
	v_cvt_f32_ubyte2_e32 v102, v88
	v_cvt_f32_ubyte3_e32 v103, v88
	v_pk_fma_f32 v[80:81], v[50:51], v[98:99], v[80:81] op_sel:[1,0,0]
	v_cvt_f32_ubyte0_e32 v104, v183
	v_cvt_f32_ubyte1_e32 v105, v183
	v_pk_fma_f32 v[78:79], v[50:51], v[102:103], v[78:79] op_sel:[1,0,0]
	v_cvt_f32_ubyte2_e32 v146, v183
	v_cvt_f32_ubyte3_e32 v147, v183
	v_pk_fma_f32 v[70:71], v[50:51], v[104:105], v[70:71] op_sel:[1,0,0]
	v_cvt_f32_ubyte0_e32 v98, v68
	v_cvt_f32_ubyte1_e32 v99, v68
	v_pk_fma_f32 v[62:63], v[50:51], v[146:147], v[62:63] op_sel:[1,0,0]
	v_cvt_f32_ubyte2_e32 v102, v68
	v_cvt_f32_ubyte3_e32 v103, v68
	v_pk_fma_f32 v[92:93], v[52:53], v[98:99], v[92:93] op_sel_hi:[0,1,1]
	v_cvt_f32_ubyte0_e32 v104, v184
	v_cvt_f32_ubyte1_e32 v105, v184
	v_pk_fma_f32 v[90:91], v[52:53], v[102:103], v[90:91] op_sel_hi:[0,1,1]
	v_cvt_f32_ubyte2_e32 v146, v184
	v_cvt_f32_ubyte3_e32 v147, v184
	v_pk_fma_f32 v[86:87], v[52:53], v[104:105], v[86:87] op_sel_hi:[0,1,1]
	v_cvt_f32_ubyte0_e32 v98, v76
	v_cvt_f32_ubyte1_e32 v99, v76
	v_pk_fma_f32 v[84:85], v[52:53], v[146:147], v[84:85] op_sel_hi:[0,1,1]
	v_and_b32_e32 v82, s0, v186
	v_and_b32_e32 v88, s0, v187
	v_cvt_f32_ubyte2_e32 v102, v76
	v_cvt_f32_ubyte3_e32 v103, v76
	v_pk_fma_f32 v[80:81], v[52:53], v[98:99], v[80:81] op_sel_hi:[0,1,1]
	v_cvt_f32_ubyte0_e32 v104, v185
	v_cvt_f32_ubyte1_e32 v105, v185
	v_pk_fma_f32 v[78:79], v[52:53], v[102:103], v[78:79] op_sel_hi:[0,1,1]
	v_cvt_f32_ubyte2_e32 v146, v185
	v_cvt_f32_ubyte3_e32 v147, v185
	v_pk_fma_f32 v[70:71], v[52:53], v[104:105], v[70:71] op_sel_hi:[0,1,1]
	v_cvt_f32_ubyte0_e32 v98, v82
	v_cvt_f32_ubyte1_e32 v99, v82
	v_pk_fma_f32 v[62:63], v[52:53], v[146:147], v[62:63] op_sel_hi:[0,1,1]
	v_cvt_f32_ubyte2_e32 v102, v82
	v_cvt_f32_ubyte3_e32 v103, v82
	v_pk_fma_f32 v[92:93], v[52:53], v[98:99], v[92:93] op_sel:[1,0,0]
	v_cvt_f32_ubyte0_e32 v104, v186
	v_cvt_f32_ubyte1_e32 v105, v186
	v_pk_fma_f32 v[90:91], v[52:53], v[102:103], v[90:91] op_sel:[1,0,0]
	v_cvt_f32_ubyte2_e32 v146, v186
	v_cvt_f32_ubyte3_e32 v147, v186
	v_pk_fma_f32 v[86:87], v[52:53], v[104:105], v[86:87] op_sel:[1,0,0]
	v_cvt_f32_ubyte0_e32 v98, v88
	v_cvt_f32_ubyte1_e32 v99, v88
	v_pk_fma_f32 v[84:85], v[52:53], v[146:147], v[84:85] op_sel:[1,0,0]
	v_and_b32_e32 v68, s0, v188
	v_and_b32_e32 v76, s0, v189
	v_cvt_f32_ubyte2_e32 v102, v88
	v_cvt_f32_ubyte3_e32 v103, v88
	v_pk_fma_f32 v[80:81], v[52:53], v[98:99], v[80:81] op_sel:[1,0,0]
	v_cvt_f32_ubyte0_e32 v104, v187
	v_cvt_f32_ubyte1_e32 v105, v187
	v_pk_fma_f32 v[78:79], v[52:53], v[102:103], v[78:79] op_sel:[1,0,0]
	v_cvt_f32_ubyte2_e32 v146, v187
	v_cvt_f32_ubyte3_e32 v147, v187
	v_pk_fma_f32 v[70:71], v[52:53], v[104:105], v[70:71] op_sel:[1,0,0]
	v_cvt_f32_ubyte0_e32 v98, v68
	v_cvt_f32_ubyte1_e32 v99, v68
	v_pk_fma_f32 v[62:63], v[52:53], v[146:147], v[62:63] op_sel:[1,0,0]
	v_cvt_f32_ubyte2_e32 v102, v68
	v_cvt_f32_ubyte3_e32 v103, v68
	v_pk_fma_f32 v[92:93], v[54:55], v[98:99], v[92:93] op_sel_hi:[0,1,1]
	v_cvt_f32_ubyte0_e32 v104, v188
	v_cvt_f32_ubyte1_e32 v105, v188
	v_pk_fma_f32 v[90:91], v[54:55], v[102:103], v[90:91] op_sel_hi:[0,1,1]
	v_cvt_f32_ubyte2_e32 v146, v188
	v_cvt_f32_ubyte3_e32 v147, v188
	v_pk_fma_f32 v[86:87], v[54:55], v[104:105], v[86:87] op_sel_hi:[0,1,1]
	v_cvt_f32_ubyte0_e32 v98, v76
	v_cvt_f32_ubyte1_e32 v99, v76
	v_pk_fma_f32 v[84:85], v[54:55], v[146:147], v[84:85] op_sel_hi:[0,1,1]
	v_and_b32_e32 v82, s0, v190
	v_and_b32_e32 v88, s0, v191
	v_cvt_f32_ubyte2_e32 v102, v76
	v_cvt_f32_ubyte3_e32 v103, v76
	v_pk_fma_f32 v[80:81], v[54:55], v[98:99], v[80:81] op_sel_hi:[0,1,1]
	v_cvt_f32_ubyte0_e32 v104, v189
	v_cvt_f32_ubyte1_e32 v105, v189
	v_pk_fma_f32 v[78:79], v[54:55], v[102:103], v[78:79] op_sel_hi:[0,1,1]
	v_cvt_f32_ubyte2_e32 v146, v189
	v_cvt_f32_ubyte3_e32 v147, v189
	v_pk_fma_f32 v[70:71], v[54:55], v[104:105], v[70:71] op_sel_hi:[0,1,1]
	v_cvt_f32_ubyte0_e32 v98, v82
	v_cvt_f32_ubyte1_e32 v99, v82
	v_pk_fma_f32 v[62:63], v[54:55], v[146:147], v[62:63] op_sel_hi:[0,1,1]
	v_cvt_f32_ubyte2_e32 v102, v82
	v_cvt_f32_ubyte3_e32 v103, v82
	v_pk_fma_f32 v[92:93], v[54:55], v[98:99], v[92:93] op_sel:[1,0,0]
	v_cvt_f32_ubyte0_e32 v104, v190
	v_cvt_f32_ubyte1_e32 v105, v190
	v_pk_fma_f32 v[90:91], v[54:55], v[102:103], v[90:91] op_sel:[1,0,0]
	v_cvt_f32_ubyte2_e32 v146, v190
	v_cvt_f32_ubyte3_e32 v147, v190
	v_pk_fma_f32 v[86:87], v[54:55], v[104:105], v[86:87] op_sel:[1,0,0]
	v_cvt_f32_ubyte0_e32 v98, v88
	v_cvt_f32_ubyte1_e32 v99, v88
	v_pk_fma_f32 v[84:85], v[54:55], v[146:147], v[84:85] op_sel:[1,0,0]
	v_and_b32_e32 v68, s0, v192
	v_and_b32_e32 v76, s0, v193
	v_cvt_f32_ubyte2_e32 v102, v88
	v_cvt_f32_ubyte3_e32 v103, v88
	v_pk_fma_f32 v[80:81], v[54:55], v[98:99], v[80:81] op_sel:[1,0,0]
	v_cvt_f32_ubyte0_e32 v104, v191
	v_cvt_f32_ubyte1_e32 v105, v191
	v_pk_fma_f32 v[78:79], v[54:55], v[102:103], v[78:79] op_sel:[1,0,0]
	v_cvt_f32_ubyte2_e32 v146, v191
	v_cvt_f32_ubyte3_e32 v147, v191
	v_pk_fma_f32 v[70:71], v[54:55], v[104:105], v[70:71] op_sel:[1,0,0]
	v_cvt_f32_ubyte0_e32 v98, v68
	v_cvt_f32_ubyte1_e32 v99, v68
	v_pk_fma_f32 v[62:63], v[54:55], v[146:147], v[62:63] op_sel:[1,0,0]
	v_cvt_f32_ubyte2_e32 v102, v68
	v_cvt_f32_ubyte3_e32 v103, v68
	v_pk_fma_f32 v[92:93], v[56:57], v[98:99], v[92:93] op_sel_hi:[0,1,1]
	v_cvt_f32_ubyte0_e32 v104, v192
	v_cvt_f32_ubyte1_e32 v105, v192
	v_pk_fma_f32 v[90:91], v[56:57], v[102:103], v[90:91] op_sel_hi:[0,1,1]
	v_cvt_f32_ubyte2_e32 v146, v192
	v_cvt_f32_ubyte3_e32 v147, v192
	v_pk_fma_f32 v[86:87], v[56:57], v[104:105], v[86:87] op_sel_hi:[0,1,1]
	v_cvt_f32_ubyte0_e32 v98, v76
	v_cvt_f32_ubyte1_e32 v99, v76
	v_pk_fma_f32 v[84:85], v[56:57], v[146:147], v[84:85] op_sel_hi:[0,1,1]
	v_and_b32_e32 v82, s0, v194
	v_and_b32_e32 v88, s0, v195
	v_cvt_f32_ubyte2_e32 v102, v76
	v_cvt_f32_ubyte3_e32 v103, v76
	v_pk_fma_f32 v[80:81], v[56:57], v[98:99], v[80:81] op_sel_hi:[0,1,1]
	v_cvt_f32_ubyte0_e32 v104, v193
	v_cvt_f32_ubyte1_e32 v105, v193
	v_pk_fma_f32 v[78:79], v[56:57], v[102:103], v[78:79] op_sel_hi:[0,1,1]
	v_cvt_f32_ubyte2_e32 v146, v193
	v_cvt_f32_ubyte3_e32 v147, v193
	v_pk_fma_f32 v[70:71], v[56:57], v[104:105], v[70:71] op_sel_hi:[0,1,1]
	v_cvt_f32_ubyte0_e32 v98, v82
	v_cvt_f32_ubyte1_e32 v99, v82
	v_pk_fma_f32 v[62:63], v[56:57], v[146:147], v[62:63] op_sel_hi:[0,1,1]
	v_cvt_f32_ubyte2_e32 v102, v82
	v_cvt_f32_ubyte3_e32 v103, v82
	v_pk_fma_f32 v[92:93], v[56:57], v[98:99], v[92:93] op_sel:[1,0,0]
	v_cvt_f32_ubyte0_e32 v104, v194
	v_cvt_f32_ubyte1_e32 v105, v194
	v_pk_fma_f32 v[90:91], v[56:57], v[102:103], v[90:91] op_sel:[1,0,0]
	v_cvt_f32_ubyte2_e32 v146, v194
	v_cvt_f32_ubyte3_e32 v147, v194
	v_pk_fma_f32 v[86:87], v[56:57], v[104:105], v[86:87] op_sel:[1,0,0]
	v_cvt_f32_ubyte0_e32 v98, v88
	v_cvt_f32_ubyte1_e32 v99, v88
	v_pk_fma_f32 v[84:85], v[56:57], v[146:147], v[84:85] op_sel:[1,0,0]
	v_cvt_f32_ubyte2_e32 v102, v88
	v_cvt_f32_ubyte3_e32 v103, v88
	v_pk_fma_f32 v[80:81], v[56:57], v[98:99], v[80:81] op_sel:[1,0,0]
	v_cvt_f32_ubyte0_e32 v104, v195
	v_cvt_f32_ubyte1_e32 v105, v195
	v_pk_fma_f32 v[78:79], v[56:57], v[102:103], v[78:79] op_sel:[1,0,0]
	v_cvt_f32_ubyte2_e32 v146, v195
	v_cvt_f32_ubyte3_e32 v147, v195
	v_pk_fma_f32 v[70:71], v[56:57], v[104:105], v[70:71] op_sel:[1,0,0]
	v_pk_fma_f32 v[62:63], v[56:57], v[146:147], v[62:63] op_sel:[1,0,0]
	s_waitcnt lgkmcnt(0)
	ds_read_b128 v[50:53], v1 offset:992
	ds_read_b128 v[54:57], v1 offset:1008
	s_waitcnt vmcnt(8)
	v_and_b32_e32 v68, s0, v196
	v_and_b32_e32 v76, s0, v197
	v_cvt_f32_ubyte0_e32 v98, v68
	v_cvt_f32_ubyte1_e32 v99, v68
	v_cvt_f32_ubyte2_e32 v102, v68
	v_cvt_f32_ubyte3_e32 v103, v68
	v_pk_fma_f32 v[92:93], v[34:35], v[98:99], v[92:93] op_sel_hi:[0,1,1]
	v_cvt_f32_ubyte0_e32 v104, v196
	v_cvt_f32_ubyte1_e32 v105, v196
	v_pk_fma_f32 v[90:91], v[34:35], v[102:103], v[90:91] op_sel_hi:[0,1,1]
	v_cvt_f32_ubyte2_e32 v146, v196
	v_cvt_f32_ubyte3_e32 v147, v196
	v_pk_fma_f32 v[86:87], v[34:35], v[104:105], v[86:87] op_sel_hi:[0,1,1]
	v_cvt_f32_ubyte0_e32 v98, v76
	v_cvt_f32_ubyte1_e32 v99, v76
	v_pk_fma_f32 v[84:85], v[34:35], v[146:147], v[84:85] op_sel_hi:[0,1,1]
	v_and_b32_e32 v82, s0, v198
	v_and_b32_e32 v88, s0, v199
	v_cvt_f32_ubyte2_e32 v102, v76
	v_cvt_f32_ubyte3_e32 v103, v76
	v_pk_fma_f32 v[80:81], v[34:35], v[98:99], v[80:81] op_sel_hi:[0,1,1]
	v_cvt_f32_ubyte0_e32 v104, v197
	v_cvt_f32_ubyte1_e32 v105, v197
	v_pk_fma_f32 v[78:79], v[34:35], v[102:103], v[78:79] op_sel_hi:[0,1,1]
	v_cvt_f32_ubyte2_e32 v146, v197
	v_cvt_f32_ubyte3_e32 v147, v197
	v_pk_fma_f32 v[70:71], v[34:35], v[104:105], v[70:71] op_sel_hi:[0,1,1]
	v_cvt_f32_ubyte0_e32 v98, v82
	v_cvt_f32_ubyte1_e32 v99, v82
	v_pk_fma_f32 v[62:63], v[34:35], v[146:147], v[62:63] op_sel_hi:[0,1,1]
	v_cvt_f32_ubyte2_e32 v102, v82
	v_cvt_f32_ubyte3_e32 v103, v82
	v_pk_fma_f32 v[92:93], v[34:35], v[98:99], v[92:93] op_sel:[1,0,0]
	v_cvt_f32_ubyte0_e32 v104, v198
	v_cvt_f32_ubyte1_e32 v105, v198
	v_pk_fma_f32 v[90:91], v[34:35], v[102:103], v[90:91] op_sel:[1,0,0]
	v_cvt_f32_ubyte2_e32 v146, v198
	v_cvt_f32_ubyte3_e32 v147, v198
	v_pk_fma_f32 v[86:87], v[34:35], v[104:105], v[86:87] op_sel:[1,0,0]
	v_cvt_f32_ubyte0_e32 v98, v88
	v_cvt_f32_ubyte1_e32 v99, v88
	v_pk_fma_f32 v[84:85], v[34:35], v[146:147], v[84:85] op_sel:[1,0,0]
	v_and_b32_e32 v68, s0, v200
	v_and_b32_e32 v76, s0, v201
	v_cvt_f32_ubyte2_e32 v102, v88
	v_cvt_f32_ubyte3_e32 v103, v88
	v_pk_fma_f32 v[80:81], v[34:35], v[98:99], v[80:81] op_sel:[1,0,0]
	v_cvt_f32_ubyte0_e32 v104, v199
	v_cvt_f32_ubyte1_e32 v105, v199
	v_pk_fma_f32 v[78:79], v[34:35], v[102:103], v[78:79] op_sel:[1,0,0]
	v_cvt_f32_ubyte2_e32 v146, v199
	v_cvt_f32_ubyte3_e32 v147, v199
	v_pk_fma_f32 v[70:71], v[34:35], v[104:105], v[70:71] op_sel:[1,0,0]
	v_cvt_f32_ubyte0_e32 v98, v68
	v_cvt_f32_ubyte1_e32 v99, v68
	v_pk_fma_f32 v[62:63], v[34:35], v[146:147], v[62:63] op_sel:[1,0,0]
	v_cvt_f32_ubyte2_e32 v102, v68
	v_cvt_f32_ubyte3_e32 v103, v68
	v_pk_fma_f32 v[92:93], v[36:37], v[98:99], v[92:93] op_sel_hi:[0,1,1]
	v_cvt_f32_ubyte0_e32 v104, v200
	v_cvt_f32_ubyte1_e32 v105, v200
	v_pk_fma_f32 v[90:91], v[36:37], v[102:103], v[90:91] op_sel_hi:[0,1,1]
	v_cvt_f32_ubyte2_e32 v146, v200
	v_cvt_f32_ubyte3_e32 v147, v200
	v_pk_fma_f32 v[86:87], v[36:37], v[104:105], v[86:87] op_sel_hi:[0,1,1]
	v_cvt_f32_ubyte0_e32 v98, v76
	v_cvt_f32_ubyte1_e32 v99, v76
	v_pk_fma_f32 v[84:85], v[36:37], v[146:147], v[84:85] op_sel_hi:[0,1,1]
	v_and_b32_e32 v82, s0, v202
	v_and_b32_e32 v88, s0, v203
	v_cvt_f32_ubyte2_e32 v102, v76
	v_cvt_f32_ubyte3_e32 v103, v76
	v_pk_fma_f32 v[80:81], v[36:37], v[98:99], v[80:81] op_sel_hi:[0,1,1]
	v_cvt_f32_ubyte0_e32 v104, v201
	v_cvt_f32_ubyte1_e32 v105, v201
	v_pk_fma_f32 v[78:79], v[36:37], v[102:103], v[78:79] op_sel_hi:[0,1,1]
	v_cvt_f32_ubyte2_e32 v146, v201
	v_cvt_f32_ubyte3_e32 v147, v201
	v_pk_fma_f32 v[70:71], v[36:37], v[104:105], v[70:71] op_sel_hi:[0,1,1]
	v_cvt_f32_ubyte0_e32 v98, v82
	v_cvt_f32_ubyte1_e32 v99, v82
	v_pk_fma_f32 v[62:63], v[36:37], v[146:147], v[62:63] op_sel_hi:[0,1,1]
	v_cvt_f32_ubyte2_e32 v102, v82
	v_cvt_f32_ubyte3_e32 v103, v82
	v_pk_fma_f32 v[92:93], v[36:37], v[98:99], v[92:93] op_sel:[1,0,0]
	v_cvt_f32_ubyte0_e32 v104, v202
	v_cvt_f32_ubyte1_e32 v105, v202
	v_pk_fma_f32 v[90:91], v[36:37], v[102:103], v[90:91] op_sel:[1,0,0]
	v_cvt_f32_ubyte2_e32 v146, v202
	v_cvt_f32_ubyte3_e32 v147, v202
	v_pk_fma_f32 v[86:87], v[36:37], v[104:105], v[86:87] op_sel:[1,0,0]
	v_cvt_f32_ubyte0_e32 v98, v88
	v_cvt_f32_ubyte1_e32 v99, v88
	v_pk_fma_f32 v[84:85], v[36:37], v[146:147], v[84:85] op_sel:[1,0,0]
	v_and_b32_e32 v68, s0, v204
	v_and_b32_e32 v76, s0, v205
	v_cvt_f32_ubyte2_e32 v102, v88
	v_cvt_f32_ubyte3_e32 v103, v88
	v_pk_fma_f32 v[80:81], v[36:37], v[98:99], v[80:81] op_sel:[1,0,0]
	v_cvt_f32_ubyte0_e32 v104, v203
	v_cvt_f32_ubyte1_e32 v105, v203
	v_pk_fma_f32 v[78:79], v[36:37], v[102:103], v[78:79] op_sel:[1,0,0]
	v_cvt_f32_ubyte2_e32 v146, v203
	v_cvt_f32_ubyte3_e32 v147, v203
	v_pk_fma_f32 v[70:71], v[36:37], v[104:105], v[70:71] op_sel:[1,0,0]
	v_cvt_f32_ubyte0_e32 v98, v68
	v_cvt_f32_ubyte1_e32 v99, v68
	v_pk_fma_f32 v[62:63], v[36:37], v[146:147], v[62:63] op_sel:[1,0,0]
	v_cvt_f32_ubyte2_e32 v102, v68
	v_cvt_f32_ubyte3_e32 v103, v68
	v_pk_fma_f32 v[92:93], v[38:39], v[98:99], v[92:93] op_sel_hi:[0,1,1]
	v_cvt_f32_ubyte0_e32 v104, v204
	v_cvt_f32_ubyte1_e32 v105, v204
	v_pk_fma_f32 v[90:91], v[38:39], v[102:103], v[90:91] op_sel_hi:[0,1,1]
	v_cvt_f32_ubyte2_e32 v146, v204
	v_cvt_f32_ubyte3_e32 v147, v204
	v_pk_fma_f32 v[86:87], v[38:39], v[104:105], v[86:87] op_sel_hi:[0,1,1]
	v_cvt_f32_ubyte0_e32 v98, v76
	v_cvt_f32_ubyte1_e32 v99, v76
	v_pk_fma_f32 v[84:85], v[38:39], v[146:147], v[84:85] op_sel_hi:[0,1,1]
	v_and_b32_e32 v82, s0, v206
	v_and_b32_e32 v88, s0, v207
	v_cvt_f32_ubyte2_e32 v102, v76
	v_cvt_f32_ubyte3_e32 v103, v76
	v_pk_fma_f32 v[80:81], v[38:39], v[98:99], v[80:81] op_sel_hi:[0,1,1]
	v_cvt_f32_ubyte0_e32 v104, v205
	v_cvt_f32_ubyte1_e32 v105, v205
	v_pk_fma_f32 v[78:79], v[38:39], v[102:103], v[78:79] op_sel_hi:[0,1,1]
	v_cvt_f32_ubyte2_e32 v146, v205
	v_cvt_f32_ubyte3_e32 v147, v205
	v_pk_fma_f32 v[70:71], v[38:39], v[104:105], v[70:71] op_sel_hi:[0,1,1]
	v_cvt_f32_ubyte0_e32 v98, v82
	v_cvt_f32_ubyte1_e32 v99, v82
	v_pk_fma_f32 v[62:63], v[38:39], v[146:147], v[62:63] op_sel_hi:[0,1,1]
	v_cvt_f32_ubyte2_e32 v102, v82
	v_cvt_f32_ubyte3_e32 v103, v82
	v_pk_fma_f32 v[92:93], v[38:39], v[98:99], v[92:93] op_sel:[1,0,0]
	v_cvt_f32_ubyte0_e32 v104, v206
	v_cvt_f32_ubyte1_e32 v105, v206
	v_pk_fma_f32 v[90:91], v[38:39], v[102:103], v[90:91] op_sel:[1,0,0]
	v_cvt_f32_ubyte2_e32 v146, v206
	v_cvt_f32_ubyte3_e32 v147, v206
	v_pk_fma_f32 v[86:87], v[38:39], v[104:105], v[86:87] op_sel:[1,0,0]
	v_cvt_f32_ubyte0_e32 v98, v88
	v_cvt_f32_ubyte1_e32 v99, v88
	v_pk_fma_f32 v[84:85], v[38:39], v[146:147], v[84:85] op_sel:[1,0,0]
	v_and_b32_e32 v68, s0, v208
	v_and_b32_e32 v76, s0, v209
	v_cvt_f32_ubyte2_e32 v102, v88
	v_cvt_f32_ubyte3_e32 v103, v88
	v_pk_fma_f32 v[80:81], v[38:39], v[98:99], v[80:81] op_sel:[1,0,0]
	v_cvt_f32_ubyte0_e32 v104, v207
	v_cvt_f32_ubyte1_e32 v105, v207
	v_pk_fma_f32 v[78:79], v[38:39], v[102:103], v[78:79] op_sel:[1,0,0]
	v_cvt_f32_ubyte2_e32 v146, v207
	v_cvt_f32_ubyte3_e32 v147, v207
	v_pk_fma_f32 v[70:71], v[38:39], v[104:105], v[70:71] op_sel:[1,0,0]
	v_cvt_f32_ubyte0_e32 v98, v68
	v_cvt_f32_ubyte1_e32 v99, v68
	v_pk_fma_f32 v[62:63], v[38:39], v[146:147], v[62:63] op_sel:[1,0,0]
	v_cvt_f32_ubyte2_e32 v102, v68
	v_cvt_f32_ubyte3_e32 v103, v68
	v_pk_fma_f32 v[92:93], v[40:41], v[98:99], v[92:93] op_sel_hi:[0,1,1]
	v_cvt_f32_ubyte0_e32 v104, v208
	v_cvt_f32_ubyte1_e32 v105, v208
	v_pk_fma_f32 v[90:91], v[40:41], v[102:103], v[90:91] op_sel_hi:[0,1,1]
	v_cvt_f32_ubyte2_e32 v146, v208
	v_cvt_f32_ubyte3_e32 v147, v208
	v_pk_fma_f32 v[86:87], v[40:41], v[104:105], v[86:87] op_sel_hi:[0,1,1]
	v_cvt_f32_ubyte0_e32 v98, v76
	v_cvt_f32_ubyte1_e32 v99, v76
	v_pk_fma_f32 v[84:85], v[40:41], v[146:147], v[84:85] op_sel_hi:[0,1,1]
	v_and_b32_e32 v82, s0, v210
	v_and_b32_e32 v88, s0, v211
	v_cvt_f32_ubyte2_e32 v102, v76
	v_cvt_f32_ubyte3_e32 v103, v76
	v_pk_fma_f32 v[80:81], v[40:41], v[98:99], v[80:81] op_sel_hi:[0,1,1]
	v_cvt_f32_ubyte0_e32 v104, v209
	v_cvt_f32_ubyte1_e32 v105, v209
	v_pk_fma_f32 v[78:79], v[40:41], v[102:103], v[78:79] op_sel_hi:[0,1,1]
	v_cvt_f32_ubyte2_e32 v146, v209
	v_cvt_f32_ubyte3_e32 v147, v209
	v_pk_fma_f32 v[70:71], v[40:41], v[104:105], v[70:71] op_sel_hi:[0,1,1]
	v_cvt_f32_ubyte0_e32 v98, v82
	v_cvt_f32_ubyte1_e32 v99, v82
	v_pk_fma_f32 v[62:63], v[40:41], v[146:147], v[62:63] op_sel_hi:[0,1,1]
	v_cvt_f32_ubyte2_e32 v102, v82
	v_cvt_f32_ubyte3_e32 v103, v82
	v_pk_fma_f32 v[92:93], v[40:41], v[98:99], v[92:93] op_sel:[1,0,0]
	v_cvt_f32_ubyte0_e32 v104, v210
	v_cvt_f32_ubyte1_e32 v105, v210
	v_pk_fma_f32 v[90:91], v[40:41], v[102:103], v[90:91] op_sel:[1,0,0]
	v_cvt_f32_ubyte2_e32 v146, v210
	v_cvt_f32_ubyte3_e32 v147, v210
	v_pk_fma_f32 v[86:87], v[40:41], v[104:105], v[86:87] op_sel:[1,0,0]
	v_cvt_f32_ubyte0_e32 v98, v88
	v_cvt_f32_ubyte1_e32 v99, v88
	v_pk_fma_f32 v[84:85], v[40:41], v[146:147], v[84:85] op_sel:[1,0,0]
	v_cvt_f32_ubyte2_e32 v102, v88
	v_cvt_f32_ubyte3_e32 v103, v88
	v_pk_fma_f32 v[80:81], v[40:41], v[98:99], v[80:81] op_sel:[1,0,0]
	v_cvt_f32_ubyte0_e32 v104, v211
	v_cvt_f32_ubyte1_e32 v105, v211
	v_pk_fma_f32 v[78:79], v[40:41], v[102:103], v[78:79] op_sel:[1,0,0]
	v_cvt_f32_ubyte2_e32 v146, v211
	v_cvt_f32_ubyte3_e32 v147, v211
	v_pk_fma_f32 v[70:71], v[40:41], v[104:105], v[70:71] op_sel:[1,0,0]
	v_pk_fma_f32 v[62:63], v[40:41], v[146:147], v[62:63] op_sel:[1,0,0]
	s_waitcnt lgkmcnt(0)
	s_waitcnt vmcnt(0)
	v_and_b32_e32 v68, s0, v212
	v_and_b32_e32 v76, s0, v213
	v_cvt_f32_ubyte0_e32 v98, v68
	v_cvt_f32_ubyte1_e32 v99, v68
	v_cvt_f32_ubyte2_e32 v102, v68
	v_cvt_f32_ubyte3_e32 v103, v68
	v_pk_fma_f32 v[92:93], v[50:51], v[98:99], v[92:93] op_sel_hi:[0,1,1]
	v_cvt_f32_ubyte0_e32 v104, v212
	v_cvt_f32_ubyte1_e32 v105, v212
	v_pk_fma_f32 v[90:91], v[50:51], v[102:103], v[90:91] op_sel_hi:[0,1,1]
	v_cvt_f32_ubyte2_e32 v146, v212
	v_cvt_f32_ubyte3_e32 v147, v212
	v_pk_fma_f32 v[86:87], v[50:51], v[104:105], v[86:87] op_sel_hi:[0,1,1]
	v_cvt_f32_ubyte0_e32 v98, v76
	v_cvt_f32_ubyte1_e32 v99, v76
	v_pk_fma_f32 v[84:85], v[50:51], v[146:147], v[84:85] op_sel_hi:[0,1,1]
	v_and_b32_e32 v82, s0, v214
	v_and_b32_e32 v88, s0, v215
	v_cvt_f32_ubyte2_e32 v102, v76
	v_cvt_f32_ubyte3_e32 v103, v76
	v_pk_fma_f32 v[80:81], v[50:51], v[98:99], v[80:81] op_sel_hi:[0,1,1]
	v_cvt_f32_ubyte0_e32 v104, v213
	v_cvt_f32_ubyte1_e32 v105, v213
	v_pk_fma_f32 v[78:79], v[50:51], v[102:103], v[78:79] op_sel_hi:[0,1,1]
	v_cvt_f32_ubyte2_e32 v146, v213
	v_cvt_f32_ubyte3_e32 v147, v213
	v_pk_fma_f32 v[70:71], v[50:51], v[104:105], v[70:71] op_sel_hi:[0,1,1]
	v_cvt_f32_ubyte0_e32 v98, v82
	v_cvt_f32_ubyte1_e32 v99, v82
	v_pk_fma_f32 v[62:63], v[50:51], v[146:147], v[62:63] op_sel_hi:[0,1,1]
	v_cvt_f32_ubyte2_e32 v102, v82
	v_cvt_f32_ubyte3_e32 v103, v82
	v_pk_fma_f32 v[92:93], v[50:51], v[98:99], v[92:93] op_sel:[1,0,0]
	v_cvt_f32_ubyte0_e32 v104, v214
	v_cvt_f32_ubyte1_e32 v105, v214
	v_pk_fma_f32 v[90:91], v[50:51], v[102:103], v[90:91] op_sel:[1,0,0]
	v_cvt_f32_ubyte2_e32 v146, v214
	v_cvt_f32_ubyte3_e32 v147, v214
	v_pk_fma_f32 v[86:87], v[50:51], v[104:105], v[86:87] op_sel:[1,0,0]
	v_cvt_f32_ubyte0_e32 v98, v88
	v_cvt_f32_ubyte1_e32 v99, v88
	v_pk_fma_f32 v[84:85], v[50:51], v[146:147], v[84:85] op_sel:[1,0,0]
	v_and_b32_e32 v68, s0, v216
	v_and_b32_e32 v76, s0, v217
	v_cvt_f32_ubyte2_e32 v102, v88
	v_cvt_f32_ubyte3_e32 v103, v88
	v_pk_fma_f32 v[80:81], v[50:51], v[98:99], v[80:81] op_sel:[1,0,0]
	v_cvt_f32_ubyte0_e32 v104, v215
	v_cvt_f32_ubyte1_e32 v105, v215
	v_pk_fma_f32 v[78:79], v[50:51], v[102:103], v[78:79] op_sel:[1,0,0]
	v_cvt_f32_ubyte2_e32 v146, v215
	v_cvt_f32_ubyte3_e32 v147, v215
	v_pk_fma_f32 v[70:71], v[50:51], v[104:105], v[70:71] op_sel:[1,0,0]
	v_cvt_f32_ubyte0_e32 v98, v68
	v_cvt_f32_ubyte1_e32 v99, v68
	v_pk_fma_f32 v[62:63], v[50:51], v[146:147], v[62:63] op_sel:[1,0,0]
	v_cvt_f32_ubyte2_e32 v102, v68
	v_cvt_f32_ubyte3_e32 v103, v68
	v_pk_fma_f32 v[92:93], v[52:53], v[98:99], v[92:93] op_sel_hi:[0,1,1]
	v_cvt_f32_ubyte0_e32 v104, v216
	v_cvt_f32_ubyte1_e32 v105, v216
	v_pk_fma_f32 v[90:91], v[52:53], v[102:103], v[90:91] op_sel_hi:[0,1,1]
	v_cvt_f32_ubyte2_e32 v146, v216
	v_cvt_f32_ubyte3_e32 v147, v216
	v_pk_fma_f32 v[86:87], v[52:53], v[104:105], v[86:87] op_sel_hi:[0,1,1]
	v_cvt_f32_ubyte0_e32 v98, v76
	v_cvt_f32_ubyte1_e32 v99, v76
	v_pk_fma_f32 v[84:85], v[52:53], v[146:147], v[84:85] op_sel_hi:[0,1,1]
	v_and_b32_e32 v82, s0, v218
	v_and_b32_e32 v88, s0, v219
	v_cvt_f32_ubyte2_e32 v102, v76
	v_cvt_f32_ubyte3_e32 v103, v76
	v_pk_fma_f32 v[80:81], v[52:53], v[98:99], v[80:81] op_sel_hi:[0,1,1]
	v_cvt_f32_ubyte0_e32 v104, v217
	v_cvt_f32_ubyte1_e32 v105, v217
	v_pk_fma_f32 v[78:79], v[52:53], v[102:103], v[78:79] op_sel_hi:[0,1,1]
	v_cvt_f32_ubyte2_e32 v146, v217
	v_cvt_f32_ubyte3_e32 v147, v217
	v_pk_fma_f32 v[70:71], v[52:53], v[104:105], v[70:71] op_sel_hi:[0,1,1]
	v_cvt_f32_ubyte0_e32 v98, v82
	v_cvt_f32_ubyte1_e32 v99, v82
	v_pk_fma_f32 v[62:63], v[52:53], v[146:147], v[62:63] op_sel_hi:[0,1,1]
	v_cvt_f32_ubyte2_e32 v102, v82
	v_cvt_f32_ubyte3_e32 v103, v82
	v_pk_fma_f32 v[92:93], v[52:53], v[98:99], v[92:93] op_sel:[1,0,0]
	v_cvt_f32_ubyte0_e32 v104, v218
	v_cvt_f32_ubyte1_e32 v105, v218
	v_pk_fma_f32 v[90:91], v[52:53], v[102:103], v[90:91] op_sel:[1,0,0]
	v_cvt_f32_ubyte2_e32 v146, v218
	v_cvt_f32_ubyte3_e32 v147, v218
	v_pk_fma_f32 v[86:87], v[52:53], v[104:105], v[86:87] op_sel:[1,0,0]
	v_cvt_f32_ubyte0_e32 v98, v88
	v_cvt_f32_ubyte1_e32 v99, v88
	v_pk_fma_f32 v[84:85], v[52:53], v[146:147], v[84:85] op_sel:[1,0,0]
	v_and_b32_e32 v68, s0, v220
	v_and_b32_e32 v76, s0, v221
	v_cvt_f32_ubyte2_e32 v102, v88
	v_cvt_f32_ubyte3_e32 v103, v88
	v_pk_fma_f32 v[80:81], v[52:53], v[98:99], v[80:81] op_sel:[1,0,0]
	v_cvt_f32_ubyte0_e32 v104, v219
	v_cvt_f32_ubyte1_e32 v105, v219
	v_pk_fma_f32 v[78:79], v[52:53], v[102:103], v[78:79] op_sel:[1,0,0]
	v_cvt_f32_ubyte2_e32 v146, v219
	v_cvt_f32_ubyte3_e32 v147, v219
	v_pk_fma_f32 v[70:71], v[52:53], v[104:105], v[70:71] op_sel:[1,0,0]
	v_cvt_f32_ubyte0_e32 v98, v68
	v_cvt_f32_ubyte1_e32 v99, v68
	v_pk_fma_f32 v[62:63], v[52:53], v[146:147], v[62:63] op_sel:[1,0,0]
	v_cvt_f32_ubyte2_e32 v102, v68
	v_cvt_f32_ubyte3_e32 v103, v68
	v_pk_fma_f32 v[92:93], v[54:55], v[98:99], v[92:93] op_sel_hi:[0,1,1]
	v_cvt_f32_ubyte0_e32 v104, v220
	v_cvt_f32_ubyte1_e32 v105, v220
	v_pk_fma_f32 v[90:91], v[54:55], v[102:103], v[90:91] op_sel_hi:[0,1,1]
	v_cvt_f32_ubyte2_e32 v146, v220
	v_cvt_f32_ubyte3_e32 v147, v220
	v_pk_fma_f32 v[86:87], v[54:55], v[104:105], v[86:87] op_sel_hi:[0,1,1]
	v_cvt_f32_ubyte0_e32 v98, v76
	v_cvt_f32_ubyte1_e32 v99, v76
	v_pk_fma_f32 v[84:85], v[54:55], v[146:147], v[84:85] op_sel_hi:[0,1,1]
	v_and_b32_e32 v82, s0, v222
	v_and_b32_e32 v88, s0, v223
	v_cvt_f32_ubyte2_e32 v102, v76
	v_cvt_f32_ubyte3_e32 v103, v76
	v_pk_fma_f32 v[80:81], v[54:55], v[98:99], v[80:81] op_sel_hi:[0,1,1]
	v_cvt_f32_ubyte0_e32 v104, v221
	v_cvt_f32_ubyte1_e32 v105, v221
	v_pk_fma_f32 v[78:79], v[54:55], v[102:103], v[78:79] op_sel_hi:[0,1,1]
	v_cvt_f32_ubyte2_e32 v146, v221
	v_cvt_f32_ubyte3_e32 v147, v221
	v_pk_fma_f32 v[70:71], v[54:55], v[104:105], v[70:71] op_sel_hi:[0,1,1]
	v_cvt_f32_ubyte0_e32 v98, v82
	v_cvt_f32_ubyte1_e32 v99, v82
	v_pk_fma_f32 v[62:63], v[54:55], v[146:147], v[62:63] op_sel_hi:[0,1,1]
	v_cvt_f32_ubyte2_e32 v102, v82
	v_cvt_f32_ubyte3_e32 v103, v82
	v_pk_fma_f32 v[92:93], v[54:55], v[98:99], v[92:93] op_sel:[1,0,0]
	v_cvt_f32_ubyte0_e32 v104, v222
	v_cvt_f32_ubyte1_e32 v105, v222
	v_pk_fma_f32 v[90:91], v[54:55], v[102:103], v[90:91] op_sel:[1,0,0]
	v_cvt_f32_ubyte2_e32 v146, v222
	v_cvt_f32_ubyte3_e32 v147, v222
	v_pk_fma_f32 v[86:87], v[54:55], v[104:105], v[86:87] op_sel:[1,0,0]
	v_cvt_f32_ubyte0_e32 v98, v88
	v_cvt_f32_ubyte1_e32 v99, v88
	v_pk_fma_f32 v[84:85], v[54:55], v[146:147], v[84:85] op_sel:[1,0,0]
	v_and_b32_e32 v68, s0, v224
	v_and_b32_e32 v76, s0, v225
	v_cvt_f32_ubyte2_e32 v102, v88
	v_cvt_f32_ubyte3_e32 v103, v88
	v_pk_fma_f32 v[80:81], v[54:55], v[98:99], v[80:81] op_sel:[1,0,0]
	v_cvt_f32_ubyte0_e32 v104, v223
	v_cvt_f32_ubyte1_e32 v105, v223
	v_pk_fma_f32 v[78:79], v[54:55], v[102:103], v[78:79] op_sel:[1,0,0]
	v_cvt_f32_ubyte2_e32 v146, v223
	v_cvt_f32_ubyte3_e32 v147, v223
	v_pk_fma_f32 v[70:71], v[54:55], v[104:105], v[70:71] op_sel:[1,0,0]
	v_cvt_f32_ubyte0_e32 v98, v68
	v_cvt_f32_ubyte1_e32 v99, v68
	v_pk_fma_f32 v[62:63], v[54:55], v[146:147], v[62:63] op_sel:[1,0,0]
	v_cvt_f32_ubyte2_e32 v102, v68
	v_cvt_f32_ubyte3_e32 v103, v68
	v_pk_fma_f32 v[92:93], v[56:57], v[98:99], v[92:93] op_sel_hi:[0,1,1]
	v_cvt_f32_ubyte0_e32 v104, v224
	v_cvt_f32_ubyte1_e32 v105, v224
	v_pk_fma_f32 v[90:91], v[56:57], v[102:103], v[90:91] op_sel_hi:[0,1,1]
	v_cvt_f32_ubyte2_e32 v146, v224
	v_cvt_f32_ubyte3_e32 v147, v224
	v_pk_fma_f32 v[86:87], v[56:57], v[104:105], v[86:87] op_sel_hi:[0,1,1]
	v_cvt_f32_ubyte0_e32 v98, v76
	v_cvt_f32_ubyte1_e32 v99, v76
	v_pk_fma_f32 v[84:85], v[56:57], v[146:147], v[84:85] op_sel_hi:[0,1,1]
	v_and_b32_e32 v82, s0, v226
	v_and_b32_e32 v88, s0, v227
	v_cvt_f32_ubyte2_e32 v102, v76
	v_cvt_f32_ubyte3_e32 v103, v76
	v_pk_fma_f32 v[80:81], v[56:57], v[98:99], v[80:81] op_sel_hi:[0,1,1]
	v_cvt_f32_ubyte0_e32 v104, v225
	v_cvt_f32_ubyte1_e32 v105, v225
	v_pk_fma_f32 v[78:79], v[56:57], v[102:103], v[78:79] op_sel_hi:[0,1,1]
	v_cvt_f32_ubyte2_e32 v146, v225
	v_cvt_f32_ubyte3_e32 v147, v225
	v_pk_fma_f32 v[70:71], v[56:57], v[104:105], v[70:71] op_sel_hi:[0,1,1]
	v_cvt_f32_ubyte0_e32 v98, v82
	v_cvt_f32_ubyte1_e32 v99, v82
	v_pk_fma_f32 v[62:63], v[56:57], v[146:147], v[62:63] op_sel_hi:[0,1,1]
	v_cvt_f32_ubyte2_e32 v102, v82
	v_cvt_f32_ubyte3_e32 v103, v82
	v_pk_fma_f32 v[92:93], v[56:57], v[98:99], v[92:93] op_sel:[1,0,0]
	v_cvt_f32_ubyte0_e32 v104, v226
	v_cvt_f32_ubyte1_e32 v105, v226
	v_pk_fma_f32 v[90:91], v[56:57], v[102:103], v[90:91] op_sel:[1,0,0]
	v_cvt_f32_ubyte2_e32 v146, v226
	v_cvt_f32_ubyte3_e32 v147, v226
	v_pk_fma_f32 v[86:87], v[56:57], v[104:105], v[86:87] op_sel:[1,0,0]
	v_cvt_f32_ubyte0_e32 v98, v88
	v_cvt_f32_ubyte1_e32 v99, v88
	v_pk_fma_f32 v[84:85], v[56:57], v[146:147], v[84:85] op_sel:[1,0,0]
	v_cvt_f32_ubyte2_e32 v102, v88
	v_cvt_f32_ubyte3_e32 v103, v88
	v_pk_fma_f32 v[80:81], v[56:57], v[98:99], v[80:81] op_sel:[1,0,0]
	v_cvt_f32_ubyte0_e32 v104, v227
	v_cvt_f32_ubyte1_e32 v105, v227
	v_pk_fma_f32 v[78:79], v[56:57], v[102:103], v[78:79] op_sel:[1,0,0]
	v_cvt_f32_ubyte2_e32 v146, v227
	v_cvt_f32_ubyte3_e32 v147, v227
	v_pk_fma_f32 v[70:71], v[56:57], v[104:105], v[70:71] op_sel:[1,0,0]
	v_pk_fma_f32 v[62:63], v[56:57], v[146:147], v[62:63] op_sel:[1,0,0]
	v_mov_b32_e32 v98, 0x3d800000
	v_mov_b32_e32 v99, 0x3d800000
	v_pk_add_f32 v[86:87], v[86:87], v[92:93] neg_lo:[0,1] neg_hi:[0,1]
	v_pk_add_f32 v[84:85], v[84:85], v[90:91] neg_lo:[0,1] neg_hi:[0,1]
	v_pk_add_f32 v[70:71], v[70:71], v[80:81] neg_lo:[0,1] neg_hi:[0,1]
	v_pk_add_f32 v[62:63], v[62:63], v[78:79] neg_lo:[0,1] neg_hi:[0,1]
	v_pk_mul_f32 v[86:87], v[86:87], v[98:99]
	v_pk_mul_f32 v[84:85], v[84:85], v[98:99]
	v_pk_mul_f32 v[70:71], v[70:71], v[98:99]
	v_pk_mul_f32 v[62:63], v[62:63], v[98:99]
	s_waitcnt lgkmcnt(0)
	s_branch .LBB0_608

.LBB0_986:
	s_andn2_saveexec_b64 s[34:35], s[36:37]
	v_mul_f32_e32 v5, v4, v4
	v_fmamk_f32 v6, v5, 0xba1345e1, v141
	v_fmaak_f32 v6, v5, v6, 0xbcdac9b8
	v_fmaak_f32 v6, v5, v6, 0x3de703be
	v_fmaak_f32 v6, v5, v6, 0xbec09330
	v_fmaak_f32 v5, v5, v6, 0x3e0375d0
	v_fma_f32 v5, |v4|, v5, |v4|
	s_or_b64 exec, exec, s[34:35]
	v_lshlrev_b64 v[6:7], 7, v[104:105]
	v_lshl_add_u64 v[6:7], v[6:7], 2, v[120:121]
	v_lshl_add_u64 v[8:9], v[32:33], 2, s[40:41]
	v_lshl_add_u64 v[10:11], v[34:35], 2, s[40:41]
	global_load_dwordx2 v[6:7], v[6:7], off
	s_nop 0
	global_load_dword v8, v[8:9], off
	s_nop 0
	global_load_dword v9, v[10:11], off
	v_bfi_b32 v1, s54, v2, v1
	v_mul_f32_e32 v2, 0.5, v3
	v_bfi_b32 v3, s54, v5, v4
	v_mul_f32_e32 v0, 0.5, v0
	v_add_f32_e32 v1, 1.0, v1
	v_add_f32_e32 v3, 1.0, v3
	v_mul_f32_e32 v0, v0, v1
	v_mul_f32_e32 v1, v2, v3
	v_mov_b32_e32 v90, 0
	s_mov_b32 s34, 0
	v_mov_b32_e32 v91, v90
	v_mov_b32_e32 v88, v90
	v_mov_b32_e32 v89, v90
	v_mov_b32_e32 v84, v90
	v_mov_b32_e32 v85, v90
	v_mov_b32_e32 v80, v90
	v_mov_b32_e32 v81, v90
	v_mov_b32_e32 v76, v90
	v_mov_b32_e32 v77, v90
	v_mov_b32_e32 v68, v90
	v_mov_b32_e32 v69, v90
	v_mov_b32_e32 v62, v90
	v_mov_b32_e32 v63, v90
	v_mov_b32_e32 v60, v90
	v_mov_b32_e32 v61, v90
	s_waitcnt vmcnt(2)
	v_pk_mul_f32 v[0:1], v[0:1], v[6:7]
	s_waitcnt vmcnt(0)
	v_pk_mul_f32 v[22:23], v[0:1], v[8:9]
	ds_write_b64 v131, v[22:23] offset:512
	v_lshl_add_u64 v[228:229], v[124:125], 2, v[118:119]
	global_load_dwordx4 v[212:215], v[228:229], off
	global_load_dwordx4 v[216:219], v[228:229], off offset:16
	global_load_dwordx4 v[220:223], v[228:229], off offset:32
	global_load_dwordx4 v[224:227], v[228:229], off offset:48
	v_add_u32_e32 v32, s33, v104
	v_min_u32_e32 v32, 0x7fff, v32
	v_mov_b32_e32 v33, 0
	v_lshlrev_b64 v[34:35], 9, v[32:33]
	v_lshlrev_b64 v[36:37], 10, v[32:33]
	v_lshlrev_b64 v[38:39], 2, v[32:33]
	v_lshl_add_u64 v[34:35], v[114:115], 0, v[34:35]
	v_lshl_add_u64 v[36:37], v[116:117], 0, v[36:37]
	v_lshl_add_u64 v[40:41], s[68:69], 0, v[38:39]
	v_lshl_add_u64 v[38:39], s[70:71], 0, v[38:39]
	global_load_dword v230, v[34:35], off
	global_load_dword v231, v[34:35], off offset:256
	global_load_dwordx4 v[232:235], v[36:37], off
	global_load_dword v236, v[40:41], off
	global_load_dword v237, v[38:39], off
	s_mov_b32 s34, 0x0f0f0f0f
	s_mov_b32 s35, 0xf0f0f0f0
	v_readfirstlane_b32 s36, v108
	v_readfirstlane_b32 s37, v109
	v_subrev_u32_e32 v98, s36, v108
	ds_read_b128 v[70:73], v128 offset:0
	ds_read_b128 v[92:95], v128 offset:16
	ds_read_b128 v[48:51], v128 offset:32
	ds_read_b128 v[52:55], v128 offset:48
	s_waitcnt lgkmcnt(2)
	v_lshl_add_u32 v70, v70, 9, v98
	v_lshl_add_u32 v71, v71, 9, v98
	v_lshl_add_u32 v72, v72, 9, v98
	v_lshl_add_u32 v73, v73, 9, v98
	v_lshl_add_u32 v92, v92, 9, v98
	v_lshl_add_u32 v93, v93, 9, v98
	v_lshl_add_u32 v94, v94, 9, v98
	v_lshl_add_u32 v95, v95, 9, v98
	global_load_dwordx2 v[146:147], v70, s[36:37]
	global_load_dwordx2 v[148:149], v71, s[36:37]
	global_load_dwordx2 v[150:151], v72, s[36:37]
	global_load_dwordx2 v[152:153], v73, s[36:37]
	global_load_dwordx2 v[154:155], v92, s[36:37]
	global_load_dwordx2 v[156:157], v93, s[36:37]
	global_load_dwordx2 v[158:159], v94, s[36:37]
	global_load_dwordx2 v[160:161], v95, s[36:37]
	ds_read_b128 v[70:73], v128 offset:64
	ds_read_b128 v[92:95], v128 offset:80
	s_waitcnt lgkmcnt(2)
	v_lshl_add_u32 v48, v48, 9, v98
	v_lshl_add_u32 v49, v49, 9, v98
	v_lshl_add_u32 v50, v50, 9, v98
	v_lshl_add_u32 v51, v51, 9, v98
	v_lshl_add_u32 v52, v52, 9, v98
	v_lshl_add_u32 v53, v53, 9, v98
	v_lshl_add_u32 v54, v54, 9, v98
	v_lshl_add_u32 v55, v55, 9, v98
	global_load_dwordx2 v[162:163], v48, s[36:37]
	global_load_dwordx2 v[164:165], v49, s[36:37]
	global_load_dwordx2 v[166:167], v50, s[36:37]
	global_load_dwordx2 v[168:169], v51, s[36:37]
	global_load_dwordx2 v[170:171], v52, s[36:37]
	global_load_dwordx2 v[172:173], v53, s[36:37]
	global_load_dwordx2 v[174:175], v54, s[36:37]
	global_load_dwordx2 v[176:177], v55, s[36:37]
	ds_read_b128 v[48:51], v128 offset:96
	ds_read_b128 v[52:55], v128 offset:112
	s_waitcnt lgkmcnt(2)
	v_lshl_add_u32 v70, v70, 9, v98
	v_lshl_add_u32 v71, v71, 9, v98
	v_lshl_add_u32 v72, v72, 9, v98
	v_lshl_add_u32 v73, v73, 9, v98
	v_lshl_add_u32 v92, v92, 9, v98
	v_lshl_add_u32 v93, v93, 9, v98
	v_lshl_add_u32 v94, v94, 9, v98
	v_lshl_add_u32 v95, v95, 9, v98
	global_load_dwordx2 v[178:179], v70, s[36:37]
	global_load_dwordx2 v[180:181], v71, s[36:37]
	global_load_dwordx2 v[182:183], v72, s[36:37]
	global_load_dwordx2 v[184:185], v73, s[36:37]
	global_load_dwordx2 v[186:187], v92, s[36:37]
	global_load_dwordx2 v[188:189], v93, s[36:37]
	global_load_dwordx2 v[190:191], v94, s[36:37]
	global_load_dwordx2 v[192:193], v95, s[36:37]
	ds_read_b128 v[70:73], v128 offset:128
	ds_read_b128 v[92:95], v128 offset:144
	s_waitcnt lgkmcnt(2)
	v_lshl_add_u32 v48, v48, 9, v98
	v_lshl_add_u32 v49, v49, 9, v98
	v_lshl_add_u32 v50, v50, 9, v98
	v_lshl_add_u32 v51, v51, 9, v98
	v_lshl_add_u32 v52, v52, 9, v98
	v_lshl_add_u32 v53, v53, 9, v98
	v_lshl_add_u32 v54, v54, 9, v98
	v_lshl_add_u32 v55, v55, 9, v98
	global_load_dwordx2 v[194:195], v48, s[36:37]
	global_load_dwordx2 v[196:197], v49, s[36:37]
	global_load_dwordx2 v[198:199], v50, s[36:37]
	global_load_dwordx2 v[200:201], v51, s[36:37]
	global_load_dwordx2 v[202:203], v52, s[36:37]
	global_load_dwordx2 v[204:205], v53, s[36:37]
	global_load_dwordx2 v[206:207], v54, s[36:37]
	global_load_dwordx2 v[208:209], v55, s[36:37]
	s_waitcnt lgkmcnt(0)
	v_lshl_add_u32 v70, v70, 9, v98
	v_lshl_add_u32 v71, v71, 9, v98
	v_lshl_add_u32 v72, v72, 9, v98
	v_lshl_add_u32 v73, v73, 9, v98
	v_lshl_add_u32 v92, v92, 9, v98
	v_lshl_add_u32 v93, v93, 9, v98
	v_lshl_add_u32 v94, v94, 9, v98
	v_lshl_add_u32 v95, v95, 9, v98
	global_load_dwordx2 v[0:1], v70, s[36:37]
	global_load_dwordx2 v[2:3], v71, s[36:37]
	global_load_dwordx2 v[4:5], v72, s[36:37]
	global_load_dwordx2 v[6:7], v73, s[36:37]
	global_load_dwordx2 v[8:9], v92, s[36:37]
	global_load_dwordx2 v[10:11], v93, s[36:37]
	global_load_dwordx2 v[12:13], v94, s[36:37]
	global_load_dwordx2 v[14:15], v95, s[36:37]
	v_add_f32_e32 v210, v22, v23
	ds_bpermute_b32 v211, v132, v210
	s_waitcnt lgkmcnt(0)
	v_add_f32_e32 v210, v210, v211
	ds_bpermute_b32 v211, v133, v210
	s_waitcnt lgkmcnt(0)
	v_add_f32_e32 v210, v210, v211
	ds_bpermute_b32 v211, v134, v210
	s_waitcnt lgkmcnt(0)
	v_add_f32_e32 v210, v210, v211
	ds_bpermute_b32 v211, v135, v210
	s_waitcnt lgkmcnt(0)
	v_add_f32_e32 v210, v210, v211
	ds_bpermute_b32 v211, v136, v210
	s_waitcnt lgkmcnt(0)
	v_add_f32_e32 v99, v210, v211
	ds_bpermute_b32 v105, v137, v99
	ds_read_b128 v[70:73], v128 offset:160
	ds_read_b128 v[92:95], v128 offset:176
	ds_read_b128 v[32:35], v128 offset:512
	ds_read_b128 v[36:39], v128 offset:528
	s_waitcnt lgkmcnt(0)
	v_lshl_add_u32 v70, v70, 9, v98
	v_lshl_add_u32 v71, v71, 9, v98
	v_lshl_add_u32 v72, v72, 9, v98
	v_lshl_add_u32 v73, v73, 9, v98
	v_lshl_add_u32 v92, v92, 9, v98
	v_lshl_add_u32 v93, v93, 9, v98
	v_lshl_add_u32 v94, v94, 9, v98
	v_lshl_add_u32 v95, v95, 9, v98
	global_load_dwordx2 v[16:17], v70, s[36:37]
	global_load_dwordx2 v[18:19], v71, s[36:37]
	global_load_dwordx2 v[20:21], v72, s[36:37]
	global_load_dwordx2 v[22:23], v73, s[36:37]
	global_load_dwordx2 v[24:25], v92, s[36:37]
	global_load_dwordx2 v[26:27], v93, s[36:37]
	global_load_dwordx2 v[28:29], v94, s[36:37]
	global_load_dwordx2 v[30:31], v95, s[36:37]
	ds_read_b128 v[70:73], v128 offset:192
	ds_read_b128 v[92:95], v128 offset:208
	ds_read_b128 v[48:51], v128 offset:544
	ds_read_b128 v[52:55], v128 offset:560
	s_waitcnt vmcnt(40)
	v_and_b32_e32 v74, s34, v146
	v_and_b32_e32 v78, s34, v147
	v_cvt_f32_ubyte0_e32 v96, v74
	v_cvt_f32_ubyte1_e32 v97, v74
	v_cvt_f32_ubyte2_e32 v100, v74
	v_cvt_f32_ubyte3_e32 v101, v74
	v_pk_fma_f32 v[90:91], v[32:33], v[96:97], v[90:91] op_sel_hi:[0,1,1]
	v_cvt_f32_ubyte0_e32 v102, v146
	v_cvt_f32_ubyte1_e32 v103, v146
	v_pk_fma_f32 v[88:89], v[32:33], v[100:101], v[88:89] op_sel_hi:[0,1,1]
	v_cvt_f32_ubyte2_e32 v126, v146
	v_cvt_f32_ubyte3_e32 v127, v146
	v_pk_fma_f32 v[84:85], v[32:33], v[102:103], v[84:85] op_sel_hi:[0,1,1]
	v_cvt_f32_ubyte0_e32 v96, v78
	v_cvt_f32_ubyte1_e32 v97, v78
	v_pk_fma_f32 v[80:81], v[32:33], v[126:127], v[80:81] op_sel_hi:[0,1,1]
	v_and_b32_e32 v82, s34, v148
	v_and_b32_e32 v86, s34, v149
	v_cvt_f32_ubyte2_e32 v100, v78
	v_cvt_f32_ubyte3_e32 v101, v78
	v_pk_fma_f32 v[76:77], v[32:33], v[96:97], v[76:77] op_sel_hi:[0,1,1]
	v_cvt_f32_ubyte0_e32 v102, v147
	v_cvt_f32_ubyte1_e32 v103, v147
	v_pk_fma_f32 v[68:69], v[32:33], v[100:101], v[68:69] op_sel_hi:[0,1,1]
	v_cvt_f32_ubyte2_e32 v126, v147
	v_cvt_f32_ubyte3_e32 v127, v147
	v_pk_fma_f32 v[62:63], v[32:33], v[102:103], v[62:63] op_sel_hi:[0,1,1]
	v_cvt_f32_ubyte0_e32 v96, v82
	v_cvt_f32_ubyte1_e32 v97, v82
	v_pk_fma_f32 v[60:61], v[32:33], v[126:127], v[60:61] op_sel_hi:[0,1,1]
	v_cvt_f32_ubyte2_e32 v100, v82
	v_cvt_f32_ubyte3_e32 v101, v82
	v_pk_fma_f32 v[90:91], v[32:33], v[96:97], v[90:91] op_sel:[1,0,0]
	v_cvt_f32_ubyte0_e32 v102, v148
	v_cvt_f32_ubyte1_e32 v103, v148
	v_pk_fma_f32 v[88:89], v[32:33], v[100:101], v[88:89] op_sel:[1,0,0]
	v_cvt_f32_ubyte2_e32 v126, v148
	v_cvt_f32_ubyte3_e32 v127, v148
	v_pk_fma_f32 v[84:85], v[32:33], v[102:103], v[84:85] op_sel:[1,0,0]
	v_cvt_f32_ubyte0_e32 v96, v86
	v_cvt_f32_ubyte1_e32 v97, v86
	v_pk_fma_f32 v[80:81], v[32:33], v[126:127], v[80:81] op_sel:[1,0,0]
	v_and_b32_e32 v74, s34, v150
	v_and_b32_e32 v78, s34, v151
	v_cvt_f32_ubyte2_e32 v100, v86
	v_cvt_f32_ubyte3_e32 v101, v86
	v_pk_fma_f32 v[76:77], v[32:33], v[96:97], v[76:77] op_sel:[1,0,0]
	v_cvt_f32_ubyte0_e32 v102, v149
	v_cvt_f32_ubyte1_e32 v103, v149
	v_pk_fma_f32 v[68:69], v[32:33], v[100:101], v[68:69] op_sel:[1,0,0]
	v_cvt_f32_ubyte2_e32 v126, v149
	v_cvt_f32_ubyte3_e32 v127, v149
	v_pk_fma_f32 v[62:63], v[32:33], v[102:103], v[62:63] op_sel:[1,0,0]
	v_cvt_f32_ubyte0_e32 v96, v74
	v_cvt_f32_ubyte1_e32 v97, v74
	v_pk_fma_f32 v[60:61], v[32:33], v[126:127], v[60:61] op_sel:[1,0,0]
	v_cvt_f32_ubyte2_e32 v100, v74
	v_cvt_f32_ubyte3_e32 v101, v74
	v_pk_fma_f32 v[90:91], v[34:35], v[96:97], v[90:91] op_sel_hi:[0,1,1]
	v_cvt_f32_ubyte0_e32 v102, v150
	v_cvt_f32_ubyte1_e32 v103, v150
	v_pk_fma_f32 v[88:89], v[34:35], v[100:101], v[88:89] op_sel_hi:[0,1,1]
	v_cvt_f32_ubyte2_e32 v126, v150
	v_cvt_f32_ubyte3_e32 v127, v150
	v_pk_fma_f32 v[84:85], v[34:35], v[102:103], v[84:85] op_sel_hi:[0,1,1]
	v_cvt_f32_ubyte0_e32 v96, v78
	v_cvt_f32_ubyte1_e32 v97, v78
	v_pk_fma_f32 v[80:81], v[34:35], v[126:127], v[80:81] op_sel_hi:[0,1,1]
	v_and_b32_e32 v82, s34, v152
	v_and_b32_e32 v86, s34, v153
	v_cvt_f32_ubyte2_e32 v100, v78
	v_cvt_f32_ubyte3_e32 v101, v78
	v_pk_fma_f32 v[76:77], v[34:35], v[96:97], v[76:77] op_sel_hi:[0,1,1]
	v_cvt_f32_ubyte0_e32 v102, v151
	v_cvt_f32_ubyte1_e32 v103, v151
	v_pk_fma_f32 v[68:69], v[34:35], v[100:101], v[68:69] op_sel_hi:[0,1,1]
	v_cvt_f32_ubyte2_e32 v126, v151
	v_cvt_f32_ubyte3_e32 v127, v151
	v_pk_fma_f32 v[62:63], v[34:35], v[102:103], v[62:63] op_sel_hi:[0,1,1]
	v_cvt_f32_ubyte0_e32 v96, v82
	v_cvt_f32_ubyte1_e32 v97, v82
	v_pk_fma_f32 v[60:61], v[34:35], v[126:127], v[60:61] op_sel_hi:[0,1,1]
	v_cvt_f32_ubyte2_e32 v100, v82
	v_cvt_f32_ubyte3_e32 v101, v82
	v_pk_fma_f32 v[90:91], v[34:35], v[96:97], v[90:91] op_sel:[1,0,0]
	v_cvt_f32_ubyte0_e32 v102, v152
	v_cvt_f32_ubyte1_e32 v103, v152
	v_pk_fma_f32 v[88:89], v[34:35], v[100:101], v[88:89] op_sel:[1,0,0]
	v_cvt_f32_ubyte2_e32 v126, v152
	v_cvt_f32_ubyte3_e32 v127, v152
	v_pk_fma_f32 v[84:85], v[34:35], v[102:103], v[84:85] op_sel:[1,0,0]
	v_cvt_f32_ubyte0_e32 v96, v86
	v_cvt_f32_ubyte1_e32 v97, v86
	v_pk_fma_f32 v[80:81], v[34:35], v[126:127], v[80:81] op_sel:[1,0,0]
	v_and_b32_e32 v74, s34, v154
	v_and_b32_e32 v78, s34, v155
	v_cvt_f32_ubyte2_e32 v100, v86
	v_cvt_f32_ubyte3_e32 v101, v86
	v_pk_fma_f32 v[76:77], v[34:35], v[96:97], v[76:77] op_sel:[1,0,0]
	v_cvt_f32_ubyte0_e32 v102, v153
	v_cvt_f32_ubyte1_e32 v103, v153
	v_pk_fma_f32 v[68:69], v[34:35], v[100:101], v[68:69] op_sel:[1,0,0]
	v_cvt_f32_ubyte2_e32 v126, v153
	v_cvt_f32_ubyte3_e32 v127, v153
	v_pk_fma_f32 v[62:63], v[34:35], v[102:103], v[62:63] op_sel:[1,0,0]
	v_cvt_f32_ubyte0_e32 v96, v74
	v_cvt_f32_ubyte1_e32 v97, v74
	v_pk_fma_f32 v[60:61], v[34:35], v[126:127], v[60:61] op_sel:[1,0,0]
	v_cvt_f32_ubyte2_e32 v100, v74
	v_cvt_f32_ubyte3_e32 v101, v74
	v_pk_fma_f32 v[90:91], v[36:37], v[96:97], v[90:91] op_sel_hi:[0,1,1]
	v_cvt_f32_ubyte0_e32 v102, v154
	v_cvt_f32_ubyte1_e32 v103, v154
	v_pk_fma_f32 v[88:89], v[36:37], v[100:101], v[88:89] op_sel_hi:[0,1,1]
	v_cvt_f32_ubyte2_e32 v126, v154
	v_cvt_f32_ubyte3_e32 v127, v154
	v_pk_fma_f32 v[84:85], v[36:37], v[102:103], v[84:85] op_sel_hi:[0,1,1]
	v_cvt_f32_ubyte0_e32 v96, v78
	v_cvt_f32_ubyte1_e32 v97, v78
	v_pk_fma_f32 v[80:81], v[36:37], v[126:127], v[80:81] op_sel_hi:[0,1,1]
	v_and_b32_e32 v82, s34, v156
	v_and_b32_e32 v86, s34, v157
	v_cvt_f32_ubyte2_e32 v100, v78
	v_cvt_f32_ubyte3_e32 v101, v78
	v_pk_fma_f32 v[76:77], v[36:37], v[96:97], v[76:77] op_sel_hi:[0,1,1]
	v_cvt_f32_ubyte0_e32 v102, v155
	v_cvt_f32_ubyte1_e32 v103, v155
	v_pk_fma_f32 v[68:69], v[36:37], v[100:101], v[68:69] op_sel_hi:[0,1,1]
	v_cvt_f32_ubyte2_e32 v126, v155
	v_cvt_f32_ubyte3_e32 v127, v155
	v_pk_fma_f32 v[62:63], v[36:37], v[102:103], v[62:63] op_sel_hi:[0,1,1]
	v_cvt_f32_ubyte0_e32 v96, v82
	v_cvt_f32_ubyte1_e32 v97, v82
	v_pk_fma_f32 v[60:61], v[36:37], v[126:127], v[60:61] op_sel_hi:[0,1,1]
	v_cvt_f32_ubyte2_e32 v100, v82
	v_cvt_f32_ubyte3_e32 v101, v82
	v_pk_fma_f32 v[90:91], v[36:37], v[96:97], v[90:91] op_sel:[1,0,0]
	v_cvt_f32_ubyte0_e32 v102, v156
	v_cvt_f32_ubyte1_e32 v103, v156
	v_pk_fma_f32 v[88:89], v[36:37], v[100:101], v[88:89] op_sel:[1,0,0]
	v_cvt_f32_ubyte2_e32 v126, v156
	v_cvt_f32_ubyte3_e32 v127, v156
	v_pk_fma_f32 v[84:85], v[36:37], v[102:103], v[84:85] op_sel:[1,0,0]
	v_cvt_f32_ubyte0_e32 v96, v86
	v_cvt_f32_ubyte1_e32 v97, v86
	v_pk_fma_f32 v[80:81], v[36:37], v[126:127], v[80:81] op_sel:[1,0,0]
	v_and_b32_e32 v74, s34, v158
	v_and_b32_e32 v78, s34, v159
	v_cvt_f32_ubyte2_e32 v100, v86
	v_cvt_f32_ubyte3_e32 v101, v86
	v_pk_fma_f32 v[76:77], v[36:37], v[96:97], v[76:77] op_sel:[1,0,0]
	v_cvt_f32_ubyte0_e32 v102, v157
	v_cvt_f32_ubyte1_e32 v103, v157
	v_pk_fma_f32 v[68:69], v[36:37], v[100:101], v[68:69] op_sel:[1,0,0]
	v_cvt_f32_ubyte2_e32 v126, v157
	v_cvt_f32_ubyte3_e32 v127, v157
	v_pk_fma_f32 v[62:63], v[36:37], v[102:103], v[62:63] op_sel:[1,0,0]
	v_cvt_f32_ubyte0_e32 v96, v74
	v_cvt_f32_ubyte1_e32 v97, v74
	v_pk_fma_f32 v[60:61], v[36:37], v[126:127], v[60:61] op_sel:[1,0,0]
	v_cvt_f32_ubyte2_e32 v100, v74
	v_cvt_f32_ubyte3_e32 v101, v74
	v_pk_fma_f32 v[90:91], v[38:39], v[96:97], v[90:91] op_sel_hi:[0,1,1]
	v_cvt_f32_ubyte0_e32 v102, v158
	v_cvt_f32_ubyte1_e32 v103, v158
	v_pk_fma_f32 v[88:89], v[38:39], v[100:101], v[88:89] op_sel_hi:[0,1,1]
	v_cvt_f32_ubyte2_e32 v126, v158
	v_cvt_f32_ubyte3_e32 v127, v158
	v_pk_fma_f32 v[84:85], v[38:39], v[102:103], v[84:85] op_sel_hi:[0,1,1]
	v_cvt_f32_ubyte0_e32 v96, v78
	v_cvt_f32_ubyte1_e32 v97, v78
	v_pk_fma_f32 v[80:81], v[38:39], v[126:127], v[80:81] op_sel_hi:[0,1,1]
	v_and_b32_e32 v82, s34, v160
	v_and_b32_e32 v86, s34, v161
	v_cvt_f32_ubyte2_e32 v100, v78
	v_cvt_f32_ubyte3_e32 v101, v78
	v_pk_fma_f32 v[76:77], v[38:39], v[96:97], v[76:77] op_sel_hi:[0,1,1]
	v_cvt_f32_ubyte0_e32 v102, v159
	v_cvt_f32_ubyte1_e32 v103, v159
	v_pk_fma_f32 v[68:69], v[38:39], v[100:101], v[68:69] op_sel_hi:[0,1,1]
	v_cvt_f32_ubyte2_e32 v126, v159
	v_cvt_f32_ubyte3_e32 v127, v159
	v_pk_fma_f32 v[62:63], v[38:39], v[102:103], v[62:63] op_sel_hi:[0,1,1]
	v_cvt_f32_ubyte0_e32 v96, v82
	v_cvt_f32_ubyte1_e32 v97, v82
	v_pk_fma_f32 v[60:61], v[38:39], v[126:127], v[60:61] op_sel_hi:[0,1,1]
	v_cvt_f32_ubyte2_e32 v100, v82
	v_cvt_f32_ubyte3_e32 v101, v82
	v_pk_fma_f32 v[90:91], v[38:39], v[96:97], v[90:91] op_sel:[1,0,0]
	v_cvt_f32_ubyte0_e32 v102, v160
	v_cvt_f32_ubyte1_e32 v103, v160
	v_pk_fma_f32 v[88:89], v[38:39], v[100:101], v[88:89] op_sel:[1,0,0]
	v_cvt_f32_ubyte2_e32 v126, v160
	v_cvt_f32_ubyte3_e32 v127, v160
	v_pk_fma_f32 v[84:85], v[38:39], v[102:103], v[84:85] op_sel:[1,0,0]
	v_cvt_f32_ubyte0_e32 v96, v86
	v_cvt_f32_ubyte1_e32 v97, v86
	v_pk_fma_f32 v[80:81], v[38:39], v[126:127], v[80:81] op_sel:[1,0,0]
	v_cvt_f32_ubyte2_e32 v100, v86
	v_cvt_f32_ubyte3_e32 v101, v86
	v_pk_fma_f32 v[76:77], v[38:39], v[96:97], v[76:77] op_sel:[1,0,0]
	v_cvt_f32_ubyte0_e32 v102, v161
	v_cvt_f32_ubyte1_e32 v103, v161
	v_pk_fma_f32 v[68:69], v[38:39], v[100:101], v[68:69] op_sel:[1,0,0]
	v_cvt_f32_ubyte2_e32 v126, v161
	v_cvt_f32_ubyte3_e32 v127, v161
	v_pk_fma_f32 v[62:63], v[38:39], v[102:103], v[62:63] op_sel:[1,0,0]
	v_pk_fma_f32 v[60:61], v[38:39], v[126:127], v[60:61] op_sel:[1,0,0]
	s_waitcnt lgkmcnt(0)
	v_lshl_add_u32 v70, v70, 9, v98
	v_lshl_add_u32 v71, v71, 9, v98
	v_lshl_add_u32 v72, v72, 9, v98
	v_lshl_add_u32 v73, v73, 9, v98
	v_lshl_add_u32 v92, v92, 9, v98
	v_lshl_add_u32 v93, v93, 9, v98
	v_lshl_add_u32 v94, v94, 9, v98
	v_lshl_add_u32 v95, v95, 9, v98
	global_load_dwordx2 v[146:147], v70, s[36:37]
	global_load_dwordx2 v[148:149], v71, s[36:37]
	global_load_dwordx2 v[150:151], v72, s[36:37]
	global_load_dwordx2 v[152:153], v73, s[36:37]
	global_load_dwordx2 v[154:155], v92, s[36:37]
	global_load_dwordx2 v[156:157], v93, s[36:37]
	global_load_dwordx2 v[158:159], v94, s[36:37]
	global_load_dwordx2 v[160:161], v95, s[36:37]
	ds_read_b128 v[70:73], v128 offset:224
	ds_read_b128 v[92:95], v128 offset:240
	ds_read_b128 v[32:35], v128 offset:576
	ds_read_b128 v[36:39], v128 offset:592
	s_waitcnt vmcnt(40)
	v_and_b32_e32 v74, s34, v162
	v_and_b32_e32 v78, s34, v163
	v_cvt_f32_ubyte0_e32 v96, v74
	v_cvt_f32_ubyte1_e32 v97, v74
	v_cvt_f32_ubyte2_e32 v100, v74
	v_cvt_f32_ubyte3_e32 v101, v74
	v_pk_fma_f32 v[90:91], v[48:49], v[96:97], v[90:91] op_sel_hi:[0,1,1]
	v_cvt_f32_ubyte0_e32 v102, v162
	v_cvt_f32_ubyte1_e32 v103, v162
	v_pk_fma_f32 v[88:89], v[48:49], v[100:101], v[88:89] op_sel_hi:[0,1,1]
	v_cvt_f32_ubyte2_e32 v126, v162
	v_cvt_f32_ubyte3_e32 v127, v162
	v_pk_fma_f32 v[84:85], v[48:49], v[102:103], v[84:85] op_sel_hi:[0,1,1]
	v_cvt_f32_ubyte0_e32 v96, v78
	v_cvt_f32_ubyte1_e32 v97, v78
	v_pk_fma_f32 v[80:81], v[48:49], v[126:127], v[80:81] op_sel_hi:[0,1,1]
	v_and_b32_e32 v82, s34, v164
	v_and_b32_e32 v86, s34, v165
	v_cvt_f32_ubyte2_e32 v100, v78
	v_cvt_f32_ubyte3_e32 v101, v78
	v_pk_fma_f32 v[76:77], v[48:49], v[96:97], v[76:77] op_sel_hi:[0,1,1]
	v_cvt_f32_ubyte0_e32 v102, v163
	v_cvt_f32_ubyte1_e32 v103, v163
	v_pk_fma_f32 v[68:69], v[48:49], v[100:101], v[68:69] op_sel_hi:[0,1,1]
	v_cvt_f32_ubyte2_e32 v126, v163
	v_cvt_f32_ubyte3_e32 v127, v163
	v_pk_fma_f32 v[62:63], v[48:49], v[102:103], v[62:63] op_sel_hi:[0,1,1]
	v_cvt_f32_ubyte0_e32 v96, v82
	v_cvt_f32_ubyte1_e32 v97, v82
	v_pk_fma_f32 v[60:61], v[48:49], v[126:127], v[60:61] op_sel_hi:[0,1,1]
	v_cvt_f32_ubyte2_e32 v100, v82
	v_cvt_f32_ubyte3_e32 v101, v82
	v_pk_fma_f32 v[90:91], v[48:49], v[96:97], v[90:91] op_sel:[1,0,0]
	v_cvt_f32_ubyte0_e32 v102, v164
	v_cvt_f32_ubyte1_e32 v103, v164
	v_pk_fma_f32 v[88:89], v[48:49], v[100:101], v[88:89] op_sel:[1,0,0]
	v_cvt_f32_ubyte2_e32 v126, v164
	v_cvt_f32_ubyte3_e32 v127, v164
	v_pk_fma_f32 v[84:85], v[48:49], v[102:103], v[84:85] op_sel:[1,0,0]
	v_cvt_f32_ubyte0_e32 v96, v86
	v_cvt_f32_ubyte1_e32 v97, v86
	v_pk_fma_f32 v[80:81], v[48:49], v[126:127], v[80:81] op_sel:[1,0,0]
	v_and_b32_e32 v74, s34, v166
	v_and_b32_e32 v78, s34, v167
	v_cvt_f32_ubyte2_e32 v100, v86
	v_cvt_f32_ubyte3_e32 v101, v86
	v_pk_fma_f32 v[76:77], v[48:49], v[96:97], v[76:77] op_sel:[1,0,0]
	v_cvt_f32_ubyte0_e32 v102, v165
	v_cvt_f32_ubyte1_e32 v103, v165
	v_pk_fma_f32 v[68:69], v[48:49], v[100:101], v[68:69] op_sel:[1,0,0]
	v_cvt_f32_ubyte2_e32 v126, v165
	v_cvt_f32_ubyte3_e32 v127, v165
	v_pk_fma_f32 v[62:63], v[48:49], v[102:103], v[62:63] op_sel:[1,0,0]
	v_cvt_f32_ubyte0_e32 v96, v74
	v_cvt_f32_ubyte1_e32 v97, v74
	v_pk_fma_f32 v[60:61], v[48:49], v[126:127], v[60:61] op_sel:[1,0,0]
	v_cvt_f32_ubyte2_e32 v100, v74
	v_cvt_f32_ubyte3_e32 v101, v74
	v_pk_fma_f32 v[90:91], v[50:51], v[96:97], v[90:91] op_sel_hi:[0,1,1]
	v_cvt_f32_ubyte0_e32 v102, v166
	v_cvt_f32_ubyte1_e32 v103, v166
	v_pk_fma_f32 v[88:89], v[50:51], v[100:101], v[88:89] op_sel_hi:[0,1,1]
	v_cvt_f32_ubyte2_e32 v126, v166
	v_cvt_f32_ubyte3_e32 v127, v166
	v_pk_fma_f32 v[84:85], v[50:51], v[102:103], v[84:85] op_sel_hi:[0,1,1]
	v_cvt_f32_ubyte0_e32 v96, v78
	v_cvt_f32_ubyte1_e32 v97, v78
	v_pk_fma_f32 v[80:81], v[50:51], v[126:127], v[80:81] op_sel_hi:[0,1,1]
	v_and_b32_e32 v82, s34, v168
	v_and_b32_e32 v86, s34, v169
	v_cvt_f32_ubyte2_e32 v100, v78
	v_cvt_f32_ubyte3_e32 v101, v78
	v_pk_fma_f32 v[76:77], v[50:51], v[96:97], v[76:77] op_sel_hi:[0,1,1]
	v_cvt_f32_ubyte0_e32 v102, v167
	v_cvt_f32_ubyte1_e32 v103, v167
	v_pk_fma_f32 v[68:69], v[50:51], v[100:101], v[68:69] op_sel_hi:[0,1,1]
	v_cvt_f32_ubyte2_e32 v126, v167
	v_cvt_f32_ubyte3_e32 v127, v167
	v_pk_fma_f32 v[62:63], v[50:51], v[102:103], v[62:63] op_sel_hi:[0,1,1]
	v_cvt_f32_ubyte0_e32 v96, v82
	v_cvt_f32_ubyte1_e32 v97, v82
	v_pk_fma_f32 v[60:61], v[50:51], v[126:127], v[60:61] op_sel_hi:[0,1,1]
	v_cvt_f32_ubyte2_e32 v100, v82
	v_cvt_f32_ubyte3_e32 v101, v82
	v_pk_fma_f32 v[90:91], v[50:51], v[96:97], v[90:91] op_sel:[1,0,0]
	v_cvt_f32_ubyte0_e32 v102, v168
	v_cvt_f32_ubyte1_e32 v103, v168
	v_pk_fma_f32 v[88:89], v[50:51], v[100:101], v[88:89] op_sel:[1,0,0]
	v_cvt_f32_ubyte2_e32 v126, v168
	v_cvt_f32_ubyte3_e32 v127, v168
	v_pk_fma_f32 v[84:85], v[50:51], v[102:103], v[84:85] op_sel:[1,0,0]
	v_cvt_f32_ubyte0_e32 v96, v86
	v_cvt_f32_ubyte1_e32 v97, v86
	v_pk_fma_f32 v[80:81], v[50:51], v[126:127], v[80:81] op_sel:[1,0,0]
	v_and_b32_e32 v74, s34, v170
	v_and_b32_e32 v78, s34, v171
	v_cvt_f32_ubyte2_e32 v100, v86
	v_cvt_f32_ubyte3_e32 v101, v86
	v_pk_fma_f32 v[76:77], v[50:51], v[96:97], v[76:77] op_sel:[1,0,0]
	v_cvt_f32_ubyte0_e32 v102, v169
	v_cvt_f32_ubyte1_e32 v103, v169
	v_pk_fma_f32 v[68:69], v[50:51], v[100:101], v[68:69] op_sel:[1,0,0]
	v_cvt_f32_ubyte2_e32 v126, v169
	v_cvt_f32_ubyte3_e32 v127, v169
	v_pk_fma_f32 v[62:63], v[50:51], v[102:103], v[62:63] op_sel:[1,0,0]
	v_cvt_f32_ubyte0_e32 v96, v74
	v_cvt_f32_ubyte1_e32 v97, v74
	v_pk_fma_f32 v[60:61], v[50:51], v[126:127], v[60:61] op_sel:[1,0,0]
	v_cvt_f32_ubyte2_e32 v100, v74
	v_cvt_f32_ubyte3_e32 v101, v74
	v_pk_fma_f32 v[90:91], v[52:53], v[96:97], v[90:91] op_sel_hi:[0,1,1]
	v_cvt_f32_ubyte0_e32 v102, v170
	v_cvt_f32_ubyte1_e32 v103, v170
	v_pk_fma_f32 v[88:89], v[52:53], v[100:101], v[88:89] op_sel_hi:[0,1,1]
	v_cvt_f32_ubyte2_e32 v126, v170
	v_cvt_f32_ubyte3_e32 v127, v170
	v_pk_fma_f32 v[84:85], v[52:53], v[102:103], v[84:85] op_sel_hi:[0,1,1]
	v_cvt_f32_ubyte0_e32 v96, v78
	v_cvt_f32_ubyte1_e32 v97, v78
	v_pk_fma_f32 v[80:81], v[52:53], v[126:127], v[80:81] op_sel_hi:[0,1,1]
	v_and_b32_e32 v82, s34, v172
	v_and_b32_e32 v86, s34, v173
	v_cvt_f32_ubyte2_e32 v100, v78
	v_cvt_f32_ubyte3_e32 v101, v78
	v_pk_fma_f32 v[76:77], v[52:53], v[96:97], v[76:77] op_sel_hi:[0,1,1]
	v_cvt_f32_ubyte0_e32 v102, v171
	v_cvt_f32_ubyte1_e32 v103, v171
	v_pk_fma_f32 v[68:69], v[52:53], v[100:101], v[68:69] op_sel_hi:[0,1,1]
	v_cvt_f32_ubyte2_e32 v126, v171
	v_cvt_f32_ubyte3_e32 v127, v171
	v_pk_fma_f32 v[62:63], v[52:53], v[102:103], v[62:63] op_sel_hi:[0,1,1]
	v_cvt_f32_ubyte0_e32 v96, v82
	v_cvt_f32_ubyte1_e32 v97, v82
	v_pk_fma_f32 v[60:61], v[52:53], v[126:127], v[60:61] op_sel_hi:[0,1,1]
	v_cvt_f32_ubyte2_e32 v100, v82
	v_cvt_f32_ubyte3_e32 v101, v82
	v_pk_fma_f32 v[90:91], v[52:53], v[96:97], v[90:91] op_sel:[1,0,0]
	v_cvt_f32_ubyte0_e32 v102, v172
	v_cvt_f32_ubyte1_e32 v103, v172
	v_pk_fma_f32 v[88:89], v[52:53], v[100:101], v[88:89] op_sel:[1,0,0]
	v_cvt_f32_ubyte2_e32 v126, v172
	v_cvt_f32_ubyte3_e32 v127, v172
	v_pk_fma_f32 v[84:85], v[52:53], v[102:103], v[84:85] op_sel:[1,0,0]
	v_cvt_f32_ubyte0_e32 v96, v86
	v_cvt_f32_ubyte1_e32 v97, v86
	v_pk_fma_f32 v[80:81], v[52:53], v[126:127], v[80:81] op_sel:[1,0,0]
	v_and_b32_e32 v74, s34, v174
	v_and_b32_e32 v78, s34, v175
	v_cvt_f32_ubyte2_e32 v100, v86
	v_cvt_f32_ubyte3_e32 v101, v86
	v_pk_fma_f32 v[76:77], v[52:53], v[96:97], v[76:77] op_sel:[1,0,0]
	v_cvt_f32_ubyte0_e32 v102, v173
	v_cvt_f32_ubyte1_e32 v103, v173
	v_pk_fma_f32 v[68:69], v[52:53], v[100:101], v[68:69] op_sel:[1,0,0]
	v_cvt_f32_ubyte2_e32 v126, v173
	v_cvt_f32_ubyte3_e32 v127, v173
	v_pk_fma_f32 v[62:63], v[52:53], v[102:103], v[62:63] op_sel:[1,0,0]
	v_cvt_f32_ubyte0_e32 v96, v74
	v_cvt_f32_ubyte1_e32 v97, v74
	v_pk_fma_f32 v[60:61], v[52:53], v[126:127], v[60:61] op_sel:[1,0,0]
	v_cvt_f32_ubyte2_e32 v100, v74
	v_cvt_f32_ubyte3_e32 v101, v74
	v_pk_fma_f32 v[90:91], v[54:55], v[96:97], v[90:91] op_sel_hi:[0,1,1]
	v_cvt_f32_ubyte0_e32 v102, v174
	v_cvt_f32_ubyte1_e32 v103, v174
	v_pk_fma_f32 v[88:89], v[54:55], v[100:101], v[88:89] op_sel_hi:[0,1,1]
	v_cvt_f32_ubyte2_e32 v126, v174
	v_cvt_f32_ubyte3_e32 v127, v174
	v_pk_fma_f32 v[84:85], v[54:55], v[102:103], v[84:85] op_sel_hi:[0,1,1]
	v_cvt_f32_ubyte0_e32 v96, v78
	v_cvt_f32_ubyte1_e32 v97, v78
	v_pk_fma_f32 v[80:81], v[54:55], v[126:127], v[80:81] op_sel_hi:[0,1,1]
	v_and_b32_e32 v82, s34, v176
	v_and_b32_e32 v86, s34, v177
	v_cvt_f32_ubyte2_e32 v100, v78
	v_cvt_f32_ubyte3_e32 v101, v78
	v_pk_fma_f32 v[76:77], v[54:55], v[96:97], v[76:77] op_sel_hi:[0,1,1]
	v_cvt_f32_ubyte0_e32 v102, v175
	v_cvt_f32_ubyte1_e32 v103, v175
	v_pk_fma_f32 v[68:69], v[54:55], v[100:101], v[68:69] op_sel_hi:[0,1,1]
	v_cvt_f32_ubyte2_e32 v126, v175
	v_cvt_f32_ubyte3_e32 v127, v175
	v_pk_fma_f32 v[62:63], v[54:55], v[102:103], v[62:63] op_sel_hi:[0,1,1]
	v_cvt_f32_ubyte0_e32 v96, v82
	v_cvt_f32_ubyte1_e32 v97, v82
	v_pk_fma_f32 v[60:61], v[54:55], v[126:127], v[60:61] op_sel_hi:[0,1,1]
	v_cvt_f32_ubyte2_e32 v100, v82
	v_cvt_f32_ubyte3_e32 v101, v82
	v_pk_fma_f32 v[90:91], v[54:55], v[96:97], v[90:91] op_sel:[1,0,0]
	v_cvt_f32_ubyte0_e32 v102, v176
	v_cvt_f32_ubyte1_e32 v103, v176
	v_pk_fma_f32 v[88:89], v[54:55], v[100:101], v[88:89] op_sel:[1,0,0]
	v_cvt_f32_ubyte2_e32 v126, v176
	v_cvt_f32_ubyte3_e32 v127, v176
	v_pk_fma_f32 v[84:85], v[54:55], v[102:103], v[84:85] op_sel:[1,0,0]
	v_cvt_f32_ubyte0_e32 v96, v86
	v_cvt_f32_ubyte1_e32 v97, v86
	v_pk_fma_f32 v[80:81], v[54:55], v[126:127], v[80:81] op_sel:[1,0,0]
	v_cvt_f32_ubyte2_e32 v100, v86
	v_cvt_f32_ubyte3_e32 v101, v86
	v_pk_fma_f32 v[76:77], v[54:55], v[96:97], v[76:77] op_sel:[1,0,0]
	v_cvt_f32_ubyte0_e32 v102, v177
	v_cvt_f32_ubyte1_e32 v103, v177
	v_pk_fma_f32 v[68:69], v[54:55], v[100:101], v[68:69] op_sel:[1,0,0]
	v_cvt_f32_ubyte2_e32 v126, v177
	v_cvt_f32_ubyte3_e32 v127, v177
	v_pk_fma_f32 v[62:63], v[54:55], v[102:103], v[62:63] op_sel:[1,0,0]
	v_pk_fma_f32 v[60:61], v[54:55], v[126:127], v[60:61] op_sel:[1,0,0]
	s_waitcnt lgkmcnt(0)
	v_lshl_add_u32 v70, v70, 9, v98
	v_lshl_add_u32 v71, v71, 9, v98
	v_lshl_add_u32 v72, v72, 9, v98
	v_lshl_add_u32 v73, v73, 9, v98
	v_lshl_add_u32 v92, v92, 9, v98
	v_lshl_add_u32 v93, v93, 9, v98
	v_lshl_add_u32 v94, v94, 9, v98
	v_lshl_add_u32 v95, v95, 9, v98
	global_load_dwordx2 v[162:163], v70, s[36:37]
	global_load_dwordx2 v[164:165], v71, s[36:37]
	global_load_dwordx2 v[166:167], v72, s[36:37]
	global_load_dwordx2 v[168:169], v73, s[36:37]
	global_load_dwordx2 v[170:171], v92, s[36:37]
	global_load_dwordx2 v[172:173], v93, s[36:37]
	global_load_dwordx2 v[174:175], v94, s[36:37]
	global_load_dwordx2 v[176:177], v95, s[36:37]
	ds_read_b128 v[70:73], v128 offset:256
	ds_read_b128 v[92:95], v128 offset:272
	ds_read_b128 v[48:51], v128 offset:608
	ds_read_b128 v[52:55], v128 offset:624
	s_waitcnt vmcnt(40)
	v_and_b32_e32 v74, s34, v178
	v_and_b32_e32 v78, s34, v179
	v_cvt_f32_ubyte0_e32 v96, v74
	v_cvt_f32_ubyte1_e32 v97, v74
	v_cvt_f32_ubyte2_e32 v100, v74
	v_cvt_f32_ubyte3_e32 v101, v74
	v_pk_fma_f32 v[90:91], v[32:33], v[96:97], v[90:91] op_sel_hi:[0,1,1]
	v_cvt_f32_ubyte0_e32 v102, v178
	v_cvt_f32_ubyte1_e32 v103, v178
	v_pk_fma_f32 v[88:89], v[32:33], v[100:101], v[88:89] op_sel_hi:[0,1,1]
	v_cvt_f32_ubyte2_e32 v126, v178
	v_cvt_f32_ubyte3_e32 v127, v178
	v_pk_fma_f32 v[84:85], v[32:33], v[102:103], v[84:85] op_sel_hi:[0,1,1]
	v_cvt_f32_ubyte0_e32 v96, v78
	v_cvt_f32_ubyte1_e32 v97, v78
	v_pk_fma_f32 v[80:81], v[32:33], v[126:127], v[80:81] op_sel_hi:[0,1,1]
	v_and_b32_e32 v82, s34, v180
	v_and_b32_e32 v86, s34, v181
	v_cvt_f32_ubyte2_e32 v100, v78
	v_cvt_f32_ubyte3_e32 v101, v78
	v_pk_fma_f32 v[76:77], v[32:33], v[96:97], v[76:77] op_sel_hi:[0,1,1]
	v_cvt_f32_ubyte0_e32 v102, v179
	v_cvt_f32_ubyte1_e32 v103, v179
	v_pk_fma_f32 v[68:69], v[32:33], v[100:101], v[68:69] op_sel_hi:[0,1,1]
	v_cvt_f32_ubyte2_e32 v126, v179
	v_cvt_f32_ubyte3_e32 v127, v179
	v_pk_fma_f32 v[62:63], v[32:33], v[102:103], v[62:63] op_sel_hi:[0,1,1]
	v_cvt_f32_ubyte0_e32 v96, v82
	v_cvt_f32_ubyte1_e32 v97, v82
	v_pk_fma_f32 v[60:61], v[32:33], v[126:127], v[60:61] op_sel_hi:[0,1,1]
	v_cvt_f32_ubyte2_e32 v100, v82
	v_cvt_f32_ubyte3_e32 v101, v82
	v_pk_fma_f32 v[90:91], v[32:33], v[96:97], v[90:91] op_sel:[1,0,0]
	v_cvt_f32_ubyte0_e32 v102, v180
	v_cvt_f32_ubyte1_e32 v103, v180
	v_pk_fma_f32 v[88:89], v[32:33], v[100:101], v[88:89] op_sel:[1,0,0]
	v_cvt_f32_ubyte2_e32 v126, v180
	v_cvt_f32_ubyte3_e32 v127, v180
	v_pk_fma_f32 v[84:85], v[32:33], v[102:103], v[84:85] op_sel:[1,0,0]
	v_cvt_f32_ubyte0_e32 v96, v86
	v_cvt_f32_ubyte1_e32 v97, v86
	v_pk_fma_f32 v[80:81], v[32:33], v[126:127], v[80:81] op_sel:[1,0,0]
	v_and_b32_e32 v74, s34, v182
	v_and_b32_e32 v78, s34, v183
	v_cvt_f32_ubyte2_e32 v100, v86
	v_cvt_f32_ubyte3_e32 v101, v86
	v_pk_fma_f32 v[76:77], v[32:33], v[96:97], v[76:77] op_sel:[1,0,0]
	v_cvt_f32_ubyte0_e32 v102, v181
	v_cvt_f32_ubyte1_e32 v103, v181
	v_pk_fma_f32 v[68:69], v[32:33], v[100:101], v[68:69] op_sel:[1,0,0]
	v_cvt_f32_ubyte2_e32 v126, v181
	v_cvt_f32_ubyte3_e32 v127, v181
	v_pk_fma_f32 v[62:63], v[32:33], v[102:103], v[62:63] op_sel:[1,0,0]
	v_cvt_f32_ubyte0_e32 v96, v74
	v_cvt_f32_ubyte1_e32 v97, v74
	v_pk_fma_f32 v[60:61], v[32:33], v[126:127], v[60:61] op_sel:[1,0,0]
	v_cvt_f32_ubyte2_e32 v100, v74
	v_cvt_f32_ubyte3_e32 v101, v74
	v_pk_fma_f32 v[90:91], v[34:35], v[96:97], v[90:91] op_sel_hi:[0,1,1]
	v_cvt_f32_ubyte0_e32 v102, v182
	v_cvt_f32_ubyte1_e32 v103, v182
	v_pk_fma_f32 v[88:89], v[34:35], v[100:101], v[88:89] op_sel_hi:[0,1,1]
	v_cvt_f32_ubyte2_e32 v126, v182
	v_cvt_f32_ubyte3_e32 v127, v182
	v_pk_fma_f32 v[84:85], v[34:35], v[102:103], v[84:85] op_sel_hi:[0,1,1]
	v_cvt_f32_ubyte0_e32 v96, v78
	v_cvt_f32_ubyte1_e32 v97, v78
	v_pk_fma_f32 v[80:81], v[34:35], v[126:127], v[80:81] op_sel_hi:[0,1,1]
	v_and_b32_e32 v82, s34, v184
	v_and_b32_e32 v86, s34, v185
	v_cvt_f32_ubyte2_e32 v100, v78
	v_cvt_f32_ubyte3_e32 v101, v78
	v_pk_fma_f32 v[76:77], v[34:35], v[96:97], v[76:77] op_sel_hi:[0,1,1]
	v_cvt_f32_ubyte0_e32 v102, v183
	v_cvt_f32_ubyte1_e32 v103, v183
	v_pk_fma_f32 v[68:69], v[34:35], v[100:101], v[68:69] op_sel_hi:[0,1,1]
	v_cvt_f32_ubyte2_e32 v126, v183
	v_cvt_f32_ubyte3_e32 v127, v183
	v_pk_fma_f32 v[62:63], v[34:35], v[102:103], v[62:63] op_sel_hi:[0,1,1]
	v_cvt_f32_ubyte0_e32 v96, v82
	v_cvt_f32_ubyte1_e32 v97, v82
	v_pk_fma_f32 v[60:61], v[34:35], v[126:127], v[60:61] op_sel_hi:[0,1,1]
	v_cvt_f32_ubyte2_e32 v100, v82
	v_cvt_f32_ubyte3_e32 v101, v82
	v_pk_fma_f32 v[90:91], v[34:35], v[96:97], v[90:91] op_sel:[1,0,0]
	v_cvt_f32_ubyte0_e32 v102, v184
	v_cvt_f32_ubyte1_e32 v103, v184
	v_pk_fma_f32 v[88:89], v[34:35], v[100:101], v[88:89] op_sel:[1,0,0]
	v_cvt_f32_ubyte2_e32 v126, v184
	v_cvt_f32_ubyte3_e32 v127, v184
	v_pk_fma_f32 v[84:85], v[34:35], v[102:103], v[84:85] op_sel:[1,0,0]
	v_cvt_f32_ubyte0_e32 v96, v86
	v_cvt_f32_ubyte1_e32 v97, v86
	v_pk_fma_f32 v[80:81], v[34:35], v[126:127], v[80:81] op_sel:[1,0,0]
	v_and_b32_e32 v74, s34, v186
	v_and_b32_e32 v78, s34, v187
	v_cvt_f32_ubyte2_e32 v100, v86
	v_cvt_f32_ubyte3_e32 v101, v86
	v_pk_fma_f32 v[76:77], v[34:35], v[96:97], v[76:77] op_sel:[1,0,0]
	v_cvt_f32_ubyte0_e32 v102, v185
	v_cvt_f32_ubyte1_e32 v103, v185
	v_pk_fma_f32 v[68:69], v[34:35], v[100:101], v[68:69] op_sel:[1,0,0]
	v_cvt_f32_ubyte2_e32 v126, v185
	v_cvt_f32_ubyte3_e32 v127, v185
	v_pk_fma_f32 v[62:63], v[34:35], v[102:103], v[62:63] op_sel:[1,0,0]
	v_cvt_f32_ubyte0_e32 v96, v74
	v_cvt_f32_ubyte1_e32 v97, v74
	v_pk_fma_f32 v[60:61], v[34:35], v[126:127], v[60:61] op_sel:[1,0,0]
	v_cvt_f32_ubyte2_e32 v100, v74
	v_cvt_f32_ubyte3_e32 v101, v74
	v_pk_fma_f32 v[90:91], v[36:37], v[96:97], v[90:91] op_sel_hi:[0,1,1]
	v_cvt_f32_ubyte0_e32 v102, v186
	v_cvt_f32_ubyte1_e32 v103, v186
	v_pk_fma_f32 v[88:89], v[36:37], v[100:101], v[88:89] op_sel_hi:[0,1,1]
	v_cvt_f32_ubyte2_e32 v126, v186
	v_cvt_f32_ubyte3_e32 v127, v186
	v_pk_fma_f32 v[84:85], v[36:37], v[102:103], v[84:85] op_sel_hi:[0,1,1]
	v_cvt_f32_ubyte0_e32 v96, v78
	v_cvt_f32_ubyte1_e32 v97, v78
	v_pk_fma_f32 v[80:81], v[36:37], v[126:127], v[80:81] op_sel_hi:[0,1,1]
	v_and_b32_e32 v82, s34, v188
	v_and_b32_e32 v86, s34, v189
	v_cvt_f32_ubyte2_e32 v100, v78
	v_cvt_f32_ubyte3_e32 v101, v78
	v_pk_fma_f32 v[76:77], v[36:37], v[96:97], v[76:77] op_sel_hi:[0,1,1]
	v_cvt_f32_ubyte0_e32 v102, v187
	v_cvt_f32_ubyte1_e32 v103, v187
	v_pk_fma_f32 v[68:69], v[36:37], v[100:101], v[68:69] op_sel_hi:[0,1,1]
	v_cvt_f32_ubyte2_e32 v126, v187
	v_cvt_f32_ubyte3_e32 v127, v187
	v_pk_fma_f32 v[62:63], v[36:37], v[102:103], v[62:63] op_sel_hi:[0,1,1]
	v_cvt_f32_ubyte0_e32 v96, v82
	v_cvt_f32_ubyte1_e32 v97, v82
	v_pk_fma_f32 v[60:61], v[36:37], v[126:127], v[60:61] op_sel_hi:[0,1,1]
	v_cvt_f32_ubyte2_e32 v100, v82
	v_cvt_f32_ubyte3_e32 v101, v82
	v_pk_fma_f32 v[90:91], v[36:37], v[96:97], v[90:91] op_sel:[1,0,0]
	v_cvt_f32_ubyte0_e32 v102, v188
	v_cvt_f32_ubyte1_e32 v103, v188
	v_pk_fma_f32 v[88:89], v[36:37], v[100:101], v[88:89] op_sel:[1,0,0]
	v_cvt_f32_ubyte2_e32 v126, v188
	v_cvt_f32_ubyte3_e32 v127, v188
	v_pk_fma_f32 v[84:85], v[36:37], v[102:103], v[84:85] op_sel:[1,0,0]
	v_cvt_f32_ubyte0_e32 v96, v86
	v_cvt_f32_ubyte1_e32 v97, v86
	v_pk_fma_f32 v[80:81], v[36:37], v[126:127], v[80:81] op_sel:[1,0,0]
	v_and_b32_e32 v74, s34, v190
	v_and_b32_e32 v78, s34, v191
	v_cvt_f32_ubyte2_e32 v100, v86
	v_cvt_f32_ubyte3_e32 v101, v86
	v_pk_fma_f32 v[76:77], v[36:37], v[96:97], v[76:77] op_sel:[1,0,0]
	v_cvt_f32_ubyte0_e32 v102, v189
	v_cvt_f32_ubyte1_e32 v103, v189
	v_pk_fma_f32 v[68:69], v[36:37], v[100:101], v[68:69] op_sel:[1,0,0]
	v_cvt_f32_ubyte2_e32 v126, v189
	v_cvt_f32_ubyte3_e32 v127, v189
	v_pk_fma_f32 v[62:63], v[36:37], v[102:103], v[62:63] op_sel:[1,0,0]
	v_cvt_f32_ubyte0_e32 v96, v74
	v_cvt_f32_ubyte1_e32 v97, v74
	v_pk_fma_f32 v[60:61], v[36:37], v[126:127], v[60:61] op_sel:[1,0,0]
	v_cvt_f32_ubyte2_e32 v100, v74
	v_cvt_f32_ubyte3_e32 v101, v74
	v_pk_fma_f32 v[90:91], v[38:39], v[96:97], v[90:91] op_sel_hi:[0,1,1]
	v_cvt_f32_ubyte0_e32 v102, v190
	v_cvt_f32_ubyte1_e32 v103, v190
	v_pk_fma_f32 v[88:89], v[38:39], v[100:101], v[88:89] op_sel_hi:[0,1,1]
	v_cvt_f32_ubyte2_e32 v126, v190
	v_cvt_f32_ubyte3_e32 v127, v190
	v_pk_fma_f32 v[84:85], v[38:39], v[102:103], v[84:85] op_sel_hi:[0,1,1]
	v_cvt_f32_ubyte0_e32 v96, v78
	v_cvt_f32_ubyte1_e32 v97, v78
	v_pk_fma_f32 v[80:81], v[38:39], v[126:127], v[80:81] op_sel_hi:[0,1,1]
	v_and_b32_e32 v82, s34, v192
	v_and_b32_e32 v86, s34, v193
	v_cvt_f32_ubyte2_e32 v100, v78
	v_cvt_f32_ubyte3_e32 v101, v78
	v_pk_fma_f32 v[76:77], v[38:39], v[96:97], v[76:77] op_sel_hi:[0,1,1]
	v_cvt_f32_ubyte0_e32 v102, v191
	v_cvt_f32_ubyte1_e32 v103, v191
	v_pk_fma_f32 v[68:69], v[38:39], v[100:101], v[68:69] op_sel_hi:[0,1,1]
	v_cvt_f32_ubyte2_e32 v126, v191
	v_cvt_f32_ubyte3_e32 v127, v191
	v_pk_fma_f32 v[62:63], v[38:39], v[102:103], v[62:63] op_sel_hi:[0,1,1]
	v_cvt_f32_ubyte0_e32 v96, v82
	v_cvt_f32_ubyte1_e32 v97, v82
	v_pk_fma_f32 v[60:61], v[38:39], v[126:127], v[60:61] op_sel_hi:[0,1,1]
	v_cvt_f32_ubyte2_e32 v100, v82
	v_cvt_f32_ubyte3_e32 v101, v82
	v_pk_fma_f32 v[90:91], v[38:39], v[96:97], v[90:91] op_sel:[1,0,0]
	v_cvt_f32_ubyte0_e32 v102, v192
	v_cvt_f32_ubyte1_e32 v103, v192
	v_pk_fma_f32 v[88:89], v[38:39], v[100:101], v[88:89] op_sel:[1,0,0]
	v_cvt_f32_ubyte2_e32 v126, v192
	v_cvt_f32_ubyte3_e32 v127, v192
	v_pk_fma_f32 v[84:85], v[38:39], v[102:103], v[84:85] op_sel:[1,0,0]
	v_cvt_f32_ubyte0_e32 v96, v86
	v_cvt_f32_ubyte1_e32 v97, v86
	v_pk_fma_f32 v[80:81], v[38:39], v[126:127], v[80:81] op_sel:[1,0,0]
	v_cvt_f32_ubyte2_e32 v100, v86
	v_cvt_f32_ubyte3_e32 v101, v86
	v_pk_fma_f32 v[76:77], v[38:39], v[96:97], v[76:77] op_sel:[1,0,0]
	v_cvt_f32_ubyte0_e32 v102, v193
	v_cvt_f32_ubyte1_e32 v103, v193
	v_pk_fma_f32 v[68:69], v[38:39], v[100:101], v[68:69] op_sel:[1,0,0]
	v_cvt_f32_ubyte2_e32 v126, v193
	v_cvt_f32_ubyte3_e32 v127, v193
	v_pk_fma_f32 v[62:63], v[38:39], v[102:103], v[62:63] op_sel:[1,0,0]
	v_pk_fma_f32 v[60:61], v[38:39], v[126:127], v[60:61] op_sel:[1,0,0]
	s_waitcnt lgkmcnt(0)
	v_lshl_add_u32 v70, v70, 9, v98
	v_lshl_add_u32 v71, v71, 9, v98
	v_lshl_add_u32 v72, v72, 9, v98
	v_lshl_add_u32 v73, v73, 9, v98
	v_lshl_add_u32 v92, v92, 9, v98
	v_lshl_add_u32 v93, v93, 9, v98
	v_lshl_add_u32 v94, v94, 9, v98
	v_lshl_add_u32 v95, v95, 9, v98
	global_load_dwordx2 v[178:179], v70, s[36:37]
	global_load_dwordx2 v[180:181], v71, s[36:37]
	global_load_dwordx2 v[182:183], v72, s[36:37]
	global_load_dwordx2 v[184:185], v73, s[36:37]
	global_load_dwordx2 v[186:187], v92, s[36:37]
	global_load_dwordx2 v[188:189], v93, s[36:37]
	global_load_dwordx2 v[190:191], v94, s[36:37]
	global_load_dwordx2 v[192:193], v95, s[36:37]
	ds_read_b128 v[70:73], v128 offset:288
	ds_read_b128 v[92:95], v128 offset:304
	ds_read_b128 v[32:35], v128 offset:640
	ds_read_b128 v[36:39], v128 offset:656
	s_waitcnt vmcnt(40)
	v_and_b32_e32 v74, s34, v194
	v_and_b32_e32 v78, s34, v195
	v_cvt_f32_ubyte0_e32 v96, v74
	v_cvt_f32_ubyte1_e32 v97, v74
	v_cvt_f32_ubyte2_e32 v100, v74
	v_cvt_f32_ubyte3_e32 v101, v74
	v_pk_fma_f32 v[90:91], v[48:49], v[96:97], v[90:91] op_sel_hi:[0,1,1]
	v_cvt_f32_ubyte0_e32 v102, v194
	v_cvt_f32_ubyte1_e32 v103, v194
	v_pk_fma_f32 v[88:89], v[48:49], v[100:101], v[88:89] op_sel_hi:[0,1,1]
	v_cvt_f32_ubyte2_e32 v126, v194
	v_cvt_f32_ubyte3_e32 v127, v194
	v_pk_fma_f32 v[84:85], v[48:49], v[102:103], v[84:85] op_sel_hi:[0,1,1]
	v_cvt_f32_ubyte0_e32 v96, v78
	v_cvt_f32_ubyte1_e32 v97, v78
	v_pk_fma_f32 v[80:81], v[48:49], v[126:127], v[80:81] op_sel_hi:[0,1,1]
	v_and_b32_e32 v82, s34, v196
	v_and_b32_e32 v86, s34, v197
	v_cvt_f32_ubyte2_e32 v100, v78
	v_cvt_f32_ubyte3_e32 v101, v78
	v_pk_fma_f32 v[76:77], v[48:49], v[96:97], v[76:77] op_sel_hi:[0,1,1]
	v_cvt_f32_ubyte0_e32 v102, v195
	v_cvt_f32_ubyte1_e32 v103, v195
	v_pk_fma_f32 v[68:69], v[48:49], v[100:101], v[68:69] op_sel_hi:[0,1,1]
	v_cvt_f32_ubyte2_e32 v126, v195
	v_cvt_f32_ubyte3_e32 v127, v195
	v_pk_fma_f32 v[62:63], v[48:49], v[102:103], v[62:63] op_sel_hi:[0,1,1]
	v_cvt_f32_ubyte0_e32 v96, v82
	v_cvt_f32_ubyte1_e32 v97, v82
	v_pk_fma_f32 v[60:61], v[48:49], v[126:127], v[60:61] op_sel_hi:[0,1,1]
	v_cvt_f32_ubyte2_e32 v100, v82
	v_cvt_f32_ubyte3_e32 v101, v82
	v_pk_fma_f32 v[90:91], v[48:49], v[96:97], v[90:91] op_sel:[1,0,0]
	v_cvt_f32_ubyte0_e32 v102, v196
	v_cvt_f32_ubyte1_e32 v103, v196
	v_pk_fma_f32 v[88:89], v[48:49], v[100:101], v[88:89] op_sel:[1,0,0]
	v_cvt_f32_ubyte2_e32 v126, v196
	v_cvt_f32_ubyte3_e32 v127, v196
	v_pk_fma_f32 v[84:85], v[48:49], v[102:103], v[84:85] op_sel:[1,0,0]
	v_cvt_f32_ubyte0_e32 v96, v86
	v_cvt_f32_ubyte1_e32 v97, v86
	v_pk_fma_f32 v[80:81], v[48:49], v[126:127], v[80:81] op_sel:[1,0,0]
	v_and_b32_e32 v74, s34, v198
	v_and_b32_e32 v78, s34, v199
	v_cvt_f32_ubyte2_e32 v100, v86
	v_cvt_f32_ubyte3_e32 v101, v86
	v_pk_fma_f32 v[76:77], v[48:49], v[96:97], v[76:77] op_sel:[1,0,0]
	v_cvt_f32_ubyte0_e32 v102, v197
	v_cvt_f32_ubyte1_e32 v103, v197
	v_pk_fma_f32 v[68:69], v[48:49], v[100:101], v[68:69] op_sel:[1,0,0]
	v_cvt_f32_ubyte2_e32 v126, v197
	v_cvt_f32_ubyte3_e32 v127, v197
	v_pk_fma_f32 v[62:63], v[48:49], v[102:103], v[62:63] op_sel:[1,0,0]
	v_cvt_f32_ubyte0_e32 v96, v74
	v_cvt_f32_ubyte1_e32 v97, v74
	v_pk_fma_f32 v[60:61], v[48:49], v[126:127], v[60:61] op_sel:[1,0,0]
	v_cvt_f32_ubyte2_e32 v100, v74
	v_cvt_f32_ubyte3_e32 v101, v74
	v_pk_fma_f32 v[90:91], v[50:51], v[96:97], v[90:91] op_sel_hi:[0,1,1]
	v_cvt_f32_ubyte0_e32 v102, v198
	v_cvt_f32_ubyte1_e32 v103, v198
	v_pk_fma_f32 v[88:89], v[50:51], v[100:101], v[88:89] op_sel_hi:[0,1,1]
	v_cvt_f32_ubyte2_e32 v126, v198
	v_cvt_f32_ubyte3_e32 v127, v198
	v_pk_fma_f32 v[84:85], v[50:51], v[102:103], v[84:85] op_sel_hi:[0,1,1]
	v_cvt_f32_ubyte0_e32 v96, v78
	v_cvt_f32_ubyte1_e32 v97, v78
	v_pk_fma_f32 v[80:81], v[50:51], v[126:127], v[80:81] op_sel_hi:[0,1,1]
	v_and_b32_e32 v82, s34, v200
	v_and_b32_e32 v86, s34, v201
	v_cvt_f32_ubyte2_e32 v100, v78
	v_cvt_f32_ubyte3_e32 v101, v78
	v_pk_fma_f32 v[76:77], v[50:51], v[96:97], v[76:77] op_sel_hi:[0,1,1]
	v_cvt_f32_ubyte0_e32 v102, v199
	v_cvt_f32_ubyte1_e32 v103, v199
	v_pk_fma_f32 v[68:69], v[50:51], v[100:101], v[68:69] op_sel_hi:[0,1,1]
	v_cvt_f32_ubyte2_e32 v126, v199
	v_cvt_f32_ubyte3_e32 v127, v199
	v_pk_fma_f32 v[62:63], v[50:51], v[102:103], v[62:63] op_sel_hi:[0,1,1]
	v_cvt_f32_ubyte0_e32 v96, v82
	v_cvt_f32_ubyte1_e32 v97, v82
	v_pk_fma_f32 v[60:61], v[50:51], v[126:127], v[60:61] op_sel_hi:[0,1,1]
	v_cvt_f32_ubyte2_e32 v100, v82
	v_cvt_f32_ubyte3_e32 v101, v82
	v_pk_fma_f32 v[90:91], v[50:51], v[96:97], v[90:91] op_sel:[1,0,0]
	v_cvt_f32_ubyte0_e32 v102, v200
	v_cvt_f32_ubyte1_e32 v103, v200
	v_pk_fma_f32 v[88:89], v[50:51], v[100:101], v[88:89] op_sel:[1,0,0]
	v_cvt_f32_ubyte2_e32 v126, v200
	v_cvt_f32_ubyte3_e32 v127, v200
	v_pk_fma_f32 v[84:85], v[50:51], v[102:103], v[84:85] op_sel:[1,0,0]
	v_cvt_f32_ubyte0_e32 v96, v86
	v_cvt_f32_ubyte1_e32 v97, v86
	v_pk_fma_f32 v[80:81], v[50:51], v[126:127], v[80:81] op_sel:[1,0,0]
	v_and_b32_e32 v74, s34, v202
	v_and_b32_e32 v78, s34, v203
	v_cvt_f32_ubyte2_e32 v100, v86
	v_cvt_f32_ubyte3_e32 v101, v86
	v_pk_fma_f32 v[76:77], v[50:51], v[96:97], v[76:77] op_sel:[1,0,0]
	v_cvt_f32_ubyte0_e32 v102, v201
	v_cvt_f32_ubyte1_e32 v103, v201
	v_pk_fma_f32 v[68:69], v[50:51], v[100:101], v[68:69] op_sel:[1,0,0]
	v_cvt_f32_ubyte2_e32 v126, v201
	v_cvt_f32_ubyte3_e32 v127, v201
	v_pk_fma_f32 v[62:63], v[50:51], v[102:103], v[62:63] op_sel:[1,0,0]
	v_cvt_f32_ubyte0_e32 v96, v74
	v_cvt_f32_ubyte1_e32 v97, v74
	v_pk_fma_f32 v[60:61], v[50:51], v[126:127], v[60:61] op_sel:[1,0,0]
	v_cvt_f32_ubyte2_e32 v100, v74
	v_cvt_f32_ubyte3_e32 v101, v74
	v_pk_fma_f32 v[90:91], v[52:53], v[96:97], v[90:91] op_sel_hi:[0,1,1]
	v_cvt_f32_ubyte0_e32 v102, v202
	v_cvt_f32_ubyte1_e32 v103, v202
	v_pk_fma_f32 v[88:89], v[52:53], v[100:101], v[88:89] op_sel_hi:[0,1,1]
	v_cvt_f32_ubyte2_e32 v126, v202
	v_cvt_f32_ubyte3_e32 v127, v202
	v_pk_fma_f32 v[84:85], v[52:53], v[102:103], v[84:85] op_sel_hi:[0,1,1]
	v_cvt_f32_ubyte0_e32 v96, v78
	v_cvt_f32_ubyte1_e32 v97, v78
	v_pk_fma_f32 v[80:81], v[52:53], v[126:127], v[80:81] op_sel_hi:[0,1,1]
	v_and_b32_e32 v82, s34, v204
	v_and_b32_e32 v86, s34, v205
	v_cvt_f32_ubyte2_e32 v100, v78
	v_cvt_f32_ubyte3_e32 v101, v78
	v_pk_fma_f32 v[76:77], v[52:53], v[96:97], v[76:77] op_sel_hi:[0,1,1]
	v_cvt_f32_ubyte0_e32 v102, v203
	v_cvt_f32_ubyte1_e32 v103, v203
	v_pk_fma_f32 v[68:69], v[52:53], v[100:101], v[68:69] op_sel_hi:[0,1,1]
	v_cvt_f32_ubyte2_e32 v126, v203
	v_cvt_f32_ubyte3_e32 v127, v203
	v_pk_fma_f32 v[62:63], v[52:53], v[102:103], v[62:63] op_sel_hi:[0,1,1]
	v_cvt_f32_ubyte0_e32 v96, v82
	v_cvt_f32_ubyte1_e32 v97, v82
	v_pk_fma_f32 v[60:61], v[52:53], v[126:127], v[60:61] op_sel_hi:[0,1,1]
	v_cvt_f32_ubyte2_e32 v100, v82
	v_cvt_f32_ubyte3_e32 v101, v82
	v_pk_fma_f32 v[90:91], v[52:53], v[96:97], v[90:91] op_sel:[1,0,0]
	v_cvt_f32_ubyte0_e32 v102, v204
	v_cvt_f32_ubyte1_e32 v103, v204
	v_pk_fma_f32 v[88:89], v[52:53], v[100:101], v[88:89] op_sel:[1,0,0]
	v_cvt_f32_ubyte2_e32 v126, v204
	v_cvt_f32_ubyte3_e32 v127, v204
	v_pk_fma_f32 v[84:85], v[52:53], v[102:103], v[84:85] op_sel:[1,0,0]
	v_cvt_f32_ubyte0_e32 v96, v86
	v_cvt_f32_ubyte1_e32 v97, v86
	v_pk_fma_f32 v[80:81], v[52:53], v[126:127], v[80:81] op_sel:[1,0,0]
	v_and_b32_e32 v74, s34, v206
	v_and_b32_e32 v78, s34, v207
	v_cvt_f32_ubyte2_e32 v100, v86
	v_cvt_f32_ubyte3_e32 v101, v86
	v_pk_fma_f32 v[76:77], v[52:53], v[96:97], v[76:77] op_sel:[1,0,0]
	v_cvt_f32_ubyte0_e32 v102, v205
	v_cvt_f32_ubyte1_e32 v103, v205
	v_pk_fma_f32 v[68:69], v[52:53], v[100:101], v[68:69] op_sel:[1,0,0]
	v_cvt_f32_ubyte2_e32 v126, v205
	v_cvt_f32_ubyte3_e32 v127, v205
	v_pk_fma_f32 v[62:63], v[52:53], v[102:103], v[62:63] op_sel:[1,0,0]
	v_cvt_f32_ubyte0_e32 v96, v74
	v_cvt_f32_ubyte1_e32 v97, v74
	v_pk_fma_f32 v[60:61], v[52:53], v[126:127], v[60:61] op_sel:[1,0,0]
	v_cvt_f32_ubyte2_e32 v100, v74
	v_cvt_f32_ubyte3_e32 v101, v74
	v_pk_fma_f32 v[90:91], v[54:55], v[96:97], v[90:91] op_sel_hi:[0,1,1]
	v_cvt_f32_ubyte0_e32 v102, v206
	v_cvt_f32_ubyte1_e32 v103, v206
	v_pk_fma_f32 v[88:89], v[54:55], v[100:101], v[88:89] op_sel_hi:[0,1,1]
	v_cvt_f32_ubyte2_e32 v126, v206
	v_cvt_f32_ubyte3_e32 v127, v206
	v_pk_fma_f32 v[84:85], v[54:55], v[102:103], v[84:85] op_sel_hi:[0,1,1]
	v_cvt_f32_ubyte0_e32 v96, v78
	v_cvt_f32_ubyte1_e32 v97, v78
	v_pk_fma_f32 v[80:81], v[54:55], v[126:127], v[80:81] op_sel_hi:[0,1,1]
	v_and_b32_e32 v82, s34, v208
	v_and_b32_e32 v86, s34, v209
	v_cvt_f32_ubyte2_e32 v100, v78
	v_cvt_f32_ubyte3_e32 v101, v78
	v_pk_fma_f32 v[76:77], v[54:55], v[96:97], v[76:77] op_sel_hi:[0,1,1]
	v_cvt_f32_ubyte0_e32 v102, v207
	v_cvt_f32_ubyte1_e32 v103, v207
	v_pk_fma_f32 v[68:69], v[54:55], v[100:101], v[68:69] op_sel_hi:[0,1,1]
	v_cvt_f32_ubyte2_e32 v126, v207
	v_cvt_f32_ubyte3_e32 v127, v207
	v_pk_fma_f32 v[62:63], v[54:55], v[102:103], v[62:63] op_sel_hi:[0,1,1]
	v_cvt_f32_ubyte0_e32 v96, v82
	v_cvt_f32_ubyte1_e32 v97, v82
	v_pk_fma_f32 v[60:61], v[54:55], v[126:127], v[60:61] op_sel_hi:[0,1,1]
	v_cvt_f32_ubyte2_e32 v100, v82
	v_cvt_f32_ubyte3_e32 v101, v82
	v_pk_fma_f32 v[90:91], v[54:55], v[96:97], v[90:91] op_sel:[1,0,0]
	v_cvt_f32_ubyte0_e32 v102, v208
	v_cvt_f32_ubyte1_e32 v103, v208
	v_pk_fma_f32 v[88:89], v[54:55], v[100:101], v[88:89] op_sel:[1,0,0]
	v_cvt_f32_ubyte2_e32 v126, v208
	v_cvt_f32_ubyte3_e32 v127, v208
	v_pk_fma_f32 v[84:85], v[54:55], v[102:103], v[84:85] op_sel:[1,0,0]
	v_cvt_f32_ubyte0_e32 v96, v86
	v_cvt_f32_ubyte1_e32 v97, v86
	v_pk_fma_f32 v[80:81], v[54:55], v[126:127], v[80:81] op_sel:[1,0,0]
	v_cvt_f32_ubyte2_e32 v100, v86
	v_cvt_f32_ubyte3_e32 v101, v86
	v_pk_fma_f32 v[76:77], v[54:55], v[96:97], v[76:77] op_sel:[1,0,0]
	v_cvt_f32_ubyte0_e32 v102, v209
	v_cvt_f32_ubyte1_e32 v103, v209
	v_pk_fma_f32 v[68:69], v[54:55], v[100:101], v[68:69] op_sel:[1,0,0]
	v_cvt_f32_ubyte2_e32 v126, v209
	v_cvt_f32_ubyte3_e32 v127, v209
	v_pk_fma_f32 v[62:63], v[54:55], v[102:103], v[62:63] op_sel:[1,0,0]
	v_pk_fma_f32 v[60:61], v[54:55], v[126:127], v[60:61] op_sel:[1,0,0]
	s_waitcnt lgkmcnt(0)
	v_lshl_add_u32 v70, v70, 9, v98
	v_lshl_add_u32 v71, v71, 9, v98
	v_lshl_add_u32 v72, v72, 9, v98
	v_lshl_add_u32 v73, v73, 9, v98
	v_lshl_add_u32 v92, v92, 9, v98
	v_lshl_add_u32 v93, v93, 9, v98
	v_lshl_add_u32 v94, v94, 9, v98
	v_lshl_add_u32 v95, v95, 9, v98
	global_load_dwordx2 v[194:195], v70, s[36:37]
	global_load_dwordx2 v[196:197], v71, s[36:37]
	global_load_dwordx2 v[198:199], v72, s[36:37]
	global_load_dwordx2 v[200:201], v73, s[36:37]
	global_load_dwordx2 v[202:203], v92, s[36:37]
	global_load_dwordx2 v[204:205], v93, s[36:37]
	global_load_dwordx2 v[206:207], v94, s[36:37]
	global_load_dwordx2 v[208:209], v95, s[36:37]
	ds_read_b128 v[70:73], v128 offset:320
	ds_read_b128 v[92:95], v128 offset:336
	ds_read_b128 v[48:51], v128 offset:672
	ds_read_b128 v[52:55], v128 offset:688
	s_waitcnt vmcnt(40)
	v_and_b32_e32 v74, s34, v0
	v_and_b32_e32 v78, s34, v1
	v_cvt_f32_ubyte0_e32 v96, v74
	v_cvt_f32_ubyte1_e32 v97, v74
	v_cvt_f32_ubyte2_e32 v100, v74
	v_cvt_f32_ubyte3_e32 v101, v74
	v_pk_fma_f32 v[90:91], v[32:33], v[96:97], v[90:91] op_sel_hi:[0,1,1]
	v_cvt_f32_ubyte0_e32 v102, v0
	v_cvt_f32_ubyte1_e32 v103, v0
	v_pk_fma_f32 v[88:89], v[32:33], v[100:101], v[88:89] op_sel_hi:[0,1,1]
	v_cvt_f32_ubyte2_e32 v126, v0
	v_cvt_f32_ubyte3_e32 v127, v0
	v_pk_fma_f32 v[84:85], v[32:33], v[102:103], v[84:85] op_sel_hi:[0,1,1]
	v_cvt_f32_ubyte0_e32 v96, v78
	v_cvt_f32_ubyte1_e32 v97, v78
	v_pk_fma_f32 v[80:81], v[32:33], v[126:127], v[80:81] op_sel_hi:[0,1,1]
	v_and_b32_e32 v82, s34, v2
	v_and_b32_e32 v86, s34, v3
	v_cvt_f32_ubyte2_e32 v100, v78
	v_cvt_f32_ubyte3_e32 v101, v78
	v_pk_fma_f32 v[76:77], v[32:33], v[96:97], v[76:77] op_sel_hi:[0,1,1]
	v_cvt_f32_ubyte0_e32 v102, v1
	v_cvt_f32_ubyte1_e32 v103, v1
	v_pk_fma_f32 v[68:69], v[32:33], v[100:101], v[68:69] op_sel_hi:[0,1,1]
	v_cvt_f32_ubyte2_e32 v126, v1
	v_cvt_f32_ubyte3_e32 v127, v1
	v_pk_fma_f32 v[62:63], v[32:33], v[102:103], v[62:63] op_sel_hi:[0,1,1]
	v_cvt_f32_ubyte0_e32 v96, v82
	v_cvt_f32_ubyte1_e32 v97, v82
	v_pk_fma_f32 v[60:61], v[32:33], v[126:127], v[60:61] op_sel_hi:[0,1,1]
	v_cvt_f32_ubyte2_e32 v100, v82
	v_cvt_f32_ubyte3_e32 v101, v82
	v_pk_fma_f32 v[90:91], v[32:33], v[96:97], v[90:91] op_sel:[1,0,0]
	v_cvt_f32_ubyte0_e32 v102, v2
	v_cvt_f32_ubyte1_e32 v103, v2
	v_pk_fma_f32 v[88:89], v[32:33], v[100:101], v[88:89] op_sel:[1,0,0]
	v_cvt_f32_ubyte2_e32 v126, v2
	v_cvt_f32_ubyte3_e32 v127, v2
	v_pk_fma_f32 v[84:85], v[32:33], v[102:103], v[84:85] op_sel:[1,0,0]
	v_cvt_f32_ubyte0_e32 v96, v86
	v_cvt_f32_ubyte1_e32 v97, v86
	v_pk_fma_f32 v[80:81], v[32:33], v[126:127], v[80:81] op_sel:[1,0,0]
	v_and_b32_e32 v74, s34, v4
	v_and_b32_e32 v78, s34, v5
	v_cvt_f32_ubyte2_e32 v100, v86
	v_cvt_f32_ubyte3_e32 v101, v86
	v_pk_fma_f32 v[76:77], v[32:33], v[96:97], v[76:77] op_sel:[1,0,0]
	v_cvt_f32_ubyte0_e32 v102, v3
	v_cvt_f32_ubyte1_e32 v103, v3
	v_pk_fma_f32 v[68:69], v[32:33], v[100:101], v[68:69] op_sel:[1,0,0]
	v_cvt_f32_ubyte2_e32 v126, v3
	v_cvt_f32_ubyte3_e32 v127, v3
	v_pk_fma_f32 v[62:63], v[32:33], v[102:103], v[62:63] op_sel:[1,0,0]
	v_cvt_f32_ubyte0_e32 v96, v74
	v_cvt_f32_ubyte1_e32 v97, v74
	v_pk_fma_f32 v[60:61], v[32:33], v[126:127], v[60:61] op_sel:[1,0,0]
	v_cvt_f32_ubyte2_e32 v100, v74
	v_cvt_f32_ubyte3_e32 v101, v74
	v_pk_fma_f32 v[90:91], v[34:35], v[96:97], v[90:91] op_sel_hi:[0,1,1]
	v_cvt_f32_ubyte0_e32 v102, v4
	v_cvt_f32_ubyte1_e32 v103, v4
	v_pk_fma_f32 v[88:89], v[34:35], v[100:101], v[88:89] op_sel_hi:[0,1,1]
	v_cvt_f32_ubyte2_e32 v126, v4
	v_cvt_f32_ubyte3_e32 v127, v4
	v_pk_fma_f32 v[84:85], v[34:35], v[102:103], v[84:85] op_sel_hi:[0,1,1]
	v_cvt_f32_ubyte0_e32 v96, v78
	v_cvt_f32_ubyte1_e32 v97, v78
	v_pk_fma_f32 v[80:81], v[34:35], v[126:127], v[80:81] op_sel_hi:[0,1,1]
	v_and_b32_e32 v82, s34, v6
	v_and_b32_e32 v86, s34, v7
	v_cvt_f32_ubyte2_e32 v100, v78
	v_cvt_f32_ubyte3_e32 v101, v78
	v_pk_fma_f32 v[76:77], v[34:35], v[96:97], v[76:77] op_sel_hi:[0,1,1]
	v_cvt_f32_ubyte0_e32 v102, v5
	v_cvt_f32_ubyte1_e32 v103, v5
	v_pk_fma_f32 v[68:69], v[34:35], v[100:101], v[68:69] op_sel_hi:[0,1,1]
	v_cvt_f32_ubyte2_e32 v126, v5
	v_cvt_f32_ubyte3_e32 v127, v5
	v_pk_fma_f32 v[62:63], v[34:35], v[102:103], v[62:63] op_sel_hi:[0,1,1]
	v_cvt_f32_ubyte0_e32 v96, v82
	v_cvt_f32_ubyte1_e32 v97, v82
	v_pk_fma_f32 v[60:61], v[34:35], v[126:127], v[60:61] op_sel_hi:[0,1,1]
	v_cvt_f32_ubyte2_e32 v100, v82
	v_cvt_f32_ubyte3_e32 v101, v82
	v_pk_fma_f32 v[90:91], v[34:35], v[96:97], v[90:91] op_sel:[1,0,0]
	v_cvt_f32_ubyte0_e32 v102, v6
	v_cvt_f32_ubyte1_e32 v103, v6
	v_pk_fma_f32 v[88:89], v[34:35], v[100:101], v[88:89] op_sel:[1,0,0]
	v_cvt_f32_ubyte2_e32 v126, v6
	v_cvt_f32_ubyte3_e32 v127, v6
	v_pk_fma_f32 v[84:85], v[34:35], v[102:103], v[84:85] op_sel:[1,0,0]
	v_cvt_f32_ubyte0_e32 v96, v86
	v_cvt_f32_ubyte1_e32 v97, v86
	v_pk_fma_f32 v[80:81], v[34:35], v[126:127], v[80:81] op_sel:[1,0,0]
	v_and_b32_e32 v74, s34, v8
	v_and_b32_e32 v78, s34, v9
	v_cvt_f32_ubyte2_e32 v100, v86
	v_cvt_f32_ubyte3_e32 v101, v86
	v_pk_fma_f32 v[76:77], v[34:35], v[96:97], v[76:77] op_sel:[1,0,0]
	v_cvt_f32_ubyte0_e32 v102, v7
	v_cvt_f32_ubyte1_e32 v103, v7
	v_pk_fma_f32 v[68:69], v[34:35], v[100:101], v[68:69] op_sel:[1,0,0]
	v_cvt_f32_ubyte2_e32 v126, v7
	v_cvt_f32_ubyte3_e32 v127, v7
	v_pk_fma_f32 v[62:63], v[34:35], v[102:103], v[62:63] op_sel:[1,0,0]
	v_cvt_f32_ubyte0_e32 v96, v74
	v_cvt_f32_ubyte1_e32 v97, v74
	v_pk_fma_f32 v[60:61], v[34:35], v[126:127], v[60:61] op_sel:[1,0,0]
	v_cvt_f32_ubyte2_e32 v100, v74
	v_cvt_f32_ubyte3_e32 v101, v74
	v_pk_fma_f32 v[90:91], v[36:37], v[96:97], v[90:91] op_sel_hi:[0,1,1]
	v_cvt_f32_ubyte0_e32 v102, v8
	v_cvt_f32_ubyte1_e32 v103, v8
	v_pk_fma_f32 v[88:89], v[36:37], v[100:101], v[88:89] op_sel_hi:[0,1,1]
	v_cvt_f32_ubyte2_e32 v126, v8
	v_cvt_f32_ubyte3_e32 v127, v8
	v_pk_fma_f32 v[84:85], v[36:37], v[102:103], v[84:85] op_sel_hi:[0,1,1]
	v_cvt_f32_ubyte0_e32 v96, v78
	v_cvt_f32_ubyte1_e32 v97, v78
	v_pk_fma_f32 v[80:81], v[36:37], v[126:127], v[80:81] op_sel_hi:[0,1,1]
	v_and_b32_e32 v82, s34, v10
	v_and_b32_e32 v86, s34, v11
	v_cvt_f32_ubyte2_e32 v100, v78
	v_cvt_f32_ubyte3_e32 v101, v78
	v_pk_fma_f32 v[76:77], v[36:37], v[96:97], v[76:77] op_sel_hi:[0,1,1]
	v_cvt_f32_ubyte0_e32 v102, v9
	v_cvt_f32_ubyte1_e32 v103, v9
	v_pk_fma_f32 v[68:69], v[36:37], v[100:101], v[68:69] op_sel_hi:[0,1,1]
	v_cvt_f32_ubyte2_e32 v126, v9
	v_cvt_f32_ubyte3_e32 v127, v9
	v_pk_fma_f32 v[62:63], v[36:37], v[102:103], v[62:63] op_sel_hi:[0,1,1]
	v_cvt_f32_ubyte0_e32 v96, v82
	v_cvt_f32_ubyte1_e32 v97, v82
	v_pk_fma_f32 v[60:61], v[36:37], v[126:127], v[60:61] op_sel_hi:[0,1,1]
	v_cvt_f32_ubyte2_e32 v100, v82
	v_cvt_f32_ubyte3_e32 v101, v82
	v_pk_fma_f32 v[90:91], v[36:37], v[96:97], v[90:91] op_sel:[1,0,0]
	v_cvt_f32_ubyte0_e32 v102, v10
	v_cvt_f32_ubyte1_e32 v103, v10
	v_pk_fma_f32 v[88:89], v[36:37], v[100:101], v[88:89] op_sel:[1,0,0]
	v_cvt_f32_ubyte2_e32 v126, v10
	v_cvt_f32_ubyte3_e32 v127, v10
	v_pk_fma_f32 v[84:85], v[36:37], v[102:103], v[84:85] op_sel:[1,0,0]
	v_cvt_f32_ubyte0_e32 v96, v86
	v_cvt_f32_ubyte1_e32 v97, v86
	v_pk_fma_f32 v[80:81], v[36:37], v[126:127], v[80:81] op_sel:[1,0,0]
	v_and_b32_e32 v74, s34, v12
	v_and_b32_e32 v78, s34, v13
	v_cvt_f32_ubyte2_e32 v100, v86
	v_cvt_f32_ubyte3_e32 v101, v86
	v_pk_fma_f32 v[76:77], v[36:37], v[96:97], v[76:77] op_sel:[1,0,0]
	v_cvt_f32_ubyte0_e32 v102, v11
	v_cvt_f32_ubyte1_e32 v103, v11
	v_pk_fma_f32 v[68:69], v[36:37], v[100:101], v[68:69] op_sel:[1,0,0]
	v_cvt_f32_ubyte2_e32 v126, v11
	v_cvt_f32_ubyte3_e32 v127, v11
	v_pk_fma_f32 v[62:63], v[36:37], v[102:103], v[62:63] op_sel:[1,0,0]
	v_cvt_f32_ubyte0_e32 v96, v74
	v_cvt_f32_ubyte1_e32 v97, v74
	v_pk_fma_f32 v[60:61], v[36:37], v[126:127], v[60:61] op_sel:[1,0,0]
	v_cvt_f32_ubyte2_e32 v100, v74
	v_cvt_f32_ubyte3_e32 v101, v74
	v_pk_fma_f32 v[90:91], v[38:39], v[96:97], v[90:91] op_sel_hi:[0,1,1]
	v_cvt_f32_ubyte0_e32 v102, v12
	v_cvt_f32_ubyte1_e32 v103, v12
	v_pk_fma_f32 v[88:89], v[38:39], v[100:101], v[88:89] op_sel_hi:[0,1,1]
	v_cvt_f32_ubyte2_e32 v126, v12
	v_cvt_f32_ubyte3_e32 v127, v12
	v_pk_fma_f32 v[84:85], v[38:39], v[102:103], v[84:85] op_sel_hi:[0,1,1]
	v_cvt_f32_ubyte0_e32 v96, v78
	v_cvt_f32_ubyte1_e32 v97, v78
	v_pk_fma_f32 v[80:81], v[38:39], v[126:127], v[80:81] op_sel_hi:[0,1,1]
	v_and_b32_e32 v82, s34, v14
	v_and_b32_e32 v86, s34, v15
	v_cvt_f32_ubyte2_e32 v100, v78
	v_cvt_f32_ubyte3_e32 v101, v78
	v_pk_fma_f32 v[76:77], v[38:39], v[96:97], v[76:77] op_sel_hi:[0,1,1]
	v_cvt_f32_ubyte0_e32 v102, v13
	v_cvt_f32_ubyte1_e32 v103, v13
	v_pk_fma_f32 v[68:69], v[38:39], v[100:101], v[68:69] op_sel_hi:[0,1,1]
	v_cvt_f32_ubyte2_e32 v126, v13
	v_cvt_f32_ubyte3_e32 v127, v13
	v_pk_fma_f32 v[62:63], v[38:39], v[102:103], v[62:63] op_sel_hi:[0,1,1]
	v_cvt_f32_ubyte0_e32 v96, v82
	v_cvt_f32_ubyte1_e32 v97, v82
	v_pk_fma_f32 v[60:61], v[38:39], v[126:127], v[60:61] op_sel_hi:[0,1,1]
	v_cvt_f32_ubyte2_e32 v100, v82
	v_cvt_f32_ubyte3_e32 v101, v82
	v_pk_fma_f32 v[90:91], v[38:39], v[96:97], v[90:91] op_sel:[1,0,0]
	v_cvt_f32_ubyte0_e32 v102, v14
	v_cvt_f32_ubyte1_e32 v103, v14
	v_pk_fma_f32 v[88:89], v[38:39], v[100:101], v[88:89] op_sel:[1,0,0]
	v_cvt_f32_ubyte2_e32 v126, v14
	v_cvt_f32_ubyte3_e32 v127, v14
	v_pk_fma_f32 v[84:85], v[38:39], v[102:103], v[84:85] op_sel:[1,0,0]
	v_cvt_f32_ubyte0_e32 v96, v86
	v_cvt_f32_ubyte1_e32 v97, v86
	v_pk_fma_f32 v[80:81], v[38:39], v[126:127], v[80:81] op_sel:[1,0,0]
	v_cvt_f32_ubyte2_e32 v100, v86
	v_cvt_f32_ubyte3_e32 v101, v86
	v_pk_fma_f32 v[76:77], v[38:39], v[96:97], v[76:77] op_sel:[1,0,0]
	v_cvt_f32_ubyte0_e32 v102, v15
	v_cvt_f32_ubyte1_e32 v103, v15
	v_pk_fma_f32 v[68:69], v[38:39], v[100:101], v[68:69] op_sel:[1,0,0]
	v_cvt_f32_ubyte2_e32 v126, v15
	v_cvt_f32_ubyte3_e32 v127, v15
	v_pk_fma_f32 v[62:63], v[38:39], v[102:103], v[62:63] op_sel:[1,0,0]
	v_pk_fma_f32 v[60:61], v[38:39], v[126:127], v[60:61] op_sel:[1,0,0]
	s_waitcnt lgkmcnt(0)
	v_lshl_add_u32 v70, v70, 9, v98
	v_lshl_add_u32 v71, v71, 9, v98
	v_lshl_add_u32 v72, v72, 9, v98
	v_lshl_add_u32 v73, v73, 9, v98
	v_lshl_add_u32 v92, v92, 9, v98
	v_lshl_add_u32 v93, v93, 9, v98
	v_lshl_add_u32 v94, v94, 9, v98
	v_lshl_add_u32 v95, v95, 9, v98
	global_load_dwordx2 v[0:1], v70, s[36:37]
	global_load_dwordx2 v[2:3], v71, s[36:37]
	global_load_dwordx2 v[4:5], v72, s[36:37]
	global_load_dwordx2 v[6:7], v73, s[36:37]
	global_load_dwordx2 v[8:9], v92, s[36:37]
	global_load_dwordx2 v[10:11], v93, s[36:37]
	global_load_dwordx2 v[12:13], v94, s[36:37]
	global_load_dwordx2 v[14:15], v95, s[36:37]
	ds_read_b128 v[70:73], v128 offset:352
	ds_read_b128 v[92:95], v128 offset:368
	ds_read_b128 v[32:35], v128 offset:704
	ds_read_b128 v[36:39], v128 offset:720
	s_waitcnt vmcnt(40)
	v_and_b32_e32 v74, s34, v16
	v_and_b32_e32 v78, s34, v17
	v_cvt_f32_ubyte0_e32 v96, v74
	v_cvt_f32_ubyte1_e32 v97, v74
	v_cvt_f32_ubyte2_e32 v100, v74
	v_cvt_f32_ubyte3_e32 v101, v74
	v_pk_fma_f32 v[90:91], v[48:49], v[96:97], v[90:91] op_sel_hi:[0,1,1]
	v_cvt_f32_ubyte0_e32 v102, v16
	v_cvt_f32_ubyte1_e32 v103, v16
	v_pk_fma_f32 v[88:89], v[48:49], v[100:101], v[88:89] op_sel_hi:[0,1,1]
	v_cvt_f32_ubyte2_e32 v126, v16
	v_cvt_f32_ubyte3_e32 v127, v16
	v_pk_fma_f32 v[84:85], v[48:49], v[102:103], v[84:85] op_sel_hi:[0,1,1]
	v_cvt_f32_ubyte0_e32 v96, v78
	v_cvt_f32_ubyte1_e32 v97, v78
	v_pk_fma_f32 v[80:81], v[48:49], v[126:127], v[80:81] op_sel_hi:[0,1,1]
	v_and_b32_e32 v82, s34, v18
	v_and_b32_e32 v86, s34, v19
	v_cvt_f32_ubyte2_e32 v100, v78
	v_cvt_f32_ubyte3_e32 v101, v78
	v_pk_fma_f32 v[76:77], v[48:49], v[96:97], v[76:77] op_sel_hi:[0,1,1]
	v_cvt_f32_ubyte0_e32 v102, v17
	v_cvt_f32_ubyte1_e32 v103, v17
	v_pk_fma_f32 v[68:69], v[48:49], v[100:101], v[68:69] op_sel_hi:[0,1,1]
	v_cvt_f32_ubyte2_e32 v126, v17
	v_cvt_f32_ubyte3_e32 v127, v17
	v_pk_fma_f32 v[62:63], v[48:49], v[102:103], v[62:63] op_sel_hi:[0,1,1]
	v_cvt_f32_ubyte0_e32 v96, v82
	v_cvt_f32_ubyte1_e32 v97, v82
	v_pk_fma_f32 v[60:61], v[48:49], v[126:127], v[60:61] op_sel_hi:[0,1,1]
	v_cvt_f32_ubyte2_e32 v100, v82
	v_cvt_f32_ubyte3_e32 v101, v82
	v_pk_fma_f32 v[90:91], v[48:49], v[96:97], v[90:91] op_sel:[1,0,0]
	v_cvt_f32_ubyte0_e32 v102, v18
	v_cvt_f32_ubyte1_e32 v103, v18
	v_pk_fma_f32 v[88:89], v[48:49], v[100:101], v[88:89] op_sel:[1,0,0]
	v_cvt_f32_ubyte2_e32 v126, v18
	v_cvt_f32_ubyte3_e32 v127, v18
	v_pk_fma_f32 v[84:85], v[48:49], v[102:103], v[84:85] op_sel:[1,0,0]
	v_cvt_f32_ubyte0_e32 v96, v86
	v_cvt_f32_ubyte1_e32 v97, v86
	v_pk_fma_f32 v[80:81], v[48:49], v[126:127], v[80:81] op_sel:[1,0,0]
	v_and_b32_e32 v74, s34, v20
	v_and_b32_e32 v78, s34, v21
	v_cvt_f32_ubyte2_e32 v100, v86
	v_cvt_f32_ubyte3_e32 v101, v86
	v_pk_fma_f32 v[76:77], v[48:49], v[96:97], v[76:77] op_sel:[1,0,0]
	v_cvt_f32_ubyte0_e32 v102, v19
	v_cvt_f32_ubyte1_e32 v103, v19
	v_pk_fma_f32 v[68:69], v[48:49], v[100:101], v[68:69] op_sel:[1,0,0]
	v_cvt_f32_ubyte2_e32 v126, v19
	v_cvt_f32_ubyte3_e32 v127, v19
	v_pk_fma_f32 v[62:63], v[48:49], v[102:103], v[62:63] op_sel:[1,0,0]
	v_cvt_f32_ubyte0_e32 v96, v74
	v_cvt_f32_ubyte1_e32 v97, v74
	v_pk_fma_f32 v[60:61], v[48:49], v[126:127], v[60:61] op_sel:[1,0,0]
	v_cvt_f32_ubyte2_e32 v100, v74
	v_cvt_f32_ubyte3_e32 v101, v74
	v_pk_fma_f32 v[90:91], v[50:51], v[96:97], v[90:91] op_sel_hi:[0,1,1]
	v_cvt_f32_ubyte0_e32 v102, v20
	v_cvt_f32_ubyte1_e32 v103, v20
	v_pk_fma_f32 v[88:89], v[50:51], v[100:101], v[88:89] op_sel_hi:[0,1,1]
	v_cvt_f32_ubyte2_e32 v126, v20
	v_cvt_f32_ubyte3_e32 v127, v20
	v_pk_fma_f32 v[84:85], v[50:51], v[102:103], v[84:85] op_sel_hi:[0,1,1]
	v_cvt_f32_ubyte0_e32 v96, v78
	v_cvt_f32_ubyte1_e32 v97, v78
	v_pk_fma_f32 v[80:81], v[50:51], v[126:127], v[80:81] op_sel_hi:[0,1,1]
	v_and_b32_e32 v82, s34, v22
	v_and_b32_e32 v86, s34, v23
	v_cvt_f32_ubyte2_e32 v100, v78
	v_cvt_f32_ubyte3_e32 v101, v78
	v_pk_fma_f32 v[76:77], v[50:51], v[96:97], v[76:77] op_sel_hi:[0,1,1]
	v_cvt_f32_ubyte0_e32 v102, v21
	v_cvt_f32_ubyte1_e32 v103, v21
	v_pk_fma_f32 v[68:69], v[50:51], v[100:101], v[68:69] op_sel_hi:[0,1,1]
	v_cvt_f32_ubyte2_e32 v126, v21
	v_cvt_f32_ubyte3_e32 v127, v21
	v_pk_fma_f32 v[62:63], v[50:51], v[102:103], v[62:63] op_sel_hi:[0,1,1]
	v_cvt_f32_ubyte0_e32 v96, v82
	v_cvt_f32_ubyte1_e32 v97, v82
	v_pk_fma_f32 v[60:61], v[50:51], v[126:127], v[60:61] op_sel_hi:[0,1,1]
	v_cvt_f32_ubyte2_e32 v100, v82
	v_cvt_f32_ubyte3_e32 v101, v82
	v_pk_fma_f32 v[90:91], v[50:51], v[96:97], v[90:91] op_sel:[1,0,0]
	v_cvt_f32_ubyte0_e32 v102, v22
	v_cvt_f32_ubyte1_e32 v103, v22
	v_pk_fma_f32 v[88:89], v[50:51], v[100:101], v[88:89] op_sel:[1,0,0]
	v_cvt_f32_ubyte2_e32 v126, v22
	v_cvt_f32_ubyte3_e32 v127, v22
	v_pk_fma_f32 v[84:85], v[50:51], v[102:103], v[84:85] op_sel:[1,0,0]
	v_cvt_f32_ubyte0_e32 v96, v86
	v_cvt_f32_ubyte1_e32 v97, v86
	v_pk_fma_f32 v[80:81], v[50:51], v[126:127], v[80:81] op_sel:[1,0,0]
	v_and_b32_e32 v74, s34, v24
	v_and_b32_e32 v78, s34, v25
	v_cvt_f32_ubyte2_e32 v100, v86
	v_cvt_f32_ubyte3_e32 v101, v86
	v_pk_fma_f32 v[76:77], v[50:51], v[96:97], v[76:77] op_sel:[1,0,0]
	v_cvt_f32_ubyte0_e32 v102, v23
	v_cvt_f32_ubyte1_e32 v103, v23
	v_pk_fma_f32 v[68:69], v[50:51], v[100:101], v[68:69] op_sel:[1,0,0]
	v_cvt_f32_ubyte2_e32 v126, v23
	v_cvt_f32_ubyte3_e32 v127, v23
	v_pk_fma_f32 v[62:63], v[50:51], v[102:103], v[62:63] op_sel:[1,0,0]
	v_cvt_f32_ubyte0_e32 v96, v74
	v_cvt_f32_ubyte1_e32 v97, v74
	v_pk_fma_f32 v[60:61], v[50:51], v[126:127], v[60:61] op_sel:[1,0,0]
	v_cvt_f32_ubyte2_e32 v100, v74
	v_cvt_f32_ubyte3_e32 v101, v74
	v_pk_fma_f32 v[90:91], v[52:53], v[96:97], v[90:91] op_sel_hi:[0,1,1]
	v_cvt_f32_ubyte0_e32 v102, v24
	v_cvt_f32_ubyte1_e32 v103, v24
	v_pk_fma_f32 v[88:89], v[52:53], v[100:101], v[88:89] op_sel_hi:[0,1,1]
	v_cvt_f32_ubyte2_e32 v126, v24
	v_cvt_f32_ubyte3_e32 v127, v24
	v_pk_fma_f32 v[84:85], v[52:53], v[102:103], v[84:85] op_sel_hi:[0,1,1]
	v_cvt_f32_ubyte0_e32 v96, v78
	v_cvt_f32_ubyte1_e32 v97, v78
	v_pk_fma_f32 v[80:81], v[52:53], v[126:127], v[80:81] op_sel_hi:[0,1,1]
	v_and_b32_e32 v82, s34, v26
	v_and_b32_e32 v86, s34, v27
	v_cvt_f32_ubyte2_e32 v100, v78
	v_cvt_f32_ubyte3_e32 v101, v78
	v_pk_fma_f32 v[76:77], v[52:53], v[96:97], v[76:77] op_sel_hi:[0,1,1]
	v_cvt_f32_ubyte0_e32 v102, v25
	v_cvt_f32_ubyte1_e32 v103, v25
	v_pk_fma_f32 v[68:69], v[52:53], v[100:101], v[68:69] op_sel_hi:[0,1,1]
	v_cvt_f32_ubyte2_e32 v126, v25
	v_cvt_f32_ubyte3_e32 v127, v25
	v_pk_fma_f32 v[62:63], v[52:53], v[102:103], v[62:63] op_sel_hi:[0,1,1]
	v_cvt_f32_ubyte0_e32 v96, v82
	v_cvt_f32_ubyte1_e32 v97, v82
	v_pk_fma_f32 v[60:61], v[52:53], v[126:127], v[60:61] op_sel_hi:[0,1,1]
	v_cvt_f32_ubyte2_e32 v100, v82
	v_cvt_f32_ubyte3_e32 v101, v82
	v_pk_fma_f32 v[90:91], v[52:53], v[96:97], v[90:91] op_sel:[1,0,0]
	v_cvt_f32_ubyte0_e32 v102, v26
	v_cvt_f32_ubyte1_e32 v103, v26
	v_pk_fma_f32 v[88:89], v[52:53], v[100:101], v[88:89] op_sel:[1,0,0]
	v_cvt_f32_ubyte2_e32 v126, v26
	v_cvt_f32_ubyte3_e32 v127, v26
	v_pk_fma_f32 v[84:85], v[52:53], v[102:103], v[84:85] op_sel:[1,0,0]
	v_cvt_f32_ubyte0_e32 v96, v86
	v_cvt_f32_ubyte1_e32 v97, v86
	v_pk_fma_f32 v[80:81], v[52:53], v[126:127], v[80:81] op_sel:[1,0,0]
	v_and_b32_e32 v74, s34, v28
	v_and_b32_e32 v78, s34, v29
	v_cvt_f32_ubyte2_e32 v100, v86
	v_cvt_f32_ubyte3_e32 v101, v86
	v_pk_fma_f32 v[76:77], v[52:53], v[96:97], v[76:77] op_sel:[1,0,0]
	v_cvt_f32_ubyte0_e32 v102, v27
	v_cvt_f32_ubyte1_e32 v103, v27
	v_pk_fma_f32 v[68:69], v[52:53], v[100:101], v[68:69] op_sel:[1,0,0]
	v_cvt_f32_ubyte2_e32 v126, v27
	v_cvt_f32_ubyte3_e32 v127, v27
	v_pk_fma_f32 v[62:63], v[52:53], v[102:103], v[62:63] op_sel:[1,0,0]
	v_cvt_f32_ubyte0_e32 v96, v74
	v_cvt_f32_ubyte1_e32 v97, v74
	v_pk_fma_f32 v[60:61], v[52:53], v[126:127], v[60:61] op_sel:[1,0,0]
	v_cvt_f32_ubyte2_e32 v100, v74
	v_cvt_f32_ubyte3_e32 v101, v74
	v_pk_fma_f32 v[90:91], v[54:55], v[96:97], v[90:91] op_sel_hi:[0,1,1]
	v_cvt_f32_ubyte0_e32 v102, v28
	v_cvt_f32_ubyte1_e32 v103, v28
	v_pk_fma_f32 v[88:89], v[54:55], v[100:101], v[88:89] op_sel_hi:[0,1,1]
	v_cvt_f32_ubyte2_e32 v126, v28
	v_cvt_f32_ubyte3_e32 v127, v28
	v_pk_fma_f32 v[84:85], v[54:55], v[102:103], v[84:85] op_sel_hi:[0,1,1]
	v_cvt_f32_ubyte0_e32 v96, v78
	v_cvt_f32_ubyte1_e32 v97, v78
	v_pk_fma_f32 v[80:81], v[54:55], v[126:127], v[80:81] op_sel_hi:[0,1,1]
	v_and_b32_e32 v82, s34, v30
	v_and_b32_e32 v86, s34, v31
	v_cvt_f32_ubyte2_e32 v100, v78
	v_cvt_f32_ubyte3_e32 v101, v78
	v_pk_fma_f32 v[76:77], v[54:55], v[96:97], v[76:77] op_sel_hi:[0,1,1]
	v_cvt_f32_ubyte0_e32 v102, v29
	v_cvt_f32_ubyte1_e32 v103, v29
	v_pk_fma_f32 v[68:69], v[54:55], v[100:101], v[68:69] op_sel_hi:[0,1,1]
	v_cvt_f32_ubyte2_e32 v126, v29
	v_cvt_f32_ubyte3_e32 v127, v29
	v_pk_fma_f32 v[62:63], v[54:55], v[102:103], v[62:63] op_sel_hi:[0,1,1]
	v_cvt_f32_ubyte0_e32 v96, v82
	v_cvt_f32_ubyte1_e32 v97, v82
	v_pk_fma_f32 v[60:61], v[54:55], v[126:127], v[60:61] op_sel_hi:[0,1,1]
	v_cvt_f32_ubyte2_e32 v100, v82
	v_cvt_f32_ubyte3_e32 v101, v82
	v_pk_fma_f32 v[90:91], v[54:55], v[96:97], v[90:91] op_sel:[1,0,0]
	v_cvt_f32_ubyte0_e32 v102, v30
	v_cvt_f32_ubyte1_e32 v103, v30
	v_pk_fma_f32 v[88:89], v[54:55], v[100:101], v[88:89] op_sel:[1,0,0]
	v_cvt_f32_ubyte2_e32 v126, v30
	v_cvt_f32_ubyte3_e32 v127, v30
	v_pk_fma_f32 v[84:85], v[54:55], v[102:103], v[84:85] op_sel:[1,0,0]
	v_cvt_f32_ubyte0_e32 v96, v86
	v_cvt_f32_ubyte1_e32 v97, v86
	v_pk_fma_f32 v[80:81], v[54:55], v[126:127], v[80:81] op_sel:[1,0,0]
	v_cvt_f32_ubyte2_e32 v100, v86
	v_cvt_f32_ubyte3_e32 v101, v86
	v_pk_fma_f32 v[76:77], v[54:55], v[96:97], v[76:77] op_sel:[1,0,0]
	v_cvt_f32_ubyte0_e32 v102, v31
	v_cvt_f32_ubyte1_e32 v103, v31
	v_pk_fma_f32 v[68:69], v[54:55], v[100:101], v[68:69] op_sel:[1,0,0]
	v_cvt_f32_ubyte2_e32 v126, v31
	v_cvt_f32_ubyte3_e32 v127, v31
	v_pk_fma_f32 v[62:63], v[54:55], v[102:103], v[62:63] op_sel:[1,0,0]
	v_pk_fma_f32 v[60:61], v[54:55], v[126:127], v[60:61] op_sel:[1,0,0]
	s_waitcnt lgkmcnt(0)
	v_lshl_add_u32 v70, v70, 9, v98
	v_lshl_add_u32 v71, v71, 9, v98
	v_lshl_add_u32 v72, v72, 9, v98
	v_lshl_add_u32 v73, v73, 9, v98
	v_lshl_add_u32 v92, v92, 9, v98
	v_lshl_add_u32 v93, v93, 9, v98
	v_lshl_add_u32 v94, v94, 9, v98
	v_lshl_add_u32 v95, v95, 9, v98
	global_load_dwordx2 v[16:17], v70, s[36:37]
	global_load_dwordx2 v[18:19], v71, s[36:37]
	global_load_dwordx2 v[20:21], v72, s[36:37]
	global_load_dwordx2 v[22:23], v73, s[36:37]
	global_load_dwordx2 v[24:25], v92, s[36:37]
	global_load_dwordx2 v[26:27], v93, s[36:37]
	global_load_dwordx2 v[28:29], v94, s[36:37]
	global_load_dwordx2 v[30:31], v95, s[36:37]
	ds_read_b128 v[70:73], v128 offset:384
	ds_read_b128 v[92:95], v128 offset:400
	ds_read_b128 v[48:51], v128 offset:736
	ds_read_b128 v[52:55], v128 offset:752
	s_waitcnt vmcnt(40)
	v_and_b32_e32 v74, s34, v146
	v_and_b32_e32 v78, s34, v147
	v_cvt_f32_ubyte0_e32 v96, v74
	v_cvt_f32_ubyte1_e32 v97, v74
	v_cvt_f32_ubyte2_e32 v100, v74
	v_cvt_f32_ubyte3_e32 v101, v74
	v_pk_fma_f32 v[90:91], v[32:33], v[96:97], v[90:91] op_sel_hi:[0,1,1]
	v_cvt_f32_ubyte0_e32 v102, v146
	v_cvt_f32_ubyte1_e32 v103, v146
	v_pk_fma_f32 v[88:89], v[32:33], v[100:101], v[88:89] op_sel_hi:[0,1,1]
	v_cvt_f32_ubyte2_e32 v126, v146
	v_cvt_f32_ubyte3_e32 v127, v146
	v_pk_fma_f32 v[84:85], v[32:33], v[102:103], v[84:85] op_sel_hi:[0,1,1]
	v_cvt_f32_ubyte0_e32 v96, v78
	v_cvt_f32_ubyte1_e32 v97, v78
	v_pk_fma_f32 v[80:81], v[32:33], v[126:127], v[80:81] op_sel_hi:[0,1,1]
	v_and_b32_e32 v82, s34, v148
	v_and_b32_e32 v86, s34, v149
	v_cvt_f32_ubyte2_e32 v100, v78
	v_cvt_f32_ubyte3_e32 v101, v78
	v_pk_fma_f32 v[76:77], v[32:33], v[96:97], v[76:77] op_sel_hi:[0,1,1]
	v_cvt_f32_ubyte0_e32 v102, v147
	v_cvt_f32_ubyte1_e32 v103, v147
	v_pk_fma_f32 v[68:69], v[32:33], v[100:101], v[68:69] op_sel_hi:[0,1,1]
	v_cvt_f32_ubyte2_e32 v126, v147
	v_cvt_f32_ubyte3_e32 v127, v147
	v_pk_fma_f32 v[62:63], v[32:33], v[102:103], v[62:63] op_sel_hi:[0,1,1]
	v_cvt_f32_ubyte0_e32 v96, v82
	v_cvt_f32_ubyte1_e32 v97, v82
	v_pk_fma_f32 v[60:61], v[32:33], v[126:127], v[60:61] op_sel_hi:[0,1,1]
	v_cvt_f32_ubyte2_e32 v100, v82
	v_cvt_f32_ubyte3_e32 v101, v82
	v_pk_fma_f32 v[90:91], v[32:33], v[96:97], v[90:91] op_sel:[1,0,0]
	v_cvt_f32_ubyte0_e32 v102, v148
	v_cvt_f32_ubyte1_e32 v103, v148
	v_pk_fma_f32 v[88:89], v[32:33], v[100:101], v[88:89] op_sel:[1,0,0]
	v_cvt_f32_ubyte2_e32 v126, v148
	v_cvt_f32_ubyte3_e32 v127, v148
	v_pk_fma_f32 v[84:85], v[32:33], v[102:103], v[84:85] op_sel:[1,0,0]
	v_cvt_f32_ubyte0_e32 v96, v86
	v_cvt_f32_ubyte1_e32 v97, v86
	v_pk_fma_f32 v[80:81], v[32:33], v[126:127], v[80:81] op_sel:[1,0,0]
	v_and_b32_e32 v74, s34, v150
	v_and_b32_e32 v78, s34, v151
	v_cvt_f32_ubyte2_e32 v100, v86
	v_cvt_f32_ubyte3_e32 v101, v86
	v_pk_fma_f32 v[76:77], v[32:33], v[96:97], v[76:77] op_sel:[1,0,0]
	v_cvt_f32_ubyte0_e32 v102, v149
	v_cvt_f32_ubyte1_e32 v103, v149
	v_pk_fma_f32 v[68:69], v[32:33], v[100:101], v[68:69] op_sel:[1,0,0]
	v_cvt_f32_ubyte2_e32 v126, v149
	v_cvt_f32_ubyte3_e32 v127, v149
	v_pk_fma_f32 v[62:63], v[32:33], v[102:103], v[62:63] op_sel:[1,0,0]
	v_cvt_f32_ubyte0_e32 v96, v74
	v_cvt_f32_ubyte1_e32 v97, v74
	v_pk_fma_f32 v[60:61], v[32:33], v[126:127], v[60:61] op_sel:[1,0,0]
	v_cvt_f32_ubyte2_e32 v100, v74
	v_cvt_f32_ubyte3_e32 v101, v74
	v_pk_fma_f32 v[90:91], v[34:35], v[96:97], v[90:91] op_sel_hi:[0,1,1]
	v_cvt_f32_ubyte0_e32 v102, v150
	v_cvt_f32_ubyte1_e32 v103, v150
	v_pk_fma_f32 v[88:89], v[34:35], v[100:101], v[88:89] op_sel_hi:[0,1,1]
	v_cvt_f32_ubyte2_e32 v126, v150
	v_cvt_f32_ubyte3_e32 v127, v150
	v_pk_fma_f32 v[84:85], v[34:35], v[102:103], v[84:85] op_sel_hi:[0,1,1]
	v_cvt_f32_ubyte0_e32 v96, v78
	v_cvt_f32_ubyte1_e32 v97, v78
	v_pk_fma_f32 v[80:81], v[34:35], v[126:127], v[80:81] op_sel_hi:[0,1,1]
	v_and_b32_e32 v82, s34, v152
	v_and_b32_e32 v86, s34, v153
	v_cvt_f32_ubyte2_e32 v100, v78
	v_cvt_f32_ubyte3_e32 v101, v78
	v_pk_fma_f32 v[76:77], v[34:35], v[96:97], v[76:77] op_sel_hi:[0,1,1]
	v_cvt_f32_ubyte0_e32 v102, v151
	v_cvt_f32_ubyte1_e32 v103, v151
	v_pk_fma_f32 v[68:69], v[34:35], v[100:101], v[68:69] op_sel_hi:[0,1,1]
	v_cvt_f32_ubyte2_e32 v126, v151
	v_cvt_f32_ubyte3_e32 v127, v151
	v_pk_fma_f32 v[62:63], v[34:35], v[102:103], v[62:63] op_sel_hi:[0,1,1]
	v_cvt_f32_ubyte0_e32 v96, v82
	v_cvt_f32_ubyte1_e32 v97, v82
	v_pk_fma_f32 v[60:61], v[34:35], v[126:127], v[60:61] op_sel_hi:[0,1,1]
	v_cvt_f32_ubyte2_e32 v100, v82
	v_cvt_f32_ubyte3_e32 v101, v82
	v_pk_fma_f32 v[90:91], v[34:35], v[96:97], v[90:91] op_sel:[1,0,0]
	v_cvt_f32_ubyte0_e32 v102, v152
	v_cvt_f32_ubyte1_e32 v103, v152
	v_pk_fma_f32 v[88:89], v[34:35], v[100:101], v[88:89] op_sel:[1,0,0]
	v_cvt_f32_ubyte2_e32 v126, v152
	v_cvt_f32_ubyte3_e32 v127, v152
	v_pk_fma_f32 v[84:85], v[34:35], v[102:103], v[84:85] op_sel:[1,0,0]
	v_cvt_f32_ubyte0_e32 v96, v86
	v_cvt_f32_ubyte1_e32 v97, v86
	v_pk_fma_f32 v[80:81], v[34:35], v[126:127], v[80:81] op_sel:[1,0,0]
	v_and_b32_e32 v74, s34, v154
	v_and_b32_e32 v78, s34, v155
	v_cvt_f32_ubyte2_e32 v100, v86
	v_cvt_f32_ubyte3_e32 v101, v86
	v_pk_fma_f32 v[76:77], v[34:35], v[96:97], v[76:77] op_sel:[1,0,0]
	v_cvt_f32_ubyte0_e32 v102, v153
	v_cvt_f32_ubyte1_e32 v103, v153
	v_pk_fma_f32 v[68:69], v[34:35], v[100:101], v[68:69] op_sel:[1,0,0]
	v_cvt_f32_ubyte2_e32 v126, v153
	v_cvt_f32_ubyte3_e32 v127, v153
	v_pk_fma_f32 v[62:63], v[34:35], v[102:103], v[62:63] op_sel:[1,0,0]
	v_cvt_f32_ubyte0_e32 v96, v74
	v_cvt_f32_ubyte1_e32 v97, v74
	v_pk_fma_f32 v[60:61], v[34:35], v[126:127], v[60:61] op_sel:[1,0,0]
	v_cvt_f32_ubyte2_e32 v100, v74
	v_cvt_f32_ubyte3_e32 v101, v74
	v_pk_fma_f32 v[90:91], v[36:37], v[96:97], v[90:91] op_sel_hi:[0,1,1]
	v_cvt_f32_ubyte0_e32 v102, v154
	v_cvt_f32_ubyte1_e32 v103, v154
	v_pk_fma_f32 v[88:89], v[36:37], v[100:101], v[88:89] op_sel_hi:[0,1,1]
	v_cvt_f32_ubyte2_e32 v126, v154
	v_cvt_f32_ubyte3_e32 v127, v154
	v_pk_fma_f32 v[84:85], v[36:37], v[102:103], v[84:85] op_sel_hi:[0,1,1]
	v_cvt_f32_ubyte0_e32 v96, v78
	v_cvt_f32_ubyte1_e32 v97, v78
	v_pk_fma_f32 v[80:81], v[36:37], v[126:127], v[80:81] op_sel_hi:[0,1,1]
	v_and_b32_e32 v82, s34, v156
	v_and_b32_e32 v86, s34, v157
	v_cvt_f32_ubyte2_e32 v100, v78
	v_cvt_f32_ubyte3_e32 v101, v78
	v_pk_fma_f32 v[76:77], v[36:37], v[96:97], v[76:77] op_sel_hi:[0,1,1]
	v_cvt_f32_ubyte0_e32 v102, v155
	v_cvt_f32_ubyte1_e32 v103, v155
	v_pk_fma_f32 v[68:69], v[36:37], v[100:101], v[68:69] op_sel_hi:[0,1,1]
	v_cvt_f32_ubyte2_e32 v126, v155
	v_cvt_f32_ubyte3_e32 v127, v155
	v_pk_fma_f32 v[62:63], v[36:37], v[102:103], v[62:63] op_sel_hi:[0,1,1]
	v_cvt_f32_ubyte0_e32 v96, v82
	v_cvt_f32_ubyte1_e32 v97, v82
	v_pk_fma_f32 v[60:61], v[36:37], v[126:127], v[60:61] op_sel_hi:[0,1,1]
	v_cvt_f32_ubyte2_e32 v100, v82
	v_cvt_f32_ubyte3_e32 v101, v82
	v_pk_fma_f32 v[90:91], v[36:37], v[96:97], v[90:91] op_sel:[1,0,0]
	v_cvt_f32_ubyte0_e32 v102, v156
	v_cvt_f32_ubyte1_e32 v103, v156
	v_pk_fma_f32 v[88:89], v[36:37], v[100:101], v[88:89] op_sel:[1,0,0]
	v_cvt_f32_ubyte2_e32 v126, v156
	v_cvt_f32_ubyte3_e32 v127, v156
	v_pk_fma_f32 v[84:85], v[36:37], v[102:103], v[84:85] op_sel:[1,0,0]
	v_cvt_f32_ubyte0_e32 v96, v86
	v_cvt_f32_ubyte1_e32 v97, v86
	v_pk_fma_f32 v[80:81], v[36:37], v[126:127], v[80:81] op_sel:[1,0,0]
	v_and_b32_e32 v74, s34, v158
	v_and_b32_e32 v78, s34, v159
	v_cvt_f32_ubyte2_e32 v100, v86
	v_cvt_f32_ubyte3_e32 v101, v86
	v_pk_fma_f32 v[76:77], v[36:37], v[96:97], v[76:77] op_sel:[1,0,0]
	v_cvt_f32_ubyte0_e32 v102, v157
	v_cvt_f32_ubyte1_e32 v103, v157
	v_pk_fma_f32 v[68:69], v[36:37], v[100:101], v[68:69] op_sel:[1,0,0]
	v_cvt_f32_ubyte2_e32 v126, v157
	v_cvt_f32_ubyte3_e32 v127, v157
	v_pk_fma_f32 v[62:63], v[36:37], v[102:103], v[62:63] op_sel:[1,0,0]
	v_cvt_f32_ubyte0_e32 v96, v74
	v_cvt_f32_ubyte1_e32 v97, v74
	v_pk_fma_f32 v[60:61], v[36:37], v[126:127], v[60:61] op_sel:[1,0,0]
	v_cvt_f32_ubyte2_e32 v100, v74
	v_cvt_f32_ubyte3_e32 v101, v74
	v_pk_fma_f32 v[90:91], v[38:39], v[96:97], v[90:91] op_sel_hi:[0,1,1]
	v_cvt_f32_ubyte0_e32 v102, v158
	v_cvt_f32_ubyte1_e32 v103, v158
	v_pk_fma_f32 v[88:89], v[38:39], v[100:101], v[88:89] op_sel_hi:[0,1,1]
	v_cvt_f32_ubyte2_e32 v126, v158
	v_cvt_f32_ubyte3_e32 v127, v158
	v_pk_fma_f32 v[84:85], v[38:39], v[102:103], v[84:85] op_sel_hi:[0,1,1]
	v_cvt_f32_ubyte0_e32 v96, v78
	v_cvt_f32_ubyte1_e32 v97, v78
	v_pk_fma_f32 v[80:81], v[38:39], v[126:127], v[80:81] op_sel_hi:[0,1,1]
	v_and_b32_e32 v82, s34, v160
	v_and_b32_e32 v86, s34, v161
	v_cvt_f32_ubyte2_e32 v100, v78
	v_cvt_f32_ubyte3_e32 v101, v78
	v_pk_fma_f32 v[76:77], v[38:39], v[96:97], v[76:77] op_sel_hi:[0,1,1]
	v_cvt_f32_ubyte0_e32 v102, v159
	v_cvt_f32_ubyte1_e32 v103, v159
	v_pk_fma_f32 v[68:69], v[38:39], v[100:101], v[68:69] op_sel_hi:[0,1,1]
	v_cvt_f32_ubyte2_e32 v126, v159
	v_cvt_f32_ubyte3_e32 v127, v159
	v_pk_fma_f32 v[62:63], v[38:39], v[102:103], v[62:63] op_sel_hi:[0,1,1]
	v_cvt_f32_ubyte0_e32 v96, v82
	v_cvt_f32_ubyte1_e32 v97, v82
	v_pk_fma_f32 v[60:61], v[38:39], v[126:127], v[60:61] op_sel_hi:[0,1,1]
	v_cvt_f32_ubyte2_e32 v100, v82
	v_cvt_f32_ubyte3_e32 v101, v82
	v_pk_fma_f32 v[90:91], v[38:39], v[96:97], v[90:91] op_sel:[1,0,0]
	v_cvt_f32_ubyte0_e32 v102, v160
	v_cvt_f32_ubyte1_e32 v103, v160
	v_pk_fma_f32 v[88:89], v[38:39], v[100:101], v[88:89] op_sel:[1,0,0]
	v_cvt_f32_ubyte2_e32 v126, v160
	v_cvt_f32_ubyte3_e32 v127, v160
	v_pk_fma_f32 v[84:85], v[38:39], v[102:103], v[84:85] op_sel:[1,0,0]
	v_cvt_f32_ubyte0_e32 v96, v86
	v_cvt_f32_ubyte1_e32 v97, v86
	v_pk_fma_f32 v[80:81], v[38:39], v[126:127], v[80:81] op_sel:[1,0,0]
	v_cvt_f32_ubyte2_e32 v100, v86
	v_cvt_f32_ubyte3_e32 v101, v86
	v_pk_fma_f32 v[76:77], v[38:39], v[96:97], v[76:77] op_sel:[1,0,0]
	v_cvt_f32_ubyte0_e32 v102, v161
	v_cvt_f32_ubyte1_e32 v103, v161
	v_pk_fma_f32 v[68:69], v[38:39], v[100:101], v[68:69] op_sel:[1,0,0]
	v_cvt_f32_ubyte2_e32 v126, v161
	v_cvt_f32_ubyte3_e32 v127, v161
	v_pk_fma_f32 v[62:63], v[38:39], v[102:103], v[62:63] op_sel:[1,0,0]
	v_pk_fma_f32 v[60:61], v[38:39], v[126:127], v[60:61] op_sel:[1,0,0]
	s_waitcnt lgkmcnt(0)
	v_lshl_add_u32 v70, v70, 9, v98
	v_lshl_add_u32 v71, v71, 9, v98
	v_lshl_add_u32 v72, v72, 9, v98
	v_lshl_add_u32 v73, v73, 9, v98
	v_lshl_add_u32 v92, v92, 9, v98
	v_lshl_add_u32 v93, v93, 9, v98
	v_lshl_add_u32 v94, v94, 9, v98
	v_lshl_add_u32 v95, v95, 9, v98
	global_load_dwordx2 v[146:147], v70, s[36:37]
	global_load_dwordx2 v[148:149], v71, s[36:37]
	global_load_dwordx2 v[150:151], v72, s[36:37]
	global_load_dwordx2 v[152:153], v73, s[36:37]
	global_load_dwordx2 v[154:155], v92, s[36:37]
	global_load_dwordx2 v[156:157], v93, s[36:37]
	global_load_dwordx2 v[158:159], v94, s[36:37]
	global_load_dwordx2 v[160:161], v95, s[36:37]
	ds_read_b128 v[70:73], v128 offset:416
	ds_read_b128 v[92:95], v128 offset:432
	ds_read_b128 v[32:35], v128 offset:768
	ds_read_b128 v[36:39], v128 offset:784
	s_waitcnt vmcnt(40)
	v_and_b32_e32 v74, s34, v162
	v_and_b32_e32 v78, s34, v163
	v_cvt_f32_ubyte0_e32 v96, v74
	v_cvt_f32_ubyte1_e32 v97, v74
	v_cvt_f32_ubyte2_e32 v100, v74
	v_cvt_f32_ubyte3_e32 v101, v74
	v_pk_fma_f32 v[90:91], v[48:49], v[96:97], v[90:91] op_sel_hi:[0,1,1]
	v_cvt_f32_ubyte0_e32 v102, v162
	v_cvt_f32_ubyte1_e32 v103, v162
	v_pk_fma_f32 v[88:89], v[48:49], v[100:101], v[88:89] op_sel_hi:[0,1,1]
	v_cvt_f32_ubyte2_e32 v126, v162
	v_cvt_f32_ubyte3_e32 v127, v162
	v_pk_fma_f32 v[84:85], v[48:49], v[102:103], v[84:85] op_sel_hi:[0,1,1]
	v_cvt_f32_ubyte0_e32 v96, v78
	v_cvt_f32_ubyte1_e32 v97, v78
	v_pk_fma_f32 v[80:81], v[48:49], v[126:127], v[80:81] op_sel_hi:[0,1,1]
	v_and_b32_e32 v82, s34, v164
	v_and_b32_e32 v86, s34, v165
	v_cvt_f32_ubyte2_e32 v100, v78
	v_cvt_f32_ubyte3_e32 v101, v78
	v_pk_fma_f32 v[76:77], v[48:49], v[96:97], v[76:77] op_sel_hi:[0,1,1]
	v_cvt_f32_ubyte0_e32 v102, v163
	v_cvt_f32_ubyte1_e32 v103, v163
	v_pk_fma_f32 v[68:69], v[48:49], v[100:101], v[68:69] op_sel_hi:[0,1,1]
	v_cvt_f32_ubyte2_e32 v126, v163
	v_cvt_f32_ubyte3_e32 v127, v163
	v_pk_fma_f32 v[62:63], v[48:49], v[102:103], v[62:63] op_sel_hi:[0,1,1]
	v_cvt_f32_ubyte0_e32 v96, v82
	v_cvt_f32_ubyte1_e32 v97, v82
	v_pk_fma_f32 v[60:61], v[48:49], v[126:127], v[60:61] op_sel_hi:[0,1,1]
	v_cvt_f32_ubyte2_e32 v100, v82
	v_cvt_f32_ubyte3_e32 v101, v82
	v_pk_fma_f32 v[90:91], v[48:49], v[96:97], v[90:91] op_sel:[1,0,0]
	v_cvt_f32_ubyte0_e32 v102, v164
	v_cvt_f32_ubyte1_e32 v103, v164
	v_pk_fma_f32 v[88:89], v[48:49], v[100:101], v[88:89] op_sel:[1,0,0]
	v_cvt_f32_ubyte2_e32 v126, v164
	v_cvt_f32_ubyte3_e32 v127, v164
	v_pk_fma_f32 v[84:85], v[48:49], v[102:103], v[84:85] op_sel:[1,0,0]
	v_cvt_f32_ubyte0_e32 v96, v86
	v_cvt_f32_ubyte1_e32 v97, v86
	v_pk_fma_f32 v[80:81], v[48:49], v[126:127], v[80:81] op_sel:[1,0,0]
	v_and_b32_e32 v74, s34, v166
	v_and_b32_e32 v78, s34, v167
	v_cvt_f32_ubyte2_e32 v100, v86
	v_cvt_f32_ubyte3_e32 v101, v86
	v_pk_fma_f32 v[76:77], v[48:49], v[96:97], v[76:77] op_sel:[1,0,0]
	v_cvt_f32_ubyte0_e32 v102, v165
	v_cvt_f32_ubyte1_e32 v103, v165
	v_pk_fma_f32 v[68:69], v[48:49], v[100:101], v[68:69] op_sel:[1,0,0]
	v_cvt_f32_ubyte2_e32 v126, v165
	v_cvt_f32_ubyte3_e32 v127, v165
	v_pk_fma_f32 v[62:63], v[48:49], v[102:103], v[62:63] op_sel:[1,0,0]
	v_cvt_f32_ubyte0_e32 v96, v74
	v_cvt_f32_ubyte1_e32 v97, v74
	v_pk_fma_f32 v[60:61], v[48:49], v[126:127], v[60:61] op_sel:[1,0,0]
	v_cvt_f32_ubyte2_e32 v100, v74
	v_cvt_f32_ubyte3_e32 v101, v74
	v_pk_fma_f32 v[90:91], v[50:51], v[96:97], v[90:91] op_sel_hi:[0,1,1]
	v_cvt_f32_ubyte0_e32 v102, v166
	v_cvt_f32_ubyte1_e32 v103, v166
	v_pk_fma_f32 v[88:89], v[50:51], v[100:101], v[88:89] op_sel_hi:[0,1,1]
	v_cvt_f32_ubyte2_e32 v126, v166
	v_cvt_f32_ubyte3_e32 v127, v166
	v_pk_fma_f32 v[84:85], v[50:51], v[102:103], v[84:85] op_sel_hi:[0,1,1]
	v_cvt_f32_ubyte0_e32 v96, v78
	v_cvt_f32_ubyte1_e32 v97, v78
	v_pk_fma_f32 v[80:81], v[50:51], v[126:127], v[80:81] op_sel_hi:[0,1,1]
	v_and_b32_e32 v82, s34, v168
	v_and_b32_e32 v86, s34, v169
	v_cvt_f32_ubyte2_e32 v100, v78
	v_cvt_f32_ubyte3_e32 v101, v78
	v_pk_fma_f32 v[76:77], v[50:51], v[96:97], v[76:77] op_sel_hi:[0,1,1]
	v_cvt_f32_ubyte0_e32 v102, v167
	v_cvt_f32_ubyte1_e32 v103, v167
	v_pk_fma_f32 v[68:69], v[50:51], v[100:101], v[68:69] op_sel_hi:[0,1,1]
	v_cvt_f32_ubyte2_e32 v126, v167
	v_cvt_f32_ubyte3_e32 v127, v167
	v_pk_fma_f32 v[62:63], v[50:51], v[102:103], v[62:63] op_sel_hi:[0,1,1]
	v_cvt_f32_ubyte0_e32 v96, v82
	v_cvt_f32_ubyte1_e32 v97, v82
	v_pk_fma_f32 v[60:61], v[50:51], v[126:127], v[60:61] op_sel_hi:[0,1,1]
	v_cvt_f32_ubyte2_e32 v100, v82
	v_cvt_f32_ubyte3_e32 v101, v82
	v_pk_fma_f32 v[90:91], v[50:51], v[96:97], v[90:91] op_sel:[1,0,0]
	v_cvt_f32_ubyte0_e32 v102, v168
	v_cvt_f32_ubyte1_e32 v103, v168
	v_pk_fma_f32 v[88:89], v[50:51], v[100:101], v[88:89] op_sel:[1,0,0]
	v_cvt_f32_ubyte2_e32 v126, v168
	v_cvt_f32_ubyte3_e32 v127, v168
	v_pk_fma_f32 v[84:85], v[50:51], v[102:103], v[84:85] op_sel:[1,0,0]
	v_cvt_f32_ubyte0_e32 v96, v86
	v_cvt_f32_ubyte1_e32 v97, v86
	v_pk_fma_f32 v[80:81], v[50:51], v[126:127], v[80:81] op_sel:[1,0,0]
	v_and_b32_e32 v74, s34, v170
	v_and_b32_e32 v78, s34, v171
	v_cvt_f32_ubyte2_e32 v100, v86
	v_cvt_f32_ubyte3_e32 v101, v86
	v_pk_fma_f32 v[76:77], v[50:51], v[96:97], v[76:77] op_sel:[1,0,0]
	v_cvt_f32_ubyte0_e32 v102, v169
	v_cvt_f32_ubyte1_e32 v103, v169
	v_pk_fma_f32 v[68:69], v[50:51], v[100:101], v[68:69] op_sel:[1,0,0]
	v_cvt_f32_ubyte2_e32 v126, v169
	v_cvt_f32_ubyte3_e32 v127, v169
	v_pk_fma_f32 v[62:63], v[50:51], v[102:103], v[62:63] op_sel:[1,0,0]
	v_cvt_f32_ubyte0_e32 v96, v74
	v_cvt_f32_ubyte1_e32 v97, v74
	v_pk_fma_f32 v[60:61], v[50:51], v[126:127], v[60:61] op_sel:[1,0,0]
	v_cvt_f32_ubyte2_e32 v100, v74
	v_cvt_f32_ubyte3_e32 v101, v74
	v_pk_fma_f32 v[90:91], v[52:53], v[96:97], v[90:91] op_sel_hi:[0,1,1]
	v_cvt_f32_ubyte0_e32 v102, v170
	v_cvt_f32_ubyte1_e32 v103, v170
	v_pk_fma_f32 v[88:89], v[52:53], v[100:101], v[88:89] op_sel_hi:[0,1,1]
	v_cvt_f32_ubyte2_e32 v126, v170
	v_cvt_f32_ubyte3_e32 v127, v170
	v_pk_fma_f32 v[84:85], v[52:53], v[102:103], v[84:85] op_sel_hi:[0,1,1]
	v_cvt_f32_ubyte0_e32 v96, v78
	v_cvt_f32_ubyte1_e32 v97, v78
	v_pk_fma_f32 v[80:81], v[52:53], v[126:127], v[80:81] op_sel_hi:[0,1,1]
	v_and_b32_e32 v82, s34, v172
	v_and_b32_e32 v86, s34, v173
	v_cvt_f32_ubyte2_e32 v100, v78
	v_cvt_f32_ubyte3_e32 v101, v78
	v_pk_fma_f32 v[76:77], v[52:53], v[96:97], v[76:77] op_sel_hi:[0,1,1]
	v_cvt_f32_ubyte0_e32 v102, v171
	v_cvt_f32_ubyte1_e32 v103, v171
	v_pk_fma_f32 v[68:69], v[52:53], v[100:101], v[68:69] op_sel_hi:[0,1,1]
	v_cvt_f32_ubyte2_e32 v126, v171
	v_cvt_f32_ubyte3_e32 v127, v171
	v_pk_fma_f32 v[62:63], v[52:53], v[102:103], v[62:63] op_sel_hi:[0,1,1]
	v_cvt_f32_ubyte0_e32 v96, v82
	v_cvt_f32_ubyte1_e32 v97, v82
	v_pk_fma_f32 v[60:61], v[52:53], v[126:127], v[60:61] op_sel_hi:[0,1,1]
	v_cvt_f32_ubyte2_e32 v100, v82
	v_cvt_f32_ubyte3_e32 v101, v82
	v_pk_fma_f32 v[90:91], v[52:53], v[96:97], v[90:91] op_sel:[1,0,0]
	v_cvt_f32_ubyte0_e32 v102, v172
	v_cvt_f32_ubyte1_e32 v103, v172
	v_pk_fma_f32 v[88:89], v[52:53], v[100:101], v[88:89] op_sel:[1,0,0]
	v_cvt_f32_ubyte2_e32 v126, v172
	v_cvt_f32_ubyte3_e32 v127, v172
	v_pk_fma_f32 v[84:85], v[52:53], v[102:103], v[84:85] op_sel:[1,0,0]
	v_cvt_f32_ubyte0_e32 v96, v86
	v_cvt_f32_ubyte1_e32 v97, v86
	v_pk_fma_f32 v[80:81], v[52:53], v[126:127], v[80:81] op_sel:[1,0,0]
	v_and_b32_e32 v74, s34, v174
	v_and_b32_e32 v78, s34, v175
	v_cvt_f32_ubyte2_e32 v100, v86
	v_cvt_f32_ubyte3_e32 v101, v86
	v_pk_fma_f32 v[76:77], v[52:53], v[96:97], v[76:77] op_sel:[1,0,0]
	v_cvt_f32_ubyte0_e32 v102, v173
	v_cvt_f32_ubyte1_e32 v103, v173
	v_pk_fma_f32 v[68:69], v[52:53], v[100:101], v[68:69] op_sel:[1,0,0]
	v_cvt_f32_ubyte2_e32 v126, v173
	v_cvt_f32_ubyte3_e32 v127, v173
	v_pk_fma_f32 v[62:63], v[52:53], v[102:103], v[62:63] op_sel:[1,0,0]
	v_cvt_f32_ubyte0_e32 v96, v74
	v_cvt_f32_ubyte1_e32 v97, v74
	v_pk_fma_f32 v[60:61], v[52:53], v[126:127], v[60:61] op_sel:[1,0,0]
	v_cvt_f32_ubyte2_e32 v100, v74
	v_cvt_f32_ubyte3_e32 v101, v74
	v_pk_fma_f32 v[90:91], v[54:55], v[96:97], v[90:91] op_sel_hi:[0,1,1]
	v_cvt_f32_ubyte0_e32 v102, v174
	v_cvt_f32_ubyte1_e32 v103, v174
	v_pk_fma_f32 v[88:89], v[54:55], v[100:101], v[88:89] op_sel_hi:[0,1,1]
	v_cvt_f32_ubyte2_e32 v126, v174
	v_cvt_f32_ubyte3_e32 v127, v174
	v_pk_fma_f32 v[84:85], v[54:55], v[102:103], v[84:85] op_sel_hi:[0,1,1]
	v_cvt_f32_ubyte0_e32 v96, v78
	v_cvt_f32_ubyte1_e32 v97, v78
	v_pk_fma_f32 v[80:81], v[54:55], v[126:127], v[80:81] op_sel_hi:[0,1,1]
	v_and_b32_e32 v82, s34, v176
	v_and_b32_e32 v86, s34, v177
	v_cvt_f32_ubyte2_e32 v100, v78
	v_cvt_f32_ubyte3_e32 v101, v78
	v_pk_fma_f32 v[76:77], v[54:55], v[96:97], v[76:77] op_sel_hi:[0,1,1]
	v_cvt_f32_ubyte0_e32 v102, v175
	v_cvt_f32_ubyte1_e32 v103, v175
	v_pk_fma_f32 v[68:69], v[54:55], v[100:101], v[68:69] op_sel_hi:[0,1,1]
	v_cvt_f32_ubyte2_e32 v126, v175
	v_cvt_f32_ubyte3_e32 v127, v175
	v_pk_fma_f32 v[62:63], v[54:55], v[102:103], v[62:63] op_sel_hi:[0,1,1]
	v_cvt_f32_ubyte0_e32 v96, v82
	v_cvt_f32_ubyte1_e32 v97, v82
	v_pk_fma_f32 v[60:61], v[54:55], v[126:127], v[60:61] op_sel_hi:[0,1,1]
	v_cvt_f32_ubyte2_e32 v100, v82
	v_cvt_f32_ubyte3_e32 v101, v82
	v_pk_fma_f32 v[90:91], v[54:55], v[96:97], v[90:91] op_sel:[1,0,0]
	v_cvt_f32_ubyte0_e32 v102, v176
	v_cvt_f32_ubyte1_e32 v103, v176
	v_pk_fma_f32 v[88:89], v[54:55], v[100:101], v[88:89] op_sel:[1,0,0]
	v_cvt_f32_ubyte2_e32 v126, v176
	v_cvt_f32_ubyte3_e32 v127, v176
	v_pk_fma_f32 v[84:85], v[54:55], v[102:103], v[84:85] op_sel:[1,0,0]
	v_cvt_f32_ubyte0_e32 v96, v86
	v_cvt_f32_ubyte1_e32 v97, v86
	v_pk_fma_f32 v[80:81], v[54:55], v[126:127], v[80:81] op_sel:[1,0,0]
	v_cvt_f32_ubyte2_e32 v100, v86
	v_cvt_f32_ubyte3_e32 v101, v86
	v_pk_fma_f32 v[76:77], v[54:55], v[96:97], v[76:77] op_sel:[1,0,0]
	v_cvt_f32_ubyte0_e32 v102, v177
	v_cvt_f32_ubyte1_e32 v103, v177
	v_pk_fma_f32 v[68:69], v[54:55], v[100:101], v[68:69] op_sel:[1,0,0]
	v_cvt_f32_ubyte2_e32 v126, v177
	v_cvt_f32_ubyte3_e32 v127, v177
	v_pk_fma_f32 v[62:63], v[54:55], v[102:103], v[62:63] op_sel:[1,0,0]
	v_pk_fma_f32 v[60:61], v[54:55], v[126:127], v[60:61] op_sel:[1,0,0]
	s_waitcnt lgkmcnt(0)
	v_lshl_add_u32 v70, v70, 9, v98
	v_lshl_add_u32 v71, v71, 9, v98
	v_lshl_add_u32 v72, v72, 9, v98
	v_lshl_add_u32 v73, v73, 9, v98
	v_lshl_add_u32 v92, v92, 9, v98
	v_lshl_add_u32 v93, v93, 9, v98
	v_lshl_add_u32 v94, v94, 9, v98
	v_lshl_add_u32 v95, v95, 9, v98
	global_load_dwordx2 v[162:163], v70, s[36:37]
	global_load_dwordx2 v[164:165], v71, s[36:37]
	global_load_dwordx2 v[166:167], v72, s[36:37]
	global_load_dwordx2 v[168:169], v73, s[36:37]
	global_load_dwordx2 v[170:171], v92, s[36:37]
	global_load_dwordx2 v[172:173], v93, s[36:37]
	global_load_dwordx2 v[174:175], v94, s[36:37]
	global_load_dwordx2 v[176:177], v95, s[36:37]
	ds_read_b128 v[70:73], v128 offset:448
	ds_read_b128 v[92:95], v128 offset:464
	ds_read_b128 v[48:51], v128 offset:800
	ds_read_b128 v[52:55], v128 offset:816
	s_waitcnt vmcnt(40)
	v_and_b32_e32 v74, s34, v178
	v_and_b32_e32 v78, s34, v179
	v_cvt_f32_ubyte0_e32 v96, v74
	v_cvt_f32_ubyte1_e32 v97, v74
	v_cvt_f32_ubyte2_e32 v100, v74
	v_cvt_f32_ubyte3_e32 v101, v74
	v_pk_fma_f32 v[90:91], v[32:33], v[96:97], v[90:91] op_sel_hi:[0,1,1]
	v_cvt_f32_ubyte0_e32 v102, v178
	v_cvt_f32_ubyte1_e32 v103, v178
	v_pk_fma_f32 v[88:89], v[32:33], v[100:101], v[88:89] op_sel_hi:[0,1,1]
	v_cvt_f32_ubyte2_e32 v126, v178
	v_cvt_f32_ubyte3_e32 v127, v178
	v_pk_fma_f32 v[84:85], v[32:33], v[102:103], v[84:85] op_sel_hi:[0,1,1]
	v_cvt_f32_ubyte0_e32 v96, v78
	v_cvt_f32_ubyte1_e32 v97, v78
	v_pk_fma_f32 v[80:81], v[32:33], v[126:127], v[80:81] op_sel_hi:[0,1,1]
	v_and_b32_e32 v82, s34, v180
	v_and_b32_e32 v86, s34, v181
	v_cvt_f32_ubyte2_e32 v100, v78
	v_cvt_f32_ubyte3_e32 v101, v78
	v_pk_fma_f32 v[76:77], v[32:33], v[96:97], v[76:77] op_sel_hi:[0,1,1]
	v_cvt_f32_ubyte0_e32 v102, v179
	v_cvt_f32_ubyte1_e32 v103, v179
	v_pk_fma_f32 v[68:69], v[32:33], v[100:101], v[68:69] op_sel_hi:[0,1,1]
	v_cvt_f32_ubyte2_e32 v126, v179
	v_cvt_f32_ubyte3_e32 v127, v179
	v_pk_fma_f32 v[62:63], v[32:33], v[102:103], v[62:63] op_sel_hi:[0,1,1]
	v_cvt_f32_ubyte0_e32 v96, v82
	v_cvt_f32_ubyte1_e32 v97, v82
	v_pk_fma_f32 v[60:61], v[32:33], v[126:127], v[60:61] op_sel_hi:[0,1,1]
	v_cvt_f32_ubyte2_e32 v100, v82
	v_cvt_f32_ubyte3_e32 v101, v82
	v_pk_fma_f32 v[90:91], v[32:33], v[96:97], v[90:91] op_sel:[1,0,0]
	v_cvt_f32_ubyte0_e32 v102, v180
	v_cvt_f32_ubyte1_e32 v103, v180
	v_pk_fma_f32 v[88:89], v[32:33], v[100:101], v[88:89] op_sel:[1,0,0]
	v_cvt_f32_ubyte2_e32 v126, v180
	v_cvt_f32_ubyte3_e32 v127, v180
	v_pk_fma_f32 v[84:85], v[32:33], v[102:103], v[84:85] op_sel:[1,0,0]
	v_cvt_f32_ubyte0_e32 v96, v86
	v_cvt_f32_ubyte1_e32 v97, v86
	v_pk_fma_f32 v[80:81], v[32:33], v[126:127], v[80:81] op_sel:[1,0,0]
	v_and_b32_e32 v74, s34, v182
	v_and_b32_e32 v78, s34, v183
	v_cvt_f32_ubyte2_e32 v100, v86
	v_cvt_f32_ubyte3_e32 v101, v86
	v_pk_fma_f32 v[76:77], v[32:33], v[96:97], v[76:77] op_sel:[1,0,0]
	v_cvt_f32_ubyte0_e32 v102, v181
	v_cvt_f32_ubyte1_e32 v103, v181
	v_pk_fma_f32 v[68:69], v[32:33], v[100:101], v[68:69] op_sel:[1,0,0]
	v_cvt_f32_ubyte2_e32 v126, v181
	v_cvt_f32_ubyte3_e32 v127, v181
	v_pk_fma_f32 v[62:63], v[32:33], v[102:103], v[62:63] op_sel:[1,0,0]
	v_cvt_f32_ubyte0_e32 v96, v74
	v_cvt_f32_ubyte1_e32 v97, v74
	v_pk_fma_f32 v[60:61], v[32:33], v[126:127], v[60:61] op_sel:[1,0,0]
	v_cvt_f32_ubyte2_e32 v100, v74
	v_cvt_f32_ubyte3_e32 v101, v74
	v_pk_fma_f32 v[90:91], v[34:35], v[96:97], v[90:91] op_sel_hi:[0,1,1]
	v_cvt_f32_ubyte0_e32 v102, v182
	v_cvt_f32_ubyte1_e32 v103, v182
	v_pk_fma_f32 v[88:89], v[34:35], v[100:101], v[88:89] op_sel_hi:[0,1,1]
	v_cvt_f32_ubyte2_e32 v126, v182
	v_cvt_f32_ubyte3_e32 v127, v182
	v_pk_fma_f32 v[84:85], v[34:35], v[102:103], v[84:85] op_sel_hi:[0,1,1]
	v_cvt_f32_ubyte0_e32 v96, v78
	v_cvt_f32_ubyte1_e32 v97, v78
	v_pk_fma_f32 v[80:81], v[34:35], v[126:127], v[80:81] op_sel_hi:[0,1,1]
	v_and_b32_e32 v82, s34, v184
	v_and_b32_e32 v86, s34, v185
	v_cvt_f32_ubyte2_e32 v100, v78
	v_cvt_f32_ubyte3_e32 v101, v78
	v_pk_fma_f32 v[76:77], v[34:35], v[96:97], v[76:77] op_sel_hi:[0,1,1]
	v_cvt_f32_ubyte0_e32 v102, v183
	v_cvt_f32_ubyte1_e32 v103, v183
	v_pk_fma_f32 v[68:69], v[34:35], v[100:101], v[68:69] op_sel_hi:[0,1,1]
	v_cvt_f32_ubyte2_e32 v126, v183
	v_cvt_f32_ubyte3_e32 v127, v183
	v_pk_fma_f32 v[62:63], v[34:35], v[102:103], v[62:63] op_sel_hi:[0,1,1]
	v_cvt_f32_ubyte0_e32 v96, v82
	v_cvt_f32_ubyte1_e32 v97, v82
	v_pk_fma_f32 v[60:61], v[34:35], v[126:127], v[60:61] op_sel_hi:[0,1,1]
	v_cvt_f32_ubyte2_e32 v100, v82
	v_cvt_f32_ubyte3_e32 v101, v82
	v_pk_fma_f32 v[90:91], v[34:35], v[96:97], v[90:91] op_sel:[1,0,0]
	v_cvt_f32_ubyte0_e32 v102, v184
	v_cvt_f32_ubyte1_e32 v103, v184
	v_pk_fma_f32 v[88:89], v[34:35], v[100:101], v[88:89] op_sel:[1,0,0]
	v_cvt_f32_ubyte2_e32 v126, v184
	v_cvt_f32_ubyte3_e32 v127, v184
	v_pk_fma_f32 v[84:85], v[34:35], v[102:103], v[84:85] op_sel:[1,0,0]
	v_cvt_f32_ubyte0_e32 v96, v86
	v_cvt_f32_ubyte1_e32 v97, v86
	v_pk_fma_f32 v[80:81], v[34:35], v[126:127], v[80:81] op_sel:[1,0,0]
	v_and_b32_e32 v74, s34, v186
	v_and_b32_e32 v78, s34, v187
	v_cvt_f32_ubyte2_e32 v100, v86
	v_cvt_f32_ubyte3_e32 v101, v86
	v_pk_fma_f32 v[76:77], v[34:35], v[96:97], v[76:77] op_sel:[1,0,0]
	v_cvt_f32_ubyte0_e32 v102, v185
	v_cvt_f32_ubyte1_e32 v103, v185
	v_pk_fma_f32 v[68:69], v[34:35], v[100:101], v[68:69] op_sel:[1,0,0]
	v_cvt_f32_ubyte2_e32 v126, v185
	v_cvt_f32_ubyte3_e32 v127, v185
	v_pk_fma_f32 v[62:63], v[34:35], v[102:103], v[62:63] op_sel:[1,0,0]
	v_cvt_f32_ubyte0_e32 v96, v74
	v_cvt_f32_ubyte1_e32 v97, v74
	v_pk_fma_f32 v[60:61], v[34:35], v[126:127], v[60:61] op_sel:[1,0,0]
	v_cvt_f32_ubyte2_e32 v100, v74
	v_cvt_f32_ubyte3_e32 v101, v74
	v_pk_fma_f32 v[90:91], v[36:37], v[96:97], v[90:91] op_sel_hi:[0,1,1]
	v_cvt_f32_ubyte0_e32 v102, v186
	v_cvt_f32_ubyte1_e32 v103, v186
	v_pk_fma_f32 v[88:89], v[36:37], v[100:101], v[88:89] op_sel_hi:[0,1,1]
	v_cvt_f32_ubyte2_e32 v126, v186
	v_cvt_f32_ubyte3_e32 v127, v186
	v_pk_fma_f32 v[84:85], v[36:37], v[102:103], v[84:85] op_sel_hi:[0,1,1]
	v_cvt_f32_ubyte0_e32 v96, v78
	v_cvt_f32_ubyte1_e32 v97, v78
	v_pk_fma_f32 v[80:81], v[36:37], v[126:127], v[80:81] op_sel_hi:[0,1,1]
	v_and_b32_e32 v82, s34, v188
	v_and_b32_e32 v86, s34, v189
	v_cvt_f32_ubyte2_e32 v100, v78
	v_cvt_f32_ubyte3_e32 v101, v78
	v_pk_fma_f32 v[76:77], v[36:37], v[96:97], v[76:77] op_sel_hi:[0,1,1]
	v_cvt_f32_ubyte0_e32 v102, v187
	v_cvt_f32_ubyte1_e32 v103, v187
	v_pk_fma_f32 v[68:69], v[36:37], v[100:101], v[68:69] op_sel_hi:[0,1,1]
	v_cvt_f32_ubyte2_e32 v126, v187
	v_cvt_f32_ubyte3_e32 v127, v187
	v_pk_fma_f32 v[62:63], v[36:37], v[102:103], v[62:63] op_sel_hi:[0,1,1]
	v_cvt_f32_ubyte0_e32 v96, v82
	v_cvt_f32_ubyte1_e32 v97, v82
	v_pk_fma_f32 v[60:61], v[36:37], v[126:127], v[60:61] op_sel_hi:[0,1,1]
	v_cvt_f32_ubyte2_e32 v100, v82
	v_cvt_f32_ubyte3_e32 v101, v82
	v_pk_fma_f32 v[90:91], v[36:37], v[96:97], v[90:91] op_sel:[1,0,0]
	v_cvt_f32_ubyte0_e32 v102, v188
	v_cvt_f32_ubyte1_e32 v103, v188
	v_pk_fma_f32 v[88:89], v[36:37], v[100:101], v[88:89] op_sel:[1,0,0]
	v_cvt_f32_ubyte2_e32 v126, v188
	v_cvt_f32_ubyte3_e32 v127, v188
	v_pk_fma_f32 v[84:85], v[36:37], v[102:103], v[84:85] op_sel:[1,0,0]
	v_cvt_f32_ubyte0_e32 v96, v86
	v_cvt_f32_ubyte1_e32 v97, v86
	v_pk_fma_f32 v[80:81], v[36:37], v[126:127], v[80:81] op_sel:[1,0,0]
	v_and_b32_e32 v74, s34, v190
	v_and_b32_e32 v78, s34, v191
	v_cvt_f32_ubyte2_e32 v100, v86
	v_cvt_f32_ubyte3_e32 v101, v86
	v_pk_fma_f32 v[76:77], v[36:37], v[96:97], v[76:77] op_sel:[1,0,0]
	v_cvt_f32_ubyte0_e32 v102, v189
	v_cvt_f32_ubyte1_e32 v103, v189
	v_pk_fma_f32 v[68:69], v[36:37], v[100:101], v[68:69] op_sel:[1,0,0]
	v_cvt_f32_ubyte2_e32 v126, v189
	v_cvt_f32_ubyte3_e32 v127, v189
	v_pk_fma_f32 v[62:63], v[36:37], v[102:103], v[62:63] op_sel:[1,0,0]
	v_cvt_f32_ubyte0_e32 v96, v74
	v_cvt_f32_ubyte1_e32 v97, v74
	v_pk_fma_f32 v[60:61], v[36:37], v[126:127], v[60:61] op_sel:[1,0,0]
	v_cvt_f32_ubyte2_e32 v100, v74
	v_cvt_f32_ubyte3_e32 v101, v74
	v_pk_fma_f32 v[90:91], v[38:39], v[96:97], v[90:91] op_sel_hi:[0,1,1]
	v_cvt_f32_ubyte0_e32 v102, v190
	v_cvt_f32_ubyte1_e32 v103, v190
	v_pk_fma_f32 v[88:89], v[38:39], v[100:101], v[88:89] op_sel_hi:[0,1,1]
	v_cvt_f32_ubyte2_e32 v126, v190
	v_cvt_f32_ubyte3_e32 v127, v190
	v_pk_fma_f32 v[84:85], v[38:39], v[102:103], v[84:85] op_sel_hi:[0,1,1]
	v_cvt_f32_ubyte0_e32 v96, v78
	v_cvt_f32_ubyte1_e32 v97, v78
	v_pk_fma_f32 v[80:81], v[38:39], v[126:127], v[80:81] op_sel_hi:[0,1,1]
	v_and_b32_e32 v82, s34, v192
	v_and_b32_e32 v86, s34, v193
	v_cvt_f32_ubyte2_e32 v100, v78
	v_cvt_f32_ubyte3_e32 v101, v78
	v_pk_fma_f32 v[76:77], v[38:39], v[96:97], v[76:77] op_sel_hi:[0,1,1]
	v_cvt_f32_ubyte0_e32 v102, v191
	v_cvt_f32_ubyte1_e32 v103, v191
	v_pk_fma_f32 v[68:69], v[38:39], v[100:101], v[68:69] op_sel_hi:[0,1,1]
	v_cvt_f32_ubyte2_e32 v126, v191
	v_cvt_f32_ubyte3_e32 v127, v191
	v_pk_fma_f32 v[62:63], v[38:39], v[102:103], v[62:63] op_sel_hi:[0,1,1]
	v_cvt_f32_ubyte0_e32 v96, v82
	v_cvt_f32_ubyte1_e32 v97, v82
	v_pk_fma_f32 v[60:61], v[38:39], v[126:127], v[60:61] op_sel_hi:[0,1,1]
	v_cvt_f32_ubyte2_e32 v100, v82
	v_cvt_f32_ubyte3_e32 v101, v82
	v_pk_fma_f32 v[90:91], v[38:39], v[96:97], v[90:91] op_sel:[1,0,0]
	v_cvt_f32_ubyte0_e32 v102, v192
	v_cvt_f32_ubyte1_e32 v103, v192
	v_pk_fma_f32 v[88:89], v[38:39], v[100:101], v[88:89] op_sel:[1,0,0]
	v_cvt_f32_ubyte2_e32 v126, v192
	v_cvt_f32_ubyte3_e32 v127, v192
	v_pk_fma_f32 v[84:85], v[38:39], v[102:103], v[84:85] op_sel:[1,0,0]
	v_cvt_f32_ubyte0_e32 v96, v86
	v_cvt_f32_ubyte1_e32 v97, v86
	v_pk_fma_f32 v[80:81], v[38:39], v[126:127], v[80:81] op_sel:[1,0,0]
	v_cvt_f32_ubyte2_e32 v100, v86
	v_cvt_f32_ubyte3_e32 v101, v86
	v_pk_fma_f32 v[76:77], v[38:39], v[96:97], v[76:77] op_sel:[1,0,0]
	v_cvt_f32_ubyte0_e32 v102, v193
	v_cvt_f32_ubyte1_e32 v103, v193
	v_pk_fma_f32 v[68:69], v[38:39], v[100:101], v[68:69] op_sel:[1,0,0]
	v_cvt_f32_ubyte2_e32 v126, v193
	v_cvt_f32_ubyte3_e32 v127, v193
	v_pk_fma_f32 v[62:63], v[38:39], v[102:103], v[62:63] op_sel:[1,0,0]
	v_pk_fma_f32 v[60:61], v[38:39], v[126:127], v[60:61] op_sel:[1,0,0]
	s_waitcnt lgkmcnt(0)
	v_lshl_add_u32 v70, v70, 9, v98
	v_lshl_add_u32 v71, v71, 9, v98
	v_lshl_add_u32 v72, v72, 9, v98
	v_lshl_add_u32 v73, v73, 9, v98
	v_lshl_add_u32 v92, v92, 9, v98
	v_lshl_add_u32 v93, v93, 9, v98
	v_lshl_add_u32 v94, v94, 9, v98
	v_lshl_add_u32 v95, v95, 9, v98
	global_load_dwordx2 v[178:179], v70, s[36:37]
	global_load_dwordx2 v[180:181], v71, s[36:37]
	global_load_dwordx2 v[182:183], v72, s[36:37]
	global_load_dwordx2 v[184:185], v73, s[36:37]
	global_load_dwordx2 v[186:187], v92, s[36:37]
	global_load_dwordx2 v[188:189], v93, s[36:37]
	global_load_dwordx2 v[190:191], v94, s[36:37]
	global_load_dwordx2 v[192:193], v95, s[36:37]
	ds_read_b128 v[70:73], v128 offset:480
	ds_read_b128 v[92:95], v128 offset:496
	ds_read_b128 v[32:35], v128 offset:832
	ds_read_b128 v[36:39], v128 offset:848
	s_waitcnt vmcnt(40)
	v_and_b32_e32 v74, s34, v194
	v_and_b32_e32 v78, s34, v195
	v_cvt_f32_ubyte0_e32 v96, v74
	v_cvt_f32_ubyte1_e32 v97, v74
	v_cvt_f32_ubyte2_e32 v100, v74
	v_cvt_f32_ubyte3_e32 v101, v74
	v_pk_fma_f32 v[90:91], v[48:49], v[96:97], v[90:91] op_sel_hi:[0,1,1]
	v_cvt_f32_ubyte0_e32 v102, v194
	v_cvt_f32_ubyte1_e32 v103, v194
	v_pk_fma_f32 v[88:89], v[48:49], v[100:101], v[88:89] op_sel_hi:[0,1,1]
	v_cvt_f32_ubyte2_e32 v126, v194
	v_cvt_f32_ubyte3_e32 v127, v194
	v_pk_fma_f32 v[84:85], v[48:49], v[102:103], v[84:85] op_sel_hi:[0,1,1]
	v_cvt_f32_ubyte0_e32 v96, v78
	v_cvt_f32_ubyte1_e32 v97, v78
	v_pk_fma_f32 v[80:81], v[48:49], v[126:127], v[80:81] op_sel_hi:[0,1,1]
	v_and_b32_e32 v82, s34, v196
	v_and_b32_e32 v86, s34, v197
	v_cvt_f32_ubyte2_e32 v100, v78
	v_cvt_f32_ubyte3_e32 v101, v78
	v_pk_fma_f32 v[76:77], v[48:49], v[96:97], v[76:77] op_sel_hi:[0,1,1]
	v_cvt_f32_ubyte0_e32 v102, v195
	v_cvt_f32_ubyte1_e32 v103, v195
	v_pk_fma_f32 v[68:69], v[48:49], v[100:101], v[68:69] op_sel_hi:[0,1,1]
	v_cvt_f32_ubyte2_e32 v126, v195
	v_cvt_f32_ubyte3_e32 v127, v195
	v_pk_fma_f32 v[62:63], v[48:49], v[102:103], v[62:63] op_sel_hi:[0,1,1]
	v_cvt_f32_ubyte0_e32 v96, v82
	v_cvt_f32_ubyte1_e32 v97, v82
	v_pk_fma_f32 v[60:61], v[48:49], v[126:127], v[60:61] op_sel_hi:[0,1,1]
	v_cvt_f32_ubyte2_e32 v100, v82
	v_cvt_f32_ubyte3_e32 v101, v82
	v_pk_fma_f32 v[90:91], v[48:49], v[96:97], v[90:91] op_sel:[1,0,0]
	v_cvt_f32_ubyte0_e32 v102, v196
	v_cvt_f32_ubyte1_e32 v103, v196
	v_pk_fma_f32 v[88:89], v[48:49], v[100:101], v[88:89] op_sel:[1,0,0]
	v_cvt_f32_ubyte2_e32 v126, v196
	v_cvt_f32_ubyte3_e32 v127, v196
	v_pk_fma_f32 v[84:85], v[48:49], v[102:103], v[84:85] op_sel:[1,0,0]
	v_cvt_f32_ubyte0_e32 v96, v86
	v_cvt_f32_ubyte1_e32 v97, v86
	v_pk_fma_f32 v[80:81], v[48:49], v[126:127], v[80:81] op_sel:[1,0,0]
	v_and_b32_e32 v74, s34, v198
	v_and_b32_e32 v78, s34, v199
	v_cvt_f32_ubyte2_e32 v100, v86
	v_cvt_f32_ubyte3_e32 v101, v86
	v_pk_fma_f32 v[76:77], v[48:49], v[96:97], v[76:77] op_sel:[1,0,0]
	v_cvt_f32_ubyte0_e32 v102, v197
	v_cvt_f32_ubyte1_e32 v103, v197
	v_pk_fma_f32 v[68:69], v[48:49], v[100:101], v[68:69] op_sel:[1,0,0]
	v_cvt_f32_ubyte2_e32 v126, v197
	v_cvt_f32_ubyte3_e32 v127, v197
	v_pk_fma_f32 v[62:63], v[48:49], v[102:103], v[62:63] op_sel:[1,0,0]
	v_cvt_f32_ubyte0_e32 v96, v74
	v_cvt_f32_ubyte1_e32 v97, v74
	v_pk_fma_f32 v[60:61], v[48:49], v[126:127], v[60:61] op_sel:[1,0,0]
	v_cvt_f32_ubyte2_e32 v100, v74
	v_cvt_f32_ubyte3_e32 v101, v74
	v_pk_fma_f32 v[90:91], v[50:51], v[96:97], v[90:91] op_sel_hi:[0,1,1]
	v_cvt_f32_ubyte0_e32 v102, v198
	v_cvt_f32_ubyte1_e32 v103, v198
	v_pk_fma_f32 v[88:89], v[50:51], v[100:101], v[88:89] op_sel_hi:[0,1,1]
	v_cvt_f32_ubyte2_e32 v126, v198
	v_cvt_f32_ubyte3_e32 v127, v198
	v_pk_fma_f32 v[84:85], v[50:51], v[102:103], v[84:85] op_sel_hi:[0,1,1]
	v_cvt_f32_ubyte0_e32 v96, v78
	v_cvt_f32_ubyte1_e32 v97, v78
	v_pk_fma_f32 v[80:81], v[50:51], v[126:127], v[80:81] op_sel_hi:[0,1,1]
	v_and_b32_e32 v82, s34, v200
	v_and_b32_e32 v86, s34, v201
	v_cvt_f32_ubyte2_e32 v100, v78
	v_cvt_f32_ubyte3_e32 v101, v78
	v_pk_fma_f32 v[76:77], v[50:51], v[96:97], v[76:77] op_sel_hi:[0,1,1]
	v_cvt_f32_ubyte0_e32 v102, v199
	v_cvt_f32_ubyte1_e32 v103, v199
	v_pk_fma_f32 v[68:69], v[50:51], v[100:101], v[68:69] op_sel_hi:[0,1,1]
	v_cvt_f32_ubyte2_e32 v126, v199
	v_cvt_f32_ubyte3_e32 v127, v199
	v_pk_fma_f32 v[62:63], v[50:51], v[102:103], v[62:63] op_sel_hi:[0,1,1]
	v_cvt_f32_ubyte0_e32 v96, v82
	v_cvt_f32_ubyte1_e32 v97, v82
	v_pk_fma_f32 v[60:61], v[50:51], v[126:127], v[60:61] op_sel_hi:[0,1,1]
	v_cvt_f32_ubyte2_e32 v100, v82
	v_cvt_f32_ubyte3_e32 v101, v82
	v_pk_fma_f32 v[90:91], v[50:51], v[96:97], v[90:91] op_sel:[1,0,0]
	v_cvt_f32_ubyte0_e32 v102, v200
	v_cvt_f32_ubyte1_e32 v103, v200
	v_pk_fma_f32 v[88:89], v[50:51], v[100:101], v[88:89] op_sel:[1,0,0]
	v_cvt_f32_ubyte2_e32 v126, v200
	v_cvt_f32_ubyte3_e32 v127, v200
	v_pk_fma_f32 v[84:85], v[50:51], v[102:103], v[84:85] op_sel:[1,0,0]
	v_cvt_f32_ubyte0_e32 v96, v86
	v_cvt_f32_ubyte1_e32 v97, v86
	v_pk_fma_f32 v[80:81], v[50:51], v[126:127], v[80:81] op_sel:[1,0,0]
	v_and_b32_e32 v74, s34, v202
	v_and_b32_e32 v78, s34, v203
	v_cvt_f32_ubyte2_e32 v100, v86
	v_cvt_f32_ubyte3_e32 v101, v86
	v_pk_fma_f32 v[76:77], v[50:51], v[96:97], v[76:77] op_sel:[1,0,0]
	v_cvt_f32_ubyte0_e32 v102, v201
	v_cvt_f32_ubyte1_e32 v103, v201
	v_pk_fma_f32 v[68:69], v[50:51], v[100:101], v[68:69] op_sel:[1,0,0]
	v_cvt_f32_ubyte2_e32 v126, v201
	v_cvt_f32_ubyte3_e32 v127, v201
	v_pk_fma_f32 v[62:63], v[50:51], v[102:103], v[62:63] op_sel:[1,0,0]
	v_cvt_f32_ubyte0_e32 v96, v74
	v_cvt_f32_ubyte1_e32 v97, v74
	v_pk_fma_f32 v[60:61], v[50:51], v[126:127], v[60:61] op_sel:[1,0,0]
	v_cvt_f32_ubyte2_e32 v100, v74
	v_cvt_f32_ubyte3_e32 v101, v74
	v_pk_fma_f32 v[90:91], v[52:53], v[96:97], v[90:91] op_sel_hi:[0,1,1]
	v_cvt_f32_ubyte0_e32 v102, v202
	v_cvt_f32_ubyte1_e32 v103, v202
	v_pk_fma_f32 v[88:89], v[52:53], v[100:101], v[88:89] op_sel_hi:[0,1,1]
	v_cvt_f32_ubyte2_e32 v126, v202
	v_cvt_f32_ubyte3_e32 v127, v202
	v_pk_fma_f32 v[84:85], v[52:53], v[102:103], v[84:85] op_sel_hi:[0,1,1]
	v_cvt_f32_ubyte0_e32 v96, v78
	v_cvt_f32_ubyte1_e32 v97, v78
	v_pk_fma_f32 v[80:81], v[52:53], v[126:127], v[80:81] op_sel_hi:[0,1,1]
	v_and_b32_e32 v82, s34, v204
	v_and_b32_e32 v86, s34, v205
	v_cvt_f32_ubyte2_e32 v100, v78
	v_cvt_f32_ubyte3_e32 v101, v78
	v_pk_fma_f32 v[76:77], v[52:53], v[96:97], v[76:77] op_sel_hi:[0,1,1]
	v_cvt_f32_ubyte0_e32 v102, v203
	v_cvt_f32_ubyte1_e32 v103, v203
	v_pk_fma_f32 v[68:69], v[52:53], v[100:101], v[68:69] op_sel_hi:[0,1,1]
	v_cvt_f32_ubyte2_e32 v126, v203
	v_cvt_f32_ubyte3_e32 v127, v203
	v_pk_fma_f32 v[62:63], v[52:53], v[102:103], v[62:63] op_sel_hi:[0,1,1]
	v_cvt_f32_ubyte0_e32 v96, v82
	v_cvt_f32_ubyte1_e32 v97, v82
	v_pk_fma_f32 v[60:61], v[52:53], v[126:127], v[60:61] op_sel_hi:[0,1,1]
	v_cvt_f32_ubyte2_e32 v100, v82
	v_cvt_f32_ubyte3_e32 v101, v82
	v_pk_fma_f32 v[90:91], v[52:53], v[96:97], v[90:91] op_sel:[1,0,0]
	v_cvt_f32_ubyte0_e32 v102, v204
	v_cvt_f32_ubyte1_e32 v103, v204
	v_pk_fma_f32 v[88:89], v[52:53], v[100:101], v[88:89] op_sel:[1,0,0]
	v_cvt_f32_ubyte2_e32 v126, v204
	v_cvt_f32_ubyte3_e32 v127, v204
	v_pk_fma_f32 v[84:85], v[52:53], v[102:103], v[84:85] op_sel:[1,0,0]
	v_cvt_f32_ubyte0_e32 v96, v86
	v_cvt_f32_ubyte1_e32 v97, v86
	v_pk_fma_f32 v[80:81], v[52:53], v[126:127], v[80:81] op_sel:[1,0,0]
	v_and_b32_e32 v74, s34, v206
	v_and_b32_e32 v78, s34, v207
	v_cvt_f32_ubyte2_e32 v100, v86
	v_cvt_f32_ubyte3_e32 v101, v86
	v_pk_fma_f32 v[76:77], v[52:53], v[96:97], v[76:77] op_sel:[1,0,0]
	v_cvt_f32_ubyte0_e32 v102, v205
	v_cvt_f32_ubyte1_e32 v103, v205
	v_pk_fma_f32 v[68:69], v[52:53], v[100:101], v[68:69] op_sel:[1,0,0]
	v_cvt_f32_ubyte2_e32 v126, v205
	v_cvt_f32_ubyte3_e32 v127, v205
	v_pk_fma_f32 v[62:63], v[52:53], v[102:103], v[62:63] op_sel:[1,0,0]
	v_cvt_f32_ubyte0_e32 v96, v74
	v_cvt_f32_ubyte1_e32 v97, v74
	v_pk_fma_f32 v[60:61], v[52:53], v[126:127], v[60:61] op_sel:[1,0,0]
	v_cvt_f32_ubyte2_e32 v100, v74
	v_cvt_f32_ubyte3_e32 v101, v74
	v_pk_fma_f32 v[90:91], v[54:55], v[96:97], v[90:91] op_sel_hi:[0,1,1]
	v_cvt_f32_ubyte0_e32 v102, v206
	v_cvt_f32_ubyte1_e32 v103, v206
	v_pk_fma_f32 v[88:89], v[54:55], v[100:101], v[88:89] op_sel_hi:[0,1,1]
	v_cvt_f32_ubyte2_e32 v126, v206
	v_cvt_f32_ubyte3_e32 v127, v206
	v_pk_fma_f32 v[84:85], v[54:55], v[102:103], v[84:85] op_sel_hi:[0,1,1]
	v_cvt_f32_ubyte0_e32 v96, v78
	v_cvt_f32_ubyte1_e32 v97, v78
	v_pk_fma_f32 v[80:81], v[54:55], v[126:127], v[80:81] op_sel_hi:[0,1,1]
	v_and_b32_e32 v82, s34, v208
	v_and_b32_e32 v86, s34, v209
	v_cvt_f32_ubyte2_e32 v100, v78
	v_cvt_f32_ubyte3_e32 v101, v78
	v_pk_fma_f32 v[76:77], v[54:55], v[96:97], v[76:77] op_sel_hi:[0,1,1]
	v_cvt_f32_ubyte0_e32 v102, v207
	v_cvt_f32_ubyte1_e32 v103, v207
	v_pk_fma_f32 v[68:69], v[54:55], v[100:101], v[68:69] op_sel_hi:[0,1,1]
	v_cvt_f32_ubyte2_e32 v126, v207
	v_cvt_f32_ubyte3_e32 v127, v207
	v_pk_fma_f32 v[62:63], v[54:55], v[102:103], v[62:63] op_sel_hi:[0,1,1]
	v_cvt_f32_ubyte0_e32 v96, v82
	v_cvt_f32_ubyte1_e32 v97, v82
	v_pk_fma_f32 v[60:61], v[54:55], v[126:127], v[60:61] op_sel_hi:[0,1,1]
	v_cvt_f32_ubyte2_e32 v100, v82
	v_cvt_f32_ubyte3_e32 v101, v82
	v_pk_fma_f32 v[90:91], v[54:55], v[96:97], v[90:91] op_sel:[1,0,0]
	v_cvt_f32_ubyte0_e32 v102, v208
	v_cvt_f32_ubyte1_e32 v103, v208
	v_pk_fma_f32 v[88:89], v[54:55], v[100:101], v[88:89] op_sel:[1,0,0]
	v_cvt_f32_ubyte2_e32 v126, v208
	v_cvt_f32_ubyte3_e32 v127, v208
	v_pk_fma_f32 v[84:85], v[54:55], v[102:103], v[84:85] op_sel:[1,0,0]
	v_cvt_f32_ubyte0_e32 v96, v86
	v_cvt_f32_ubyte1_e32 v97, v86
	v_pk_fma_f32 v[80:81], v[54:55], v[126:127], v[80:81] op_sel:[1,0,0]
	v_cvt_f32_ubyte2_e32 v100, v86
	v_cvt_f32_ubyte3_e32 v101, v86
	v_pk_fma_f32 v[76:77], v[54:55], v[96:97], v[76:77] op_sel:[1,0,0]
	v_cvt_f32_ubyte0_e32 v102, v209
	v_cvt_f32_ubyte1_e32 v103, v209
	v_pk_fma_f32 v[68:69], v[54:55], v[100:101], v[68:69] op_sel:[1,0,0]
	v_cvt_f32_ubyte2_e32 v126, v209
	v_cvt_f32_ubyte3_e32 v127, v209
	v_pk_fma_f32 v[62:63], v[54:55], v[102:103], v[62:63] op_sel:[1,0,0]
	v_pk_fma_f32 v[60:61], v[54:55], v[126:127], v[60:61] op_sel:[1,0,0]
	s_waitcnt lgkmcnt(0)
	v_lshl_add_u32 v70, v70, 9, v98
	v_lshl_add_u32 v71, v71, 9, v98
	v_lshl_add_u32 v72, v72, 9, v98
	v_lshl_add_u32 v73, v73, 9, v98
	v_lshl_add_u32 v92, v92, 9, v98
	v_lshl_add_u32 v93, v93, 9, v98
	v_lshl_add_u32 v94, v94, 9, v98
	v_lshl_add_u32 v95, v95, 9, v98
	global_load_dwordx2 v[194:195], v70, s[36:37]
	global_load_dwordx2 v[196:197], v71, s[36:37]
	global_load_dwordx2 v[198:199], v72, s[36:37]
	global_load_dwordx2 v[200:201], v73, s[36:37]
	global_load_dwordx2 v[202:203], v92, s[36:37]
	global_load_dwordx2 v[204:205], v93, s[36:37]
	global_load_dwordx2 v[206:207], v94, s[36:37]
	global_load_dwordx2 v[208:209], v95, s[36:37]
	ds_read_b128 v[48:51], v128 offset:864
	ds_read_b128 v[52:55], v128 offset:880
	s_waitcnt vmcnt(40)
	v_and_b32_e32 v74, s34, v0
	v_and_b32_e32 v78, s34, v1
	v_cvt_f32_ubyte0_e32 v96, v74
	v_cvt_f32_ubyte1_e32 v97, v74
	v_cvt_f32_ubyte2_e32 v100, v74
	v_cvt_f32_ubyte3_e32 v101, v74
	v_pk_fma_f32 v[90:91], v[32:33], v[96:97], v[90:91] op_sel_hi:[0,1,1]
	v_cvt_f32_ubyte0_e32 v102, v0
	v_cvt_f32_ubyte1_e32 v103, v0
	v_pk_fma_f32 v[88:89], v[32:33], v[100:101], v[88:89] op_sel_hi:[0,1,1]
	v_cvt_f32_ubyte2_e32 v126, v0
	v_cvt_f32_ubyte3_e32 v127, v0
	v_pk_fma_f32 v[84:85], v[32:33], v[102:103], v[84:85] op_sel_hi:[0,1,1]
	v_cvt_f32_ubyte0_e32 v96, v78
	v_cvt_f32_ubyte1_e32 v97, v78
	v_pk_fma_f32 v[80:81], v[32:33], v[126:127], v[80:81] op_sel_hi:[0,1,1]
	v_and_b32_e32 v82, s34, v2
	v_and_b32_e32 v86, s34, v3
	v_cvt_f32_ubyte2_e32 v100, v78
	v_cvt_f32_ubyte3_e32 v101, v78
	v_pk_fma_f32 v[76:77], v[32:33], v[96:97], v[76:77] op_sel_hi:[0,1,1]
	v_cvt_f32_ubyte0_e32 v102, v1
	v_cvt_f32_ubyte1_e32 v103, v1
	v_pk_fma_f32 v[68:69], v[32:33], v[100:101], v[68:69] op_sel_hi:[0,1,1]
	v_cvt_f32_ubyte2_e32 v126, v1
	v_cvt_f32_ubyte3_e32 v127, v1
	v_pk_fma_f32 v[62:63], v[32:33], v[102:103], v[62:63] op_sel_hi:[0,1,1]
	v_cvt_f32_ubyte0_e32 v96, v82
	v_cvt_f32_ubyte1_e32 v97, v82
	v_pk_fma_f32 v[60:61], v[32:33], v[126:127], v[60:61] op_sel_hi:[0,1,1]
	v_cvt_f32_ubyte2_e32 v100, v82
	v_cvt_f32_ubyte3_e32 v101, v82
	v_pk_fma_f32 v[90:91], v[32:33], v[96:97], v[90:91] op_sel:[1,0,0]
	v_cvt_f32_ubyte0_e32 v102, v2
	v_cvt_f32_ubyte1_e32 v103, v2
	v_pk_fma_f32 v[88:89], v[32:33], v[100:101], v[88:89] op_sel:[1,0,0]
	v_cvt_f32_ubyte2_e32 v126, v2
	v_cvt_f32_ubyte3_e32 v127, v2
	v_pk_fma_f32 v[84:85], v[32:33], v[102:103], v[84:85] op_sel:[1,0,0]
	v_cvt_f32_ubyte0_e32 v96, v86
	v_cvt_f32_ubyte1_e32 v97, v86
	v_pk_fma_f32 v[80:81], v[32:33], v[126:127], v[80:81] op_sel:[1,0,0]
	v_and_b32_e32 v74, s34, v4
	v_and_b32_e32 v78, s34, v5
	v_cvt_f32_ubyte2_e32 v100, v86
	v_cvt_f32_ubyte3_e32 v101, v86
	v_pk_fma_f32 v[76:77], v[32:33], v[96:97], v[76:77] op_sel:[1,0,0]
	v_cvt_f32_ubyte0_e32 v102, v3
	v_cvt_f32_ubyte1_e32 v103, v3
	v_pk_fma_f32 v[68:69], v[32:33], v[100:101], v[68:69] op_sel:[1,0,0]
	v_cvt_f32_ubyte2_e32 v126, v3
	v_cvt_f32_ubyte3_e32 v127, v3
	v_pk_fma_f32 v[62:63], v[32:33], v[102:103], v[62:63] op_sel:[1,0,0]
	v_cvt_f32_ubyte0_e32 v96, v74
	v_cvt_f32_ubyte1_e32 v97, v74
	v_pk_fma_f32 v[60:61], v[32:33], v[126:127], v[60:61] op_sel:[1,0,0]
	v_cvt_f32_ubyte2_e32 v100, v74
	v_cvt_f32_ubyte3_e32 v101, v74
	v_pk_fma_f32 v[90:91], v[34:35], v[96:97], v[90:91] op_sel_hi:[0,1,1]
	v_cvt_f32_ubyte0_e32 v102, v4
	v_cvt_f32_ubyte1_e32 v103, v4
	v_pk_fma_f32 v[88:89], v[34:35], v[100:101], v[88:89] op_sel_hi:[0,1,1]
	v_cvt_f32_ubyte2_e32 v126, v4
	v_cvt_f32_ubyte3_e32 v127, v4
	v_pk_fma_f32 v[84:85], v[34:35], v[102:103], v[84:85] op_sel_hi:[0,1,1]
	v_cvt_f32_ubyte0_e32 v96, v78
	v_cvt_f32_ubyte1_e32 v97, v78
	v_pk_fma_f32 v[80:81], v[34:35], v[126:127], v[80:81] op_sel_hi:[0,1,1]
	v_and_b32_e32 v82, s34, v6
	v_and_b32_e32 v86, s34, v7
	v_cvt_f32_ubyte2_e32 v100, v78
	v_cvt_f32_ubyte3_e32 v101, v78
	v_pk_fma_f32 v[76:77], v[34:35], v[96:97], v[76:77] op_sel_hi:[0,1,1]
	v_cvt_f32_ubyte0_e32 v102, v5
	v_cvt_f32_ubyte1_e32 v103, v5
	v_pk_fma_f32 v[68:69], v[34:35], v[100:101], v[68:69] op_sel_hi:[0,1,1]
	v_cvt_f32_ubyte2_e32 v126, v5
	v_cvt_f32_ubyte3_e32 v127, v5
	v_pk_fma_f32 v[62:63], v[34:35], v[102:103], v[62:63] op_sel_hi:[0,1,1]
	v_cvt_f32_ubyte0_e32 v96, v82
	v_cvt_f32_ubyte1_e32 v97, v82
	v_pk_fma_f32 v[60:61], v[34:35], v[126:127], v[60:61] op_sel_hi:[0,1,1]
	v_cvt_f32_ubyte2_e32 v100, v82
	v_cvt_f32_ubyte3_e32 v101, v82
	v_pk_fma_f32 v[90:91], v[34:35], v[96:97], v[90:91] op_sel:[1,0,0]
	v_cvt_f32_ubyte0_e32 v102, v6
	v_cvt_f32_ubyte1_e32 v103, v6
	v_pk_fma_f32 v[88:89], v[34:35], v[100:101], v[88:89] op_sel:[1,0,0]
	v_cvt_f32_ubyte2_e32 v126, v6
	v_cvt_f32_ubyte3_e32 v127, v6
	v_pk_fma_f32 v[84:85], v[34:35], v[102:103], v[84:85] op_sel:[1,0,0]
	v_cvt_f32_ubyte0_e32 v96, v86
	v_cvt_f32_ubyte1_e32 v97, v86
	v_pk_fma_f32 v[80:81], v[34:35], v[126:127], v[80:81] op_sel:[1,0,0]
	v_and_b32_e32 v74, s34, v8
	v_and_b32_e32 v78, s34, v9
	v_cvt_f32_ubyte2_e32 v100, v86
	v_cvt_f32_ubyte3_e32 v101, v86
	v_pk_fma_f32 v[76:77], v[34:35], v[96:97], v[76:77] op_sel:[1,0,0]
	v_cvt_f32_ubyte0_e32 v102, v7
	v_cvt_f32_ubyte1_e32 v103, v7
	v_pk_fma_f32 v[68:69], v[34:35], v[100:101], v[68:69] op_sel:[1,0,0]
	v_cvt_f32_ubyte2_e32 v126, v7
	v_cvt_f32_ubyte3_e32 v127, v7
	v_pk_fma_f32 v[62:63], v[34:35], v[102:103], v[62:63] op_sel:[1,0,0]
	v_cvt_f32_ubyte0_e32 v96, v74
	v_cvt_f32_ubyte1_e32 v97, v74
	v_pk_fma_f32 v[60:61], v[34:35], v[126:127], v[60:61] op_sel:[1,0,0]
	v_cvt_f32_ubyte2_e32 v100, v74
	v_cvt_f32_ubyte3_e32 v101, v74
	v_pk_fma_f32 v[90:91], v[36:37], v[96:97], v[90:91] op_sel_hi:[0,1,1]
	v_cvt_f32_ubyte0_e32 v102, v8
	v_cvt_f32_ubyte1_e32 v103, v8
	v_pk_fma_f32 v[88:89], v[36:37], v[100:101], v[88:89] op_sel_hi:[0,1,1]
	v_cvt_f32_ubyte2_e32 v126, v8
	v_cvt_f32_ubyte3_e32 v127, v8
	v_pk_fma_f32 v[84:85], v[36:37], v[102:103], v[84:85] op_sel_hi:[0,1,1]
	v_cvt_f32_ubyte0_e32 v96, v78
	v_cvt_f32_ubyte1_e32 v97, v78
	v_pk_fma_f32 v[80:81], v[36:37], v[126:127], v[80:81] op_sel_hi:[0,1,1]
	v_and_b32_e32 v82, s34, v10
	v_and_b32_e32 v86, s34, v11
	v_cvt_f32_ubyte2_e32 v100, v78
	v_cvt_f32_ubyte3_e32 v101, v78
	v_pk_fma_f32 v[76:77], v[36:37], v[96:97], v[76:77] op_sel_hi:[0,1,1]
	v_cvt_f32_ubyte0_e32 v102, v9
	v_cvt_f32_ubyte1_e32 v103, v9
	v_pk_fma_f32 v[68:69], v[36:37], v[100:101], v[68:69] op_sel_hi:[0,1,1]
	v_cvt_f32_ubyte2_e32 v126, v9
	v_cvt_f32_ubyte3_e32 v127, v9
	v_pk_fma_f32 v[62:63], v[36:37], v[102:103], v[62:63] op_sel_hi:[0,1,1]
	v_cvt_f32_ubyte0_e32 v96, v82
	v_cvt_f32_ubyte1_e32 v97, v82
	v_pk_fma_f32 v[60:61], v[36:37], v[126:127], v[60:61] op_sel_hi:[0,1,1]
	v_cvt_f32_ubyte2_e32 v100, v82
	v_cvt_f32_ubyte3_e32 v101, v82
	v_pk_fma_f32 v[90:91], v[36:37], v[96:97], v[90:91] op_sel:[1,0,0]
	v_cvt_f32_ubyte0_e32 v102, v10
	v_cvt_f32_ubyte1_e32 v103, v10
	v_pk_fma_f32 v[88:89], v[36:37], v[100:101], v[88:89] op_sel:[1,0,0]
	v_cvt_f32_ubyte2_e32 v126, v10
	v_cvt_f32_ubyte3_e32 v127, v10
	v_pk_fma_f32 v[84:85], v[36:37], v[102:103], v[84:85] op_sel:[1,0,0]
	v_cvt_f32_ubyte0_e32 v96, v86
	v_cvt_f32_ubyte1_e32 v97, v86
	v_pk_fma_f32 v[80:81], v[36:37], v[126:127], v[80:81] op_sel:[1,0,0]
	v_and_b32_e32 v74, s34, v12
	v_and_b32_e32 v78, s34, v13
	v_cvt_f32_ubyte2_e32 v100, v86
	v_cvt_f32_ubyte3_e32 v101, v86
	v_pk_fma_f32 v[76:77], v[36:37], v[96:97], v[76:77] op_sel:[1,0,0]
	v_cvt_f32_ubyte0_e32 v102, v11
	v_cvt_f32_ubyte1_e32 v103, v11
	v_pk_fma_f32 v[68:69], v[36:37], v[100:101], v[68:69] op_sel:[1,0,0]
	v_cvt_f32_ubyte2_e32 v126, v11
	v_cvt_f32_ubyte3_e32 v127, v11
	v_pk_fma_f32 v[62:63], v[36:37], v[102:103], v[62:63] op_sel:[1,0,0]
	v_cvt_f32_ubyte0_e32 v96, v74
	v_cvt_f32_ubyte1_e32 v97, v74
	v_pk_fma_f32 v[60:61], v[36:37], v[126:127], v[60:61] op_sel:[1,0,0]
	v_cvt_f32_ubyte2_e32 v100, v74
	v_cvt_f32_ubyte3_e32 v101, v74
	v_pk_fma_f32 v[90:91], v[38:39], v[96:97], v[90:91] op_sel_hi:[0,1,1]
	v_cvt_f32_ubyte0_e32 v102, v12
	v_cvt_f32_ubyte1_e32 v103, v12
	v_pk_fma_f32 v[88:89], v[38:39], v[100:101], v[88:89] op_sel_hi:[0,1,1]
	v_cvt_f32_ubyte2_e32 v126, v12
	v_cvt_f32_ubyte3_e32 v127, v12
	v_pk_fma_f32 v[84:85], v[38:39], v[102:103], v[84:85] op_sel_hi:[0,1,1]
	v_cvt_f32_ubyte0_e32 v96, v78
	v_cvt_f32_ubyte1_e32 v97, v78
	v_pk_fma_f32 v[80:81], v[38:39], v[126:127], v[80:81] op_sel_hi:[0,1,1]
	v_and_b32_e32 v82, s34, v14
	v_and_b32_e32 v86, s34, v15
	v_cvt_f32_ubyte2_e32 v100, v78
	v_cvt_f32_ubyte3_e32 v101, v78
	v_pk_fma_f32 v[76:77], v[38:39], v[96:97], v[76:77] op_sel_hi:[0,1,1]
	v_cvt_f32_ubyte0_e32 v102, v13
	v_cvt_f32_ubyte1_e32 v103, v13
	v_pk_fma_f32 v[68:69], v[38:39], v[100:101], v[68:69] op_sel_hi:[0,1,1]
	v_cvt_f32_ubyte2_e32 v126, v13
	v_cvt_f32_ubyte3_e32 v127, v13
	v_pk_fma_f32 v[62:63], v[38:39], v[102:103], v[62:63] op_sel_hi:[0,1,1]
	v_cvt_f32_ubyte0_e32 v96, v82
	v_cvt_f32_ubyte1_e32 v97, v82
	v_pk_fma_f32 v[60:61], v[38:39], v[126:127], v[60:61] op_sel_hi:[0,1,1]
	v_cvt_f32_ubyte2_e32 v100, v82
	v_cvt_f32_ubyte3_e32 v101, v82
	v_pk_fma_f32 v[90:91], v[38:39], v[96:97], v[90:91] op_sel:[1,0,0]
	v_cvt_f32_ubyte0_e32 v102, v14
	v_cvt_f32_ubyte1_e32 v103, v14
	v_pk_fma_f32 v[88:89], v[38:39], v[100:101], v[88:89] op_sel:[1,0,0]
	v_cvt_f32_ubyte2_e32 v126, v14
	v_cvt_f32_ubyte3_e32 v127, v14
	v_pk_fma_f32 v[84:85], v[38:39], v[102:103], v[84:85] op_sel:[1,0,0]
	v_cvt_f32_ubyte0_e32 v96, v86
	v_cvt_f32_ubyte1_e32 v97, v86
	v_pk_fma_f32 v[80:81], v[38:39], v[126:127], v[80:81] op_sel:[1,0,0]
	v_cvt_f32_ubyte2_e32 v100, v86
	v_cvt_f32_ubyte3_e32 v101, v86
	v_pk_fma_f32 v[76:77], v[38:39], v[96:97], v[76:77] op_sel:[1,0,0]
	v_cvt_f32_ubyte0_e32 v102, v15
	v_cvt_f32_ubyte1_e32 v103, v15
	v_pk_fma_f32 v[68:69], v[38:39], v[100:101], v[68:69] op_sel:[1,0,0]
	v_cvt_f32_ubyte2_e32 v126, v15
	v_cvt_f32_ubyte3_e32 v127, v15
	v_pk_fma_f32 v[62:63], v[38:39], v[102:103], v[62:63] op_sel:[1,0,0]
	v_pk_fma_f32 v[60:61], v[38:39], v[126:127], v[60:61] op_sel:[1,0,0]
	s_waitcnt lgkmcnt(0)
	ds_read_b128 v[32:35], v128 offset:896
	ds_read_b128 v[36:39], v128 offset:912
	s_waitcnt vmcnt(32)
	v_and_b32_e32 v74, s34, v16
	v_and_b32_e32 v78, s34, v17
	v_cvt_f32_ubyte0_e32 v96, v74
	v_cvt_f32_ubyte1_e32 v97, v74
	v_cvt_f32_ubyte2_e32 v100, v74
	v_cvt_f32_ubyte3_e32 v101, v74
	v_pk_fma_f32 v[90:91], v[48:49], v[96:97], v[90:91] op_sel_hi:[0,1,1]
	v_cvt_f32_ubyte0_e32 v102, v16
	v_cvt_f32_ubyte1_e32 v103, v16
	v_pk_fma_f32 v[88:89], v[48:49], v[100:101], v[88:89] op_sel_hi:[0,1,1]
	v_cvt_f32_ubyte2_e32 v126, v16
	v_cvt_f32_ubyte3_e32 v127, v16
	v_pk_fma_f32 v[84:85], v[48:49], v[102:103], v[84:85] op_sel_hi:[0,1,1]
	v_cvt_f32_ubyte0_e32 v96, v78
	v_cvt_f32_ubyte1_e32 v97, v78
	v_pk_fma_f32 v[80:81], v[48:49], v[126:127], v[80:81] op_sel_hi:[0,1,1]
	v_and_b32_e32 v82, s34, v18
	v_and_b32_e32 v86, s34, v19
	v_cvt_f32_ubyte2_e32 v100, v78
	v_cvt_f32_ubyte3_e32 v101, v78
	v_pk_fma_f32 v[76:77], v[48:49], v[96:97], v[76:77] op_sel_hi:[0,1,1]
	v_cvt_f32_ubyte0_e32 v102, v17
	v_cvt_f32_ubyte1_e32 v103, v17
	v_pk_fma_f32 v[68:69], v[48:49], v[100:101], v[68:69] op_sel_hi:[0,1,1]
	v_cvt_f32_ubyte2_e32 v126, v17
	v_cvt_f32_ubyte3_e32 v127, v17
	v_pk_fma_f32 v[62:63], v[48:49], v[102:103], v[62:63] op_sel_hi:[0,1,1]
	v_cvt_f32_ubyte0_e32 v96, v82
	v_cvt_f32_ubyte1_e32 v97, v82
	v_pk_fma_f32 v[60:61], v[48:49], v[126:127], v[60:61] op_sel_hi:[0,1,1]
	v_cvt_f32_ubyte2_e32 v100, v82
	v_cvt_f32_ubyte3_e32 v101, v82
	v_pk_fma_f32 v[90:91], v[48:49], v[96:97], v[90:91] op_sel:[1,0,0]
	v_cvt_f32_ubyte0_e32 v102, v18
	v_cvt_f32_ubyte1_e32 v103, v18
	v_pk_fma_f32 v[88:89], v[48:49], v[100:101], v[88:89] op_sel:[1,0,0]
	v_cvt_f32_ubyte2_e32 v126, v18
	v_cvt_f32_ubyte3_e32 v127, v18
	v_pk_fma_f32 v[84:85], v[48:49], v[102:103], v[84:85] op_sel:[1,0,0]
	v_cvt_f32_ubyte0_e32 v96, v86
	v_cvt_f32_ubyte1_e32 v97, v86
	v_pk_fma_f32 v[80:81], v[48:49], v[126:127], v[80:81] op_sel:[1,0,0]
	v_and_b32_e32 v74, s34, v20
	v_and_b32_e32 v78, s34, v21
	v_cvt_f32_ubyte2_e32 v100, v86
	v_cvt_f32_ubyte3_e32 v101, v86
	v_pk_fma_f32 v[76:77], v[48:49], v[96:97], v[76:77] op_sel:[1,0,0]
	v_cvt_f32_ubyte0_e32 v102, v19
	v_cvt_f32_ubyte1_e32 v103, v19
	v_pk_fma_f32 v[68:69], v[48:49], v[100:101], v[68:69] op_sel:[1,0,0]
	v_cvt_f32_ubyte2_e32 v126, v19
	v_cvt_f32_ubyte3_e32 v127, v19
	v_pk_fma_f32 v[62:63], v[48:49], v[102:103], v[62:63] op_sel:[1,0,0]
	v_cvt_f32_ubyte0_e32 v96, v74
	v_cvt_f32_ubyte1_e32 v97, v74
	v_pk_fma_f32 v[60:61], v[48:49], v[126:127], v[60:61] op_sel:[1,0,0]
	v_cvt_f32_ubyte2_e32 v100, v74
	v_cvt_f32_ubyte3_e32 v101, v74
	v_pk_fma_f32 v[90:91], v[50:51], v[96:97], v[90:91] op_sel_hi:[0,1,1]
	v_cvt_f32_ubyte0_e32 v102, v20
	v_cvt_f32_ubyte1_e32 v103, v20
	v_pk_fma_f32 v[88:89], v[50:51], v[100:101], v[88:89] op_sel_hi:[0,1,1]
	v_cvt_f32_ubyte2_e32 v126, v20
	v_cvt_f32_ubyte3_e32 v127, v20
	v_pk_fma_f32 v[84:85], v[50:51], v[102:103], v[84:85] op_sel_hi:[0,1,1]
	v_cvt_f32_ubyte0_e32 v96, v78
	v_cvt_f32_ubyte1_e32 v97, v78
	v_pk_fma_f32 v[80:81], v[50:51], v[126:127], v[80:81] op_sel_hi:[0,1,1]
	v_and_b32_e32 v82, s34, v22
	v_and_b32_e32 v86, s34, v23
	v_cvt_f32_ubyte2_e32 v100, v78
	v_cvt_f32_ubyte3_e32 v101, v78
	v_pk_fma_f32 v[76:77], v[50:51], v[96:97], v[76:77] op_sel_hi:[0,1,1]
	v_cvt_f32_ubyte0_e32 v102, v21
	v_cvt_f32_ubyte1_e32 v103, v21
	v_pk_fma_f32 v[68:69], v[50:51], v[100:101], v[68:69] op_sel_hi:[0,1,1]
	v_cvt_f32_ubyte2_e32 v126, v21
	v_cvt_f32_ubyte3_e32 v127, v21
	v_pk_fma_f32 v[62:63], v[50:51], v[102:103], v[62:63] op_sel_hi:[0,1,1]
	v_cvt_f32_ubyte0_e32 v96, v82
	v_cvt_f32_ubyte1_e32 v97, v82
	v_pk_fma_f32 v[60:61], v[50:51], v[126:127], v[60:61] op_sel_hi:[0,1,1]
	v_cvt_f32_ubyte2_e32 v100, v82
	v_cvt_f32_ubyte3_e32 v101, v82
	v_pk_fma_f32 v[90:91], v[50:51], v[96:97], v[90:91] op_sel:[1,0,0]
	v_cvt_f32_ubyte0_e32 v102, v22
	v_cvt_f32_ubyte1_e32 v103, v22
	v_pk_fma_f32 v[88:89], v[50:51], v[100:101], v[88:89] op_sel:[1,0,0]
	v_cvt_f32_ubyte2_e32 v126, v22
	v_cvt_f32_ubyte3_e32 v127, v22
	v_pk_fma_f32 v[84:85], v[50:51], v[102:103], v[84:85] op_sel:[1,0,0]
	v_cvt_f32_ubyte0_e32 v96, v86
	v_cvt_f32_ubyte1_e32 v97, v86
	v_pk_fma_f32 v[80:81], v[50:51], v[126:127], v[80:81] op_sel:[1,0,0]
	v_and_b32_e32 v74, s34, v24
	v_and_b32_e32 v78, s34, v25
	v_cvt_f32_ubyte2_e32 v100, v86
	v_cvt_f32_ubyte3_e32 v101, v86
	v_pk_fma_f32 v[76:77], v[50:51], v[96:97], v[76:77] op_sel:[1,0,0]
	v_cvt_f32_ubyte0_e32 v102, v23
	v_cvt_f32_ubyte1_e32 v103, v23
	v_pk_fma_f32 v[68:69], v[50:51], v[100:101], v[68:69] op_sel:[1,0,0]
	v_cvt_f32_ubyte2_e32 v126, v23
	v_cvt_f32_ubyte3_e32 v127, v23
	v_pk_fma_f32 v[62:63], v[50:51], v[102:103], v[62:63] op_sel:[1,0,0]
	v_cvt_f32_ubyte0_e32 v96, v74
	v_cvt_f32_ubyte1_e32 v97, v74
	v_pk_fma_f32 v[60:61], v[50:51], v[126:127], v[60:61] op_sel:[1,0,0]
	v_cvt_f32_ubyte2_e32 v100, v74
	v_cvt_f32_ubyte3_e32 v101, v74
	v_pk_fma_f32 v[90:91], v[52:53], v[96:97], v[90:91] op_sel_hi:[0,1,1]
	v_cvt_f32_ubyte0_e32 v102, v24
	v_cvt_f32_ubyte1_e32 v103, v24
	v_pk_fma_f32 v[88:89], v[52:53], v[100:101], v[88:89] op_sel_hi:[0,1,1]
	v_cvt_f32_ubyte2_e32 v126, v24
	v_cvt_f32_ubyte3_e32 v127, v24
	v_pk_fma_f32 v[84:85], v[52:53], v[102:103], v[84:85] op_sel_hi:[0,1,1]
	v_cvt_f32_ubyte0_e32 v96, v78
	v_cvt_f32_ubyte1_e32 v97, v78
	v_pk_fma_f32 v[80:81], v[52:53], v[126:127], v[80:81] op_sel_hi:[0,1,1]
	v_and_b32_e32 v82, s34, v26
	v_and_b32_e32 v86, s34, v27
	v_cvt_f32_ubyte2_e32 v100, v78
	v_cvt_f32_ubyte3_e32 v101, v78
	v_pk_fma_f32 v[76:77], v[52:53], v[96:97], v[76:77] op_sel_hi:[0,1,1]
	v_cvt_f32_ubyte0_e32 v102, v25
	v_cvt_f32_ubyte1_e32 v103, v25
	v_pk_fma_f32 v[68:69], v[52:53], v[100:101], v[68:69] op_sel_hi:[0,1,1]
	v_cvt_f32_ubyte2_e32 v126, v25
	v_cvt_f32_ubyte3_e32 v127, v25
	v_pk_fma_f32 v[62:63], v[52:53], v[102:103], v[62:63] op_sel_hi:[0,1,1]
	v_cvt_f32_ubyte0_e32 v96, v82
	v_cvt_f32_ubyte1_e32 v97, v82
	v_pk_fma_f32 v[60:61], v[52:53], v[126:127], v[60:61] op_sel_hi:[0,1,1]
	v_cvt_f32_ubyte2_e32 v100, v82
	v_cvt_f32_ubyte3_e32 v101, v82
	v_pk_fma_f32 v[90:91], v[52:53], v[96:97], v[90:91] op_sel:[1,0,0]
	v_cvt_f32_ubyte0_e32 v102, v26
	v_cvt_f32_ubyte1_e32 v103, v26
	v_pk_fma_f32 v[88:89], v[52:53], v[100:101], v[88:89] op_sel:[1,0,0]
	v_cvt_f32_ubyte2_e32 v126, v26
	v_cvt_f32_ubyte3_e32 v127, v26
	v_pk_fma_f32 v[84:85], v[52:53], v[102:103], v[84:85] op_sel:[1,0,0]
	v_cvt_f32_ubyte0_e32 v96, v86
	v_cvt_f32_ubyte1_e32 v97, v86
	v_pk_fma_f32 v[80:81], v[52:53], v[126:127], v[80:81] op_sel:[1,0,0]
	v_and_b32_e32 v74, s34, v28
	v_and_b32_e32 v78, s34, v29
	v_cvt_f32_ubyte2_e32 v100, v86
	v_cvt_f32_ubyte3_e32 v101, v86
	v_pk_fma_f32 v[76:77], v[52:53], v[96:97], v[76:77] op_sel:[1,0,0]
	v_cvt_f32_ubyte0_e32 v102, v27
	v_cvt_f32_ubyte1_e32 v103, v27
	v_pk_fma_f32 v[68:69], v[52:53], v[100:101], v[68:69] op_sel:[1,0,0]
	v_cvt_f32_ubyte2_e32 v126, v27
	v_cvt_f32_ubyte3_e32 v127, v27
	v_pk_fma_f32 v[62:63], v[52:53], v[102:103], v[62:63] op_sel:[1,0,0]
	v_cvt_f32_ubyte0_e32 v96, v74
	v_cvt_f32_ubyte1_e32 v97, v74
	v_pk_fma_f32 v[60:61], v[52:53], v[126:127], v[60:61] op_sel:[1,0,0]
	v_cvt_f32_ubyte2_e32 v100, v74
	v_cvt_f32_ubyte3_e32 v101, v74
	v_pk_fma_f32 v[90:91], v[54:55], v[96:97], v[90:91] op_sel_hi:[0,1,1]
	v_cvt_f32_ubyte0_e32 v102, v28
	v_cvt_f32_ubyte1_e32 v103, v28
	v_pk_fma_f32 v[88:89], v[54:55], v[100:101], v[88:89] op_sel_hi:[0,1,1]
	v_cvt_f32_ubyte2_e32 v126, v28
	v_cvt_f32_ubyte3_e32 v127, v28
	v_pk_fma_f32 v[84:85], v[54:55], v[102:103], v[84:85] op_sel_hi:[0,1,1]
	v_cvt_f32_ubyte0_e32 v96, v78
	v_cvt_f32_ubyte1_e32 v97, v78
	v_pk_fma_f32 v[80:81], v[54:55], v[126:127], v[80:81] op_sel_hi:[0,1,1]
	v_and_b32_e32 v82, s34, v30
	v_and_b32_e32 v86, s34, v31
	v_cvt_f32_ubyte2_e32 v100, v78
	v_cvt_f32_ubyte3_e32 v101, v78
	v_pk_fma_f32 v[76:77], v[54:55], v[96:97], v[76:77] op_sel_hi:[0,1,1]
	v_cvt_f32_ubyte0_e32 v102, v29
	v_cvt_f32_ubyte1_e32 v103, v29
	v_pk_fma_f32 v[68:69], v[54:55], v[100:101], v[68:69] op_sel_hi:[0,1,1]
	v_cvt_f32_ubyte2_e32 v126, v29
	v_cvt_f32_ubyte3_e32 v127, v29
	v_pk_fma_f32 v[62:63], v[54:55], v[102:103], v[62:63] op_sel_hi:[0,1,1]
	v_cvt_f32_ubyte0_e32 v96, v82
	v_cvt_f32_ubyte1_e32 v97, v82
	v_pk_fma_f32 v[60:61], v[54:55], v[126:127], v[60:61] op_sel_hi:[0,1,1]
	v_cvt_f32_ubyte2_e32 v100, v82
	v_cvt_f32_ubyte3_e32 v101, v82
	v_pk_fma_f32 v[90:91], v[54:55], v[96:97], v[90:91] op_sel:[1,0,0]
	v_cvt_f32_ubyte0_e32 v102, v30
	v_cvt_f32_ubyte1_e32 v103, v30
	v_pk_fma_f32 v[88:89], v[54:55], v[100:101], v[88:89] op_sel:[1,0,0]
	v_cvt_f32_ubyte2_e32 v126, v30
	v_cvt_f32_ubyte3_e32 v127, v30
	v_pk_fma_f32 v[84:85], v[54:55], v[102:103], v[84:85] op_sel:[1,0,0]
	v_cvt_f32_ubyte0_e32 v96, v86
	v_cvt_f32_ubyte1_e32 v97, v86
	v_pk_fma_f32 v[80:81], v[54:55], v[126:127], v[80:81] op_sel:[1,0,0]
	v_cvt_f32_ubyte2_e32 v100, v86
	v_cvt_f32_ubyte3_e32 v101, v86
	v_pk_fma_f32 v[76:77], v[54:55], v[96:97], v[76:77] op_sel:[1,0,0]
	v_cvt_f32_ubyte0_e32 v102, v31
	v_cvt_f32_ubyte1_e32 v103, v31
	v_pk_fma_f32 v[68:69], v[54:55], v[100:101], v[68:69] op_sel:[1,0,0]
	v_cvt_f32_ubyte2_e32 v126, v31
	v_cvt_f32_ubyte3_e32 v127, v31
	v_pk_fma_f32 v[62:63], v[54:55], v[102:103], v[62:63] op_sel:[1,0,0]
	v_pk_fma_f32 v[60:61], v[54:55], v[126:127], v[60:61] op_sel:[1,0,0]
	s_waitcnt lgkmcnt(0)
	ds_read_b128 v[48:51], v128 offset:928
	ds_read_b128 v[52:55], v128 offset:944
	s_waitcnt vmcnt(24)
	v_and_b32_e32 v74, s34, v146
	v_and_b32_e32 v78, s34, v147
	v_cvt_f32_ubyte0_e32 v96, v74
	v_cvt_f32_ubyte1_e32 v97, v74
	v_cvt_f32_ubyte2_e32 v100, v74
	v_cvt_f32_ubyte3_e32 v101, v74
	v_pk_fma_f32 v[90:91], v[32:33], v[96:97], v[90:91] op_sel_hi:[0,1,1]
	v_cvt_f32_ubyte0_e32 v102, v146
	v_cvt_f32_ubyte1_e32 v103, v146
	v_pk_fma_f32 v[88:89], v[32:33], v[100:101], v[88:89] op_sel_hi:[0,1,1]
	v_cvt_f32_ubyte2_e32 v126, v146
	v_cvt_f32_ubyte3_e32 v127, v146
	v_pk_fma_f32 v[84:85], v[32:33], v[102:103], v[84:85] op_sel_hi:[0,1,1]
	v_cvt_f32_ubyte0_e32 v96, v78
	v_cvt_f32_ubyte1_e32 v97, v78
	v_pk_fma_f32 v[80:81], v[32:33], v[126:127], v[80:81] op_sel_hi:[0,1,1]
	v_and_b32_e32 v82, s34, v148
	v_and_b32_e32 v86, s34, v149
	v_cvt_f32_ubyte2_e32 v100, v78
	v_cvt_f32_ubyte3_e32 v101, v78
	v_pk_fma_f32 v[76:77], v[32:33], v[96:97], v[76:77] op_sel_hi:[0,1,1]
	v_cvt_f32_ubyte0_e32 v102, v147
	v_cvt_f32_ubyte1_e32 v103, v147
	v_pk_fma_f32 v[68:69], v[32:33], v[100:101], v[68:69] op_sel_hi:[0,1,1]
	v_cvt_f32_ubyte2_e32 v126, v147
	v_cvt_f32_ubyte3_e32 v127, v147
	v_pk_fma_f32 v[62:63], v[32:33], v[102:103], v[62:63] op_sel_hi:[0,1,1]
	v_cvt_f32_ubyte0_e32 v96, v82
	v_cvt_f32_ubyte1_e32 v97, v82
	v_pk_fma_f32 v[60:61], v[32:33], v[126:127], v[60:61] op_sel_hi:[0,1,1]
	v_cvt_f32_ubyte2_e32 v100, v82
	v_cvt_f32_ubyte3_e32 v101, v82
	v_pk_fma_f32 v[90:91], v[32:33], v[96:97], v[90:91] op_sel:[1,0,0]
	v_cvt_f32_ubyte0_e32 v102, v148
	v_cvt_f32_ubyte1_e32 v103, v148
	v_pk_fma_f32 v[88:89], v[32:33], v[100:101], v[88:89] op_sel:[1,0,0]
	v_cvt_f32_ubyte2_e32 v126, v148
	v_cvt_f32_ubyte3_e32 v127, v148
	v_pk_fma_f32 v[84:85], v[32:33], v[102:103], v[84:85] op_sel:[1,0,0]
	v_cvt_f32_ubyte0_e32 v96, v86
	v_cvt_f32_ubyte1_e32 v97, v86
	v_pk_fma_f32 v[80:81], v[32:33], v[126:127], v[80:81] op_sel:[1,0,0]
	v_and_b32_e32 v74, s34, v150
	v_and_b32_e32 v78, s34, v151
	v_cvt_f32_ubyte2_e32 v100, v86
	v_cvt_f32_ubyte3_e32 v101, v86
	v_pk_fma_f32 v[76:77], v[32:33], v[96:97], v[76:77] op_sel:[1,0,0]
	v_cvt_f32_ubyte0_e32 v102, v149
	v_cvt_f32_ubyte1_e32 v103, v149
	v_pk_fma_f32 v[68:69], v[32:33], v[100:101], v[68:69] op_sel:[1,0,0]
	v_cvt_f32_ubyte2_e32 v126, v149
	v_cvt_f32_ubyte3_e32 v127, v149
	v_pk_fma_f32 v[62:63], v[32:33], v[102:103], v[62:63] op_sel:[1,0,0]
	v_cvt_f32_ubyte0_e32 v96, v74
	v_cvt_f32_ubyte1_e32 v97, v74
	v_pk_fma_f32 v[60:61], v[32:33], v[126:127], v[60:61] op_sel:[1,0,0]
	v_cvt_f32_ubyte2_e32 v100, v74
	v_cvt_f32_ubyte3_e32 v101, v74
	v_pk_fma_f32 v[90:91], v[34:35], v[96:97], v[90:91] op_sel_hi:[0,1,1]
	v_cvt_f32_ubyte0_e32 v102, v150
	v_cvt_f32_ubyte1_e32 v103, v150
	v_pk_fma_f32 v[88:89], v[34:35], v[100:101], v[88:89] op_sel_hi:[0,1,1]
	v_cvt_f32_ubyte2_e32 v126, v150
	v_cvt_f32_ubyte3_e32 v127, v150
	v_pk_fma_f32 v[84:85], v[34:35], v[102:103], v[84:85] op_sel_hi:[0,1,1]
	v_cvt_f32_ubyte0_e32 v96, v78
	v_cvt_f32_ubyte1_e32 v97, v78
	v_pk_fma_f32 v[80:81], v[34:35], v[126:127], v[80:81] op_sel_hi:[0,1,1]
	v_and_b32_e32 v82, s34, v152
	v_and_b32_e32 v86, s34, v153
	v_cvt_f32_ubyte2_e32 v100, v78
	v_cvt_f32_ubyte3_e32 v101, v78
	v_pk_fma_f32 v[76:77], v[34:35], v[96:97], v[76:77] op_sel_hi:[0,1,1]
	v_cvt_f32_ubyte0_e32 v102, v151
	v_cvt_f32_ubyte1_e32 v103, v151
	v_pk_fma_f32 v[68:69], v[34:35], v[100:101], v[68:69] op_sel_hi:[0,1,1]
	v_cvt_f32_ubyte2_e32 v126, v151
	v_cvt_f32_ubyte3_e32 v127, v151
	v_pk_fma_f32 v[62:63], v[34:35], v[102:103], v[62:63] op_sel_hi:[0,1,1]
	v_cvt_f32_ubyte0_e32 v96, v82
	v_cvt_f32_ubyte1_e32 v97, v82
	v_pk_fma_f32 v[60:61], v[34:35], v[126:127], v[60:61] op_sel_hi:[0,1,1]
	v_cvt_f32_ubyte2_e32 v100, v82
	v_cvt_f32_ubyte3_e32 v101, v82
	v_pk_fma_f32 v[90:91], v[34:35], v[96:97], v[90:91] op_sel:[1,0,0]
	v_cvt_f32_ubyte0_e32 v102, v152
	v_cvt_f32_ubyte1_e32 v103, v152
	v_pk_fma_f32 v[88:89], v[34:35], v[100:101], v[88:89] op_sel:[1,0,0]
	v_cvt_f32_ubyte2_e32 v126, v152
	v_cvt_f32_ubyte3_e32 v127, v152
	v_pk_fma_f32 v[84:85], v[34:35], v[102:103], v[84:85] op_sel:[1,0,0]
	v_cvt_f32_ubyte0_e32 v96, v86
	v_cvt_f32_ubyte1_e32 v97, v86
	v_pk_fma_f32 v[80:81], v[34:35], v[126:127], v[80:81] op_sel:[1,0,0]
	v_and_b32_e32 v74, s34, v154
	v_and_b32_e32 v78, s34, v155
	v_cvt_f32_ubyte2_e32 v100, v86
	v_cvt_f32_ubyte3_e32 v101, v86
	v_pk_fma_f32 v[76:77], v[34:35], v[96:97], v[76:77] op_sel:[1,0,0]
	v_cvt_f32_ubyte0_e32 v102, v153
	v_cvt_f32_ubyte1_e32 v103, v153
	v_pk_fma_f32 v[68:69], v[34:35], v[100:101], v[68:69] op_sel:[1,0,0]
	v_cvt_f32_ubyte2_e32 v126, v153
	v_cvt_f32_ubyte3_e32 v127, v153
	v_pk_fma_f32 v[62:63], v[34:35], v[102:103], v[62:63] op_sel:[1,0,0]
	v_cvt_f32_ubyte0_e32 v96, v74
	v_cvt_f32_ubyte1_e32 v97, v74
	v_pk_fma_f32 v[60:61], v[34:35], v[126:127], v[60:61] op_sel:[1,0,0]
	v_cvt_f32_ubyte2_e32 v100, v74
	v_cvt_f32_ubyte3_e32 v101, v74
	v_pk_fma_f32 v[90:91], v[36:37], v[96:97], v[90:91] op_sel_hi:[0,1,1]
	v_cvt_f32_ubyte0_e32 v102, v154
	v_cvt_f32_ubyte1_e32 v103, v154
	v_pk_fma_f32 v[88:89], v[36:37], v[100:101], v[88:89] op_sel_hi:[0,1,1]
	v_cvt_f32_ubyte2_e32 v126, v154
	v_cvt_f32_ubyte3_e32 v127, v154
	v_pk_fma_f32 v[84:85], v[36:37], v[102:103], v[84:85] op_sel_hi:[0,1,1]
	v_cvt_f32_ubyte0_e32 v96, v78
	v_cvt_f32_ubyte1_e32 v97, v78
	v_pk_fma_f32 v[80:81], v[36:37], v[126:127], v[80:81] op_sel_hi:[0,1,1]
	v_and_b32_e32 v82, s34, v156
	v_and_b32_e32 v86, s34, v157
	v_cvt_f32_ubyte2_e32 v100, v78
	v_cvt_f32_ubyte3_e32 v101, v78
	v_pk_fma_f32 v[76:77], v[36:37], v[96:97], v[76:77] op_sel_hi:[0,1,1]
	v_cvt_f32_ubyte0_e32 v102, v155
	v_cvt_f32_ubyte1_e32 v103, v155
	v_pk_fma_f32 v[68:69], v[36:37], v[100:101], v[68:69] op_sel_hi:[0,1,1]
	v_cvt_f32_ubyte2_e32 v126, v155
	v_cvt_f32_ubyte3_e32 v127, v155
	v_pk_fma_f32 v[62:63], v[36:37], v[102:103], v[62:63] op_sel_hi:[0,1,1]
	v_cvt_f32_ubyte0_e32 v96, v82
	v_cvt_f32_ubyte1_e32 v97, v82
	v_pk_fma_f32 v[60:61], v[36:37], v[126:127], v[60:61] op_sel_hi:[0,1,1]
	v_cvt_f32_ubyte2_e32 v100, v82
	v_cvt_f32_ubyte3_e32 v101, v82
	v_pk_fma_f32 v[90:91], v[36:37], v[96:97], v[90:91] op_sel:[1,0,0]
	v_cvt_f32_ubyte0_e32 v102, v156
	v_cvt_f32_ubyte1_e32 v103, v156
	v_pk_fma_f32 v[88:89], v[36:37], v[100:101], v[88:89] op_sel:[1,0,0]
	v_cvt_f32_ubyte2_e32 v126, v156
	v_cvt_f32_ubyte3_e32 v127, v156
	v_pk_fma_f32 v[84:85], v[36:37], v[102:103], v[84:85] op_sel:[1,0,0]
	v_cvt_f32_ubyte0_e32 v96, v86
	v_cvt_f32_ubyte1_e32 v97, v86
	v_pk_fma_f32 v[80:81], v[36:37], v[126:127], v[80:81] op_sel:[1,0,0]
	v_and_b32_e32 v74, s34, v158
	v_and_b32_e32 v78, s34, v159
	v_cvt_f32_ubyte2_e32 v100, v86
	v_cvt_f32_ubyte3_e32 v101, v86
	v_pk_fma_f32 v[76:77], v[36:37], v[96:97], v[76:77] op_sel:[1,0,0]
	v_cvt_f32_ubyte0_e32 v102, v157
	v_cvt_f32_ubyte1_e32 v103, v157
	v_pk_fma_f32 v[68:69], v[36:37], v[100:101], v[68:69] op_sel:[1,0,0]
	v_cvt_f32_ubyte2_e32 v126, v157
	v_cvt_f32_ubyte3_e32 v127, v157
	v_pk_fma_f32 v[62:63], v[36:37], v[102:103], v[62:63] op_sel:[1,0,0]
	v_cvt_f32_ubyte0_e32 v96, v74
	v_cvt_f32_ubyte1_e32 v97, v74
	v_pk_fma_f32 v[60:61], v[36:37], v[126:127], v[60:61] op_sel:[1,0,0]
	v_cvt_f32_ubyte2_e32 v100, v74
	v_cvt_f32_ubyte3_e32 v101, v74
	v_pk_fma_f32 v[90:91], v[38:39], v[96:97], v[90:91] op_sel_hi:[0,1,1]
	v_cvt_f32_ubyte0_e32 v102, v158
	v_cvt_f32_ubyte1_e32 v103, v158
	v_pk_fma_f32 v[88:89], v[38:39], v[100:101], v[88:89] op_sel_hi:[0,1,1]
	v_cvt_f32_ubyte2_e32 v126, v158
	v_cvt_f32_ubyte3_e32 v127, v158
	v_pk_fma_f32 v[84:85], v[38:39], v[102:103], v[84:85] op_sel_hi:[0,1,1]
	v_cvt_f32_ubyte0_e32 v96, v78
	v_cvt_f32_ubyte1_e32 v97, v78
	v_pk_fma_f32 v[80:81], v[38:39], v[126:127], v[80:81] op_sel_hi:[0,1,1]
	v_and_b32_e32 v82, s34, v160
	v_and_b32_e32 v86, s34, v161
	v_cvt_f32_ubyte2_e32 v100, v78
	v_cvt_f32_ubyte3_e32 v101, v78
	v_pk_fma_f32 v[76:77], v[38:39], v[96:97], v[76:77] op_sel_hi:[0,1,1]
	v_cvt_f32_ubyte0_e32 v102, v159
	v_cvt_f32_ubyte1_e32 v103, v159
	v_pk_fma_f32 v[68:69], v[38:39], v[100:101], v[68:69] op_sel_hi:[0,1,1]
	v_cvt_f32_ubyte2_e32 v126, v159
	v_cvt_f32_ubyte3_e32 v127, v159
	v_pk_fma_f32 v[62:63], v[38:39], v[102:103], v[62:63] op_sel_hi:[0,1,1]
	v_cvt_f32_ubyte0_e32 v96, v82
	v_cvt_f32_ubyte1_e32 v97, v82
	v_pk_fma_f32 v[60:61], v[38:39], v[126:127], v[60:61] op_sel_hi:[0,1,1]
	v_cvt_f32_ubyte2_e32 v100, v82
	v_cvt_f32_ubyte3_e32 v101, v82
	v_pk_fma_f32 v[90:91], v[38:39], v[96:97], v[90:91] op_sel:[1,0,0]
	v_cvt_f32_ubyte0_e32 v102, v160
	v_cvt_f32_ubyte1_e32 v103, v160
	v_pk_fma_f32 v[88:89], v[38:39], v[100:101], v[88:89] op_sel:[1,0,0]
	v_cvt_f32_ubyte2_e32 v126, v160
	v_cvt_f32_ubyte3_e32 v127, v160
	v_pk_fma_f32 v[84:85], v[38:39], v[102:103], v[84:85] op_sel:[1,0,0]
	v_cvt_f32_ubyte0_e32 v96, v86
	v_cvt_f32_ubyte1_e32 v97, v86
	v_pk_fma_f32 v[80:81], v[38:39], v[126:127], v[80:81] op_sel:[1,0,0]
	v_cvt_f32_ubyte2_e32 v100, v86
	v_cvt_f32_ubyte3_e32 v101, v86
	v_pk_fma_f32 v[76:77], v[38:39], v[96:97], v[76:77] op_sel:[1,0,0]
	v_cvt_f32_ubyte0_e32 v102, v161
	v_cvt_f32_ubyte1_e32 v103, v161
	v_pk_fma_f32 v[68:69], v[38:39], v[100:101], v[68:69] op_sel:[1,0,0]
	v_cvt_f32_ubyte2_e32 v126, v161
	v_cvt_f32_ubyte3_e32 v127, v161
	v_pk_fma_f32 v[62:63], v[38:39], v[102:103], v[62:63] op_sel:[1,0,0]
	v_pk_fma_f32 v[60:61], v[38:39], v[126:127], v[60:61] op_sel:[1,0,0]
	s_waitcnt lgkmcnt(0)
	ds_read_b128 v[32:35], v128 offset:960
	ds_read_b128 v[36:39], v128 offset:976
	s_waitcnt vmcnt(16)
	v_and_b32_e32 v74, s34, v162
	v_and_b32_e32 v78, s34, v163
	v_cvt_f32_ubyte0_e32 v96, v74
	v_cvt_f32_ubyte1_e32 v97, v74
	v_cvt_f32_ubyte2_e32 v100, v74
	v_cvt_f32_ubyte3_e32 v101, v74
	v_pk_fma_f32 v[90:91], v[48:49], v[96:97], v[90:91] op_sel_hi:[0,1,1]
	v_cvt_f32_ubyte0_e32 v102, v162
	v_cvt_f32_ubyte1_e32 v103, v162
	v_pk_fma_f32 v[88:89], v[48:49], v[100:101], v[88:89] op_sel_hi:[0,1,1]
	v_cvt_f32_ubyte2_e32 v126, v162
	v_cvt_f32_ubyte3_e32 v127, v162
	v_pk_fma_f32 v[84:85], v[48:49], v[102:103], v[84:85] op_sel_hi:[0,1,1]
	v_cvt_f32_ubyte0_e32 v96, v78
	v_cvt_f32_ubyte1_e32 v97, v78
	v_pk_fma_f32 v[80:81], v[48:49], v[126:127], v[80:81] op_sel_hi:[0,1,1]
	v_and_b32_e32 v82, s34, v164
	v_and_b32_e32 v86, s34, v165
	v_cvt_f32_ubyte2_e32 v100, v78
	v_cvt_f32_ubyte3_e32 v101, v78
	v_pk_fma_f32 v[76:77], v[48:49], v[96:97], v[76:77] op_sel_hi:[0,1,1]
	v_cvt_f32_ubyte0_e32 v102, v163
	v_cvt_f32_ubyte1_e32 v103, v163
	v_pk_fma_f32 v[68:69], v[48:49], v[100:101], v[68:69] op_sel_hi:[0,1,1]
	v_cvt_f32_ubyte2_e32 v126, v163
	v_cvt_f32_ubyte3_e32 v127, v163
	v_pk_fma_f32 v[62:63], v[48:49], v[102:103], v[62:63] op_sel_hi:[0,1,1]
	v_cvt_f32_ubyte0_e32 v96, v82
	v_cvt_f32_ubyte1_e32 v97, v82
	v_pk_fma_f32 v[60:61], v[48:49], v[126:127], v[60:61] op_sel_hi:[0,1,1]
	v_cvt_f32_ubyte2_e32 v100, v82
	v_cvt_f32_ubyte3_e32 v101, v82
	v_pk_fma_f32 v[90:91], v[48:49], v[96:97], v[90:91] op_sel:[1,0,0]
	v_cvt_f32_ubyte0_e32 v102, v164
	v_cvt_f32_ubyte1_e32 v103, v164
	v_pk_fma_f32 v[88:89], v[48:49], v[100:101], v[88:89] op_sel:[1,0,0]
	v_cvt_f32_ubyte2_e32 v126, v164
	v_cvt_f32_ubyte3_e32 v127, v164
	v_pk_fma_f32 v[84:85], v[48:49], v[102:103], v[84:85] op_sel:[1,0,0]
	v_cvt_f32_ubyte0_e32 v96, v86
	v_cvt_f32_ubyte1_e32 v97, v86
	v_pk_fma_f32 v[80:81], v[48:49], v[126:127], v[80:81] op_sel:[1,0,0]
	v_and_b32_e32 v74, s34, v166
	v_and_b32_e32 v78, s34, v167
	v_cvt_f32_ubyte2_e32 v100, v86
	v_cvt_f32_ubyte3_e32 v101, v86
	v_pk_fma_f32 v[76:77], v[48:49], v[96:97], v[76:77] op_sel:[1,0,0]
	v_cvt_f32_ubyte0_e32 v102, v165
	v_cvt_f32_ubyte1_e32 v103, v165
	v_pk_fma_f32 v[68:69], v[48:49], v[100:101], v[68:69] op_sel:[1,0,0]
	v_cvt_f32_ubyte2_e32 v126, v165
	v_cvt_f32_ubyte3_e32 v127, v165
	v_pk_fma_f32 v[62:63], v[48:49], v[102:103], v[62:63] op_sel:[1,0,0]
	v_cvt_f32_ubyte0_e32 v96, v74
	v_cvt_f32_ubyte1_e32 v97, v74
	v_pk_fma_f32 v[60:61], v[48:49], v[126:127], v[60:61] op_sel:[1,0,0]
	v_cvt_f32_ubyte2_e32 v100, v74
	v_cvt_f32_ubyte3_e32 v101, v74
	v_pk_fma_f32 v[90:91], v[50:51], v[96:97], v[90:91] op_sel_hi:[0,1,1]
	v_cvt_f32_ubyte0_e32 v102, v166
	v_cvt_f32_ubyte1_e32 v103, v166
	v_pk_fma_f32 v[88:89], v[50:51], v[100:101], v[88:89] op_sel_hi:[0,1,1]
	v_cvt_f32_ubyte2_e32 v126, v166
	v_cvt_f32_ubyte3_e32 v127, v166
	v_pk_fma_f32 v[84:85], v[50:51], v[102:103], v[84:85] op_sel_hi:[0,1,1]
	v_cvt_f32_ubyte0_e32 v96, v78
	v_cvt_f32_ubyte1_e32 v97, v78
	v_pk_fma_f32 v[80:81], v[50:51], v[126:127], v[80:81] op_sel_hi:[0,1,1]
	v_and_b32_e32 v82, s34, v168
	v_and_b32_e32 v86, s34, v169
	v_cvt_f32_ubyte2_e32 v100, v78
	v_cvt_f32_ubyte3_e32 v101, v78
	v_pk_fma_f32 v[76:77], v[50:51], v[96:97], v[76:77] op_sel_hi:[0,1,1]
	v_cvt_f32_ubyte0_e32 v102, v167
	v_cvt_f32_ubyte1_e32 v103, v167
	v_pk_fma_f32 v[68:69], v[50:51], v[100:101], v[68:69] op_sel_hi:[0,1,1]
	v_cvt_f32_ubyte2_e32 v126, v167
	v_cvt_f32_ubyte3_e32 v127, v167
	v_pk_fma_f32 v[62:63], v[50:51], v[102:103], v[62:63] op_sel_hi:[0,1,1]
	v_cvt_f32_ubyte0_e32 v96, v82
	v_cvt_f32_ubyte1_e32 v97, v82
	v_pk_fma_f32 v[60:61], v[50:51], v[126:127], v[60:61] op_sel_hi:[0,1,1]
	v_cvt_f32_ubyte2_e32 v100, v82
	v_cvt_f32_ubyte3_e32 v101, v82
	v_pk_fma_f32 v[90:91], v[50:51], v[96:97], v[90:91] op_sel:[1,0,0]
	v_cvt_f32_ubyte0_e32 v102, v168
	v_cvt_f32_ubyte1_e32 v103, v168
	v_pk_fma_f32 v[88:89], v[50:51], v[100:101], v[88:89] op_sel:[1,0,0]
	v_cvt_f32_ubyte2_e32 v126, v168
	v_cvt_f32_ubyte3_e32 v127, v168
	v_pk_fma_f32 v[84:85], v[50:51], v[102:103], v[84:85] op_sel:[1,0,0]
	v_cvt_f32_ubyte0_e32 v96, v86
	v_cvt_f32_ubyte1_e32 v97, v86
	v_pk_fma_f32 v[80:81], v[50:51], v[126:127], v[80:81] op_sel:[1,0,0]
	v_and_b32_e32 v74, s34, v170
	v_and_b32_e32 v78, s34, v171
	v_cvt_f32_ubyte2_e32 v100, v86
	v_cvt_f32_ubyte3_e32 v101, v86
	v_pk_fma_f32 v[76:77], v[50:51], v[96:97], v[76:77] op_sel:[1,0,0]
	v_cvt_f32_ubyte0_e32 v102, v169
	v_cvt_f32_ubyte1_e32 v103, v169
	v_pk_fma_f32 v[68:69], v[50:51], v[100:101], v[68:69] op_sel:[1,0,0]
	v_cvt_f32_ubyte2_e32 v126, v169
	v_cvt_f32_ubyte3_e32 v127, v169
	v_pk_fma_f32 v[62:63], v[50:51], v[102:103], v[62:63] op_sel:[1,0,0]
	v_cvt_f32_ubyte0_e32 v96, v74
	v_cvt_f32_ubyte1_e32 v97, v74
	v_pk_fma_f32 v[60:61], v[50:51], v[126:127], v[60:61] op_sel:[1,0,0]
	v_cvt_f32_ubyte2_e32 v100, v74
	v_cvt_f32_ubyte3_e32 v101, v74
	v_pk_fma_f32 v[90:91], v[52:53], v[96:97], v[90:91] op_sel_hi:[0,1,1]
	v_cvt_f32_ubyte0_e32 v102, v170
	v_cvt_f32_ubyte1_e32 v103, v170
	v_pk_fma_f32 v[88:89], v[52:53], v[100:101], v[88:89] op_sel_hi:[0,1,1]
	v_cvt_f32_ubyte2_e32 v126, v170
	v_cvt_f32_ubyte3_e32 v127, v170
	v_pk_fma_f32 v[84:85], v[52:53], v[102:103], v[84:85] op_sel_hi:[0,1,1]
	v_cvt_f32_ubyte0_e32 v96, v78
	v_cvt_f32_ubyte1_e32 v97, v78
	v_pk_fma_f32 v[80:81], v[52:53], v[126:127], v[80:81] op_sel_hi:[0,1,1]
	v_and_b32_e32 v82, s34, v172
	v_and_b32_e32 v86, s34, v173
	v_cvt_f32_ubyte2_e32 v100, v78
	v_cvt_f32_ubyte3_e32 v101, v78
	v_pk_fma_f32 v[76:77], v[52:53], v[96:97], v[76:77] op_sel_hi:[0,1,1]
	v_cvt_f32_ubyte0_e32 v102, v171
	v_cvt_f32_ubyte1_e32 v103, v171
	v_pk_fma_f32 v[68:69], v[52:53], v[100:101], v[68:69] op_sel_hi:[0,1,1]
	v_cvt_f32_ubyte2_e32 v126, v171
	v_cvt_f32_ubyte3_e32 v127, v171
	v_pk_fma_f32 v[62:63], v[52:53], v[102:103], v[62:63] op_sel_hi:[0,1,1]
	v_cvt_f32_ubyte0_e32 v96, v82
	v_cvt_f32_ubyte1_e32 v97, v82
	v_pk_fma_f32 v[60:61], v[52:53], v[126:127], v[60:61] op_sel_hi:[0,1,1]
	v_cvt_f32_ubyte2_e32 v100, v82
	v_cvt_f32_ubyte3_e32 v101, v82
	v_pk_fma_f32 v[90:91], v[52:53], v[96:97], v[90:91] op_sel:[1,0,0]
	v_cvt_f32_ubyte0_e32 v102, v172
	v_cvt_f32_ubyte1_e32 v103, v172
	v_pk_fma_f32 v[88:89], v[52:53], v[100:101], v[88:89] op_sel:[1,0,0]
	v_cvt_f32_ubyte2_e32 v126, v172
	v_cvt_f32_ubyte3_e32 v127, v172
	v_pk_fma_f32 v[84:85], v[52:53], v[102:103], v[84:85] op_sel:[1,0,0]
	v_cvt_f32_ubyte0_e32 v96, v86
	v_cvt_f32_ubyte1_e32 v97, v86
	v_pk_fma_f32 v[80:81], v[52:53], v[126:127], v[80:81] op_sel:[1,0,0]
	v_and_b32_e32 v74, s34, v174
	v_and_b32_e32 v78, s34, v175
	v_cvt_f32_ubyte2_e32 v100, v86
	v_cvt_f32_ubyte3_e32 v101, v86
	v_pk_fma_f32 v[76:77], v[52:53], v[96:97], v[76:77] op_sel:[1,0,0]
	v_cvt_f32_ubyte0_e32 v102, v173
	v_cvt_f32_ubyte1_e32 v103, v173
	v_pk_fma_f32 v[68:69], v[52:53], v[100:101], v[68:69] op_sel:[1,0,0]
	v_cvt_f32_ubyte2_e32 v126, v173
	v_cvt_f32_ubyte3_e32 v127, v173
	v_pk_fma_f32 v[62:63], v[52:53], v[102:103], v[62:63] op_sel:[1,0,0]
	v_cvt_f32_ubyte0_e32 v96, v74
	v_cvt_f32_ubyte1_e32 v97, v74
	v_pk_fma_f32 v[60:61], v[52:53], v[126:127], v[60:61] op_sel:[1,0,0]
	v_cvt_f32_ubyte2_e32 v100, v74
	v_cvt_f32_ubyte3_e32 v101, v74
	v_pk_fma_f32 v[90:91], v[54:55], v[96:97], v[90:91] op_sel_hi:[0,1,1]
	v_cvt_f32_ubyte0_e32 v102, v174
	v_cvt_f32_ubyte1_e32 v103, v174
	v_pk_fma_f32 v[88:89], v[54:55], v[100:101], v[88:89] op_sel_hi:[0,1,1]
	v_cvt_f32_ubyte2_e32 v126, v174
	v_cvt_f32_ubyte3_e32 v127, v174
	v_pk_fma_f32 v[84:85], v[54:55], v[102:103], v[84:85] op_sel_hi:[0,1,1]
	v_cvt_f32_ubyte0_e32 v96, v78
	v_cvt_f32_ubyte1_e32 v97, v78
	v_pk_fma_f32 v[80:81], v[54:55], v[126:127], v[80:81] op_sel_hi:[0,1,1]
	v_and_b32_e32 v82, s34, v176
	v_and_b32_e32 v86, s34, v177
	v_cvt_f32_ubyte2_e32 v100, v78
	v_cvt_f32_ubyte3_e32 v101, v78
	v_pk_fma_f32 v[76:77], v[54:55], v[96:97], v[76:77] op_sel_hi:[0,1,1]
	v_cvt_f32_ubyte0_e32 v102, v175
	v_cvt_f32_ubyte1_e32 v103, v175
	v_pk_fma_f32 v[68:69], v[54:55], v[100:101], v[68:69] op_sel_hi:[0,1,1]
	v_cvt_f32_ubyte2_e32 v126, v175
	v_cvt_f32_ubyte3_e32 v127, v175
	v_pk_fma_f32 v[62:63], v[54:55], v[102:103], v[62:63] op_sel_hi:[0,1,1]
	v_cvt_f32_ubyte0_e32 v96, v82
	v_cvt_f32_ubyte1_e32 v97, v82
	v_pk_fma_f32 v[60:61], v[54:55], v[126:127], v[60:61] op_sel_hi:[0,1,1]
	v_cvt_f32_ubyte2_e32 v100, v82
	v_cvt_f32_ubyte3_e32 v101, v82
	v_pk_fma_f32 v[90:91], v[54:55], v[96:97], v[90:91] op_sel:[1,0,0]
	v_cvt_f32_ubyte0_e32 v102, v176
	v_cvt_f32_ubyte1_e32 v103, v176
	v_pk_fma_f32 v[88:89], v[54:55], v[100:101], v[88:89] op_sel:[1,0,0]
	v_cvt_f32_ubyte2_e32 v126, v176
	v_cvt_f32_ubyte3_e32 v127, v176
	v_pk_fma_f32 v[84:85], v[54:55], v[102:103], v[84:85] op_sel:[1,0,0]
	v_cvt_f32_ubyte0_e32 v96, v86
	v_cvt_f32_ubyte1_e32 v97, v86
	v_pk_fma_f32 v[80:81], v[54:55], v[126:127], v[80:81] op_sel:[1,0,0]
	v_cvt_f32_ubyte2_e32 v100, v86
	v_cvt_f32_ubyte3_e32 v101, v86
	v_pk_fma_f32 v[76:77], v[54:55], v[96:97], v[76:77] op_sel:[1,0,0]
	v_cvt_f32_ubyte0_e32 v102, v177
	v_cvt_f32_ubyte1_e32 v103, v177
	v_pk_fma_f32 v[68:69], v[54:55], v[100:101], v[68:69] op_sel:[1,0,0]
	v_cvt_f32_ubyte2_e32 v126, v177
	v_cvt_f32_ubyte3_e32 v127, v177
	v_pk_fma_f32 v[62:63], v[54:55], v[102:103], v[62:63] op_sel:[1,0,0]
	v_pk_fma_f32 v[60:61], v[54:55], v[126:127], v[60:61] op_sel:[1,0,0]
	s_waitcnt lgkmcnt(0)
	ds_read_b128 v[48:51], v128 offset:992
	ds_read_b128 v[52:55], v128 offset:1008
	s_waitcnt vmcnt(8)
	v_and_b32_e32 v74, s34, v178
	v_and_b32_e32 v78, s34, v179
	v_cvt_f32_ubyte0_e32 v96, v74
	v_cvt_f32_ubyte1_e32 v97, v74
	v_cvt_f32_ubyte2_e32 v100, v74
	v_cvt_f32_ubyte3_e32 v101, v74
	v_pk_fma_f32 v[90:91], v[32:33], v[96:97], v[90:91] op_sel_hi:[0,1,1]
	v_cvt_f32_ubyte0_e32 v102, v178
	v_cvt_f32_ubyte1_e32 v103, v178
	v_pk_fma_f32 v[88:89], v[32:33], v[100:101], v[88:89] op_sel_hi:[0,1,1]
	v_cvt_f32_ubyte2_e32 v126, v178
	v_cvt_f32_ubyte3_e32 v127, v178
	v_pk_fma_f32 v[84:85], v[32:33], v[102:103], v[84:85] op_sel_hi:[0,1,1]
	v_cvt_f32_ubyte0_e32 v96, v78
	v_cvt_f32_ubyte1_e32 v97, v78
	v_pk_fma_f32 v[80:81], v[32:33], v[126:127], v[80:81] op_sel_hi:[0,1,1]
	v_and_b32_e32 v82, s34, v180
	v_and_b32_e32 v86, s34, v181
	v_cvt_f32_ubyte2_e32 v100, v78
	v_cvt_f32_ubyte3_e32 v101, v78
	v_pk_fma_f32 v[76:77], v[32:33], v[96:97], v[76:77] op_sel_hi:[0,1,1]
	v_cvt_f32_ubyte0_e32 v102, v179
	v_cvt_f32_ubyte1_e32 v103, v179
	v_pk_fma_f32 v[68:69], v[32:33], v[100:101], v[68:69] op_sel_hi:[0,1,1]
	v_cvt_f32_ubyte2_e32 v126, v179
	v_cvt_f32_ubyte3_e32 v127, v179
	v_pk_fma_f32 v[62:63], v[32:33], v[102:103], v[62:63] op_sel_hi:[0,1,1]
	v_cvt_f32_ubyte0_e32 v96, v82
	v_cvt_f32_ubyte1_e32 v97, v82
	v_pk_fma_f32 v[60:61], v[32:33], v[126:127], v[60:61] op_sel_hi:[0,1,1]
	v_cvt_f32_ubyte2_e32 v100, v82
	v_cvt_f32_ubyte3_e32 v101, v82
	v_pk_fma_f32 v[90:91], v[32:33], v[96:97], v[90:91] op_sel:[1,0,0]
	v_cvt_f32_ubyte0_e32 v102, v180
	v_cvt_f32_ubyte1_e32 v103, v180
	v_pk_fma_f32 v[88:89], v[32:33], v[100:101], v[88:89] op_sel:[1,0,0]
	v_cvt_f32_ubyte2_e32 v126, v180
	v_cvt_f32_ubyte3_e32 v127, v180
	v_pk_fma_f32 v[84:85], v[32:33], v[102:103], v[84:85] op_sel:[1,0,0]
	v_cvt_f32_ubyte0_e32 v96, v86
	v_cvt_f32_ubyte1_e32 v97, v86
	v_pk_fma_f32 v[80:81], v[32:33], v[126:127], v[80:81] op_sel:[1,0,0]
	v_and_b32_e32 v74, s34, v182
	v_and_b32_e32 v78, s34, v183
	v_cvt_f32_ubyte2_e32 v100, v86
	v_cvt_f32_ubyte3_e32 v101, v86
	v_pk_fma_f32 v[76:77], v[32:33], v[96:97], v[76:77] op_sel:[1,0,0]
	v_cvt_f32_ubyte0_e32 v102, v181
	v_cvt_f32_ubyte1_e32 v103, v181
	v_pk_fma_f32 v[68:69], v[32:33], v[100:101], v[68:69] op_sel:[1,0,0]
	v_cvt_f32_ubyte2_e32 v126, v181
	v_cvt_f32_ubyte3_e32 v127, v181
	v_pk_fma_f32 v[62:63], v[32:33], v[102:103], v[62:63] op_sel:[1,0,0]
	v_cvt_f32_ubyte0_e32 v96, v74
	v_cvt_f32_ubyte1_e32 v97, v74
	v_pk_fma_f32 v[60:61], v[32:33], v[126:127], v[60:61] op_sel:[1,0,0]
	v_cvt_f32_ubyte2_e32 v100, v74
	v_cvt_f32_ubyte3_e32 v101, v74
	v_pk_fma_f32 v[90:91], v[34:35], v[96:97], v[90:91] op_sel_hi:[0,1,1]
	v_cvt_f32_ubyte0_e32 v102, v182
	v_cvt_f32_ubyte1_e32 v103, v182
	v_pk_fma_f32 v[88:89], v[34:35], v[100:101], v[88:89] op_sel_hi:[0,1,1]
	v_cvt_f32_ubyte2_e32 v126, v182
	v_cvt_f32_ubyte3_e32 v127, v182
	v_pk_fma_f32 v[84:85], v[34:35], v[102:103], v[84:85] op_sel_hi:[0,1,1]
	v_cvt_f32_ubyte0_e32 v96, v78
	v_cvt_f32_ubyte1_e32 v97, v78
	v_pk_fma_f32 v[80:81], v[34:35], v[126:127], v[80:81] op_sel_hi:[0,1,1]
	v_and_b32_e32 v82, s34, v184
	v_and_b32_e32 v86, s34, v185
	v_cvt_f32_ubyte2_e32 v100, v78
	v_cvt_f32_ubyte3_e32 v101, v78
	v_pk_fma_f32 v[76:77], v[34:35], v[96:97], v[76:77] op_sel_hi:[0,1,1]
	v_cvt_f32_ubyte0_e32 v102, v183
	v_cvt_f32_ubyte1_e32 v103, v183
	v_pk_fma_f32 v[68:69], v[34:35], v[100:101], v[68:69] op_sel_hi:[0,1,1]
	v_cvt_f32_ubyte2_e32 v126, v183
	v_cvt_f32_ubyte3_e32 v127, v183
	v_pk_fma_f32 v[62:63], v[34:35], v[102:103], v[62:63] op_sel_hi:[0,1,1]
	v_cvt_f32_ubyte0_e32 v96, v82
	v_cvt_f32_ubyte1_e32 v97, v82
	v_pk_fma_f32 v[60:61], v[34:35], v[126:127], v[60:61] op_sel_hi:[0,1,1]
	v_cvt_f32_ubyte2_e32 v100, v82
	v_cvt_f32_ubyte3_e32 v101, v82
	v_pk_fma_f32 v[90:91], v[34:35], v[96:97], v[90:91] op_sel:[1,0,0]
	v_cvt_f32_ubyte0_e32 v102, v184
	v_cvt_f32_ubyte1_e32 v103, v184
	v_pk_fma_f32 v[88:89], v[34:35], v[100:101], v[88:89] op_sel:[1,0,0]
	v_cvt_f32_ubyte2_e32 v126, v184
	v_cvt_f32_ubyte3_e32 v127, v184
	v_pk_fma_f32 v[84:85], v[34:35], v[102:103], v[84:85] op_sel:[1,0,0]
	v_cvt_f32_ubyte0_e32 v96, v86
	v_cvt_f32_ubyte1_e32 v97, v86
	v_pk_fma_f32 v[80:81], v[34:35], v[126:127], v[80:81] op_sel:[1,0,0]
	v_and_b32_e32 v74, s34, v186
	v_and_b32_e32 v78, s34, v187
	v_cvt_f32_ubyte2_e32 v100, v86
	v_cvt_f32_ubyte3_e32 v101, v86
	v_pk_fma_f32 v[76:77], v[34:35], v[96:97], v[76:77] op_sel:[1,0,0]
	v_cvt_f32_ubyte0_e32 v102, v185
	v_cvt_f32_ubyte1_e32 v103, v185
	v_pk_fma_f32 v[68:69], v[34:35], v[100:101], v[68:69] op_sel:[1,0,0]
	v_cvt_f32_ubyte2_e32 v126, v185
	v_cvt_f32_ubyte3_e32 v127, v185
	v_pk_fma_f32 v[62:63], v[34:35], v[102:103], v[62:63] op_sel:[1,0,0]
	v_cvt_f32_ubyte0_e32 v96, v74
	v_cvt_f32_ubyte1_e32 v97, v74
	v_pk_fma_f32 v[60:61], v[34:35], v[126:127], v[60:61] op_sel:[1,0,0]
	v_cvt_f32_ubyte2_e32 v100, v74
	v_cvt_f32_ubyte3_e32 v101, v74
	v_pk_fma_f32 v[90:91], v[36:37], v[96:97], v[90:91] op_sel_hi:[0,1,1]
	v_cvt_f32_ubyte0_e32 v102, v186
	v_cvt_f32_ubyte1_e32 v103, v186
	v_pk_fma_f32 v[88:89], v[36:37], v[100:101], v[88:89] op_sel_hi:[0,1,1]
	v_cvt_f32_ubyte2_e32 v126, v186
	v_cvt_f32_ubyte3_e32 v127, v186
	v_pk_fma_f32 v[84:85], v[36:37], v[102:103], v[84:85] op_sel_hi:[0,1,1]
	v_cvt_f32_ubyte0_e32 v96, v78
	v_cvt_f32_ubyte1_e32 v97, v78
	v_pk_fma_f32 v[80:81], v[36:37], v[126:127], v[80:81] op_sel_hi:[0,1,1]
	v_and_b32_e32 v82, s34, v188
	v_and_b32_e32 v86, s34, v189
	v_cvt_f32_ubyte2_e32 v100, v78
	v_cvt_f32_ubyte3_e32 v101, v78
	v_pk_fma_f32 v[76:77], v[36:37], v[96:97], v[76:77] op_sel_hi:[0,1,1]
	v_cvt_f32_ubyte0_e32 v102, v187
	v_cvt_f32_ubyte1_e32 v103, v187
	v_pk_fma_f32 v[68:69], v[36:37], v[100:101], v[68:69] op_sel_hi:[0,1,1]
	v_cvt_f32_ubyte2_e32 v126, v187
	v_cvt_f32_ubyte3_e32 v127, v187
	v_pk_fma_f32 v[62:63], v[36:37], v[102:103], v[62:63] op_sel_hi:[0,1,1]
	v_cvt_f32_ubyte0_e32 v96, v82
	v_cvt_f32_ubyte1_e32 v97, v82
	v_pk_fma_f32 v[60:61], v[36:37], v[126:127], v[60:61] op_sel_hi:[0,1,1]
	v_cvt_f32_ubyte2_e32 v100, v82
	v_cvt_f32_ubyte3_e32 v101, v82
	v_pk_fma_f32 v[90:91], v[36:37], v[96:97], v[90:91] op_sel:[1,0,0]
	v_cvt_f32_ubyte0_e32 v102, v188
	v_cvt_f32_ubyte1_e32 v103, v188
	v_pk_fma_f32 v[88:89], v[36:37], v[100:101], v[88:89] op_sel:[1,0,0]
	v_cvt_f32_ubyte2_e32 v126, v188
	v_cvt_f32_ubyte3_e32 v127, v188
	v_pk_fma_f32 v[84:85], v[36:37], v[102:103], v[84:85] op_sel:[1,0,0]
	v_cvt_f32_ubyte0_e32 v96, v86
	v_cvt_f32_ubyte1_e32 v97, v86
	v_pk_fma_f32 v[80:81], v[36:37], v[126:127], v[80:81] op_sel:[1,0,0]
	v_and_b32_e32 v74, s34, v190
	v_and_b32_e32 v78, s34, v191
	v_cvt_f32_ubyte2_e32 v100, v86
	v_cvt_f32_ubyte3_e32 v101, v86
	v_pk_fma_f32 v[76:77], v[36:37], v[96:97], v[76:77] op_sel:[1,0,0]
	v_cvt_f32_ubyte0_e32 v102, v189
	v_cvt_f32_ubyte1_e32 v103, v189
	v_pk_fma_f32 v[68:69], v[36:37], v[100:101], v[68:69] op_sel:[1,0,0]
	v_cvt_f32_ubyte2_e32 v126, v189
	v_cvt_f32_ubyte3_e32 v127, v189
	v_pk_fma_f32 v[62:63], v[36:37], v[102:103], v[62:63] op_sel:[1,0,0]
	v_cvt_f32_ubyte0_e32 v96, v74
	v_cvt_f32_ubyte1_e32 v97, v74
	v_pk_fma_f32 v[60:61], v[36:37], v[126:127], v[60:61] op_sel:[1,0,0]
	v_cvt_f32_ubyte2_e32 v100, v74
	v_cvt_f32_ubyte3_e32 v101, v74
	v_pk_fma_f32 v[90:91], v[38:39], v[96:97], v[90:91] op_sel_hi:[0,1,1]
	v_cvt_f32_ubyte0_e32 v102, v190
	v_cvt_f32_ubyte1_e32 v103, v190
	v_pk_fma_f32 v[88:89], v[38:39], v[100:101], v[88:89] op_sel_hi:[0,1,1]
	v_cvt_f32_ubyte2_e32 v126, v190
	v_cvt_f32_ubyte3_e32 v127, v190
	v_pk_fma_f32 v[84:85], v[38:39], v[102:103], v[84:85] op_sel_hi:[0,1,1]
	v_cvt_f32_ubyte0_e32 v96, v78
	v_cvt_f32_ubyte1_e32 v97, v78
	v_pk_fma_f32 v[80:81], v[38:39], v[126:127], v[80:81] op_sel_hi:[0,1,1]
	v_and_b32_e32 v82, s34, v192
	v_and_b32_e32 v86, s34, v193
	v_cvt_f32_ubyte2_e32 v100, v78
	v_cvt_f32_ubyte3_e32 v101, v78
	v_pk_fma_f32 v[76:77], v[38:39], v[96:97], v[76:77] op_sel_hi:[0,1,1]
	v_cvt_f32_ubyte0_e32 v102, v191
	v_cvt_f32_ubyte1_e32 v103, v191
	v_pk_fma_f32 v[68:69], v[38:39], v[100:101], v[68:69] op_sel_hi:[0,1,1]
	v_cvt_f32_ubyte2_e32 v126, v191
	v_cvt_f32_ubyte3_e32 v127, v191
	v_pk_fma_f32 v[62:63], v[38:39], v[102:103], v[62:63] op_sel_hi:[0,1,1]
	v_cvt_f32_ubyte0_e32 v96, v82
	v_cvt_f32_ubyte1_e32 v97, v82
	v_pk_fma_f32 v[60:61], v[38:39], v[126:127], v[60:61] op_sel_hi:[0,1,1]
	v_cvt_f32_ubyte2_e32 v100, v82
	v_cvt_f32_ubyte3_e32 v101, v82
	v_pk_fma_f32 v[90:91], v[38:39], v[96:97], v[90:91] op_sel:[1,0,0]
	v_cvt_f32_ubyte0_e32 v102, v192
	v_cvt_f32_ubyte1_e32 v103, v192
	v_pk_fma_f32 v[88:89], v[38:39], v[100:101], v[88:89] op_sel:[1,0,0]
	v_cvt_f32_ubyte2_e32 v126, v192
	v_cvt_f32_ubyte3_e32 v127, v192
	v_pk_fma_f32 v[84:85], v[38:39], v[102:103], v[84:85] op_sel:[1,0,0]
	v_cvt_f32_ubyte0_e32 v96, v86
	v_cvt_f32_ubyte1_e32 v97, v86
	v_pk_fma_f32 v[80:81], v[38:39], v[126:127], v[80:81] op_sel:[1,0,0]
	v_cvt_f32_ubyte2_e32 v100, v86
	v_cvt_f32_ubyte3_e32 v101, v86
	v_pk_fma_f32 v[76:77], v[38:39], v[96:97], v[76:77] op_sel:[1,0,0]
	v_cvt_f32_ubyte0_e32 v102, v193
	v_cvt_f32_ubyte1_e32 v103, v193
	v_pk_fma_f32 v[68:69], v[38:39], v[100:101], v[68:69] op_sel:[1,0,0]
	v_cvt_f32_ubyte2_e32 v126, v193
	v_cvt_f32_ubyte3_e32 v127, v193
	v_pk_fma_f32 v[62:63], v[38:39], v[102:103], v[62:63] op_sel:[1,0,0]
	v_pk_fma_f32 v[60:61], v[38:39], v[126:127], v[60:61] op_sel:[1,0,0]
	s_waitcnt lgkmcnt(0)
	s_waitcnt vmcnt(0)
	v_and_b32_e32 v74, s34, v194
	v_and_b32_e32 v78, s34, v195
	v_cvt_f32_ubyte0_e32 v96, v74
	v_cvt_f32_ubyte1_e32 v97, v74
	v_cvt_f32_ubyte2_e32 v100, v74
	v_cvt_f32_ubyte3_e32 v101, v74
	v_pk_fma_f32 v[90:91], v[48:49], v[96:97], v[90:91] op_sel_hi:[0,1,1]
	v_cvt_f32_ubyte0_e32 v102, v194
	v_cvt_f32_ubyte1_e32 v103, v194
	v_pk_fma_f32 v[88:89], v[48:49], v[100:101], v[88:89] op_sel_hi:[0,1,1]
	v_cvt_f32_ubyte2_e32 v126, v194
	v_cvt_f32_ubyte3_e32 v127, v194
	v_pk_fma_f32 v[84:85], v[48:49], v[102:103], v[84:85] op_sel_hi:[0,1,1]
	v_cvt_f32_ubyte0_e32 v96, v78
	v_cvt_f32_ubyte1_e32 v97, v78
	v_pk_fma_f32 v[80:81], v[48:49], v[126:127], v[80:81] op_sel_hi:[0,1,1]
	v_and_b32_e32 v82, s34, v196
	v_and_b32_e32 v86, s34, v197
	v_cvt_f32_ubyte2_e32 v100, v78
	v_cvt_f32_ubyte3_e32 v101, v78
	v_pk_fma_f32 v[76:77], v[48:49], v[96:97], v[76:77] op_sel_hi:[0,1,1]
	v_cvt_f32_ubyte0_e32 v102, v195
	v_cvt_f32_ubyte1_e32 v103, v195
	v_pk_fma_f32 v[68:69], v[48:49], v[100:101], v[68:69] op_sel_hi:[0,1,1]
	v_cvt_f32_ubyte2_e32 v126, v195
	v_cvt_f32_ubyte3_e32 v127, v195
	v_pk_fma_f32 v[62:63], v[48:49], v[102:103], v[62:63] op_sel_hi:[0,1,1]
	v_cvt_f32_ubyte0_e32 v96, v82
	v_cvt_f32_ubyte1_e32 v97, v82
	v_pk_fma_f32 v[60:61], v[48:49], v[126:127], v[60:61] op_sel_hi:[0,1,1]
	v_cvt_f32_ubyte2_e32 v100, v82
	v_cvt_f32_ubyte3_e32 v101, v82
	v_pk_fma_f32 v[90:91], v[48:49], v[96:97], v[90:91] op_sel:[1,0,0]
	v_cvt_f32_ubyte0_e32 v102, v196
	v_cvt_f32_ubyte1_e32 v103, v196
	v_pk_fma_f32 v[88:89], v[48:49], v[100:101], v[88:89] op_sel:[1,0,0]
	v_cvt_f32_ubyte2_e32 v126, v196
	v_cvt_f32_ubyte3_e32 v127, v196
	v_pk_fma_f32 v[84:85], v[48:49], v[102:103], v[84:85] op_sel:[1,0,0]
	v_cvt_f32_ubyte0_e32 v96, v86
	v_cvt_f32_ubyte1_e32 v97, v86
	v_pk_fma_f32 v[80:81], v[48:49], v[126:127], v[80:81] op_sel:[1,0,0]
	v_and_b32_e32 v74, s34, v198
	v_and_b32_e32 v78, s34, v199
	v_cvt_f32_ubyte2_e32 v100, v86
	v_cvt_f32_ubyte3_e32 v101, v86
	v_pk_fma_f32 v[76:77], v[48:49], v[96:97], v[76:77] op_sel:[1,0,0]
	v_cvt_f32_ubyte0_e32 v102, v197
	v_cvt_f32_ubyte1_e32 v103, v197
	v_pk_fma_f32 v[68:69], v[48:49], v[100:101], v[68:69] op_sel:[1,0,0]
	v_cvt_f32_ubyte2_e32 v126, v197
	v_cvt_f32_ubyte3_e32 v127, v197
	v_pk_fma_f32 v[62:63], v[48:49], v[102:103], v[62:63] op_sel:[1,0,0]
	v_cvt_f32_ubyte0_e32 v96, v74
	v_cvt_f32_ubyte1_e32 v97, v74
	v_pk_fma_f32 v[60:61], v[48:49], v[126:127], v[60:61] op_sel:[1,0,0]
	v_cvt_f32_ubyte2_e32 v100, v74
	v_cvt_f32_ubyte3_e32 v101, v74
	v_pk_fma_f32 v[90:91], v[50:51], v[96:97], v[90:91] op_sel_hi:[0,1,1]
	v_cvt_f32_ubyte0_e32 v102, v198
	v_cvt_f32_ubyte1_e32 v103, v198
	v_pk_fma_f32 v[88:89], v[50:51], v[100:101], v[88:89] op_sel_hi:[0,1,1]
	v_cvt_f32_ubyte2_e32 v126, v198
	v_cvt_f32_ubyte3_e32 v127, v198
	v_pk_fma_f32 v[84:85], v[50:51], v[102:103], v[84:85] op_sel_hi:[0,1,1]
	v_cvt_f32_ubyte0_e32 v96, v78
	v_cvt_f32_ubyte1_e32 v97, v78
	v_pk_fma_f32 v[80:81], v[50:51], v[126:127], v[80:81] op_sel_hi:[0,1,1]
	v_and_b32_e32 v82, s34, v200
	v_and_b32_e32 v86, s34, v201
	v_cvt_f32_ubyte2_e32 v100, v78
	v_cvt_f32_ubyte3_e32 v101, v78
	v_pk_fma_f32 v[76:77], v[50:51], v[96:97], v[76:77] op_sel_hi:[0,1,1]
	v_cvt_f32_ubyte0_e32 v102, v199
	v_cvt_f32_ubyte1_e32 v103, v199
	v_pk_fma_f32 v[68:69], v[50:51], v[100:101], v[68:69] op_sel_hi:[0,1,1]
	v_cvt_f32_ubyte2_e32 v126, v199
	v_cvt_f32_ubyte3_e32 v127, v199
	v_pk_fma_f32 v[62:63], v[50:51], v[102:103], v[62:63] op_sel_hi:[0,1,1]
	v_cvt_f32_ubyte0_e32 v96, v82
	v_cvt_f32_ubyte1_e32 v97, v82
	v_pk_fma_f32 v[60:61], v[50:51], v[126:127], v[60:61] op_sel_hi:[0,1,1]
	v_cvt_f32_ubyte2_e32 v100, v82
	v_cvt_f32_ubyte3_e32 v101, v82
	v_pk_fma_f32 v[90:91], v[50:51], v[96:97], v[90:91] op_sel:[1,0,0]
	v_cvt_f32_ubyte0_e32 v102, v200
	v_cvt_f32_ubyte1_e32 v103, v200
	v_pk_fma_f32 v[88:89], v[50:51], v[100:101], v[88:89] op_sel:[1,0,0]
	v_cvt_f32_ubyte2_e32 v126, v200
	v_cvt_f32_ubyte3_e32 v127, v200
	v_pk_fma_f32 v[84:85], v[50:51], v[102:103], v[84:85] op_sel:[1,0,0]
	v_cvt_f32_ubyte0_e32 v96, v86
	v_cvt_f32_ubyte1_e32 v97, v86
	v_pk_fma_f32 v[80:81], v[50:51], v[126:127], v[80:81] op_sel:[1,0,0]
	v_and_b32_e32 v74, s34, v202
	v_and_b32_e32 v78, s34, v203
	v_cvt_f32_ubyte2_e32 v100, v86
	v_cvt_f32_ubyte3_e32 v101, v86
	v_pk_fma_f32 v[76:77], v[50:51], v[96:97], v[76:77] op_sel:[1,0,0]
	v_cvt_f32_ubyte0_e32 v102, v201
	v_cvt_f32_ubyte1_e32 v103, v201
	v_pk_fma_f32 v[68:69], v[50:51], v[100:101], v[68:69] op_sel:[1,0,0]
	v_cvt_f32_ubyte2_e32 v126, v201
	v_cvt_f32_ubyte3_e32 v127, v201
	v_pk_fma_f32 v[62:63], v[50:51], v[102:103], v[62:63] op_sel:[1,0,0]
	v_cvt_f32_ubyte0_e32 v96, v74
	v_cvt_f32_ubyte1_e32 v97, v74
	v_pk_fma_f32 v[60:61], v[50:51], v[126:127], v[60:61] op_sel:[1,0,0]
	v_cvt_f32_ubyte2_e32 v100, v74
	v_cvt_f32_ubyte3_e32 v101, v74
	v_pk_fma_f32 v[90:91], v[52:53], v[96:97], v[90:91] op_sel_hi:[0,1,1]
	v_cvt_f32_ubyte0_e32 v102, v202
	v_cvt_f32_ubyte1_e32 v103, v202
	v_pk_fma_f32 v[88:89], v[52:53], v[100:101], v[88:89] op_sel_hi:[0,1,1]
	v_cvt_f32_ubyte2_e32 v126, v202
	v_cvt_f32_ubyte3_e32 v127, v202
	v_pk_fma_f32 v[84:85], v[52:53], v[102:103], v[84:85] op_sel_hi:[0,1,1]
	v_cvt_f32_ubyte0_e32 v96, v78
	v_cvt_f32_ubyte1_e32 v97, v78
	v_pk_fma_f32 v[80:81], v[52:53], v[126:127], v[80:81] op_sel_hi:[0,1,1]
	v_and_b32_e32 v82, s34, v204
	v_and_b32_e32 v86, s34, v205
	v_cvt_f32_ubyte2_e32 v100, v78
	v_cvt_f32_ubyte3_e32 v101, v78
	v_pk_fma_f32 v[76:77], v[52:53], v[96:97], v[76:77] op_sel_hi:[0,1,1]
	v_cvt_f32_ubyte0_e32 v102, v203
	v_cvt_f32_ubyte1_e32 v103, v203
	v_pk_fma_f32 v[68:69], v[52:53], v[100:101], v[68:69] op_sel_hi:[0,1,1]
	v_cvt_f32_ubyte2_e32 v126, v203
	v_cvt_f32_ubyte3_e32 v127, v203
	v_pk_fma_f32 v[62:63], v[52:53], v[102:103], v[62:63] op_sel_hi:[0,1,1]
	v_cvt_f32_ubyte0_e32 v96, v82
	v_cvt_f32_ubyte1_e32 v97, v82
	v_pk_fma_f32 v[60:61], v[52:53], v[126:127], v[60:61] op_sel_hi:[0,1,1]
	v_cvt_f32_ubyte2_e32 v100, v82
	v_cvt_f32_ubyte3_e32 v101, v82
	v_pk_fma_f32 v[90:91], v[52:53], v[96:97], v[90:91] op_sel:[1,0,0]
	v_cvt_f32_ubyte0_e32 v102, v204
	v_cvt_f32_ubyte1_e32 v103, v204
	v_pk_fma_f32 v[88:89], v[52:53], v[100:101], v[88:89] op_sel:[1,0,0]
	v_cvt_f32_ubyte2_e32 v126, v204
	v_cvt_f32_ubyte3_e32 v127, v204
	v_pk_fma_f32 v[84:85], v[52:53], v[102:103], v[84:85] op_sel:[1,0,0]
	v_cvt_f32_ubyte0_e32 v96, v86
	v_cvt_f32_ubyte1_e32 v97, v86
	v_pk_fma_f32 v[80:81], v[52:53], v[126:127], v[80:81] op_sel:[1,0,0]
	v_and_b32_e32 v74, s34, v206
	v_and_b32_e32 v78, s34, v207
	v_cvt_f32_ubyte2_e32 v100, v86
	v_cvt_f32_ubyte3_e32 v101, v86
	v_pk_fma_f32 v[76:77], v[52:53], v[96:97], v[76:77] op_sel:[1,0,0]
	v_cvt_f32_ubyte0_e32 v102, v205
	v_cvt_f32_ubyte1_e32 v103, v205
	v_pk_fma_f32 v[68:69], v[52:53], v[100:101], v[68:69] op_sel:[1,0,0]
	v_cvt_f32_ubyte2_e32 v126, v205
	v_cvt_f32_ubyte3_e32 v127, v205
	v_pk_fma_f32 v[62:63], v[52:53], v[102:103], v[62:63] op_sel:[1,0,0]
	v_cvt_f32_ubyte0_e32 v96, v74
	v_cvt_f32_ubyte1_e32 v97, v74
	v_pk_fma_f32 v[60:61], v[52:53], v[126:127], v[60:61] op_sel:[1,0,0]
	v_cvt_f32_ubyte2_e32 v100, v74
	v_cvt_f32_ubyte3_e32 v101, v74
	v_pk_fma_f32 v[90:91], v[54:55], v[96:97], v[90:91] op_sel_hi:[0,1,1]
	v_cvt_f32_ubyte0_e32 v102, v206
	v_cvt_f32_ubyte1_e32 v103, v206
	v_pk_fma_f32 v[88:89], v[54:55], v[100:101], v[88:89] op_sel_hi:[0,1,1]
	v_cvt_f32_ubyte2_e32 v126, v206
	v_cvt_f32_ubyte3_e32 v127, v206
	v_pk_fma_f32 v[84:85], v[54:55], v[102:103], v[84:85] op_sel_hi:[0,1,1]
	v_cvt_f32_ubyte0_e32 v96, v78
	v_cvt_f32_ubyte1_e32 v97, v78
	v_pk_fma_f32 v[80:81], v[54:55], v[126:127], v[80:81] op_sel_hi:[0,1,1]
	v_and_b32_e32 v82, s34, v208
	v_and_b32_e32 v86, s34, v209
	v_cvt_f32_ubyte2_e32 v100, v78
	v_cvt_f32_ubyte3_e32 v101, v78
	v_pk_fma_f32 v[76:77], v[54:55], v[96:97], v[76:77] op_sel_hi:[0,1,1]
	v_cvt_f32_ubyte0_e32 v102, v207
	v_cvt_f32_ubyte1_e32 v103, v207
	v_pk_fma_f32 v[68:69], v[54:55], v[100:101], v[68:69] op_sel_hi:[0,1,1]
	v_cvt_f32_ubyte2_e32 v126, v207
	v_cvt_f32_ubyte3_e32 v127, v207
	v_pk_fma_f32 v[62:63], v[54:55], v[102:103], v[62:63] op_sel_hi:[0,1,1]
	v_cvt_f32_ubyte0_e32 v96, v82
	v_cvt_f32_ubyte1_e32 v97, v82
	v_pk_fma_f32 v[60:61], v[54:55], v[126:127], v[60:61] op_sel_hi:[0,1,1]
	v_cvt_f32_ubyte2_e32 v100, v82
	v_cvt_f32_ubyte3_e32 v101, v82
	v_pk_fma_f32 v[90:91], v[54:55], v[96:97], v[90:91] op_sel:[1,0,0]
	v_cvt_f32_ubyte0_e32 v102, v208
	v_cvt_f32_ubyte1_e32 v103, v208
	v_pk_fma_f32 v[88:89], v[54:55], v[100:101], v[88:89] op_sel:[1,0,0]
	v_cvt_f32_ubyte2_e32 v126, v208
	v_cvt_f32_ubyte3_e32 v127, v208
	v_pk_fma_f32 v[84:85], v[54:55], v[102:103], v[84:85] op_sel:[1,0,0]
	v_cvt_f32_ubyte0_e32 v96, v86
	v_cvt_f32_ubyte1_e32 v97, v86
	v_pk_fma_f32 v[80:81], v[54:55], v[126:127], v[80:81] op_sel:[1,0,0]
	v_cvt_f32_ubyte2_e32 v100, v86
	v_cvt_f32_ubyte3_e32 v101, v86
	v_pk_fma_f32 v[76:77], v[54:55], v[96:97], v[76:77] op_sel:[1,0,0]
	v_cvt_f32_ubyte0_e32 v102, v209
	v_cvt_f32_ubyte1_e32 v103, v209
	v_pk_fma_f32 v[68:69], v[54:55], v[100:101], v[68:69] op_sel:[1,0,0]
	v_cvt_f32_ubyte2_e32 v126, v209
	v_cvt_f32_ubyte3_e32 v127, v209
	v_pk_fma_f32 v[62:63], v[54:55], v[102:103], v[62:63] op_sel:[1,0,0]
	v_pk_fma_f32 v[60:61], v[54:55], v[126:127], v[60:61] op_sel:[1,0,0]
	v_mov_b32_e32 v96, 0x3d800000
	v_mov_b32_e32 v97, 0x3d800000
	v_pk_add_f32 v[84:85], v[84:85], v[90:91] neg_lo:[0,1] neg_hi:[0,1]
	v_pk_add_f32 v[80:81], v[80:81], v[88:89] neg_lo:[0,1] neg_hi:[0,1]
	v_pk_add_f32 v[62:63], v[62:63], v[76:77] neg_lo:[0,1] neg_hi:[0,1]
	v_pk_add_f32 v[60:61], v[60:61], v[68:69] neg_lo:[0,1] neg_hi:[0,1]
	v_pk_mul_f32 v[84:85], v[84:85], v[96:97]
	v_pk_mul_f32 v[80:81], v[80:81], v[96:97]
	v_pk_mul_f32 v[62:63], v[62:63], v[96:97]
	v_pk_mul_f32 v[60:61], v[60:61], v[96:97]
	s_waitcnt lgkmcnt(0)
	s_branch .LBB0_979
